# relaxvm
# speedup vs baseline: 1.0196x; 1.0085x over previous
; #define STAGE(P, BASE, LD, br, kt) do { const char* _g = (const char*)((BASE) + (size_t)(br) * (LD) + (size_t)(kt) * 64); \
;     for (int _i = 0; _i < 2; ++_i) { int _b = tidx * 16 + _i * 8192; int _r, _c; stage_rc(_b, _r, _c); \
;       __builtin_amdgcn_global_load_lds((const unsigned*)(_g + (unsigned)((_r * (LD) + _c) * 2)), (unsigned*)((char*)(P) + _b), 16, 0, 0); } } while (0)
; #define LDA(dst, b, h) for (int m = 0; m < 4; ++m) for (int k = 0; k < 2; ++k) \
;     dst[m][k] = *reinterpret_cast<const bf16x8*>((char*)SA(b, h) + lds_byte(wr * 64 + m * 16 + fr, k * 32 + fq * 8))
; #define LDB(dst, b, h) for (int n = 0; n < 2; ++n) for (int k = 0; k < 2; ++k) \
;     dst[n][k] = *reinterpret_cast<const bf16x8*>((char*)SB(b, h) + lds_byte(wc * 32 + n * 16 + fr, k * 32 + fq * 8))
; #define MMA(ai, bj, At_, Bt_) do { __builtin_amdgcn_s_setprio(1); \
;     for (int k = 0; k < 2; ++k) for (int m = 0; m < 4; ++m) for (int n = 0; n < 2; ++n) \
;       acc[ai][bj][m][n] = __builtin_amdgcn_mfma_f32_16x16x32_bf16(At_[m][k], Bt_[n][k], acc[ai][bj][m][n], 0, 0, 0); \
;     __builtin_amdgcn_s_setprio(0); } while (0)
; #define WAIT_L(n) asm volatile("s_waitcnt lgkmcnt(" #n ")" ::: "memory")
; #define BAR __builtin_amdgcn_s_barrier()
; #define SCHED __builtin_amdgcn_sched_barrier(0)
; template <int EPI, int lda, int ldb, int N, int K>
; __device__ __forceinline__ void gemm_phase(const u16* __restrict__ A, const u16* __restrict__ Bt, const GemmEpi ep, int wv) {
;     ...
;       LDB(B0, 0, 0); SCHED; LDA(At, 0, 0); STAGE(SA(1, 1), Ab, lda, brow + HALF, t + 1);
;       WAIT_L(8); BAR; WAIT_L(0); MMA(0, 0, At, B0); BAR; SCHED;
;       LDB(B1, 0, 1); STAGE(SB(0, 0), Bt, ldb, bcol, t + 2);
;       BAR; WAIT_L(0); MMA(0, 1, At, B1); BAR;
;       LDA(At, 0, 1); STAGE(SA(0, 0), Ab, lda, brow, t + 2);
;       BAR; WAIT_L(0); MMA(1, 0, At, B0); BAR; SCHED;
.LBB0_53:
	ds_read_b128 v[172:175], v161
	ds_read_b128 v[176:179], v161 offset:1024
	ds_read_b128 v[180:183], v161 offset:2048
	ds_read_b128 v[184:187], v161 offset:3072
	v_add_u32_e32 v169, 0xc000, v148
	v_lshl_add_u64 v[236:237], v[136:137], 0, s[42:43]
	v_readfirstlane_b32 s45, v169
	v_add_u32_e32 v170, 0xe000, v148
	v_lshl_add_u64 v[162:163], v[236:237], 0, s[14:15]
	s_mov_b32 m0, s45
	v_lshl_add_u64 v[238:239], v[134:135], 0, s[42:43]
	v_readfirstlane_b32 s45, v170
	ds_read_b128 v[164:167], v152
	ds_read_b128 v[188:191], v152 offset:1024
	ds_read_b128 v[192:195], v151
	ds_read_b128 v[196:199], v151 offset:1024
	ds_read_b128 v[200:203], v150
	ds_read_b128 v[204:207], v150 offset:1024
	ds_read_b128 v[208:211], v149
	ds_read_b128 v[212:215], v149 offset:1024
	global_load_lds_dwordx4 v[162:163], off
	v_lshl_add_u64 v[162:163], v[238:239], 0, s[14:15]
	s_mov_b32 m0, s45
	s_nop 0
	global_load_lds_dwordx4 v[162:163], off
	s_waitcnt lgkmcnt(8)
	s_barrier
	s_waitcnt lgkmcnt(0)
	s_waitcnt lgkmcnt(0)
	v_mfma_f32_16x16x32_bf16 v[124:127], v[172:175], v[164:167], v[124:127]
	v_mfma_f32_16x16x32_bf16 v[120:123], v[180:183], v[164:167], v[120:123]
	v_mfma_f32_16x16x32_bf16 v[116:119], v[172:175], v[192:195], v[116:119]
	v_mfma_f32_16x16x32_bf16 v[112:115], v[180:183], v[192:195], v[112:115]
	v_mfma_f32_16x16x32_bf16 v[108:111], v[172:175], v[200:203], v[108:111]
	v_mfma_f32_16x16x32_bf16 v[104:107], v[180:183], v[200:203], v[104:107]
	v_mfma_f32_16x16x32_bf16 v[100:103], v[172:175], v[208:211], v[100:103]
	v_mfma_f32_16x16x32_bf16 v[96:99], v[180:183], v[208:211], v[96:99]
	v_mfma_f32_16x16x32_bf16 v[124:127], v[176:179], v[188:191], v[124:127]
	v_mfma_f32_16x16x32_bf16 v[120:123], v[184:187], v[188:191], v[120:123]
	v_mfma_f32_16x16x32_bf16 v[116:119], v[176:179], v[196:199], v[116:119]
	v_mfma_f32_16x16x32_bf16 v[112:115], v[184:187], v[196:199], v[112:115]
	v_mfma_f32_16x16x32_bf16 v[108:111], v[176:179], v[204:207], v[108:111]
	v_mfma_f32_16x16x32_bf16 v[104:107], v[184:187], v[204:207], v[104:107]
	v_mfma_f32_16x16x32_bf16 v[100:103], v[176:179], v[212:215], v[100:103]
	v_mfma_f32_16x16x32_bf16 v[96:99], v[184:187], v[212:215], v[96:99]
	s_barrier
	v_add_u32_e32 v162, s54, v153
	v_lshl_add_u64 v[240:241], v[140:141], 0, s[42:43]
	v_readfirstlane_b32 s45, v162
	v_add_u32_e32 v163, 0x2000, v162
	v_lshl_add_u64 v[232:233], v[240:241], 0, s[16:17]
	s_mov_b32 m0, s45
	v_lshl_add_u64 v[242:243], v[138:139], 0, s[42:43]
	v_readfirstlane_b32 s45, v163
	ds_read_b128 v[216:219], v160
	ds_read_b128 v[220:223], v160 offset:1024
	ds_read_b128 v[224:227], v160 offset:2048
	ds_read_b128 v[228:231], v160 offset:3072
	global_load_lds_dwordx4 v[232:233], off
	v_lshl_add_u64 v[232:233], v[242:243], 0, s[16:17]
	s_mov_b32 m0, s45
	s_nop 0
	global_load_lds_dwordx4 v[232:233], off
	s_waitcnt vmcnt(10)
	s_barrier
	s_waitcnt lgkmcnt(0)
	s_waitcnt lgkmcnt(0)
	v_mfma_f32_16x16x32_bf16 v[92:95], v[216:219], v[164:167], v[92:95]
	v_mfma_f32_16x16x32_bf16 v[88:91], v[224:227], v[164:167], v[88:91]
	v_mfma_f32_16x16x32_bf16 v[84:87], v[216:219], v[192:195], v[84:87]
	v_mfma_f32_16x16x32_bf16 v[80:83], v[224:227], v[192:195], v[80:83]
	v_mfma_f32_16x16x32_bf16 v[76:79], v[216:219], v[200:203], v[76:79]
	v_mfma_f32_16x16x32_bf16 v[72:75], v[224:227], v[200:203], v[72:75]
	v_mfma_f32_16x16x32_bf16 v[68:71], v[216:219], v[208:211], v[68:71]
	v_mfma_f32_16x16x32_bf16 v[64:67], v[224:227], v[208:211], v[64:67]
	v_mfma_f32_16x16x32_bf16 v[92:95], v[220:223], v[188:191], v[92:95]
	v_mfma_f32_16x16x32_bf16 v[88:91], v[228:231], v[188:191], v[88:91]
	v_mfma_f32_16x16x32_bf16 v[84:87], v[220:223], v[196:199], v[84:87]
	v_mfma_f32_16x16x32_bf16 v[80:83], v[228:231], v[196:199], v[80:83]
	v_mfma_f32_16x16x32_bf16 v[76:79], v[220:223], v[204:207], v[76:79]
	v_mfma_f32_16x16x32_bf16 v[72:75], v[228:231], v[204:207], v[72:75]
	v_mfma_f32_16x16x32_bf16 v[68:71], v[220:223], v[212:215], v[68:71]
	v_mfma_f32_16x16x32_bf16 v[64:67], v[228:231], v[212:215], v[64:67]
	v_readfirstlane_b32 s45, v148
	v_lshl_add_u64 v[164:165], v[236:237], 0, s[18:19]
	s_mov_b32 m0, s45
	s_barrier
	ds_read_b128 v[188:191], v152 offset:16384
	ds_read_b128 v[192:195], v152 offset:17408
	ds_read_b128 v[196:199], v151 offset:16384
	ds_read_b128 v[200:203], v151 offset:17408
	ds_read_b128 v[204:207], v150 offset:16384
	ds_read_b128 v[208:211], v150 offset:17408
	ds_read_b128 v[212:215], v149 offset:16384
	ds_read_b128 v[232:235], v149 offset:17408
	global_load_lds_dwordx4 v[164:165], off
	v_add_u32_e32 v164, 0x2000, v148
	v_lshl_add_u64 v[166:167], v[238:239], 0, s[18:19]
	v_readfirstlane_b32 s45, v164
	s_mov_b32 m0, s45
	s_nop 0
	global_load_lds_dwordx4 v[166:167], off
	s_barrier
	s_waitcnt lgkmcnt(0)
	s_waitcnt lgkmcnt(0)
	v_mfma_f32_16x16x32_bf16 v[60:63], v[172:175], v[188:191], v[60:63]
	v_mfma_f32_16x16x32_bf16 v[56:59], v[180:183], v[188:191], v[56:59]
	v_mfma_f32_16x16x32_bf16 v[52:55], v[172:175], v[196:199], v[52:55]
	v_mfma_f32_16x16x32_bf16 v[48:51], v[180:183], v[196:199], v[48:51]
	v_mfma_f32_16x16x32_bf16 v[44:47], v[172:175], v[204:207], v[44:47]
	v_mfma_f32_16x16x32_bf16 v[40:43], v[180:183], v[204:207], v[40:43]
	v_mfma_f32_16x16x32_bf16 v[36:39], v[172:175], v[212:215], v[36:39]
	v_mfma_f32_16x16x32_bf16 v[32:35], v[180:183], v[212:215], v[32:35]
	v_mfma_f32_16x16x32_bf16 v[60:63], v[176:179], v[192:195], v[60:63]
	v_mfma_f32_16x16x32_bf16 v[56:59], v[184:187], v[192:195], v[56:59]
	v_mfma_f32_16x16x32_bf16 v[52:55], v[176:179], v[200:203], v[52:55]
	v_mfma_f32_16x16x32_bf16 v[48:51], v[184:187], v[200:203], v[48:51]
	v_mfma_f32_16x16x32_bf16 v[44:47], v[176:179], v[208:211], v[44:47]
	v_mfma_f32_16x16x32_bf16 v[40:43], v[184:187], v[208:211], v[40:43]
	v_mfma_f32_16x16x32_bf16 v[36:39], v[176:179], v[232:235], v[36:39]
	v_mfma_f32_16x16x32_bf16 v[32:35], v[184:187], v[232:235], v[32:35]
	s_barrier
; #define STAGE(P, BASE, LD, br, kt) do { const char* _g = (const char*)((BASE) + (size_t)(br) * (LD) + (size_t)(kt) * 64); \
;     for (int _i = 0; _i < 2; ++_i) { int _b = tidx * 16 + _i * 8192; int _r, _c; stage_rc(_b, _r, _c); \
;       __builtin_amdgcn_global_load_lds((const unsigned*)(_g + (unsigned)((_r * (LD) + _c) * 2)), (unsigned*)((char*)(P) + _b), 16, 0, 0); } } while (0)
; #define LDA(dst, b, h) for (int m = 0; m < 4; ++m) for (int k = 0; k < 2; ++k) \
;     dst[m][k] = *reinterpret_cast<const bf16x8*>((char*)SA(b, h) + lds_byte(wr * 64 + m * 16 + fr, k * 32 + fq * 8))
; #define LDB(dst, b, h) for (int n = 0; n < 2; ++n) for (int k = 0; k < 2; ++k) \
;     dst[n][k] = *reinterpret_cast<const bf16x8*>((char*)SB(b, h) + lds_byte(wc * 32 + n * 16 + fr, k * 32 + fq * 8))
; #define MMA(ai, bj, At_, Bt_) do { __builtin_amdgcn_s_setprio(1); \
;     for (int k = 0; k < 2; ++k) for (int m = 0; m < 4; ++m) for (int n = 0; n < 2; ++n) \
;       acc[ai][bj][m][n] = __builtin_amdgcn_mfma_f32_16x16x32_bf16(At_[m][k], Bt_[n][k], acc[ai][bj][m][n], 0, 0, 0); \
;     __builtin_amdgcn_s_setprio(0); } while (0)
; #define WAIT_V(n) asm volatile("s_waitcnt vmcnt(" #n ")" ::: "memory")
; #define WAIT_L(n) asm volatile("s_waitcnt lgkmcnt(" #n ")" ::: "memory")
; #define BAR __builtin_amdgcn_s_barrier()
; #define SCHED __builtin_amdgcn_sched_barrier(0)
; template <int EPI, int lda, int ldb, int N, int K>
; __device__ __forceinline__ void gemm_phase(const u16* __restrict__ A, const u16* __restrict__ Bt, const GemmEpi ep, int wv) {
;     ...
;       STAGE(SB(0, 1), Bt, ldb, bcol + HALF, t + 2);
;       WAIT_V(6); BAR; MMA(1, 1, At, B1); BAR;
;       LDB(B0, 1, 0); SCHED; LDA(At, 1, 0); STAGE(SA(0, 1), Ab, lda, brow + HALF, t + 2);
;       WAIT_L(8); BAR; WAIT_L(0); MMA(0, 0, At, B0); BAR; SCHED;
;       LDB(B1, 1, 1); STAGE(SB(1, 0), Bt, ldb, bcol, t + 3);
;       BAR; WAIT_L(0); MMA(0, 1, At, B1); BAR;
;       LDA(At, 1, 1); STAGE(SA(1, 0), Ab, lda, brow, t + 3);
;       BAR; WAIT_L(0); MMA(1, 0, At, B0); BAR; SCHED;
	v_add_u32_e32 v165, s55, v153
	v_lshl_add_u64 v[166:167], v[240:241], 0, s[20:21]
	v_readfirstlane_b32 s45, v165
	s_mov_b32 m0, s45
	v_lshl_add_u64 v[172:173], v[242:243], 0, s[20:21]
	global_load_lds_dwordx4 v[166:167], off
	v_add_u32_e32 v166, 0x2000, v165
	s_nop 0
	v_readfirstlane_b32 s45, v166
	s_mov_b32 m0, s45
	s_nop 0
	global_load_lds_dwordx4 v[172:173], off
	s_waitcnt vmcnt(8)
	s_barrier
	v_mfma_f32_16x16x32_bf16 v[28:31], v[216:219], v[188:191], v[28:31]
	v_mfma_f32_16x16x32_bf16 v[24:27], v[224:227], v[188:191], v[24:27]
	v_mfma_f32_16x16x32_bf16 v[20:23], v[216:219], v[196:199], v[20:23]
	v_mfma_f32_16x16x32_bf16 v[16:19], v[224:227], v[196:199], v[16:19]
	v_mfma_f32_16x16x32_bf16 v[12:15], v[216:219], v[204:207], v[12:15]
	v_mfma_f32_16x16x32_bf16 v[8:11], v[224:227], v[204:207], v[8:11]
	v_mfma_f32_16x16x32_bf16 v[4:7], v[216:219], v[212:215], v[4:7]
	v_mfma_f32_16x16x32_bf16 v[0:3], v[224:227], v[212:215], v[0:3]
	v_mfma_f32_16x16x32_bf16 v[28:31], v[220:223], v[192:195], v[28:31]
	v_mfma_f32_16x16x32_bf16 v[24:27], v[228:231], v[192:195], v[24:27]
	v_mfma_f32_16x16x32_bf16 v[20:23], v[220:223], v[200:203], v[20:23]
	v_mfma_f32_16x16x32_bf16 v[16:19], v[228:231], v[200:203], v[16:19]
	v_mfma_f32_16x16x32_bf16 v[12:15], v[220:223], v[208:211], v[12:15]
	v_mfma_f32_16x16x32_bf16 v[8:11], v[228:231], v[208:211], v[8:11]
	v_mfma_f32_16x16x32_bf16 v[4:7], v[220:223], v[232:235], v[4:7]
	v_mfma_f32_16x16x32_bf16 v[0:3], v[228:231], v[232:235], v[0:3]
	s_barrier
	ds_read_b128 v[172:175], v156
	ds_read_b128 v[176:179], v156 offset:1024
	ds_read_b128 v[180:183], v156 offset:2048
	ds_read_b128 v[184:187], v156 offset:3072
	v_add_u32_e32 v167, 0x4000, v148
	v_add_u32_e32 v168, 0x6000, v148
	v_readfirstlane_b32 s45, v167
	v_lshl_add_u64 v[220:221], v[236:237], 0, s[22:23]
	s_mov_b32 m0, s45
	v_readfirstlane_b32 s45, v168
	ds_read_b128 v[188:191], v152 offset:32768
	ds_read_b128 v[192:195], v152 offset:33792
	ds_read_b128 v[196:199], v151 offset:32768
	ds_read_b128 v[200:203], v151 offset:33792
	ds_read_b128 v[204:207], v150 offset:32768
	ds_read_b128 v[208:211], v150 offset:33792
	ds_read_b128 v[212:215], v149 offset:32768
	ds_read_b128 v[216:219], v149 offset:33792
	global_load_lds_dwordx4 v[220:221], off
	v_lshl_add_u64 v[220:221], v[238:239], 0, s[22:23]
	s_mov_b32 m0, s45
	s_nop 0
	global_load_lds_dwordx4 v[220:221], off
	s_waitcnt lgkmcnt(8)
	s_barrier
	s_waitcnt lgkmcnt(0)
	s_waitcnt lgkmcnt(0)
	v_mfma_f32_16x16x32_bf16 v[124:127], v[172:175], v[188:191], v[124:127]
	v_mfma_f32_16x16x32_bf16 v[120:123], v[180:183], v[188:191], v[120:123]
	v_mfma_f32_16x16x32_bf16 v[116:119], v[172:175], v[196:199], v[116:119]
	v_mfma_f32_16x16x32_bf16 v[112:115], v[180:183], v[196:199], v[112:115]
	v_mfma_f32_16x16x32_bf16 v[108:111], v[172:175], v[204:207], v[108:111]
	v_mfma_f32_16x16x32_bf16 v[104:107], v[180:183], v[204:207], v[104:107]
	v_mfma_f32_16x16x32_bf16 v[100:103], v[172:175], v[212:215], v[100:103]
	v_mfma_f32_16x16x32_bf16 v[96:99], v[180:183], v[212:215], v[96:99]
	v_mfma_f32_16x16x32_bf16 v[124:127], v[176:179], v[192:195], v[124:127]
	v_mfma_f32_16x16x32_bf16 v[120:123], v[184:187], v[192:195], v[120:123]
	v_mfma_f32_16x16x32_bf16 v[116:119], v[176:179], v[200:203], v[116:119]
	v_mfma_f32_16x16x32_bf16 v[112:115], v[184:187], v[200:203], v[112:115]
	v_mfma_f32_16x16x32_bf16 v[108:111], v[176:179], v[208:211], v[108:111]
	v_mfma_f32_16x16x32_bf16 v[104:107], v[184:187], v[208:211], v[104:107]
	v_mfma_f32_16x16x32_bf16 v[100:103], v[176:179], v[216:219], v[100:103]
	v_mfma_f32_16x16x32_bf16 v[96:99], v[184:187], v[216:219], v[96:99]
	s_barrier
	v_readfirstlane_b32 s45, v155
	v_add_u32_e32 v171, 0x2000, v155
	v_lshl_add_u64 v[244:245], v[240:241], 0, s[24:25]
	s_mov_b32 m0, s45
	v_readfirstlane_b32 s45, v171
	ds_read_b128 v[220:223], v154
	ds_read_b128 v[224:227], v154 offset:1024
	ds_read_b128 v[228:231], v154 offset:2048
	ds_read_b128 v[232:235], v154 offset:3072
	global_load_lds_dwordx4 v[244:245], off
	v_lshl_add_u64 v[244:245], v[242:243], 0, s[24:25]
	s_mov_b32 m0, s45
	s_nop 0
	global_load_lds_dwordx4 v[244:245], off
	s_waitcnt vmcnt(10)
	s_barrier
	s_waitcnt lgkmcnt(0)
	s_waitcnt lgkmcnt(0)
	v_mfma_f32_16x16x32_bf16 v[92:95], v[220:223], v[188:191], v[92:95]
	v_mfma_f32_16x16x32_bf16 v[88:91], v[228:231], v[188:191], v[88:91]
	v_mfma_f32_16x16x32_bf16 v[84:87], v[220:223], v[196:199], v[84:87]
	v_mfma_f32_16x16x32_bf16 v[80:83], v[228:231], v[196:199], v[80:83]
	v_mfma_f32_16x16x32_bf16 v[76:79], v[220:223], v[204:207], v[76:79]
	v_mfma_f32_16x16x32_bf16 v[72:75], v[228:231], v[204:207], v[72:75]
	v_mfma_f32_16x16x32_bf16 v[68:71], v[220:223], v[212:215], v[68:71]
	v_mfma_f32_16x16x32_bf16 v[64:67], v[228:231], v[212:215], v[64:67]
	v_mfma_f32_16x16x32_bf16 v[92:95], v[224:227], v[192:195], v[92:95]
	v_mfma_f32_16x16x32_bf16 v[88:91], v[232:235], v[192:195], v[88:91]
	v_mfma_f32_16x16x32_bf16 v[84:87], v[224:227], v[200:203], v[84:87]
	v_mfma_f32_16x16x32_bf16 v[80:83], v[232:235], v[200:203], v[80:83]
	v_mfma_f32_16x16x32_bf16 v[76:79], v[224:227], v[208:211], v[76:79]
	v_mfma_f32_16x16x32_bf16 v[72:75], v[232:235], v[208:211], v[72:75]
	v_mfma_f32_16x16x32_bf16 v[68:71], v[224:227], v[216:219], v[68:71]
	v_mfma_f32_16x16x32_bf16 v[64:67], v[232:235], v[216:219], v[64:67]
	v_readfirstlane_b32 s45, v157
	v_lshl_add_u64 v[236:237], v[236:237], 0, s[26:27]
	s_mov_b32 m0, s45
	v_readfirstlane_b32 s45, v158
	s_barrier
; #define STAGE(P, BASE, LD, br, kt) do { const char* _g = (const char*)((BASE) + (size_t)(br) * (LD) + (size_t)(kt) * 64); \
;     for (int _i = 0; _i < 2; ++_i) { int _b = tidx * 16 + _i * 8192; int _r, _c; stage_rc(_b, _r, _c); \
;       __builtin_amdgcn_global_load_lds((const unsigned*)(_g + (unsigned)((_r * (LD) + _c) * 2)), (unsigned*)((char*)(P) + _b), 16, 0, 0); } } while (0)
; #define LDA(dst, b, h) for (int m = 0; m < 4; ++m) for (int k = 0; k < 2; ++k) \
;     dst[m][k] = *reinterpret_cast<const bf16x8*>((char*)SA(b, h) + lds_byte(wr * 64 + m * 16 + fr, k * 32 + fq * 8))
; #define LDB(dst, b, h) for (int n = 0; n < 2; ++n) for (int k = 0; k < 2; ++k) \
;     dst[n][k] = *reinterpret_cast<const bf16x8*>((char*)SB(b, h) + lds_byte(wc * 32 + n * 16 + fr, k * 32 + fq * 8))
; #define MMA(ai, bj, At_, Bt_) do { __builtin_amdgcn_s_setprio(1); \
;     for (int k = 0; k < 2; ++k) for (int m = 0; m < 4; ++m) for (int n = 0; n < 2; ++n) \
;       acc[ai][bj][m][n] = __builtin_amdgcn_mfma_f32_16x16x32_bf16(At_[m][k], Bt_[n][k], acc[ai][bj][m][n], 0, 0, 0); \
;     __builtin_amdgcn_s_setprio(0); } while (0)
; #define WAIT_V(n) asm volatile("s_waitcnt vmcnt(" #n ")" ::: "memory")
; #define WAIT_L(n) asm volatile("s_waitcnt lgkmcnt(" #n ")" ::: "memory")
; #define BAR __builtin_amdgcn_s_barrier()
; #define SCHED __builtin_amdgcn_sched_barrier(0)
; template <int EPI, int lda, int ldb, int N, int K>
; __device__ __forceinline__ void gemm_phase(const u16* __restrict__ A, const u16* __restrict__ Bt, const GemmEpi ep, int wv) {
;     ...
;       LDA(At, 1, 1); STAGE(SA(1, 0), Ab, lda, brow, t + 3);
;       BAR; WAIT_L(0); MMA(1, 0, At, B0); BAR; SCHED;
;       STAGE(SB(1, 1), Bt, ldb, bcol + HALF, t + 3);
;       WAIT_V(6); BAR; MMA(1, 1, At, B1); BAR;
;     }
;     { LDB(B0, 0, 0); LDA(At, 0, 0); STAGE(SA(1, 1), Ab, lda, brow + HALF, nt - 1);
;       BAR; WAIT_L(0); MMA(0, 0, At, B0); BAR;
	ds_read_b128 v[188:191], v152 offset:49152
	ds_read_b128 v[192:195], v152 offset:50176
	ds_read_b128 v[196:199], v151 offset:49152
	ds_read_b128 v[200:203], v151 offset:50176
	ds_read_b128 v[204:207], v150 offset:49152
	ds_read_b128 v[208:211], v150 offset:50176
	ds_read_b128 v[212:215], v149 offset:49152
	ds_read_b128 v[216:219], v149 offset:50176
	global_load_lds_dwordx4 v[236:237], off
	v_lshl_add_u64 v[236:237], v[238:239], 0, s[26:27]
	s_mov_b32 m0, s45
	s_nop 0
	global_load_lds_dwordx4 v[236:237], off
	s_barrier
	s_waitcnt lgkmcnt(0)
	s_waitcnt lgkmcnt(0)
	v_mfma_f32_16x16x32_bf16 v[60:63], v[172:175], v[188:191], v[60:63]
	v_mfma_f32_16x16x32_bf16 v[56:59], v[180:183], v[188:191], v[56:59]
	v_mfma_f32_16x16x32_bf16 v[52:55], v[172:175], v[196:199], v[52:55]
	v_mfma_f32_16x16x32_bf16 v[48:51], v[180:183], v[196:199], v[48:51]
	v_mfma_f32_16x16x32_bf16 v[44:47], v[172:175], v[204:207], v[44:47]
	v_mfma_f32_16x16x32_bf16 v[40:43], v[180:183], v[204:207], v[40:43]
	v_mfma_f32_16x16x32_bf16 v[36:39], v[172:175], v[212:215], v[36:39]
	v_mfma_f32_16x16x32_bf16 v[32:35], v[180:183], v[212:215], v[32:35]
	v_mfma_f32_16x16x32_bf16 v[60:63], v[176:179], v[192:195], v[60:63]
	v_mfma_f32_16x16x32_bf16 v[56:59], v[184:187], v[192:195], v[56:59]
	v_mfma_f32_16x16x32_bf16 v[52:55], v[176:179], v[200:203], v[52:55]
	v_mfma_f32_16x16x32_bf16 v[48:51], v[184:187], v[200:203], v[48:51]
	v_mfma_f32_16x16x32_bf16 v[44:47], v[176:179], v[208:211], v[44:47]
	v_mfma_f32_16x16x32_bf16 v[40:43], v[184:187], v[208:211], v[40:43]
	v_mfma_f32_16x16x32_bf16 v[36:39], v[176:179], v[216:219], v[36:39]
	v_mfma_f32_16x16x32_bf16 v[32:35], v[184:187], v[216:219], v[32:35]
	s_barrier
	v_readfirstlane_b32 s45, v159
	v_add_u32_e32 v171, 0x2000, v159
	v_lshl_add_u64 v[172:173], v[240:241], 0, s[34:35]
	s_mov_b32 m0, s45
	v_readfirstlane_b32 s45, v171
	global_load_lds_dwordx4 v[172:173], off
	v_lshl_add_u64 v[172:173], v[242:243], 0, s[34:35]
	s_mov_b32 m0, s45
	s_nop 0
	global_load_lds_dwordx4 v[172:173], off
	s_waitcnt vmcnt(8)
	s_barrier
	v_mfma_f32_16x16x32_bf16 v[28:31], v[220:223], v[188:191], v[28:31]
	v_mfma_f32_16x16x32_bf16 v[24:27], v[228:231], v[188:191], v[24:27]
	v_mfma_f32_16x16x32_bf16 v[20:23], v[220:223], v[196:199], v[20:23]
	v_mfma_f32_16x16x32_bf16 v[16:19], v[228:231], v[196:199], v[16:19]
	v_mfma_f32_16x16x32_bf16 v[12:15], v[220:223], v[204:207], v[12:15]
	v_mfma_f32_16x16x32_bf16 v[8:11], v[228:231], v[204:207], v[8:11]
	v_mfma_f32_16x16x32_bf16 v[4:7], v[220:223], v[212:215], v[4:7]
	v_mfma_f32_16x16x32_bf16 v[0:3], v[228:231], v[212:215], v[0:3]
	v_mfma_f32_16x16x32_bf16 v[28:31], v[224:227], v[192:195], v[28:31]
	v_mfma_f32_16x16x32_bf16 v[24:27], v[232:235], v[192:195], v[24:27]
	v_mfma_f32_16x16x32_bf16 v[20:23], v[224:227], v[200:203], v[20:23]
	v_mfma_f32_16x16x32_bf16 v[16:19], v[232:235], v[200:203], v[16:19]
	v_mfma_f32_16x16x32_bf16 v[12:15], v[224:227], v[208:211], v[12:15]
	v_mfma_f32_16x16x32_bf16 v[8:11], v[232:235], v[208:211], v[8:11]
	v_mfma_f32_16x16x32_bf16 v[4:7], v[224:227], v[216:219], v[4:7]
	v_mfma_f32_16x16x32_bf16 v[0:3], v[232:235], v[216:219], v[0:3]
	s_add_i32 s44, s44, 2
	s_add_u32 s42, s42, 0x100
	s_addc_u32 s43, s43, 0
	s_cmp_gt_u32 s44, 27
	s_barrier
	s_cbranch_scc0 .LBB0_53
	s_add_i32 s42, s38, 0x80
	s_mul_hi_i32 s43, s42, 0x1080
	s_mulk_i32 s42, 0x1080
	s_add_u32 s42, s51, s42
	s_addc_u32 s43, s52, s43
	v_lshl_add_u64 v[158:159], s[42:43], 0, v[128:129]
	v_readfirstlane_b32 s44, v169
	v_lshl_add_u64 v[158:159], v[158:159], 0, s[36:37]
	s_mov_b32 m0, s44
	ds_read_b128 v[134:137], v161
	ds_read_b128 v[138:141], v161 offset:1024
	ds_read_b128 v[172:175], v161 offset:2048
	ds_read_b128 v[176:179], v161 offset:3072
	ds_read_b128 v[180:183], v152
	ds_read_b128 v[184:187], v152 offset:1024
	ds_read_b128 v[188:191], v151
	ds_read_b128 v[192:195], v151 offset:1024
	ds_read_b128 v[196:199], v150
	ds_read_b128 v[200:203], v150 offset:1024
	ds_read_b128 v[204:207], v149
	ds_read_b128 v[208:211], v149 offset:1024
	global_load_lds_dwordx4 v[158:159], off
	v_lshl_add_u64 v[158:159], s[42:43], 0, v[132:133]
	v_readfirstlane_b32 s42, v170
	v_lshl_add_u64 v[158:159], v[158:159], 0, s[36:37]
	s_mov_b32 m0, s42
	s_nop 0
	global_load_lds_dwordx4 v[158:159], off
	s_barrier
	s_waitcnt lgkmcnt(0)
	s_waitcnt lgkmcnt(0)
	v_mfma_f32_16x16x32_bf16 v[124:127], v[134:137], v[180:183], v[124:127]
	v_mfma_f32_16x16x32_bf16 v[120:123], v[172:175], v[180:183], v[120:123]
	v_mfma_f32_16x16x32_bf16 v[116:119], v[134:137], v[188:191], v[116:119]
	v_mfma_f32_16x16x32_bf16 v[112:115], v[172:175], v[188:191], v[112:115]
	v_mfma_f32_16x16x32_bf16 v[108:111], v[134:137], v[196:199], v[108:111]
	v_mfma_f32_16x16x32_bf16 v[104:107], v[172:175], v[196:199], v[104:107]
	v_mfma_f32_16x16x32_bf16 v[100:103], v[134:137], v[204:207], v[100:103]
	v_mfma_f32_16x16x32_bf16 v[96:99], v[172:175], v[204:207], v[96:99]
	v_mfma_f32_16x16x32_bf16 v[124:127], v[138:141], v[184:187], v[124:127]
	v_mfma_f32_16x16x32_bf16 v[120:123], v[176:179], v[184:187], v[120:123]
	v_mfma_f32_16x16x32_bf16 v[116:119], v[138:141], v[192:195], v[116:119]
	v_mfma_f32_16x16x32_bf16 v[112:115], v[176:179], v[192:195], v[112:115]
	v_mfma_f32_16x16x32_bf16 v[108:111], v[138:141], v[200:203], v[108:111]
	v_mfma_f32_16x16x32_bf16 v[104:107], v[176:179], v[200:203], v[104:107]
	v_mfma_f32_16x16x32_bf16 v[100:103], v[138:141], v[208:211], v[100:103]
	v_mfma_f32_16x16x32_bf16 v[96:99], v[176:179], v[208:211], v[96:99]
	s_barrier
	ds_read_b128 v[212:215], v160
	ds_read_b128 v[216:219], v160 offset:1024
	ds_read_b128 v[220:223], v160 offset:2048
	ds_read_b128 v[158:161], v160 offset:3072
	s_waitcnt vmcnt(8)
	s_barrier
; #define LDA(dst, b, h) for (int m = 0; m < 4; ++m) for (int k = 0; k < 2; ++k) \
;     dst[m][k] = *reinterpret_cast<const bf16x8*>((char*)SA(b, h) + lds_byte(wr * 64 + m * 16 + fr, k * 32 + fq * 8))
; #define LDB(dst, b, h) for (int n = 0; n < 2; ++n) for (int k = 0; k < 2; ++k) \
;     dst[n][k] = *reinterpret_cast<const bf16x8*>((char*)SB(b, h) + lds_byte(wc * 32 + n * 16 + fr, k * 32 + fq * 8))
; #define MMA(ai, bj, At_, Bt_) do { __builtin_amdgcn_s_setprio(1); \
;     for (int k = 0; k < 2; ++k) for (int m = 0; m < 4; ++m) for (int n = 0; n < 2; ++n) \
;       acc[ai][bj][m][n] = __builtin_amdgcn_mfma_f32_16x16x32_bf16(At_[m][k], Bt_[n][k], acc[ai][bj][m][n], 0, 0, 0); \
;     __builtin_amdgcn_s_setprio(0); } while (0)
; #define WAIT_V(n) asm volatile("s_waitcnt vmcnt(" #n ")" ::: "memory")
; #define WAIT_L(n) asm volatile("s_waitcnt lgkmcnt(" #n ")" ::: "memory")
; #define BAR __builtin_amdgcn_s_barrier()
; template <int EPI, int lda, int ldb, int N, int K>
; __device__ __forceinline__ void gemm_phase(const u16* __restrict__ A, const u16* __restrict__ Bt, const GemmEpi ep, int wv) {
;     ...
;       LDB(B1, 0, 1); BAR; WAIT_L(0); MMA(0, 1, At, B1); BAR;
;       LDA(At, 0, 1); WAIT_V(4); BAR; WAIT_L(0); MMA(1, 0, At, B0); MMA(1, 1, At, B1); BAR; }
;     { LDB(B0, 1, 0); LDA(At, 1, 0); WAIT_V(2); BAR; WAIT_L(0); MMA(0, 0, At, B0); BAR;
	s_waitcnt lgkmcnt(0)
	s_waitcnt lgkmcnt(0)
	v_mfma_f32_16x16x32_bf16 v[92:95], v[212:215], v[180:183], v[92:95]
	v_mfma_f32_16x16x32_bf16 v[88:91], v[220:223], v[180:183], v[88:91]
	v_mfma_f32_16x16x32_bf16 v[76:79], v[212:215], v[196:199], v[76:79]
	v_mfma_f32_16x16x32_bf16 v[72:75], v[220:223], v[196:199], v[72:75]
	v_mfma_f32_16x16x32_bf16 v[84:87], v[212:215], v[188:191], v[84:87]
	v_mfma_f32_16x16x32_bf16 v[80:83], v[220:223], v[188:191], v[80:83]
	v_mfma_f32_16x16x32_bf16 v[68:71], v[212:215], v[204:207], v[68:71]
	v_mfma_f32_16x16x32_bf16 v[64:67], v[220:223], v[204:207], v[64:67]
	v_mfma_f32_16x16x32_bf16 v[92:95], v[216:219], v[184:187], v[92:95]
	v_mfma_f32_16x16x32_bf16 v[88:91], v[158:161], v[184:187], v[88:91]
	v_mfma_f32_16x16x32_bf16 v[76:79], v[216:219], v[200:203], v[76:79]
	v_mfma_f32_16x16x32_bf16 v[72:75], v[158:161], v[200:203], v[72:75]
	v_mfma_f32_16x16x32_bf16 v[180:183], v[216:219], v[192:195], v[84:87]
	v_mfma_f32_16x16x32_bf16 v[184:187], v[158:161], v[192:195], v[80:83]
	v_mfma_f32_16x16x32_bf16 v[188:191], v[216:219], v[208:211], v[68:71]
	v_mfma_f32_16x16x32_bf16 v[192:195], v[158:161], v[208:211], v[64:67]
	s_barrier
	s_nop 0
	ds_read_b128 v[64:67], v152 offset:16384
	ds_read_b128 v[68:71], v152 offset:17408
	ds_read_b128 v[80:83], v151 offset:16384
	ds_read_b128 v[84:87], v151 offset:17408
	ds_read_b128 v[196:199], v150 offset:16384
	ds_read_b128 v[200:203], v150 offset:17408
	ds_read_b128 v[204:207], v149 offset:16384
	ds_read_b128 v[208:211], v149 offset:17408
	s_waitcnt vmcnt(4)
	s_barrier
	s_waitcnt lgkmcnt(0)
	s_waitcnt lgkmcnt(0)
	v_mfma_f32_16x16x32_bf16 v[60:63], v[134:137], v[64:67], v[60:63]
	v_mfma_f32_16x16x32_bf16 v[56:59], v[172:175], v[64:67], v[56:59]
	v_mfma_f32_16x16x32_bf16 v[52:55], v[134:137], v[80:83], v[52:55]
	v_mfma_f32_16x16x32_bf16 v[48:51], v[172:175], v[80:83], v[48:51]
	v_mfma_f32_16x16x32_bf16 v[44:47], v[134:137], v[196:199], v[44:47]
	v_mfma_f32_16x16x32_bf16 v[40:43], v[172:175], v[196:199], v[40:43]
	v_mfma_f32_16x16x32_bf16 v[36:39], v[134:137], v[204:207], v[36:39]
	v_mfma_f32_16x16x32_bf16 v[32:35], v[172:175], v[204:207], v[32:35]
	v_mfma_f32_16x16x32_bf16 v[60:63], v[138:141], v[68:71], v[60:63]
	v_mfma_f32_16x16x32_bf16 v[56:59], v[176:179], v[68:71], v[56:59]
	v_mfma_f32_16x16x32_bf16 v[52:55], v[138:141], v[84:87], v[52:55]
	v_mfma_f32_16x16x32_bf16 v[48:51], v[176:179], v[84:87], v[48:51]
	v_mfma_f32_16x16x32_bf16 v[44:47], v[138:141], v[200:203], v[44:47]
	v_mfma_f32_16x16x32_bf16 v[40:43], v[176:179], v[200:203], v[40:43]
	v_mfma_f32_16x16x32_bf16 v[36:39], v[138:141], v[208:211], v[36:39]
	v_mfma_f32_16x16x32_bf16 v[32:35], v[176:179], v[208:211], v[32:35]
	v_mfma_f32_16x16x32_bf16 v[28:31], v[212:215], v[64:67], v[28:31]
	v_mfma_f32_16x16x32_bf16 v[24:27], v[220:223], v[64:67], v[24:27]
	v_mfma_f32_16x16x32_bf16 v[12:15], v[212:215], v[196:199], v[12:15]
	v_mfma_f32_16x16x32_bf16 v[8:11], v[220:223], v[196:199], v[8:11]
	v_mfma_f32_16x16x32_bf16 v[20:23], v[212:215], v[80:83], v[20:23]
	v_mfma_f32_16x16x32_bf16 v[16:19], v[220:223], v[80:83], v[16:19]
	v_mfma_f32_16x16x32_bf16 v[4:7], v[212:215], v[204:207], v[4:7]
	v_mfma_f32_16x16x32_bf16 v[0:3], v[220:223], v[204:207], v[0:3]
	v_mfma_f32_16x16x32_bf16 v[28:31], v[216:219], v[68:71], v[28:31]
	v_mfma_f32_16x16x32_bf16 v[24:27], v[158:161], v[68:71], v[24:27]
	v_mfma_f32_16x16x32_bf16 v[12:15], v[216:219], v[200:203], v[12:15]
	v_mfma_f32_16x16x32_bf16 v[8:11], v[158:161], v[200:203], v[8:11]
	v_mfma_f32_16x16x32_bf16 v[134:137], v[216:219], v[84:87], v[20:23]
	v_mfma_f32_16x16x32_bf16 v[138:141], v[158:161], v[84:87], v[16:19]
	v_mfma_f32_16x16x32_bf16 v[170:173], v[216:219], v[208:211], v[4:7]
	v_mfma_f32_16x16x32_bf16 v[158:161], v[158:161], v[208:211], v[0:3]
	s_barrier
	s_nop 0
	ds_read_b128 v[0:3], v156
	ds_read_b128 v[4:7], v156 offset:1024
	ds_read_b128 v[16:19], v156 offset:2048
	ds_read_b128 v[174:177], v156 offset:3072
	ds_read_b128 v[20:23], v152 offset:32768
	ds_read_b128 v[196:199], v152 offset:33792
	ds_read_b128 v[200:203], v151 offset:32768
	ds_read_b128 v[204:207], v151 offset:33792
	ds_read_b128 v[208:211], v150 offset:32768
	ds_read_b128 v[212:215], v150 offset:33792
	ds_read_b128 v[216:219], v149 offset:32768
	ds_read_b128 v[220:223], v149 offset:33792
	s_waitcnt vmcnt(2)
	s_barrier
; #define LDA(dst, b, h) for (int m = 0; m < 4; ++m) for (int k = 0; k < 2; ++k) \
;     dst[m][k] = *reinterpret_cast<const bf16x8*>((char*)SA(b, h) + lds_byte(wr * 64 + m * 16 + fr, k * 32 + fq * 8))
; #define LDB(dst, b, h) for (int n = 0; n < 2; ++n) for (int k = 0; k < 2; ++k) \
;     dst[n][k] = *reinterpret_cast<const bf16x8*>((char*)SB(b, h) + lds_byte(wc * 32 + n * 16 + fr, k * 32 + fq * 8))
; #define MMA(ai, bj, At_, Bt_) do { __builtin_amdgcn_s_setprio(1); \
;     for (int k = 0; k < 2; ++k) for (int m = 0; m < 4; ++m) for (int n = 0; n < 2; ++n) \
;       acc[ai][bj][m][n] = __builtin_amdgcn_mfma_f32_16x16x32_bf16(At_[m][k], Bt_[n][k], acc[ai][bj][m][n], 0, 0, 0); \
;     __builtin_amdgcn_s_setprio(0); } while (0)
; #define WAIT_V(n) asm volatile("s_waitcnt vmcnt(" #n ")" ::: "memory")
; #define WAIT_L(n) asm volatile("s_waitcnt lgkmcnt(" #n ")" ::: "memory")
; #define BAR __builtin_amdgcn_s_barrier()
; template <int EPI, int lda, int ldb, int N, int K>
; __device__ __forceinline__ void gemm_phase(const u16* __restrict__ A, const u16* __restrict__ Bt, const GemmEpi ep, int wv) {
;     ...
;     { LDB(B0, 1, 0); LDA(At, 1, 0); WAIT_V(2); BAR; WAIT_L(0); MMA(0, 0, At, B0); BAR;
;       LDB(B1, 1, 1); WAIT_V(0); BAR; WAIT_L(0); MMA(0, 1, At, B1); BAR;
;       LDA(At, 1, 1); BAR; WAIT_L(0); MMA(1, 0, At, B0); MMA(1, 1, At, B1); BAR; }
;     if (wr == 0) BAR;
	s_waitcnt lgkmcnt(0)
	s_waitcnt lgkmcnt(0)
	v_mfma_f32_16x16x32_bf16 v[64:67], v[0:3], v[20:23], v[124:127]
	v_mfma_f32_16x16x32_bf16 v[68:71], v[16:19], v[20:23], v[120:123]
	v_mfma_f32_16x16x32_bf16 v[80:83], v[0:3], v[200:203], v[116:119]
	v_mfma_f32_16x16x32_bf16 v[84:87], v[16:19], v[200:203], v[112:115]
	v_mfma_f32_16x16x32_bf16 v[108:111], v[0:3], v[208:211], v[108:111]
	v_mfma_f32_16x16x32_bf16 v[104:107], v[16:19], v[208:211], v[104:107]
	v_mfma_f32_16x16x32_bf16 v[120:123], v[0:3], v[216:219], v[100:103]
	v_mfma_f32_16x16x32_bf16 v[124:127], v[16:19], v[216:219], v[96:99]
	v_mfma_f32_16x16x32_bf16 v[116:119], v[4:7], v[196:199], v[64:67]
	v_mfma_f32_16x16x32_bf16 v[112:115], v[174:177], v[196:199], v[68:71]
	v_mfma_f32_16x16x32_bf16 v[100:103], v[4:7], v[204:207], v[80:83]
	v_mfma_f32_16x16x32_bf16 v[96:99], v[174:177], v[204:207], v[84:87]
	v_mfma_f32_16x16x32_bf16 v[84:87], v[4:7], v[212:215], v[108:111]
	v_mfma_f32_16x16x32_bf16 v[80:83], v[174:177], v[212:215], v[104:107]
	v_mfma_f32_16x16x32_bf16 v[68:71], v[4:7], v[220:223], v[120:123]
	v_mfma_f32_16x16x32_bf16 v[64:67], v[174:177], v[220:223], v[124:127]
	s_barrier
	ds_read_b128 v[224:227], v154
	ds_read_b128 v[228:231], v154 offset:1024
	ds_read_b128 v[232:235], v154 offset:2048
	ds_read_b128 v[154:157], v154 offset:3072
	s_waitcnt vmcnt(0)
	s_barrier
	s_waitcnt lgkmcnt(0)
	s_waitcnt lgkmcnt(0)
	v_mfma_f32_16x16x32_bf16 v[92:95], v[224:227], v[20:23], v[92:95]
	v_mfma_f32_16x16x32_bf16 v[20:23], v[232:235], v[20:23], v[88:91]
	v_mfma_f32_16x16x32_bf16 v[88:91], v[224:227], v[200:203], v[180:183]
	v_mfma_f32_16x16x32_bf16 v[104:107], v[232:235], v[200:203], v[184:187]
	v_mfma_f32_16x16x32_bf16 v[76:79], v[224:227], v[208:211], v[76:79]
	v_mfma_f32_16x16x32_bf16 v[72:75], v[232:235], v[208:211], v[72:75]
	v_mfma_f32_16x16x32_bf16 v[178:181], v[224:227], v[216:219], v[188:191]
	v_mfma_f32_16x16x32_bf16 v[182:185], v[232:235], v[216:219], v[192:195]
	v_mfma_f32_16x16x32_bf16 v[124:127], v[228:231], v[196:199], v[92:95]
	v_mfma_f32_16x16x32_bf16 v[120:123], v[154:157], v[196:199], v[20:23]
	v_mfma_f32_16x16x32_bf16 v[108:111], v[228:231], v[204:207], v[88:91]
	v_mfma_f32_16x16x32_bf16 v[104:107], v[154:157], v[204:207], v[104:107]
	v_mfma_f32_16x16x32_bf16 v[92:95], v[228:231], v[212:215], v[76:79]
	v_mfma_f32_16x16x32_bf16 v[88:91], v[154:157], v[212:215], v[72:75]
	v_mfma_f32_16x16x32_bf16 v[76:79], v[228:231], v[220:223], v[178:181]
	v_mfma_f32_16x16x32_bf16 v[72:75], v[154:157], v[220:223], v[182:185]
	s_barrier
	ds_read_b128 v[178:181], v152 offset:49152
	ds_read_b128 v[182:185], v152 offset:50176
	ds_read_b128 v[186:189], v151 offset:49152
	ds_read_b128 v[190:193], v151 offset:50176
	ds_read_b128 v[194:197], v150 offset:49152
	ds_read_b128 v[150:153], v150 offset:50176
	ds_read_b128 v[198:201], v149 offset:49152
	ds_read_b128 v[202:205], v149 offset:50176
	s_barrier
	s_waitcnt lgkmcnt(0)
	s_waitcnt lgkmcnt(0)
	v_mfma_f32_16x16x32_bf16 v[20:23], v[0:3], v[178:181], v[60:63]
	v_mfma_f32_16x16x32_bf16 v[56:59], v[16:19], v[178:181], v[56:59]
	v_mfma_f32_16x16x32_bf16 v[60:63], v[0:3], v[186:189], v[52:55]
	v_mfma_f32_16x16x32_bf16 v[206:209], v[16:19], v[186:189], v[48:51]
	v_mfma_f32_16x16x32_bf16 v[44:47], v[0:3], v[194:197], v[44:47]
	v_mfma_f32_16x16x32_bf16 v[40:43], v[16:19], v[194:197], v[40:43]
	v_mfma_f32_16x16x32_bf16 v[0:3], v[0:3], v[198:201], v[36:39]
	v_mfma_f32_16x16x32_bf16 v[210:213], v[16:19], v[198:201], v[32:35]
	v_mfma_f32_16x16x32_bf16 v[52:55], v[4:7], v[182:185], v[20:23]
	v_mfma_f32_16x16x32_bf16 v[48:51], v[174:177], v[182:185], v[56:59]
	v_mfma_f32_16x16x32_bf16 v[36:39], v[4:7], v[190:193], v[60:63]
	v_mfma_f32_16x16x32_bf16 v[32:35], v[174:177], v[190:193], v[206:209]
	v_mfma_f32_16x16x32_bf16 v[20:23], v[4:7], v[150:153], v[44:47]
	v_mfma_f32_16x16x32_bf16 v[16:19], v[174:177], v[150:153], v[40:43]
	v_mfma_f32_16x16x32_bf16 v[4:7], v[4:7], v[202:205], v[0:3]
	v_mfma_f32_16x16x32_bf16 v[0:3], v[174:177], v[202:205], v[210:213]
	v_mfma_f32_16x16x32_bf16 v[28:31], v[224:227], v[178:181], v[28:31]
	v_mfma_f32_16x16x32_bf16 v[24:27], v[232:235], v[178:181], v[24:27]
	v_mfma_f32_16x16x32_bf16 v[40:43], v[224:227], v[186:189], v[134:137]
	v_mfma_f32_16x16x32_bf16 v[134:137], v[232:235], v[186:189], v[138:141]
	v_mfma_f32_16x16x32_bf16 v[12:15], v[224:227], v[194:197], v[12:15]
	v_mfma_f32_16x16x32_bf16 v[8:11], v[232:235], v[194:197], v[8:11]
	v_mfma_f32_16x16x32_bf16 v[138:141], v[224:227], v[198:201], v[170:173]
	v_mfma_f32_16x16x32_bf16 v[158:161], v[232:235], v[198:201], v[158:161]
	v_mfma_f32_16x16x32_bf16 v[60:63], v[228:231], v[182:185], v[28:31]
	v_mfma_f32_16x16x32_bf16 v[56:59], v[154:157], v[182:185], v[24:27]
	v_mfma_f32_16x16x32_bf16 v[44:47], v[228:231], v[190:193], v[40:43]
	v_mfma_f32_16x16x32_bf16 v[40:43], v[154:157], v[190:193], v[134:137]
	v_mfma_f32_16x16x32_bf16 v[28:31], v[228:231], v[150:153], v[12:15]
	v_mfma_f32_16x16x32_bf16 v[24:27], v[154:157], v[150:153], v[8:11]
	v_mfma_f32_16x16x32_bf16 v[12:15], v[228:231], v[202:205], v[138:141]
	v_mfma_f32_16x16x32_bf16 v[8:11], v[154:157], v[202:205], v[158:161]
	v_cmp_gt_u32_e32 vcc, s56, v130
	s_barrier
	s_and_saveexec_b64 s[42:43], vcc
	s_cbranch_execz .LBB0_56
	s_barrier

; #define STAGE(P, BASE, LD, br, kt) do { const char* _g = (const char*)((BASE) + (size_t)(br) * (LD) + (size_t)(kt) * 64); \
;     for (int _i = 0; _i < 2; ++_i) { int _b = tidx * 16 + _i * 8192; int _r, _c; stage_rc(_b, _r, _c); \
;       __builtin_amdgcn_global_load_lds((const unsigned*)(_g + (unsigned)((_r * (LD) + _c) * 2)), (unsigned*)((char*)(P) + _b), 16, 0, 0); } } while (0)
; #define LDA(dst, b, h) for (int m = 0; m < 4; ++m) for (int k = 0; k < 2; ++k) \
;     dst[m][k] = *reinterpret_cast<const bf16x8*>((char*)SA(b, h) + lds_byte(wr * 64 + m * 16 + fr, k * 32 + fq * 8))
; #define LDB(dst, b, h) for (int n = 0; n < 2; ++n) for (int k = 0; k < 2; ++k) \
;     dst[n][k] = *reinterpret_cast<const bf16x8*>((char*)SB(b, h) + lds_byte(wc * 32 + n * 16 + fr, k * 32 + fq * 8))
; #define MMA(ai, bj, At_, Bt_) do { __builtin_amdgcn_s_setprio(1); \
;     for (int k = 0; k < 2; ++k) for (int m = 0; m < 4; ++m) for (int n = 0; n < 2; ++n) \
;       acc[ai][bj][m][n] = __builtin_amdgcn_mfma_f32_16x16x32_bf16(At_[m][k], Bt_[n][k], acc[ai][bj][m][n], 0, 0, 0); \
;     __builtin_amdgcn_s_setprio(0); } while (0)
; #define WAIT_L(n) asm volatile("s_waitcnt lgkmcnt(" #n ")" ::: "memory")
; #define BAR __builtin_amdgcn_s_barrier()
; #define SCHED __builtin_amdgcn_sched_barrier(0)
; template <int EPI, int lda, int ldb, int N, int K>
; __device__ __forceinline__ void gemm_phase(const u16* __restrict__ A, const u16* __restrict__ Bt, const GemmEpi ep, int wv) {
;     ...
;       LDB(B0, 0, 0); SCHED; LDA(At, 0, 0); STAGE(SA(1, 1), Ab, lda, brow + HALF, t + 1);
;       WAIT_L(8); BAR; WAIT_L(0); MMA(0, 0, At, B0); BAR; SCHED;
;       LDB(B1, 0, 1); STAGE(SB(0, 0), Bt, ldb, bcol, t + 2);
;       BAR; WAIT_L(0); MMA(0, 1, At, B1); BAR;
;       LDA(At, 0, 1); STAGE(SA(0, 0), Ab, lda, brow, t + 2);
;       BAR; WAIT_L(0); MMA(1, 0, At, B0); BAR; SCHED;
.LBB0_224:
	ds_read_b128 v[168:171], v164
	ds_read_b128 v[174:177], v164 offset:1024
	ds_read_b128 v[178:181], v164 offset:2048
	ds_read_b128 v[182:185], v164 offset:3072
	v_add_u32_e32 v172, 0xc000, v147
	v_lshl_add_u64 v[238:239], v[136:137], 0, s[44:45]
	v_readfirstlane_b32 s66, v172
	v_add_u32_e32 v173, 0xe000, v147
	v_lshl_add_u64 v[166:167], v[238:239], 0, s[18:19]
	s_mov_b32 m0, s66
	v_lshl_add_u64 v[240:241], v[134:135], 0, s[44:45]
	v_readfirstlane_b32 s66, v173
	ds_read_b128 v[186:189], v155
	ds_read_b128 v[190:193], v155 offset:1024
	ds_read_b128 v[194:197], v154
	ds_read_b128 v[198:201], v154 offset:1024
	ds_read_b128 v[202:205], v153
	ds_read_b128 v[206:209], v153 offset:1024
	ds_read_b128 v[210:213], v152
	ds_read_b128 v[214:217], v152 offset:1024
	global_load_lds_dwordx4 v[166:167], off
	v_lshl_add_u64 v[166:167], v[240:241], 0, s[18:19]
	s_mov_b32 m0, s66
	s_nop 0
	global_load_lds_dwordx4 v[166:167], off
	s_waitcnt lgkmcnt(8)
	s_barrier
	s_waitcnt lgkmcnt(0)
	s_waitcnt lgkmcnt(0)
	v_mfma_f32_16x16x32_bf16 v[124:127], v[168:171], v[186:189], v[124:127]
	v_mfma_f32_16x16x32_bf16 v[120:123], v[178:181], v[186:189], v[120:123]
	v_mfma_f32_16x16x32_bf16 v[116:119], v[168:171], v[194:197], v[116:119]
	v_mfma_f32_16x16x32_bf16 v[112:115], v[178:181], v[194:197], v[112:115]
	v_mfma_f32_16x16x32_bf16 v[108:111], v[168:171], v[202:205], v[108:111]
	v_mfma_f32_16x16x32_bf16 v[104:107], v[178:181], v[202:205], v[104:107]
	v_mfma_f32_16x16x32_bf16 v[100:103], v[168:171], v[210:213], v[100:103]
	v_mfma_f32_16x16x32_bf16 v[96:99], v[178:181], v[210:213], v[96:99]
	v_mfma_f32_16x16x32_bf16 v[124:127], v[174:177], v[190:193], v[124:127]
	v_mfma_f32_16x16x32_bf16 v[120:123], v[182:185], v[190:193], v[120:123]
	v_mfma_f32_16x16x32_bf16 v[116:119], v[174:177], v[198:201], v[116:119]
	v_mfma_f32_16x16x32_bf16 v[112:115], v[182:185], v[198:201], v[112:115]
	v_mfma_f32_16x16x32_bf16 v[108:111], v[174:177], v[206:209], v[108:111]
	v_mfma_f32_16x16x32_bf16 v[104:107], v[182:185], v[206:209], v[104:107]
	v_mfma_f32_16x16x32_bf16 v[100:103], v[174:177], v[214:217], v[100:103]
	v_mfma_f32_16x16x32_bf16 v[96:99], v[182:185], v[214:217], v[96:99]
	s_barrier
	v_add_u32_e32 v165, s55, v156
	v_lshl_add_u64 v[242:243], v[144:145], 0, s[44:45]
	v_readfirstlane_b32 s66, v165
	v_lshl_add_u64 v[166:167], v[242:243], 0, s[20:21]
	s_mov_b32 m0, s66
	ds_read_b128 v[218:221], v163
	ds_read_b128 v[222:225], v163 offset:1024
	ds_read_b128 v[226:229], v163 offset:2048
	ds_read_b128 v[230:233], v163 offset:3072
	global_load_lds_dwordx4 v[166:167], off
	v_add_u32_e32 v166, 0x2000, v165
	v_lshl_add_u64 v[244:245], v[142:143], 0, s[44:45]
	v_readfirstlane_b32 s66, v166
	v_lshl_add_u64 v[234:235], v[244:245], 0, s[20:21]
	s_mov_b32 m0, s66
	s_nop 0
	global_load_lds_dwordx4 v[234:235], off
	s_waitcnt vmcnt(10)
	s_barrier
	s_waitcnt lgkmcnt(0)
	s_waitcnt lgkmcnt(0)
	v_mfma_f32_16x16x32_bf16 v[92:95], v[218:221], v[186:189], v[92:95]
	v_mfma_f32_16x16x32_bf16 v[88:91], v[226:229], v[186:189], v[88:91]
	v_mfma_f32_16x16x32_bf16 v[84:87], v[218:221], v[194:197], v[84:87]
	v_mfma_f32_16x16x32_bf16 v[80:83], v[226:229], v[194:197], v[80:83]
	v_mfma_f32_16x16x32_bf16 v[76:79], v[218:221], v[202:205], v[76:79]
	v_mfma_f32_16x16x32_bf16 v[72:75], v[226:229], v[202:205], v[72:75]
	v_mfma_f32_16x16x32_bf16 v[68:71], v[218:221], v[210:213], v[68:71]
	v_mfma_f32_16x16x32_bf16 v[64:67], v[226:229], v[210:213], v[64:67]
	v_mfma_f32_16x16x32_bf16 v[92:95], v[222:225], v[190:193], v[92:95]
	v_mfma_f32_16x16x32_bf16 v[88:91], v[230:233], v[190:193], v[88:91]
	v_mfma_f32_16x16x32_bf16 v[84:87], v[222:225], v[198:201], v[84:87]
	v_mfma_f32_16x16x32_bf16 v[80:83], v[230:233], v[198:201], v[80:83]
	v_mfma_f32_16x16x32_bf16 v[76:79], v[222:225], v[206:209], v[76:79]
	v_mfma_f32_16x16x32_bf16 v[72:75], v[230:233], v[206:209], v[72:75]
	v_mfma_f32_16x16x32_bf16 v[68:71], v[222:225], v[214:217], v[68:71]
	v_mfma_f32_16x16x32_bf16 v[64:67], v[230:233], v[214:217], v[64:67]
	v_readfirstlane_b32 s66, v147
	v_add_u32_e32 v167, 0x2000, v147
	v_lshl_add_u64 v[234:235], v[238:239], 0, s[22:23]
	s_mov_b32 m0, s66
	v_readfirstlane_b32 s66, v167
	s_barrier
	ds_read_b128 v[186:189], v155 offset:16384
	ds_read_b128 v[190:193], v155 offset:17408
	ds_read_b128 v[194:197], v154 offset:16384
	ds_read_b128 v[198:201], v154 offset:17408
	ds_read_b128 v[202:205], v153 offset:16384
	ds_read_b128 v[206:209], v153 offset:17408
	ds_read_b128 v[210:213], v152 offset:16384
	ds_read_b128 v[214:217], v152 offset:17408
	global_load_lds_dwordx4 v[234:235], off
	v_lshl_add_u64 v[234:235], v[240:241], 0, s[22:23]
	s_mov_b32 m0, s66
	s_nop 0
	global_load_lds_dwordx4 v[234:235], off
	s_barrier
	s_waitcnt lgkmcnt(0)
	s_waitcnt lgkmcnt(0)
	v_mfma_f32_16x16x32_bf16 v[60:63], v[168:171], v[186:189], v[60:63]
	v_mfma_f32_16x16x32_bf16 v[56:59], v[178:181], v[186:189], v[56:59]
	v_mfma_f32_16x16x32_bf16 v[52:55], v[168:171], v[194:197], v[52:55]
	v_mfma_f32_16x16x32_bf16 v[48:51], v[178:181], v[194:197], v[48:51]
	v_mfma_f32_16x16x32_bf16 v[44:47], v[168:171], v[202:205], v[44:47]
	v_mfma_f32_16x16x32_bf16 v[40:43], v[178:181], v[202:205], v[40:43]
	v_mfma_f32_16x16x32_bf16 v[36:39], v[168:171], v[210:213], v[36:39]
	v_mfma_f32_16x16x32_bf16 v[32:35], v[178:181], v[210:213], v[32:35]
	v_mfma_f32_16x16x32_bf16 v[60:63], v[174:177], v[190:193], v[60:63]
	v_mfma_f32_16x16x32_bf16 v[56:59], v[182:185], v[190:193], v[56:59]
	v_mfma_f32_16x16x32_bf16 v[52:55], v[174:177], v[198:201], v[52:55]
	v_mfma_f32_16x16x32_bf16 v[48:51], v[182:185], v[198:201], v[48:51]
	v_mfma_f32_16x16x32_bf16 v[44:47], v[174:177], v[206:209], v[44:47]
	v_mfma_f32_16x16x32_bf16 v[40:43], v[182:185], v[206:209], v[40:43]
	v_mfma_f32_16x16x32_bf16 v[36:39], v[174:177], v[214:217], v[36:39]
	v_mfma_f32_16x16x32_bf16 v[32:35], v[182:185], v[214:217], v[32:35]
	s_barrier
; #define STAGE(P, BASE, LD, br, kt) do { const char* _g = (const char*)((BASE) + (size_t)(br) * (LD) + (size_t)(kt) * 64); \
;     for (int _i = 0; _i < 2; ++_i) { int _b = tidx * 16 + _i * 8192; int _r, _c; stage_rc(_b, _r, _c); \
;       __builtin_amdgcn_global_load_lds((const unsigned*)(_g + (unsigned)((_r * (LD) + _c) * 2)), (unsigned*)((char*)(P) + _b), 16, 0, 0); } } while (0)
; #define LDA(dst, b, h) for (int m = 0; m < 4; ++m) for (int k = 0; k < 2; ++k) \
;     dst[m][k] = *reinterpret_cast<const bf16x8*>((char*)SA(b, h) + lds_byte(wr * 64 + m * 16 + fr, k * 32 + fq * 8))
; #define LDB(dst, b, h) for (int n = 0; n < 2; ++n) for (int k = 0; k < 2; ++k) \
;     dst[n][k] = *reinterpret_cast<const bf16x8*>((char*)SB(b, h) + lds_byte(wc * 32 + n * 16 + fr, k * 32 + fq * 8))
; #define MMA(ai, bj, At_, Bt_) do { __builtin_amdgcn_s_setprio(1); \
;     for (int k = 0; k < 2; ++k) for (int m = 0; m < 4; ++m) for (int n = 0; n < 2; ++n) \
;       acc[ai][bj][m][n] = __builtin_amdgcn_mfma_f32_16x16x32_bf16(At_[m][k], Bt_[n][k], acc[ai][bj][m][n], 0, 0, 0); \
;     __builtin_amdgcn_s_setprio(0); } while (0)
; #define WAIT_V(n) asm volatile("s_waitcnt vmcnt(" #n ")" ::: "memory")
; #define WAIT_L(n) asm volatile("s_waitcnt lgkmcnt(" #n ")" ::: "memory")
; #define BAR __builtin_amdgcn_s_barrier()
; #define SCHED __builtin_amdgcn_sched_barrier(0)
; template <int EPI, int lda, int ldb, int N, int K>
; __device__ __forceinline__ void gemm_phase(const u16* __restrict__ A, const u16* __restrict__ Bt, const GemmEpi ep, int wv) {
;     ...
;       STAGE(SB(0, 1), Bt, ldb, bcol + HALF, t + 2);
;       WAIT_V(6); BAR; MMA(1, 1, At, B1); BAR;
;       LDB(B0, 1, 0); SCHED; LDA(At, 1, 0); STAGE(SA(0, 1), Ab, lda, brow + HALF, t + 2);
;       WAIT_L(8); BAR; WAIT_L(0); MMA(0, 0, At, B0); BAR; SCHED;
;       LDB(B1, 1, 1); STAGE(SB(1, 0), Bt, ldb, bcol, t + 3);
;       BAR; WAIT_L(0); MMA(0, 1, At, B1); BAR;
;       LDA(At, 1, 1); STAGE(SA(1, 0), Ab, lda, brow, t + 3);
;       BAR; WAIT_L(0); MMA(1, 0, At, B0); BAR; SCHED;
	v_add_u32_e32 v168, s56, v156
	v_lshl_add_u64 v[246:247], v[140:141], 0, s[44:45]
	v_readfirstlane_b32 s66, v168
	v_add_u32_e32 v169, 0x2000, v168
	v_lshl_add_u64 v[170:171], v[246:247], 0, s[24:25]
	s_mov_b32 m0, s66
	v_lshl_add_u64 v[248:249], v[138:139], 0, s[44:45]
	v_readfirstlane_b32 s66, v169
	global_load_lds_dwordx4 v[170:171], off
	v_lshl_add_u64 v[170:171], v[248:249], 0, s[24:25]
	s_mov_b32 m0, s66
	s_nop 0
	global_load_lds_dwordx4 v[170:171], off
	s_waitcnt vmcnt(8)
	s_barrier
	v_mfma_f32_16x16x32_bf16 v[28:31], v[218:221], v[186:189], v[28:31]
	v_mfma_f32_16x16x32_bf16 v[24:27], v[226:229], v[186:189], v[24:27]
	v_mfma_f32_16x16x32_bf16 v[20:23], v[218:221], v[194:197], v[20:23]
	v_mfma_f32_16x16x32_bf16 v[16:19], v[226:229], v[194:197], v[16:19]
	v_mfma_f32_16x16x32_bf16 v[12:15], v[218:221], v[202:205], v[12:15]
	v_mfma_f32_16x16x32_bf16 v[8:11], v[226:229], v[202:205], v[8:11]
	v_mfma_f32_16x16x32_bf16 v[4:7], v[218:221], v[210:213], v[4:7]
	v_mfma_f32_16x16x32_bf16 v[0:3], v[226:229], v[210:213], v[0:3]
	v_mfma_f32_16x16x32_bf16 v[28:31], v[222:225], v[190:193], v[28:31]
	v_mfma_f32_16x16x32_bf16 v[24:27], v[230:233], v[190:193], v[24:27]
	v_mfma_f32_16x16x32_bf16 v[20:23], v[222:225], v[198:201], v[20:23]
	v_mfma_f32_16x16x32_bf16 v[16:19], v[230:233], v[198:201], v[16:19]
	v_mfma_f32_16x16x32_bf16 v[12:15], v[222:225], v[206:209], v[12:15]
	v_mfma_f32_16x16x32_bf16 v[8:11], v[230:233], v[206:209], v[8:11]
	v_mfma_f32_16x16x32_bf16 v[4:7], v[222:225], v[214:217], v[4:7]
	v_mfma_f32_16x16x32_bf16 v[0:3], v[230:233], v[214:217], v[0:3]
	s_barrier
	ds_read_b128 v[174:177], v159
	ds_read_b128 v[178:181], v159 offset:1024
	ds_read_b128 v[182:185], v159 offset:2048
	ds_read_b128 v[186:189], v159 offset:3072
	v_add_u32_e32 v170, 0x4000, v147
	v_add_u32_e32 v171, 0x6000, v147
	v_readfirstlane_b32 s66, v170
	v_lshl_add_u64 v[222:223], v[238:239], 0, s[26:27]
	s_mov_b32 m0, s66
	v_readfirstlane_b32 s66, v171
	ds_read_b128 v[190:193], v155 offset:32768
	ds_read_b128 v[194:197], v155 offset:33792
	ds_read_b128 v[198:201], v154 offset:32768
	ds_read_b128 v[202:205], v154 offset:33792
	ds_read_b128 v[206:209], v153 offset:32768
	ds_read_b128 v[210:213], v153 offset:33792
	ds_read_b128 v[214:217], v152 offset:32768
	ds_read_b128 v[218:221], v152 offset:33792
	global_load_lds_dwordx4 v[222:223], off
	v_lshl_add_u64 v[222:223], v[240:241], 0, s[26:27]
	s_mov_b32 m0, s66
	s_nop 0
	global_load_lds_dwordx4 v[222:223], off
	s_waitcnt lgkmcnt(8)
	s_barrier
	s_waitcnt lgkmcnt(0)
	s_waitcnt lgkmcnt(0)
	v_mfma_f32_16x16x32_bf16 v[124:127], v[174:177], v[190:193], v[124:127]
	v_mfma_f32_16x16x32_bf16 v[120:123], v[182:185], v[190:193], v[120:123]
	v_mfma_f32_16x16x32_bf16 v[116:119], v[174:177], v[198:201], v[116:119]
	v_mfma_f32_16x16x32_bf16 v[112:115], v[182:185], v[198:201], v[112:115]
	v_mfma_f32_16x16x32_bf16 v[108:111], v[174:177], v[206:209], v[108:111]
	v_mfma_f32_16x16x32_bf16 v[104:107], v[182:185], v[206:209], v[104:107]
	v_mfma_f32_16x16x32_bf16 v[100:103], v[174:177], v[214:217], v[100:103]
	v_mfma_f32_16x16x32_bf16 v[96:99], v[182:185], v[214:217], v[96:99]
	v_mfma_f32_16x16x32_bf16 v[124:127], v[178:181], v[194:197], v[124:127]
	v_mfma_f32_16x16x32_bf16 v[120:123], v[186:189], v[194:197], v[120:123]
	v_mfma_f32_16x16x32_bf16 v[116:119], v[178:181], v[202:205], v[116:119]
	v_mfma_f32_16x16x32_bf16 v[112:115], v[186:189], v[202:205], v[112:115]
	v_mfma_f32_16x16x32_bf16 v[108:111], v[178:181], v[210:213], v[108:111]
	v_mfma_f32_16x16x32_bf16 v[104:107], v[186:189], v[210:213], v[104:107]
	v_mfma_f32_16x16x32_bf16 v[100:103], v[178:181], v[218:221], v[100:103]
	v_mfma_f32_16x16x32_bf16 v[96:99], v[186:189], v[218:221], v[96:99]
	s_barrier
	v_readfirstlane_b32 s66, v158
	v_lshl_add_u64 v[242:243], v[242:243], 0, s[36:37]
	s_mov_b32 m0, s66
	ds_read_b128 v[222:225], v157
	ds_read_b128 v[226:229], v157 offset:1024
	ds_read_b128 v[230:233], v157 offset:2048
	ds_read_b128 v[234:237], v157 offset:3072
	global_load_lds_dwordx4 v[242:243], off
	v_lshl_add_u64 v[242:243], v[244:245], 0, s[36:37]
	v_add_u32_e32 v244, 0x2000, v158
	s_nop 0
	v_readfirstlane_b32 s66, v244
	s_mov_b32 m0, s66
	s_nop 0
	global_load_lds_dwordx4 v[242:243], off
	s_waitcnt vmcnt(10)
	s_barrier
	s_waitcnt lgkmcnt(0)
	s_waitcnt lgkmcnt(0)
	v_mfma_f32_16x16x32_bf16 v[92:95], v[222:225], v[190:193], v[92:95]
	v_mfma_f32_16x16x32_bf16 v[88:91], v[230:233], v[190:193], v[88:91]
	v_mfma_f32_16x16x32_bf16 v[84:87], v[222:225], v[198:201], v[84:87]
	v_mfma_f32_16x16x32_bf16 v[80:83], v[230:233], v[198:201], v[80:83]
	v_mfma_f32_16x16x32_bf16 v[76:79], v[222:225], v[206:209], v[76:79]
	v_mfma_f32_16x16x32_bf16 v[72:75], v[230:233], v[206:209], v[72:75]
	v_mfma_f32_16x16x32_bf16 v[68:71], v[222:225], v[214:217], v[68:71]
	v_mfma_f32_16x16x32_bf16 v[64:67], v[230:233], v[214:217], v[64:67]
	v_mfma_f32_16x16x32_bf16 v[92:95], v[226:229], v[194:197], v[92:95]
	v_mfma_f32_16x16x32_bf16 v[88:91], v[234:237], v[194:197], v[88:91]
	v_mfma_f32_16x16x32_bf16 v[84:87], v[226:229], v[202:205], v[84:87]
	v_mfma_f32_16x16x32_bf16 v[80:83], v[234:237], v[202:205], v[80:83]
	v_mfma_f32_16x16x32_bf16 v[76:79], v[226:229], v[210:213], v[76:79]
	v_mfma_f32_16x16x32_bf16 v[72:75], v[234:237], v[210:213], v[72:75]
	v_mfma_f32_16x16x32_bf16 v[68:71], v[226:229], v[218:221], v[68:71]
	v_mfma_f32_16x16x32_bf16 v[64:67], v[234:237], v[218:221], v[64:67]
	v_readfirstlane_b32 s66, v160
	v_lshl_add_u64 v[238:239], v[238:239], 0, s[38:39]
	s_mov_b32 m0, s66
	v_readfirstlane_b32 s66, v161
	s_barrier
; #define STAGE(P, BASE, LD, br, kt) do { const char* _g = (const char*)((BASE) + (size_t)(br) * (LD) + (size_t)(kt) * 64); \
;     for (int _i = 0; _i < 2; ++_i) { int _b = tidx * 16 + _i * 8192; int _r, _c; stage_rc(_b, _r, _c); \
;       __builtin_amdgcn_global_load_lds((const unsigned*)(_g + (unsigned)((_r * (LD) + _c) * 2)), (unsigned*)((char*)(P) + _b), 16, 0, 0); } } while (0)
; #define LDA(dst, b, h) for (int m = 0; m < 4; ++m) for (int k = 0; k < 2; ++k) \
;     dst[m][k] = *reinterpret_cast<const bf16x8*>((char*)SA(b, h) + lds_byte(wr * 64 + m * 16 + fr, k * 32 + fq * 8))
; #define LDB(dst, b, h) for (int n = 0; n < 2; ++n) for (int k = 0; k < 2; ++k) \
;     dst[n][k] = *reinterpret_cast<const bf16x8*>((char*)SB(b, h) + lds_byte(wc * 32 + n * 16 + fr, k * 32 + fq * 8))
; #define MMA(ai, bj, At_, Bt_) do { __builtin_amdgcn_s_setprio(1); \
;     for (int k = 0; k < 2; ++k) for (int m = 0; m < 4; ++m) for (int n = 0; n < 2; ++n) \
;       acc[ai][bj][m][n] = __builtin_amdgcn_mfma_f32_16x16x32_bf16(At_[m][k], Bt_[n][k], acc[ai][bj][m][n], 0, 0, 0); \
;     __builtin_amdgcn_s_setprio(0); } while (0)
; #define WAIT_V(n) asm volatile("s_waitcnt vmcnt(" #n ")" ::: "memory")
; #define WAIT_L(n) asm volatile("s_waitcnt lgkmcnt(" #n ")" ::: "memory")
; #define BAR __builtin_amdgcn_s_barrier()
; #define SCHED __builtin_amdgcn_sched_barrier(0)
; template <int EPI, int lda, int ldb, int N, int K>
; __device__ __forceinline__ void gemm_phase(const u16* __restrict__ A, const u16* __restrict__ Bt, const GemmEpi ep, int wv) {
;     ...
;       LDA(At, 1, 1); STAGE(SA(1, 0), Ab, lda, brow, t + 3);
;       BAR; WAIT_L(0); MMA(1, 0, At, B0); BAR; SCHED;
;       STAGE(SB(1, 1), Bt, ldb, bcol + HALF, t + 3);
;       WAIT_V(6); BAR; MMA(1, 1, At, B1); BAR;
;     }
;     { LDB(B0, 0, 0); LDA(At, 0, 0); STAGE(SA(1, 1), Ab, lda, brow + HALF, nt - 1);
;       BAR; WAIT_L(0); MMA(0, 0, At, B0); BAR;
	ds_read_b128 v[190:193], v155 offset:49152
	ds_read_b128 v[194:197], v155 offset:50176
	ds_read_b128 v[198:201], v154 offset:49152
	ds_read_b128 v[202:205], v154 offset:50176
	ds_read_b128 v[206:209], v153 offset:49152
	ds_read_b128 v[210:213], v153 offset:50176
	ds_read_b128 v[214:217], v152 offset:49152
	ds_read_b128 v[218:221], v152 offset:50176
	global_load_lds_dwordx4 v[238:239], off
	v_lshl_add_u64 v[238:239], v[240:241], 0, s[38:39]
	s_mov_b32 m0, s66
	s_nop 0
	global_load_lds_dwordx4 v[238:239], off
	s_barrier
	s_waitcnt lgkmcnt(0)
	s_waitcnt lgkmcnt(0)
	v_mfma_f32_16x16x32_bf16 v[60:63], v[174:177], v[190:193], v[60:63]
	v_mfma_f32_16x16x32_bf16 v[56:59], v[182:185], v[190:193], v[56:59]
	v_mfma_f32_16x16x32_bf16 v[52:55], v[174:177], v[198:201], v[52:55]
	v_mfma_f32_16x16x32_bf16 v[48:51], v[182:185], v[198:201], v[48:51]
	v_mfma_f32_16x16x32_bf16 v[44:47], v[174:177], v[206:209], v[44:47]
	v_mfma_f32_16x16x32_bf16 v[40:43], v[182:185], v[206:209], v[40:43]
	v_mfma_f32_16x16x32_bf16 v[36:39], v[174:177], v[214:217], v[36:39]
	v_mfma_f32_16x16x32_bf16 v[32:35], v[182:185], v[214:217], v[32:35]
	v_mfma_f32_16x16x32_bf16 v[60:63], v[178:181], v[194:197], v[60:63]
	v_mfma_f32_16x16x32_bf16 v[56:59], v[186:189], v[194:197], v[56:59]
	v_mfma_f32_16x16x32_bf16 v[52:55], v[178:181], v[202:205], v[52:55]
	v_mfma_f32_16x16x32_bf16 v[48:51], v[186:189], v[202:205], v[48:51]
	v_mfma_f32_16x16x32_bf16 v[44:47], v[178:181], v[210:213], v[44:47]
	v_mfma_f32_16x16x32_bf16 v[40:43], v[186:189], v[210:213], v[40:43]
	v_mfma_f32_16x16x32_bf16 v[36:39], v[178:181], v[218:221], v[36:39]
	v_mfma_f32_16x16x32_bf16 v[32:35], v[186:189], v[218:221], v[32:35]
	s_barrier
	v_readfirstlane_b32 s66, v162
	v_add_u32_e32 v176, 0x2000, v162
	v_lshl_add_u64 v[174:175], v[246:247], 0, s[42:43]
	s_mov_b32 m0, s66
	v_readfirstlane_b32 s66, v176
	global_load_lds_dwordx4 v[174:175], off
	v_lshl_add_u64 v[174:175], v[248:249], 0, s[42:43]
	s_mov_b32 m0, s66
	s_nop 0
	global_load_lds_dwordx4 v[174:175], off
	s_waitcnt vmcnt(8)
	s_barrier
	v_mfma_f32_16x16x32_bf16 v[28:31], v[222:225], v[190:193], v[28:31]
	v_mfma_f32_16x16x32_bf16 v[24:27], v[230:233], v[190:193], v[24:27]
	v_mfma_f32_16x16x32_bf16 v[20:23], v[222:225], v[198:201], v[20:23]
	v_mfma_f32_16x16x32_bf16 v[16:19], v[230:233], v[198:201], v[16:19]
	v_mfma_f32_16x16x32_bf16 v[12:15], v[222:225], v[206:209], v[12:15]
	v_mfma_f32_16x16x32_bf16 v[8:11], v[230:233], v[206:209], v[8:11]
	v_mfma_f32_16x16x32_bf16 v[4:7], v[222:225], v[214:217], v[4:7]
	v_mfma_f32_16x16x32_bf16 v[0:3], v[230:233], v[214:217], v[0:3]
	v_mfma_f32_16x16x32_bf16 v[28:31], v[226:229], v[194:197], v[28:31]
	v_mfma_f32_16x16x32_bf16 v[24:27], v[234:237], v[194:197], v[24:27]
	v_mfma_f32_16x16x32_bf16 v[20:23], v[226:229], v[202:205], v[20:23]
	v_mfma_f32_16x16x32_bf16 v[16:19], v[234:237], v[202:205], v[16:19]
	v_mfma_f32_16x16x32_bf16 v[12:15], v[226:229], v[210:213], v[12:15]
	v_mfma_f32_16x16x32_bf16 v[8:11], v[234:237], v[210:213], v[8:11]
	v_mfma_f32_16x16x32_bf16 v[4:7], v[226:229], v[218:221], v[4:7]
	v_mfma_f32_16x16x32_bf16 v[0:3], v[234:237], v[218:221], v[0:3]
	s_add_i32 s65, s65, 2
	s_add_u32 s44, s44, 0x100
	s_addc_u32 s45, s45, 0
	s_cmpk_gt_u32 s65, 0x51
	s_barrier
	s_cbranch_scc0 .LBB0_224
	s_add_i32 s44, s14, 0x80
	s_mul_hi_i32 s45, s44, 0x2b00
	s_mulk_i32 s44, 0x2b00
	s_add_u32 s44, s48, s44
	s_addc_u32 s45, s49, s45
	s_add_u32 s44, s44, 0x2a80
	s_addc_u32 s45, s45, 0
	v_readfirstlane_b32 s65, v172
	v_lshl_add_u64 v[160:161], s[44:45], 0, v[128:129]
	s_mov_b32 m0, s65
	ds_read_b128 v[134:137], v164
	ds_read_b128 v[138:141], v164 offset:1024
	ds_read_b128 v[142:145], v164 offset:2048
	ds_read_b128 v[174:177], v164 offset:3072
	ds_read_b128 v[178:181], v155
	ds_read_b128 v[182:185], v155 offset:1024
	ds_read_b128 v[186:189], v154
	ds_read_b128 v[190:193], v154 offset:1024
	ds_read_b128 v[194:197], v153
	ds_read_b128 v[198:201], v153 offset:1024
	ds_read_b128 v[202:205], v152
	ds_read_b128 v[206:209], v152 offset:1024
	global_load_lds_dwordx4 v[160:161], off
	v_lshl_add_u64 v[160:161], s[44:45], 0, v[132:133]
	v_readfirstlane_b32 s44, v173
	s_mov_b32 m0, s44
	s_nop 0
	global_load_lds_dwordx4 v[160:161], off
	s_barrier
	s_waitcnt lgkmcnt(0)
	s_waitcnt lgkmcnt(0)
	v_mfma_f32_16x16x32_bf16 v[124:127], v[134:137], v[178:181], v[124:127]
	v_mfma_f32_16x16x32_bf16 v[120:123], v[142:145], v[178:181], v[120:123]
	v_mfma_f32_16x16x32_bf16 v[116:119], v[134:137], v[186:189], v[116:119]
	v_mfma_f32_16x16x32_bf16 v[112:115], v[142:145], v[186:189], v[112:115]
	v_mfma_f32_16x16x32_bf16 v[108:111], v[134:137], v[194:197], v[108:111]
	v_mfma_f32_16x16x32_bf16 v[104:107], v[142:145], v[194:197], v[104:107]
	v_mfma_f32_16x16x32_bf16 v[100:103], v[134:137], v[202:205], v[100:103]
	v_mfma_f32_16x16x32_bf16 v[96:99], v[142:145], v[202:205], v[96:99]
	v_mfma_f32_16x16x32_bf16 v[124:127], v[138:141], v[182:185], v[124:127]
	v_mfma_f32_16x16x32_bf16 v[120:123], v[174:177], v[182:185], v[120:123]
	v_mfma_f32_16x16x32_bf16 v[116:119], v[138:141], v[190:193], v[116:119]
	v_mfma_f32_16x16x32_bf16 v[112:115], v[174:177], v[190:193], v[112:115]
	v_mfma_f32_16x16x32_bf16 v[108:111], v[138:141], v[198:201], v[108:111]
	v_mfma_f32_16x16x32_bf16 v[104:107], v[174:177], v[198:201], v[104:107]
	v_mfma_f32_16x16x32_bf16 v[100:103], v[138:141], v[206:209], v[100:103]
	v_mfma_f32_16x16x32_bf16 v[96:99], v[174:177], v[206:209], v[96:99]
	s_barrier
	ds_read_b128 v[210:213], v163
	ds_read_b128 v[214:217], v163 offset:1024
	ds_read_b128 v[218:221], v163 offset:2048
	ds_read_b128 v[160:163], v163 offset:3072
	s_waitcnt vmcnt(8)
	s_barrier
; #define LDA(dst, b, h) for (int m = 0; m < 4; ++m) for (int k = 0; k < 2; ++k) \
;     dst[m][k] = *reinterpret_cast<const bf16x8*>((char*)SA(b, h) + lds_byte(wr * 64 + m * 16 + fr, k * 32 + fq * 8))
; #define LDB(dst, b, h) for (int n = 0; n < 2; ++n) for (int k = 0; k < 2; ++k) \
;     dst[n][k] = *reinterpret_cast<const bf16x8*>((char*)SB(b, h) + lds_byte(wc * 32 + n * 16 + fr, k * 32 + fq * 8))
; #define MMA(ai, bj, At_, Bt_) do { __builtin_amdgcn_s_setprio(1); \
;     for (int k = 0; k < 2; ++k) for (int m = 0; m < 4; ++m) for (int n = 0; n < 2; ++n) \
;       acc[ai][bj][m][n] = __builtin_amdgcn_mfma_f32_16x16x32_bf16(At_[m][k], Bt_[n][k], acc[ai][bj][m][n], 0, 0, 0); \
;     __builtin_amdgcn_s_setprio(0); } while (0)
; #define WAIT_V(n) asm volatile("s_waitcnt vmcnt(" #n ")" ::: "memory")
; #define WAIT_L(n) asm volatile("s_waitcnt lgkmcnt(" #n ")" ::: "memory")
; #define BAR __builtin_amdgcn_s_barrier()
; template <int EPI, int lda, int ldb, int N, int K>
; __device__ __forceinline__ void gemm_phase(const u16* __restrict__ A, const u16* __restrict__ Bt, const GemmEpi ep, int wv) {
;     ...
;       LDB(B1, 0, 1); BAR; WAIT_L(0); MMA(0, 1, At, B1); BAR;
;       LDA(At, 0, 1); WAIT_V(4); BAR; WAIT_L(0); MMA(1, 0, At, B0); MMA(1, 1, At, B1); BAR; }
;     { LDB(B0, 1, 0); LDA(At, 1, 0); WAIT_V(2); BAR; WAIT_L(0); MMA(0, 0, At, B0); BAR;
	s_waitcnt lgkmcnt(0)
	s_waitcnt lgkmcnt(0)
	v_mfma_f32_16x16x32_bf16 v[92:95], v[210:213], v[178:181], v[92:95]
	v_mfma_f32_16x16x32_bf16 v[88:91], v[218:221], v[178:181], v[88:91]
	v_mfma_f32_16x16x32_bf16 v[76:79], v[210:213], v[194:197], v[76:79]
	v_mfma_f32_16x16x32_bf16 v[72:75], v[218:221], v[194:197], v[72:75]
	v_mfma_f32_16x16x32_bf16 v[84:87], v[210:213], v[186:189], v[84:87]
	v_mfma_f32_16x16x32_bf16 v[80:83], v[218:221], v[186:189], v[80:83]
	v_mfma_f32_16x16x32_bf16 v[68:71], v[210:213], v[202:205], v[68:71]
	v_mfma_f32_16x16x32_bf16 v[64:67], v[218:221], v[202:205], v[64:67]
	v_mfma_f32_16x16x32_bf16 v[92:95], v[214:217], v[182:185], v[92:95]
	v_mfma_f32_16x16x32_bf16 v[88:91], v[160:163], v[182:185], v[88:91]
	v_mfma_f32_16x16x32_bf16 v[76:79], v[214:217], v[198:201], v[76:79]
	v_mfma_f32_16x16x32_bf16 v[72:75], v[160:163], v[198:201], v[72:75]
	v_mfma_f32_16x16x32_bf16 v[178:181], v[214:217], v[190:193], v[84:87]
	v_mfma_f32_16x16x32_bf16 v[182:185], v[160:163], v[190:193], v[80:83]
	v_mfma_f32_16x16x32_bf16 v[186:189], v[214:217], v[206:209], v[68:71]
	v_mfma_f32_16x16x32_bf16 v[190:193], v[160:163], v[206:209], v[64:67]
	s_barrier
	s_nop 0
	ds_read_b128 v[64:67], v155 offset:16384
	ds_read_b128 v[68:71], v155 offset:17408
	ds_read_b128 v[80:83], v154 offset:16384
	ds_read_b128 v[84:87], v154 offset:17408
	ds_read_b128 v[194:197], v153 offset:16384
	ds_read_b128 v[198:201], v153 offset:17408
	ds_read_b128 v[202:205], v152 offset:16384
	ds_read_b128 v[206:209], v152 offset:17408
	s_waitcnt vmcnt(4)
	s_barrier
	s_waitcnt lgkmcnt(0)
	s_waitcnt lgkmcnt(0)
	v_mfma_f32_16x16x32_bf16 v[60:63], v[134:137], v[64:67], v[60:63]
	v_mfma_f32_16x16x32_bf16 v[56:59], v[142:145], v[64:67], v[56:59]
	v_mfma_f32_16x16x32_bf16 v[52:55], v[134:137], v[80:83], v[52:55]
	v_mfma_f32_16x16x32_bf16 v[48:51], v[142:145], v[80:83], v[48:51]
	v_mfma_f32_16x16x32_bf16 v[44:47], v[134:137], v[194:197], v[44:47]
	v_mfma_f32_16x16x32_bf16 v[40:43], v[142:145], v[194:197], v[40:43]
	v_mfma_f32_16x16x32_bf16 v[36:39], v[134:137], v[202:205], v[36:39]
	v_mfma_f32_16x16x32_bf16 v[32:35], v[142:145], v[202:205], v[32:35]
	v_mfma_f32_16x16x32_bf16 v[60:63], v[138:141], v[68:71], v[60:63]
	v_mfma_f32_16x16x32_bf16 v[56:59], v[174:177], v[68:71], v[56:59]
	v_mfma_f32_16x16x32_bf16 v[52:55], v[138:141], v[84:87], v[52:55]
	v_mfma_f32_16x16x32_bf16 v[48:51], v[174:177], v[84:87], v[48:51]
	v_mfma_f32_16x16x32_bf16 v[44:47], v[138:141], v[198:201], v[44:47]
	v_mfma_f32_16x16x32_bf16 v[40:43], v[174:177], v[198:201], v[40:43]
	v_mfma_f32_16x16x32_bf16 v[36:39], v[138:141], v[206:209], v[36:39]
	v_mfma_f32_16x16x32_bf16 v[32:35], v[174:177], v[206:209], v[32:35]
	v_mfma_f32_16x16x32_bf16 v[28:31], v[210:213], v[64:67], v[28:31]
	v_mfma_f32_16x16x32_bf16 v[16:19], v[218:221], v[80:83], v[16:19]
	v_mfma_f32_16x16x32_bf16 v[12:15], v[210:213], v[194:197], v[12:15]
	v_mfma_f32_16x16x32_bf16 v[0:3], v[218:221], v[202:205], v[0:3]
	v_mfma_f32_16x16x32_bf16 v[24:27], v[218:221], v[64:67], v[24:27]
	v_mfma_f32_16x16x32_bf16 v[20:23], v[210:213], v[80:83], v[20:23]
	v_mfma_f32_16x16x32_bf16 v[8:11], v[218:221], v[194:197], v[8:11]
	v_mfma_f32_16x16x32_bf16 v[4:7], v[210:213], v[202:205], v[4:7]
	v_mfma_f32_16x16x32_bf16 v[28:31], v[214:217], v[68:71], v[28:31]
	v_mfma_f32_16x16x32_bf16 v[16:19], v[160:163], v[84:87], v[16:19]
	v_mfma_f32_16x16x32_bf16 v[12:15], v[214:217], v[198:201], v[12:15]
	v_mfma_f32_16x16x32_bf16 v[0:3], v[160:163], v[206:209], v[0:3]
	v_mfma_f32_16x16x32_bf16 v[134:137], v[160:163], v[68:71], v[24:27]
	v_mfma_f32_16x16x32_bf16 v[138:141], v[214:217], v[84:87], v[20:23]
	v_mfma_f32_16x16x32_bf16 v[142:145], v[160:163], v[198:201], v[8:11]
	v_mfma_f32_16x16x32_bf16 v[172:175], v[214:217], v[206:209], v[4:7]
	s_barrier
	s_nop 0
	ds_read_b128 v[4:7], v159
	ds_read_b128 v[8:11], v159 offset:1024
	ds_read_b128 v[20:23], v159 offset:2048
	ds_read_b128 v[158:161], v159 offset:3072
	ds_read_b128 v[24:27], v155 offset:32768
	ds_read_b128 v[194:197], v155 offset:33792
	ds_read_b128 v[198:201], v154 offset:32768
	ds_read_b128 v[202:205], v154 offset:33792
	ds_read_b128 v[206:209], v153 offset:32768
	ds_read_b128 v[210:213], v153 offset:33792
	ds_read_b128 v[214:217], v152 offset:32768
	ds_read_b128 v[218:221], v152 offset:33792
	s_waitcnt vmcnt(2)
	s_barrier
; #define LDA(dst, b, h) for (int m = 0; m < 4; ++m) for (int k = 0; k < 2; ++k) \
;     dst[m][k] = *reinterpret_cast<const bf16x8*>((char*)SA(b, h) + lds_byte(wr * 64 + m * 16 + fr, k * 32 + fq * 8))
; #define LDB(dst, b, h) for (int n = 0; n < 2; ++n) for (int k = 0; k < 2; ++k) \
;     dst[n][k] = *reinterpret_cast<const bf16x8*>((char*)SB(b, h) + lds_byte(wc * 32 + n * 16 + fr, k * 32 + fq * 8))
; #define MMA(ai, bj, At_, Bt_) do { __builtin_amdgcn_s_setprio(1); \
;     for (int k = 0; k < 2; ++k) for (int m = 0; m < 4; ++m) for (int n = 0; n < 2; ++n) \
;       acc[ai][bj][m][n] = __builtin_amdgcn_mfma_f32_16x16x32_bf16(At_[m][k], Bt_[n][k], acc[ai][bj][m][n], 0, 0, 0); \
;     __builtin_amdgcn_s_setprio(0); } while (0)
; #define WAIT_V(n) asm volatile("s_waitcnt vmcnt(" #n ")" ::: "memory")
; #define WAIT_L(n) asm volatile("s_waitcnt lgkmcnt(" #n ")" ::: "memory")
; #define BAR __builtin_amdgcn_s_barrier()
; template <int EPI, int lda, int ldb, int N, int K>
; __device__ __forceinline__ void gemm_phase(const u16* __restrict__ A, const u16* __restrict__ Bt, const GemmEpi ep, int wv) {
;     ...
;     { LDB(B0, 1, 0); LDA(At, 1, 0); WAIT_V(2); BAR; WAIT_L(0); MMA(0, 0, At, B0); BAR;
;       LDB(B1, 1, 1); WAIT_V(0); BAR; WAIT_L(0); MMA(0, 1, At, B1); BAR;
;       LDA(At, 1, 1); BAR; WAIT_L(0); MMA(1, 0, At, B0); MMA(1, 1, At, B1); BAR; }
;     if (wr == 0) BAR;
	s_waitcnt lgkmcnt(0)
	s_waitcnt lgkmcnt(0)
	v_mfma_f32_16x16x32_bf16 v[64:67], v[4:7], v[24:27], v[124:127]
	v_mfma_f32_16x16x32_bf16 v[68:71], v[20:23], v[24:27], v[120:123]
	v_mfma_f32_16x16x32_bf16 v[80:83], v[4:7], v[198:201], v[116:119]
	v_mfma_f32_16x16x32_bf16 v[84:87], v[20:23], v[198:201], v[112:115]
	v_mfma_f32_16x16x32_bf16 v[108:111], v[4:7], v[206:209], v[108:111]
	v_mfma_f32_16x16x32_bf16 v[104:107], v[20:23], v[206:209], v[104:107]
	v_mfma_f32_16x16x32_bf16 v[120:123], v[4:7], v[214:217], v[100:103]
	v_mfma_f32_16x16x32_bf16 v[124:127], v[20:23], v[214:217], v[96:99]
	v_mfma_f32_16x16x32_bf16 v[116:119], v[8:11], v[194:197], v[64:67]
	v_mfma_f32_16x16x32_bf16 v[112:115], v[158:161], v[194:197], v[68:71]
	v_mfma_f32_16x16x32_bf16 v[100:103], v[8:11], v[202:205], v[80:83]
	v_mfma_f32_16x16x32_bf16 v[96:99], v[158:161], v[202:205], v[84:87]
	v_mfma_f32_16x16x32_bf16 v[84:87], v[8:11], v[210:213], v[108:111]
	v_mfma_f32_16x16x32_bf16 v[80:83], v[158:161], v[210:213], v[104:107]
	v_mfma_f32_16x16x32_bf16 v[68:71], v[8:11], v[218:221], v[120:123]
	v_mfma_f32_16x16x32_bf16 v[64:67], v[158:161], v[218:221], v[124:127]
	s_barrier
	ds_read_b128 v[222:225], v157
	ds_read_b128 v[226:229], v157 offset:1024
	ds_read_b128 v[230:233], v157 offset:2048
	ds_read_b128 v[234:237], v157 offset:3072
	s_waitcnt vmcnt(0)
	s_barrier
	s_waitcnt lgkmcnt(0)
	s_waitcnt lgkmcnt(0)
	v_mfma_f32_16x16x32_bf16 v[92:95], v[222:225], v[24:27], v[92:95]
	v_mfma_f32_16x16x32_bf16 v[24:27], v[230:233], v[24:27], v[88:91]
	v_mfma_f32_16x16x32_bf16 v[88:91], v[222:225], v[198:201], v[178:181]
	v_mfma_f32_16x16x32_bf16 v[104:107], v[230:233], v[198:201], v[182:185]
	v_mfma_f32_16x16x32_bf16 v[76:79], v[222:225], v[206:209], v[76:79]
	v_mfma_f32_16x16x32_bf16 v[72:75], v[230:233], v[206:209], v[72:75]
	v_mfma_f32_16x16x32_bf16 v[176:179], v[222:225], v[214:217], v[186:189]
	v_mfma_f32_16x16x32_bf16 v[180:183], v[230:233], v[214:217], v[190:193]
	v_mfma_f32_16x16x32_bf16 v[124:127], v[226:229], v[194:197], v[92:95]
	v_mfma_f32_16x16x32_bf16 v[120:123], v[234:237], v[194:197], v[24:27]
	v_mfma_f32_16x16x32_bf16 v[108:111], v[226:229], v[202:205], v[88:91]
	v_mfma_f32_16x16x32_bf16 v[104:107], v[234:237], v[202:205], v[104:107]
	v_mfma_f32_16x16x32_bf16 v[92:95], v[226:229], v[210:213], v[76:79]
	v_mfma_f32_16x16x32_bf16 v[88:91], v[234:237], v[210:213], v[72:75]
	v_mfma_f32_16x16x32_bf16 v[76:79], v[226:229], v[218:221], v[176:179]
	v_mfma_f32_16x16x32_bf16 v[72:75], v[234:237], v[218:221], v[180:183]
	s_barrier
	ds_read_b128 v[176:179], v155 offset:49152
	ds_read_b128 v[180:183], v155 offset:50176
	ds_read_b128 v[184:187], v154 offset:49152
	ds_read_b128 v[154:157], v154 offset:50176
	ds_read_b128 v[188:191], v153 offset:49152
	ds_read_b128 v[192:195], v153 offset:50176
	ds_read_b128 v[196:199], v152 offset:49152
	ds_read_b128 v[200:203], v152 offset:50176
	s_barrier
	s_waitcnt lgkmcnt(0)
	s_waitcnt lgkmcnt(0)
	v_mfma_f32_16x16x32_bf16 v[24:27], v[4:7], v[176:179], v[60:63]
	v_mfma_f32_16x16x32_bf16 v[60:63], v[20:23], v[176:179], v[56:59]
	v_mfma_f32_16x16x32_bf16 v[204:207], v[4:7], v[184:187], v[52:55]
	v_mfma_f32_16x16x32_bf16 v[48:51], v[20:23], v[184:187], v[48:51]
	v_mfma_f32_16x16x32_bf16 v[44:47], v[4:7], v[188:191], v[44:47]
	v_mfma_f32_16x16x32_bf16 v[208:211], v[20:23], v[188:191], v[40:43]
	v_mfma_f32_16x16x32_bf16 v[4:7], v[4:7], v[196:199], v[36:39]
	v_mfma_f32_16x16x32_bf16 v[32:35], v[20:23], v[196:199], v[32:35]
	v_mfma_f32_16x16x32_bf16 v[56:59], v[8:11], v[180:183], v[24:27]
	v_mfma_f32_16x16x32_bf16 v[52:55], v[158:161], v[180:183], v[60:63]
	v_mfma_f32_16x16x32_bf16 v[40:43], v[8:11], v[154:157], v[204:207]
	v_mfma_f32_16x16x32_bf16 v[36:39], v[158:161], v[154:157], v[48:51]
	v_mfma_f32_16x16x32_bf16 v[24:27], v[8:11], v[192:195], v[44:47]
	v_mfma_f32_16x16x32_bf16 v[20:23], v[158:161], v[192:195], v[208:211]
	v_mfma_f32_16x16x32_bf16 v[8:11], v[8:11], v[200:203], v[4:7]
	v_mfma_f32_16x16x32_bf16 v[4:7], v[158:161], v[200:203], v[32:35]
	v_mfma_f32_16x16x32_bf16 v[28:31], v[222:225], v[176:179], v[28:31]
	v_mfma_f32_16x16x32_bf16 v[32:35], v[230:233], v[176:179], v[134:137]
	v_mfma_f32_16x16x32_bf16 v[44:47], v[222:225], v[184:187], v[138:141]
	v_mfma_f32_16x16x32_bf16 v[16:19], v[230:233], v[184:187], v[16:19]
	v_mfma_f32_16x16x32_bf16 v[12:15], v[222:225], v[188:191], v[12:15]
	v_mfma_f32_16x16x32_bf16 v[134:137], v[230:233], v[188:191], v[142:145]
	v_mfma_f32_16x16x32_bf16 v[138:141], v[222:225], v[196:199], v[172:175]
	v_mfma_f32_16x16x32_bf16 v[0:3], v[230:233], v[196:199], v[0:3]
	v_mfma_f32_16x16x32_bf16 v[60:63], v[226:229], v[180:183], v[28:31]
	v_mfma_f32_16x16x32_bf16 v[48:51], v[234:237], v[180:183], v[32:35]
	v_mfma_f32_16x16x32_bf16 v[44:47], v[226:229], v[154:157], v[44:47]
	v_mfma_f32_16x16x32_bf16 v[32:35], v[234:237], v[154:157], v[16:19]
	v_mfma_f32_16x16x32_bf16 v[28:31], v[226:229], v[192:195], v[12:15]
	v_mfma_f32_16x16x32_bf16 v[16:19], v[234:237], v[192:195], v[134:137]
	v_mfma_f32_16x16x32_bf16 v[12:15], v[226:229], v[200:203], v[138:141]
	v_mfma_f32_16x16x32_bf16 v[0:3], v[234:237], v[200:203], v[0:3]
	v_cmp_gt_u32_e32 vcc, s62, v130
	s_barrier
	s_and_saveexec_b64 s[44:45], vcc
	s_cbranch_execz .LBB0_227
	s_barrier

; #define STAGE(P, BASE, LD, br, kt) do { const char* _g = (const char*)((BASE) + (size_t)(br) * (LD) + (size_t)(kt) * 64); \
;     for (int _i = 0; _i < 2; ++_i) { int _b = tidx * 16 + _i * 8192; int _r, _c; stage_rc(_b, _r, _c); \
;       __builtin_amdgcn_global_load_lds((const unsigned*)(_g + (unsigned)((_r * (LD) + _c) * 2)), (unsigned*)((char*)(P) + _b), 16, 0, 0); } } while (0)
; #define LDA(dst, b, h) for (int m = 0; m < 4; ++m) for (int k = 0; k < 2; ++k) \
;     dst[m][k] = *reinterpret_cast<const bf16x8*>((char*)SA(b, h) + lds_byte(wr * 64 + m * 16 + fr, k * 32 + fq * 8))
; #define LDB(dst, b, h) for (int n = 0; n < 2; ++n) for (int k = 0; k < 2; ++k) \
;     dst[n][k] = *reinterpret_cast<const bf16x8*>((char*)SB(b, h) + lds_byte(wc * 32 + n * 16 + fr, k * 32 + fq * 8))
; #define MMA(ai, bj, At_, Bt_) do { __builtin_amdgcn_s_setprio(1); \
;     for (int k = 0; k < 2; ++k) for (int m = 0; m < 4; ++m) for (int n = 0; n < 2; ++n) \
;       acc[ai][bj][m][n] = __builtin_amdgcn_mfma_f32_16x16x32_bf16(At_[m][k], Bt_[n][k], acc[ai][bj][m][n], 0, 0, 0); \
;     __builtin_amdgcn_s_setprio(0); } while (0)
; #define WAIT_L(n) asm volatile("s_waitcnt lgkmcnt(" #n ")" ::: "memory")
; #define BAR __builtin_amdgcn_s_barrier()
; #define SCHED __builtin_amdgcn_sched_barrier(0)
; template <int EPI, int lda, int ldb, int N, int K>
; __device__ __forceinline__ void gemm_phase(const u16* __restrict__ A, const u16* __restrict__ Bt, const GemmEpi ep, int wv) {
;     ...
;       LDB(B0, 0, 0); SCHED; LDA(At, 0, 0); STAGE(SA(1, 1), Ab, lda, brow + HALF, t + 1);
;       WAIT_L(8); BAR; WAIT_L(0); MMA(0, 0, At, B0); BAR; SCHED;
;       LDB(B1, 0, 1); STAGE(SB(0, 0), Bt, ldb, bcol, t + 2);
;       BAR; WAIT_L(0); MMA(0, 1, At, B1); BAR;
;       LDA(At, 0, 1); STAGE(SA(0, 0), Ab, lda, brow, t + 2);
;       BAR; WAIT_L(0); MMA(1, 0, At, B0); BAR; SCHED;
.LBB0_340:
	ds_read_b128 v[166:169], v162
	ds_read_b128 v[172:175], v162 offset:1024
	ds_read_b128 v[176:179], v162 offset:2048
	ds_read_b128 v[180:183], v162 offset:3072
	v_add_u32_e32 v170, 0xc000, v149
	v_lshl_add_u64 v[236:237], v[138:139], 0, s[48:49]
	v_readfirstlane_b32 s51, v170
	v_add_u32_e32 v171, 0xe000, v149
	v_lshl_add_u64 v[164:165], v[236:237], 0, s[18:19]
	s_mov_b32 m0, s51
	v_lshl_add_u64 v[238:239], v[140:141], 0, s[48:49]
	v_readfirstlane_b32 s51, v171
	ds_read_b128 v[184:187], v153
	ds_read_b128 v[188:191], v153 offset:1024
	ds_read_b128 v[192:195], v152
	ds_read_b128 v[196:199], v152 offset:1024
	ds_read_b128 v[200:203], v151
	ds_read_b128 v[204:207], v151 offset:1024
	ds_read_b128 v[208:211], v150
	ds_read_b128 v[212:215], v150 offset:1024
	global_load_lds_dwordx4 v[164:165], off
	v_lshl_add_u64 v[164:165], v[238:239], 0, s[18:19]
	s_mov_b32 m0, s51
	s_nop 0
	global_load_lds_dwordx4 v[164:165], off
	s_waitcnt lgkmcnt(8)
	s_barrier
	s_waitcnt lgkmcnt(0)
	s_waitcnt lgkmcnt(0)
	v_mfma_f32_16x16x32_bf16 v[124:127], v[184:187], v[166:169], v[124:127]
	v_mfma_f32_16x16x32_bf16 v[120:123], v[184:187], v[176:179], v[120:123]
	v_mfma_f32_16x16x32_bf16 v[116:119], v[192:195], v[166:169], v[116:119]
	v_mfma_f32_16x16x32_bf16 v[112:115], v[192:195], v[176:179], v[112:115]
	v_mfma_f32_16x16x32_bf16 v[108:111], v[200:203], v[166:169], v[108:111]
	v_mfma_f32_16x16x32_bf16 v[104:107], v[200:203], v[176:179], v[104:107]
	v_mfma_f32_16x16x32_bf16 v[100:103], v[208:211], v[166:169], v[100:103]
	v_mfma_f32_16x16x32_bf16 v[96:99], v[208:211], v[176:179], v[96:99]
	v_mfma_f32_16x16x32_bf16 v[124:127], v[188:191], v[172:175], v[124:127]
	v_mfma_f32_16x16x32_bf16 v[120:123], v[188:191], v[180:183], v[120:123]
	v_mfma_f32_16x16x32_bf16 v[116:119], v[196:199], v[172:175], v[116:119]
	v_mfma_f32_16x16x32_bf16 v[112:115], v[196:199], v[180:183], v[112:115]
	v_mfma_f32_16x16x32_bf16 v[108:111], v[204:207], v[172:175], v[108:111]
	v_mfma_f32_16x16x32_bf16 v[104:107], v[204:207], v[180:183], v[104:107]
	v_mfma_f32_16x16x32_bf16 v[100:103], v[212:215], v[172:175], v[100:103]
	v_mfma_f32_16x16x32_bf16 v[96:99], v[212:215], v[180:183], v[96:99]
	s_barrier
	v_add_u32_e32 v163, s62, v155
	v_lshl_add_u64 v[240:241], v[134:135], 0, s[48:49]
	v_readfirstlane_b32 s51, v163
	v_lshl_add_u64 v[164:165], v[240:241], 0, s[20:21]
	s_mov_b32 m0, s51
	ds_read_b128 v[216:219], v161
	ds_read_b128 v[220:223], v161 offset:1024
	ds_read_b128 v[224:227], v161 offset:2048
	ds_read_b128 v[228:231], v161 offset:3072
	global_load_lds_dwordx4 v[164:165], off
	v_add_u32_e32 v164, 0x2000, v163
	v_lshl_add_u64 v[242:243], v[136:137], 0, s[48:49]
	v_readfirstlane_b32 s51, v164
	v_lshl_add_u64 v[232:233], v[242:243], 0, s[20:21]
	s_mov_b32 m0, s51
	s_nop 0
	global_load_lds_dwordx4 v[232:233], off
	s_waitcnt vmcnt(10)
	s_barrier
	s_waitcnt lgkmcnt(0)
	s_waitcnt lgkmcnt(0)
	v_mfma_f32_16x16x32_bf16 v[92:95], v[184:187], v[216:219], v[92:95]
	v_mfma_f32_16x16x32_bf16 v[88:91], v[184:187], v[224:227], v[88:91]
	v_mfma_f32_16x16x32_bf16 v[84:87], v[192:195], v[216:219], v[84:87]
	v_mfma_f32_16x16x32_bf16 v[80:83], v[192:195], v[224:227], v[80:83]
	v_mfma_f32_16x16x32_bf16 v[76:79], v[200:203], v[216:219], v[76:79]
	v_mfma_f32_16x16x32_bf16 v[72:75], v[200:203], v[224:227], v[72:75]
	v_mfma_f32_16x16x32_bf16 v[68:71], v[208:211], v[216:219], v[68:71]
	v_mfma_f32_16x16x32_bf16 v[64:67], v[208:211], v[224:227], v[64:67]
	v_mfma_f32_16x16x32_bf16 v[92:95], v[188:191], v[220:223], v[92:95]
	v_mfma_f32_16x16x32_bf16 v[88:91], v[188:191], v[228:231], v[88:91]
	v_mfma_f32_16x16x32_bf16 v[84:87], v[196:199], v[220:223], v[84:87]
	v_mfma_f32_16x16x32_bf16 v[80:83], v[196:199], v[228:231], v[80:83]
	v_mfma_f32_16x16x32_bf16 v[76:79], v[204:207], v[220:223], v[76:79]
	v_mfma_f32_16x16x32_bf16 v[72:75], v[204:207], v[228:231], v[72:75]
	v_mfma_f32_16x16x32_bf16 v[68:71], v[212:215], v[220:223], v[68:71]
	v_mfma_f32_16x16x32_bf16 v[64:67], v[212:215], v[228:231], v[64:67]
	v_readfirstlane_b32 s51, v149
	v_add_u32_e32 v165, 0x2000, v149
	v_lshl_add_u64 v[232:233], v[236:237], 0, s[22:23]
	s_mov_b32 m0, s51
	v_readfirstlane_b32 s51, v165
	s_barrier
	ds_read_b128 v[184:187], v153 offset:16384
	ds_read_b128 v[188:191], v153 offset:17408
	ds_read_b128 v[192:195], v152 offset:16384
	ds_read_b128 v[196:199], v152 offset:17408
	ds_read_b128 v[200:203], v151 offset:16384
	ds_read_b128 v[204:207], v151 offset:17408
	ds_read_b128 v[208:211], v150 offset:16384
	ds_read_b128 v[212:215], v150 offset:17408
	global_load_lds_dwordx4 v[232:233], off
	v_lshl_add_u64 v[232:233], v[238:239], 0, s[22:23]
	s_mov_b32 m0, s51
	s_nop 0
	global_load_lds_dwordx4 v[232:233], off
	s_barrier
	s_waitcnt lgkmcnt(0)
	s_waitcnt lgkmcnt(0)
	v_mfma_f32_16x16x32_bf16 v[60:63], v[184:187], v[166:169], v[60:63]
	v_mfma_f32_16x16x32_bf16 v[56:59], v[184:187], v[176:179], v[56:59]
	v_mfma_f32_16x16x32_bf16 v[52:55], v[192:195], v[166:169], v[52:55]
	v_mfma_f32_16x16x32_bf16 v[48:51], v[192:195], v[176:179], v[48:51]
	v_mfma_f32_16x16x32_bf16 v[44:47], v[200:203], v[166:169], v[44:47]
	v_mfma_f32_16x16x32_bf16 v[40:43], v[200:203], v[176:179], v[40:43]
	v_mfma_f32_16x16x32_bf16 v[36:39], v[208:211], v[166:169], v[36:39]
	v_mfma_f32_16x16x32_bf16 v[32:35], v[208:211], v[176:179], v[32:35]
	v_mfma_f32_16x16x32_bf16 v[60:63], v[188:191], v[172:175], v[60:63]
	v_mfma_f32_16x16x32_bf16 v[56:59], v[188:191], v[180:183], v[56:59]
	v_mfma_f32_16x16x32_bf16 v[52:55], v[196:199], v[172:175], v[52:55]
	v_mfma_f32_16x16x32_bf16 v[48:51], v[196:199], v[180:183], v[48:51]
	v_mfma_f32_16x16x32_bf16 v[44:47], v[204:207], v[172:175], v[44:47]
	v_mfma_f32_16x16x32_bf16 v[40:43], v[204:207], v[180:183], v[40:43]
	v_mfma_f32_16x16x32_bf16 v[36:39], v[212:215], v[172:175], v[36:39]
	v_mfma_f32_16x16x32_bf16 v[32:35], v[212:215], v[180:183], v[32:35]
	s_barrier
; #define STAGE(P, BASE, LD, br, kt) do { const char* _g = (const char*)((BASE) + (size_t)(br) * (LD) + (size_t)(kt) * 64); \
;     for (int _i = 0; _i < 2; ++_i) { int _b = tidx * 16 + _i * 8192; int _r, _c; stage_rc(_b, _r, _c); \
;       __builtin_amdgcn_global_load_lds((const unsigned*)(_g + (unsigned)((_r * (LD) + _c) * 2)), (unsigned*)((char*)(P) + _b), 16, 0, 0); } } while (0)
; #define LDA(dst, b, h) for (int m = 0; m < 4; ++m) for (int k = 0; k < 2; ++k) \
;     dst[m][k] = *reinterpret_cast<const bf16x8*>((char*)SA(b, h) + lds_byte(wr * 64 + m * 16 + fr, k * 32 + fq * 8))
; #define LDB(dst, b, h) for (int n = 0; n < 2; ++n) for (int k = 0; k < 2; ++k) \
;     dst[n][k] = *reinterpret_cast<const bf16x8*>((char*)SB(b, h) + lds_byte(wc * 32 + n * 16 + fr, k * 32 + fq * 8))
; #define MMA(ai, bj, At_, Bt_) do { __builtin_amdgcn_s_setprio(1); \
;     for (int k = 0; k < 2; ++k) for (int m = 0; m < 4; ++m) for (int n = 0; n < 2; ++n) \
;       acc[ai][bj][m][n] = __builtin_amdgcn_mfma_f32_16x16x32_bf16(At_[m][k], Bt_[n][k], acc[ai][bj][m][n], 0, 0, 0); \
;     __builtin_amdgcn_s_setprio(0); } while (0)
; #define WAIT_V(n) asm volatile("s_waitcnt vmcnt(" #n ")" ::: "memory")
; #define WAIT_L(n) asm volatile("s_waitcnt lgkmcnt(" #n ")" ::: "memory")
; #define BAR __builtin_amdgcn_s_barrier()
; #define SCHED __builtin_amdgcn_sched_barrier(0)
; template <int EPI, int lda, int ldb, int N, int K>
; __device__ __forceinline__ void gemm_phase(const u16* __restrict__ A, const u16* __restrict__ Bt, const GemmEpi ep, int wv) {
;     ...
;       STAGE(SB(0, 1), Bt, ldb, bcol + HALF, t + 2);
;       WAIT_V(6); BAR; MMA(1, 1, At, B1); BAR;
;       LDB(B0, 1, 0); SCHED; LDA(At, 1, 0); STAGE(SA(0, 1), Ab, lda, brow + HALF, t + 2);
;       WAIT_L(8); BAR; WAIT_L(0); MMA(0, 0, At, B0); BAR; SCHED;
;       LDB(B1, 1, 1); STAGE(SB(1, 0), Bt, ldb, bcol, t + 3);
;       BAR; WAIT_L(0); MMA(0, 1, At, B1); BAR;
	v_add_u32_e32 v166, s63, v155
	v_add_u32_e32 v167, 0x2000, v166
	v_readfirstlane_b32 s51, v166
	v_lshl_add_u64 v[168:169], v[240:241], 0, s[24:25]
	s_mov_b32 m0, s51
	v_readfirstlane_b32 s51, v167
	global_load_lds_dwordx4 v[168:169], off
	v_lshl_add_u64 v[168:169], v[242:243], 0, s[24:25]
	s_mov_b32 m0, s51
	s_nop 0
	global_load_lds_dwordx4 v[168:169], off
	s_waitcnt vmcnt(8)
	s_barrier
	v_mfma_f32_16x16x32_bf16 v[28:31], v[184:187], v[216:219], v[28:31]
	v_mfma_f32_16x16x32_bf16 v[24:27], v[184:187], v[224:227], v[24:27]
	v_mfma_f32_16x16x32_bf16 v[20:23], v[192:195], v[216:219], v[20:23]
	v_mfma_f32_16x16x32_bf16 v[16:19], v[192:195], v[224:227], v[16:19]
	v_mfma_f32_16x16x32_bf16 v[12:15], v[200:203], v[216:219], v[12:15]
	v_mfma_f32_16x16x32_bf16 v[8:11], v[200:203], v[224:227], v[8:11]
	v_mfma_f32_16x16x32_bf16 v[4:7], v[208:211], v[216:219], v[4:7]
	v_mfma_f32_16x16x32_bf16 v[0:3], v[208:211], v[224:227], v[0:3]
	v_mfma_f32_16x16x32_bf16 v[28:31], v[188:191], v[220:223], v[28:31]
	v_mfma_f32_16x16x32_bf16 v[24:27], v[188:191], v[228:231], v[24:27]
	v_mfma_f32_16x16x32_bf16 v[20:23], v[196:199], v[220:223], v[20:23]
	v_mfma_f32_16x16x32_bf16 v[16:19], v[196:199], v[228:231], v[16:19]
	v_mfma_f32_16x16x32_bf16 v[12:15], v[204:207], v[220:223], v[12:15]
	v_mfma_f32_16x16x32_bf16 v[8:11], v[204:207], v[228:231], v[8:11]
	v_mfma_f32_16x16x32_bf16 v[4:7], v[212:215], v[220:223], v[4:7]
	v_mfma_f32_16x16x32_bf16 v[0:3], v[212:215], v[228:231], v[0:3]
	s_barrier
	ds_read_b128 v[172:175], v156
	ds_read_b128 v[176:179], v156 offset:1024
	ds_read_b128 v[180:183], v156 offset:2048
	ds_read_b128 v[184:187], v156 offset:3072
	v_add_u32_e32 v168, 0x4000, v149
	v_add_u32_e32 v169, 0x6000, v149
	v_readfirstlane_b32 s51, v168
	v_lshl_add_u64 v[220:221], v[236:237], 0, s[26:27]
	s_mov_b32 m0, s51
	v_readfirstlane_b32 s51, v169
	ds_read_b128 v[188:191], v153 offset:32768
	ds_read_b128 v[192:195], v153 offset:33792
	ds_read_b128 v[196:199], v152 offset:32768
	ds_read_b128 v[200:203], v152 offset:33792
	ds_read_b128 v[204:207], v151 offset:32768
	ds_read_b128 v[208:211], v151 offset:33792
	ds_read_b128 v[212:215], v150 offset:32768
	ds_read_b128 v[216:219], v150 offset:33792
	global_load_lds_dwordx4 v[220:221], off
	v_lshl_add_u64 v[220:221], v[238:239], 0, s[26:27]
	s_mov_b32 m0, s51
	s_nop 0
	global_load_lds_dwordx4 v[220:221], off
	s_waitcnt lgkmcnt(8)
	s_barrier
	s_waitcnt lgkmcnt(0)
	s_waitcnt lgkmcnt(0)
	v_mfma_f32_16x16x32_bf16 v[124:127], v[188:191], v[172:175], v[124:127]
	v_mfma_f32_16x16x32_bf16 v[120:123], v[188:191], v[180:183], v[120:123]
	v_mfma_f32_16x16x32_bf16 v[116:119], v[196:199], v[172:175], v[116:119]
	v_mfma_f32_16x16x32_bf16 v[112:115], v[196:199], v[180:183], v[112:115]
	v_mfma_f32_16x16x32_bf16 v[108:111], v[204:207], v[172:175], v[108:111]
	v_mfma_f32_16x16x32_bf16 v[104:107], v[204:207], v[180:183], v[104:107]
	v_mfma_f32_16x16x32_bf16 v[100:103], v[212:215], v[172:175], v[100:103]
	v_mfma_f32_16x16x32_bf16 v[96:99], v[212:215], v[180:183], v[96:99]
	v_mfma_f32_16x16x32_bf16 v[124:127], v[192:195], v[176:179], v[124:127]
	v_mfma_f32_16x16x32_bf16 v[120:123], v[192:195], v[184:187], v[120:123]
	v_mfma_f32_16x16x32_bf16 v[116:119], v[200:203], v[176:179], v[116:119]
	v_mfma_f32_16x16x32_bf16 v[112:115], v[200:203], v[184:187], v[112:115]
	v_mfma_f32_16x16x32_bf16 v[108:111], v[208:211], v[176:179], v[108:111]
	v_mfma_f32_16x16x32_bf16 v[104:107], v[208:211], v[184:187], v[104:107]
	v_mfma_f32_16x16x32_bf16 v[100:103], v[216:219], v[176:179], v[100:103]
	v_mfma_f32_16x16x32_bf16 v[96:99], v[216:219], v[184:187], v[96:99]
	s_barrier
	v_readfirstlane_b32 s51, v157
	v_add_u32_e32 v246, 0x2000, v157
	v_lshl_add_u64 v[244:245], v[240:241], 0, s[36:37]
	s_mov_b32 m0, s51
	v_readfirstlane_b32 s51, v246
	ds_read_b128 v[220:223], v154
	ds_read_b128 v[224:227], v154 offset:1024
	ds_read_b128 v[228:231], v154 offset:2048
	ds_read_b128 v[232:235], v154 offset:3072
	global_load_lds_dwordx4 v[244:245], off
	v_lshl_add_u64 v[244:245], v[242:243], 0, s[36:37]
	s_mov_b32 m0, s51
	s_nop 0
	global_load_lds_dwordx4 v[244:245], off
	s_waitcnt vmcnt(10)
	s_barrier
	s_waitcnt lgkmcnt(0)
	s_waitcnt lgkmcnt(0)
	v_mfma_f32_16x16x32_bf16 v[92:95], v[188:191], v[220:223], v[92:95]
	v_mfma_f32_16x16x32_bf16 v[88:91], v[188:191], v[228:231], v[88:91]
	v_mfma_f32_16x16x32_bf16 v[84:87], v[196:199], v[220:223], v[84:87]
	v_mfma_f32_16x16x32_bf16 v[80:83], v[196:199], v[228:231], v[80:83]
	v_mfma_f32_16x16x32_bf16 v[76:79], v[204:207], v[220:223], v[76:79]
	v_mfma_f32_16x16x32_bf16 v[72:75], v[204:207], v[228:231], v[72:75]
	v_mfma_f32_16x16x32_bf16 v[68:71], v[212:215], v[220:223], v[68:71]
	v_mfma_f32_16x16x32_bf16 v[64:67], v[212:215], v[228:231], v[64:67]
	v_mfma_f32_16x16x32_bf16 v[92:95], v[192:195], v[224:227], v[92:95]
	v_mfma_f32_16x16x32_bf16 v[88:91], v[192:195], v[232:235], v[88:91]
	v_mfma_f32_16x16x32_bf16 v[84:87], v[200:203], v[224:227], v[84:87]
	v_mfma_f32_16x16x32_bf16 v[80:83], v[200:203], v[232:235], v[80:83]
	v_mfma_f32_16x16x32_bf16 v[76:79], v[208:211], v[224:227], v[76:79]
	v_mfma_f32_16x16x32_bf16 v[72:75], v[208:211], v[232:235], v[72:75]
	v_mfma_f32_16x16x32_bf16 v[68:71], v[216:219], v[224:227], v[68:71]
	v_mfma_f32_16x16x32_bf16 v[64:67], v[216:219], v[232:235], v[64:67]
	v_readfirstlane_b32 s51, v158
	v_lshl_add_u64 v[236:237], v[236:237], 0, s[38:39]
	s_mov_b32 m0, s51
	v_readfirstlane_b32 s51, v159
	s_barrier
; #define STAGE(P, BASE, LD, br, kt) do { const char* _g = (const char*)((BASE) + (size_t)(br) * (LD) + (size_t)(kt) * 64); \
;     for (int _i = 0; _i < 2; ++_i) { int _b = tidx * 16 + _i * 8192; int _r, _c; stage_rc(_b, _r, _c); \
;       __builtin_amdgcn_global_load_lds((const unsigned*)(_g + (unsigned)((_r * (LD) + _c) * 2)), (unsigned*)((char*)(P) + _b), 16, 0, 0); } } while (0)
; #define LDA(dst, b, h) for (int m = 0; m < 4; ++m) for (int k = 0; k < 2; ++k) \
;     dst[m][k] = *reinterpret_cast<const bf16x8*>((char*)SA(b, h) + lds_byte(wr * 64 + m * 16 + fr, k * 32 + fq * 8))
; #define LDB(dst, b, h) for (int n = 0; n < 2; ++n) for (int k = 0; k < 2; ++k) \
;     dst[n][k] = *reinterpret_cast<const bf16x8*>((char*)SB(b, h) + lds_byte(wc * 32 + n * 16 + fr, k * 32 + fq * 8))
; #define MMA(ai, bj, At_, Bt_) do { __builtin_amdgcn_s_setprio(1); \
;     for (int k = 0; k < 2; ++k) for (int m = 0; m < 4; ++m) for (int n = 0; n < 2; ++n) \
;       acc[ai][bj][m][n] = __builtin_amdgcn_mfma_f32_16x16x32_bf16(At_[m][k], Bt_[n][k], acc[ai][bj][m][n], 0, 0, 0); \
;     __builtin_amdgcn_s_setprio(0); } while (0)
; #define WAIT_V(n) asm volatile("s_waitcnt vmcnt(" #n ")" ::: "memory")
; #define WAIT_L(n) asm volatile("s_waitcnt lgkmcnt(" #n ")" ::: "memory")
; #define BAR __builtin_amdgcn_s_barrier()
; #define SCHED __builtin_amdgcn_sched_barrier(0)
; template <int EPI, int lda, int ldb, int N, int K>
; __device__ __forceinline__ void gemm_phase(const u16* __restrict__ A, const u16* __restrict__ Bt, const GemmEpi ep, int wv) {
;     ...
;       LDA(At, 1, 1); STAGE(SA(1, 0), Ab, lda, brow, t + 3);
;       BAR; WAIT_L(0); MMA(1, 0, At, B0); BAR; SCHED;
;       STAGE(SB(1, 1), Bt, ldb, bcol + HALF, t + 3);
;       WAIT_V(6); BAR; MMA(1, 1, At, B1); BAR;
;     }
;     { LDB(B0, 0, 0); LDA(At, 0, 0); STAGE(SA(1, 1), Ab, lda, brow + HALF, nt - 1);
;       BAR; WAIT_L(0); MMA(0, 0, At, B0); BAR;
;       LDB(B1, 0, 1); BAR; WAIT_L(0); MMA(0, 1, At, B1); BAR;
	ds_read_b128 v[188:191], v153 offset:49152
	ds_read_b128 v[192:195], v153 offset:50176
	ds_read_b128 v[196:199], v152 offset:49152
	ds_read_b128 v[200:203], v152 offset:50176
	ds_read_b128 v[204:207], v151 offset:49152
	ds_read_b128 v[208:211], v151 offset:50176
	ds_read_b128 v[212:215], v150 offset:49152
	ds_read_b128 v[216:219], v150 offset:50176
	global_load_lds_dwordx4 v[236:237], off
	v_lshl_add_u64 v[236:237], v[238:239], 0, s[38:39]
	s_mov_b32 m0, s51
	s_nop 0
	global_load_lds_dwordx4 v[236:237], off
	s_barrier
	s_waitcnt lgkmcnt(0)
	s_waitcnt lgkmcnt(0)
	v_mfma_f32_16x16x32_bf16 v[60:63], v[188:191], v[172:175], v[60:63]
	v_mfma_f32_16x16x32_bf16 v[56:59], v[188:191], v[180:183], v[56:59]
	v_mfma_f32_16x16x32_bf16 v[52:55], v[196:199], v[172:175], v[52:55]
	v_mfma_f32_16x16x32_bf16 v[48:51], v[196:199], v[180:183], v[48:51]
	v_mfma_f32_16x16x32_bf16 v[44:47], v[204:207], v[172:175], v[44:47]
	v_mfma_f32_16x16x32_bf16 v[40:43], v[204:207], v[180:183], v[40:43]
	v_mfma_f32_16x16x32_bf16 v[36:39], v[212:215], v[172:175], v[36:39]
	v_mfma_f32_16x16x32_bf16 v[32:35], v[212:215], v[180:183], v[32:35]
	v_mfma_f32_16x16x32_bf16 v[60:63], v[192:195], v[176:179], v[60:63]
	v_mfma_f32_16x16x32_bf16 v[56:59], v[192:195], v[184:187], v[56:59]
	v_mfma_f32_16x16x32_bf16 v[52:55], v[200:203], v[176:179], v[52:55]
	v_mfma_f32_16x16x32_bf16 v[48:51], v[200:203], v[184:187], v[48:51]
	v_mfma_f32_16x16x32_bf16 v[44:47], v[208:211], v[176:179], v[44:47]
	v_mfma_f32_16x16x32_bf16 v[40:43], v[208:211], v[184:187], v[40:43]
	v_mfma_f32_16x16x32_bf16 v[36:39], v[216:219], v[176:179], v[36:39]
	v_mfma_f32_16x16x32_bf16 v[32:35], v[216:219], v[184:187], v[32:35]
	s_barrier
	v_readfirstlane_b32 s51, v160
	v_add_u32_e32 v174, 0x2000, v160
	v_lshl_add_u64 v[172:173], v[240:241], 0, s[42:43]
	s_mov_b32 m0, s51
	v_readfirstlane_b32 s51, v174
	global_load_lds_dwordx4 v[172:173], off
	v_lshl_add_u64 v[172:173], v[242:243], 0, s[42:43]
	s_mov_b32 m0, s51
	s_nop 0
	global_load_lds_dwordx4 v[172:173], off
	s_waitcnt vmcnt(8)
	s_barrier
	v_mfma_f32_16x16x32_bf16 v[28:31], v[188:191], v[220:223], v[28:31]
	v_mfma_f32_16x16x32_bf16 v[24:27], v[188:191], v[228:231], v[24:27]
	v_mfma_f32_16x16x32_bf16 v[20:23], v[196:199], v[220:223], v[20:23]
	v_mfma_f32_16x16x32_bf16 v[16:19], v[196:199], v[228:231], v[16:19]
	v_mfma_f32_16x16x32_bf16 v[12:15], v[204:207], v[220:223], v[12:15]
	v_mfma_f32_16x16x32_bf16 v[8:11], v[204:207], v[228:231], v[8:11]
	v_mfma_f32_16x16x32_bf16 v[4:7], v[212:215], v[220:223], v[4:7]
	v_mfma_f32_16x16x32_bf16 v[0:3], v[212:215], v[228:231], v[0:3]
	v_mfma_f32_16x16x32_bf16 v[28:31], v[192:195], v[224:227], v[28:31]
	v_mfma_f32_16x16x32_bf16 v[24:27], v[192:195], v[232:235], v[24:27]
	v_mfma_f32_16x16x32_bf16 v[20:23], v[200:203], v[224:227], v[20:23]
	v_mfma_f32_16x16x32_bf16 v[16:19], v[200:203], v[232:235], v[16:19]
	v_mfma_f32_16x16x32_bf16 v[12:15], v[208:211], v[224:227], v[12:15]
	v_mfma_f32_16x16x32_bf16 v[8:11], v[208:211], v[232:235], v[8:11]
	v_mfma_f32_16x16x32_bf16 v[4:7], v[216:219], v[224:227], v[4:7]
	v_mfma_f32_16x16x32_bf16 v[0:3], v[216:219], v[232:235], v[0:3]
	s_add_i32 s50, s50, 2
	s_add_u32 s48, s48, 0x100
	s_addc_u32 s49, s49, 0
	s_cmp_gt_u32 s50, 27
	s_barrier
	s_cbranch_scc0 .LBB0_340
	s_add_i32 s48, s46, 0x80
	s_mul_hi_i32 s49, s48, 0x1080
	s_mulk_i32 s48, 0x1080
	s_add_u32 s48, s31, s48
	s_addc_u32 s49, s56, s49
	v_lshl_add_u64 v[158:159], s[48:49], 0, v[128:129]
	v_readfirstlane_b32 s50, v170
	v_lshl_add_u64 v[158:159], v[158:159], 0, s[44:45]
	s_mov_b32 m0, s50
	ds_read_b128 v[134:137], v162
	ds_read_b128 v[138:141], v162 offset:1024
	ds_read_b128 v[172:175], v162 offset:2048
	ds_read_b128 v[176:179], v162 offset:3072
	ds_read_b128 v[180:183], v153
	ds_read_b128 v[184:187], v153 offset:1024
	ds_read_b128 v[188:191], v152
	ds_read_b128 v[192:195], v152 offset:1024
	ds_read_b128 v[196:199], v151
	ds_read_b128 v[200:203], v151 offset:1024
	ds_read_b128 v[204:207], v150
	ds_read_b128 v[208:211], v150 offset:1024
	global_load_lds_dwordx4 v[158:159], off
	v_lshl_add_u64 v[158:159], s[48:49], 0, v[132:133]
	v_readfirstlane_b32 s48, v171
	v_lshl_add_u64 v[158:159], v[158:159], 0, s[44:45]
	s_mov_b32 m0, s48
	s_nop 0
	global_load_lds_dwordx4 v[158:159], off
	s_barrier
	s_waitcnt lgkmcnt(0)
	s_waitcnt lgkmcnt(0)
	v_mfma_f32_16x16x32_bf16 v[124:127], v[180:183], v[134:137], v[124:127]
	v_mfma_f32_16x16x32_bf16 v[120:123], v[180:183], v[172:175], v[120:123]
	v_mfma_f32_16x16x32_bf16 v[116:119], v[188:191], v[134:137], v[116:119]
	v_mfma_f32_16x16x32_bf16 v[112:115], v[188:191], v[172:175], v[112:115]
	v_mfma_f32_16x16x32_bf16 v[108:111], v[196:199], v[134:137], v[108:111]
	v_mfma_f32_16x16x32_bf16 v[104:107], v[196:199], v[172:175], v[104:107]
	v_mfma_f32_16x16x32_bf16 v[100:103], v[204:207], v[134:137], v[100:103]
	v_mfma_f32_16x16x32_bf16 v[96:99], v[204:207], v[172:175], v[96:99]
	v_mfma_f32_16x16x32_bf16 v[124:127], v[184:187], v[138:141], v[124:127]
	v_mfma_f32_16x16x32_bf16 v[120:123], v[184:187], v[176:179], v[120:123]
	v_mfma_f32_16x16x32_bf16 v[116:119], v[192:195], v[138:141], v[116:119]
	v_mfma_f32_16x16x32_bf16 v[112:115], v[192:195], v[176:179], v[112:115]
	v_mfma_f32_16x16x32_bf16 v[108:111], v[200:203], v[138:141], v[108:111]
	v_mfma_f32_16x16x32_bf16 v[104:107], v[200:203], v[176:179], v[104:107]
	v_mfma_f32_16x16x32_bf16 v[100:103], v[208:211], v[138:141], v[100:103]
	v_mfma_f32_16x16x32_bf16 v[96:99], v[208:211], v[176:179], v[96:99]
	s_barrier
	ds_read_b128 v[212:215], v161
	ds_read_b128 v[216:219], v161 offset:1024
	ds_read_b128 v[220:223], v161 offset:2048
	ds_read_b128 v[158:161], v161 offset:3072
	s_waitcnt vmcnt(8)
	s_barrier
; #define LDA(dst, b, h) for (int m = 0; m < 4; ++m) for (int k = 0; k < 2; ++k) \
;     dst[m][k] = *reinterpret_cast<const bf16x8*>((char*)SA(b, h) + lds_byte(wr * 64 + m * 16 + fr, k * 32 + fq * 8))
; #define LDB(dst, b, h) for (int n = 0; n < 2; ++n) for (int k = 0; k < 2; ++k) \
;     dst[n][k] = *reinterpret_cast<const bf16x8*>((char*)SB(b, h) + lds_byte(wc * 32 + n * 16 + fr, k * 32 + fq * 8))
; #define MMA(ai, bj, At_, Bt_) do { __builtin_amdgcn_s_setprio(1); \
;     for (int k = 0; k < 2; ++k) for (int m = 0; m < 4; ++m) for (int n = 0; n < 2; ++n) \
;       acc[ai][bj][m][n] = __builtin_amdgcn_mfma_f32_16x16x32_bf16(At_[m][k], Bt_[n][k], acc[ai][bj][m][n], 0, 0, 0); \
;     __builtin_amdgcn_s_setprio(0); } while (0)
; #define WAIT_V(n) asm volatile("s_waitcnt vmcnt(" #n ")" ::: "memory")
; #define WAIT_L(n) asm volatile("s_waitcnt lgkmcnt(" #n ")" ::: "memory")
; #define BAR __builtin_amdgcn_s_barrier()
; template <int EPI, int lda, int ldb, int N, int K>
; __device__ __forceinline__ void gemm_phase(const u16* __restrict__ A, const u16* __restrict__ Bt, const GemmEpi ep, int wv) {
;     ...
;       LDB(B1, 0, 1); BAR; WAIT_L(0); MMA(0, 1, At, B1); BAR;
;       LDA(At, 0, 1); WAIT_V(4); BAR; WAIT_L(0); MMA(1, 0, At, B0); MMA(1, 1, At, B1); BAR; }
;     { LDB(B0, 1, 0); LDA(At, 1, 0); WAIT_V(2); BAR; WAIT_L(0); MMA(0, 0, At, B0); BAR;
	s_waitcnt lgkmcnt(0)
	s_waitcnt lgkmcnt(0)
	v_mfma_f32_16x16x32_bf16 v[92:95], v[180:183], v[212:215], v[92:95]
	v_mfma_f32_16x16x32_bf16 v[88:91], v[180:183], v[220:223], v[88:91]
	v_mfma_f32_16x16x32_bf16 v[76:79], v[196:199], v[212:215], v[76:79]
	v_mfma_f32_16x16x32_bf16 v[72:75], v[196:199], v[220:223], v[72:75]
	v_mfma_f32_16x16x32_bf16 v[68:71], v[204:207], v[212:215], v[68:71]
	v_mfma_f32_16x16x32_bf16 v[64:67], v[204:207], v[220:223], v[64:67]
	v_mfma_f32_16x16x32_bf16 v[84:87], v[188:191], v[212:215], v[84:87]
	v_mfma_f32_16x16x32_bf16 v[80:83], v[188:191], v[220:223], v[80:83]
	v_mfma_f32_16x16x32_bf16 v[92:95], v[184:187], v[216:219], v[92:95]
	v_mfma_f32_16x16x32_bf16 v[88:91], v[184:187], v[158:161], v[88:91]
	v_mfma_f32_16x16x32_bf16 v[76:79], v[200:203], v[216:219], v[76:79]
	v_mfma_f32_16x16x32_bf16 v[72:75], v[200:203], v[158:161], v[72:75]
	v_mfma_f32_16x16x32_bf16 v[68:71], v[208:211], v[216:219], v[68:71]
	v_mfma_f32_16x16x32_bf16 v[64:67], v[208:211], v[158:161], v[64:67]
	v_mfma_f32_16x16x32_bf16 v[180:183], v[192:195], v[216:219], v[84:87]
	v_mfma_f32_16x16x32_bf16 v[184:187], v[192:195], v[158:161], v[80:83]
	s_barrier
	s_nop 0
	ds_read_b128 v[80:83], v153 offset:16384
	ds_read_b128 v[84:87], v153 offset:17408
	ds_read_b128 v[188:191], v152 offset:16384
	ds_read_b128 v[192:195], v152 offset:17408
	ds_read_b128 v[196:199], v151 offset:16384
	ds_read_b128 v[200:203], v151 offset:17408
	ds_read_b128 v[204:207], v150 offset:16384
	ds_read_b128 v[208:211], v150 offset:17408
	s_waitcnt vmcnt(4)
	s_barrier
	s_waitcnt lgkmcnt(0)
	s_waitcnt lgkmcnt(0)
	v_mfma_f32_16x16x32_bf16 v[60:63], v[80:83], v[134:137], v[60:63]
	v_mfma_f32_16x16x32_bf16 v[44:47], v[196:199], v[134:137], v[44:47]
	v_mfma_f32_16x16x32_bf16 v[40:43], v[196:199], v[172:175], v[40:43]
	v_mfma_f32_16x16x32_bf16 v[36:39], v[204:207], v[134:137], v[36:39]
	v_mfma_f32_16x16x32_bf16 v[32:35], v[204:207], v[172:175], v[32:35]
	v_mfma_f32_16x16x32_bf16 v[56:59], v[80:83], v[172:175], v[56:59]
	v_mfma_f32_16x16x32_bf16 v[52:55], v[188:191], v[134:137], v[52:55]
	v_mfma_f32_16x16x32_bf16 v[48:51], v[188:191], v[172:175], v[48:51]
	v_mfma_f32_16x16x32_bf16 v[60:63], v[84:87], v[138:141], v[60:63]
	v_mfma_f32_16x16x32_bf16 v[44:47], v[200:203], v[138:141], v[44:47]
	v_mfma_f32_16x16x32_bf16 v[40:43], v[200:203], v[176:179], v[40:43]
	v_mfma_f32_16x16x32_bf16 v[36:39], v[208:211], v[138:141], v[36:39]
	v_mfma_f32_16x16x32_bf16 v[32:35], v[208:211], v[176:179], v[32:35]
	v_mfma_f32_16x16x32_bf16 v[134:137], v[84:87], v[176:179], v[56:59]
	v_mfma_f32_16x16x32_bf16 v[170:173], v[192:195], v[138:141], v[52:55]
	v_mfma_f32_16x16x32_bf16 v[224:227], v[192:195], v[176:179], v[48:51]
	v_mfma_f32_16x16x32_bf16 v[28:31], v[80:83], v[212:215], v[28:31]
	v_mfma_f32_16x16x32_bf16 v[20:23], v[188:191], v[212:215], v[20:23]
	v_mfma_f32_16x16x32_bf16 v[12:15], v[196:199], v[212:215], v[12:15]
	v_mfma_f32_16x16x32_bf16 v[4:7], v[204:207], v[212:215], v[4:7]
	v_mfma_f32_16x16x32_bf16 v[24:27], v[80:83], v[220:223], v[24:27]
	v_mfma_f32_16x16x32_bf16 v[16:19], v[188:191], v[220:223], v[16:19]
	v_mfma_f32_16x16x32_bf16 v[8:11], v[196:199], v[220:223], v[8:11]
	v_mfma_f32_16x16x32_bf16 v[0:3], v[204:207], v[220:223], v[0:3]
	v_mfma_f32_16x16x32_bf16 v[28:31], v[84:87], v[216:219], v[28:31]
	v_mfma_f32_16x16x32_bf16 v[20:23], v[192:195], v[216:219], v[20:23]
	v_mfma_f32_16x16x32_bf16 v[12:15], v[200:203], v[216:219], v[12:15]
	v_mfma_f32_16x16x32_bf16 v[4:7], v[208:211], v[216:219], v[4:7]
	v_mfma_f32_16x16x32_bf16 v[138:141], v[84:87], v[158:161], v[24:27]
	v_mfma_f32_16x16x32_bf16 v[174:177], v[192:195], v[158:161], v[16:19]
	v_mfma_f32_16x16x32_bf16 v[188:191], v[200:203], v[158:161], v[8:11]
	v_mfma_f32_16x16x32_bf16 v[158:161], v[208:211], v[158:161], v[0:3]
	s_barrier
	s_nop 0
	ds_read_b128 v[0:3], v156
	ds_read_b128 v[8:11], v156 offset:1024
	ds_read_b128 v[16:19], v156 offset:2048
	ds_read_b128 v[192:195], v156 offset:3072
	ds_read_b128 v[24:27], v153 offset:32768
	ds_read_b128 v[56:59], v153 offset:33792
	ds_read_b128 v[196:199], v152 offset:32768
	ds_read_b128 v[200:203], v152 offset:33792
	ds_read_b128 v[204:207], v151 offset:32768
	ds_read_b128 v[208:211], v151 offset:33792
	ds_read_b128 v[212:215], v150 offset:32768
	ds_read_b128 v[216:219], v150 offset:33792
	s_waitcnt vmcnt(2)
	s_barrier
; #define LDA(dst, b, h) for (int m = 0; m < 4; ++m) for (int k = 0; k < 2; ++k) \
;     dst[m][k] = *reinterpret_cast<const bf16x8*>((char*)SA(b, h) + lds_byte(wr * 64 + m * 16 + fr, k * 32 + fq * 8))
; #define LDB(dst, b, h) for (int n = 0; n < 2; ++n) for (int k = 0; k < 2; ++k) \
;     dst[n][k] = *reinterpret_cast<const bf16x8*>((char*)SB(b, h) + lds_byte(wc * 32 + n * 16 + fr, k * 32 + fq * 8))
; #define MMA(ai, bj, At_, Bt_) do { __builtin_amdgcn_s_setprio(1); \
;     for (int k = 0; k < 2; ++k) for (int m = 0; m < 4; ++m) for (int n = 0; n < 2; ++n) \
;       acc[ai][bj][m][n] = __builtin_amdgcn_mfma_f32_16x16x32_bf16(At_[m][k], Bt_[n][k], acc[ai][bj][m][n], 0, 0, 0); \
;     __builtin_amdgcn_s_setprio(0); } while (0)
; #define WAIT_V(n) asm volatile("s_waitcnt vmcnt(" #n ")" ::: "memory")
; #define WAIT_L(n) asm volatile("s_waitcnt lgkmcnt(" #n ")" ::: "memory")
; #define BAR __builtin_amdgcn_s_barrier()
; template <int EPI, int lda, int ldb, int N, int K>
; __device__ __forceinline__ void gemm_phase(const u16* __restrict__ A, const u16* __restrict__ Bt, const GemmEpi ep, int wv) {
;     ...
;     { LDB(B0, 1, 0); LDA(At, 1, 0); WAIT_V(2); BAR; WAIT_L(0); MMA(0, 0, At, B0); BAR;
;       LDB(B1, 1, 1); WAIT_V(0); BAR; WAIT_L(0); MMA(0, 1, At, B1); BAR;
;       LDA(At, 1, 1); BAR; WAIT_L(0); MMA(1, 0, At, B0); MMA(1, 1, At, B1); BAR; }
;     if (wr == 0) BAR;
	s_waitcnt lgkmcnt(0)
	s_waitcnt lgkmcnt(0)
	v_mfma_f32_16x16x32_bf16 v[48:51], v[24:27], v[0:3], v[124:127]
	v_mfma_f32_16x16x32_bf16 v[52:55], v[24:27], v[16:19], v[120:123]
	v_mfma_f32_16x16x32_bf16 v[80:83], v[196:199], v[0:3], v[116:119]
	v_mfma_f32_16x16x32_bf16 v[84:87], v[196:199], v[16:19], v[112:115]
	v_mfma_f32_16x16x32_bf16 v[108:111], v[204:207], v[0:3], v[108:111]
	v_mfma_f32_16x16x32_bf16 v[104:107], v[204:207], v[16:19], v[104:107]
	v_mfma_f32_16x16x32_bf16 v[112:115], v[212:215], v[0:3], v[100:103]
	v_mfma_f32_16x16x32_bf16 v[120:123], v[212:215], v[16:19], v[96:99]
	v_mfma_f32_16x16x32_bf16 v[124:127], v[56:59], v[8:11], v[48:51]
	v_mfma_f32_16x16x32_bf16 v[116:119], v[56:59], v[192:195], v[52:55]
	v_mfma_f32_16x16x32_bf16 v[100:103], v[200:203], v[8:11], v[80:83]
	v_mfma_f32_16x16x32_bf16 v[96:99], v[200:203], v[192:195], v[84:87]
	v_mfma_f32_16x16x32_bf16 v[84:87], v[208:211], v[8:11], v[108:111]
	v_mfma_f32_16x16x32_bf16 v[80:83], v[208:211], v[192:195], v[104:107]
	v_mfma_f32_16x16x32_bf16 v[52:55], v[216:219], v[8:11], v[112:115]
	v_mfma_f32_16x16x32_bf16 v[48:51], v[216:219], v[192:195], v[120:123]
	s_barrier
	ds_read_b128 v[220:223], v154
	ds_read_b128 v[228:231], v154 offset:1024
	ds_read_b128 v[232:235], v154 offset:2048
	ds_read_b128 v[154:157], v154 offset:3072
	s_waitcnt vmcnt(0)
	s_barrier
	s_waitcnt lgkmcnt(0)
	s_waitcnt lgkmcnt(0)
	v_mfma_f32_16x16x32_bf16 v[92:95], v[24:27], v[220:223], v[92:95]
	v_mfma_f32_16x16x32_bf16 v[24:27], v[24:27], v[232:235], v[88:91]
	v_mfma_f32_16x16x32_bf16 v[88:91], v[196:199], v[220:223], v[180:183]
	v_mfma_f32_16x16x32_bf16 v[104:107], v[196:199], v[232:235], v[184:187]
	v_mfma_f32_16x16x32_bf16 v[76:79], v[204:207], v[220:223], v[76:79]
	v_mfma_f32_16x16x32_bf16 v[72:75], v[204:207], v[232:235], v[72:75]
	v_mfma_f32_16x16x32_bf16 v[68:71], v[212:215], v[220:223], v[68:71]
	v_mfma_f32_16x16x32_bf16 v[64:67], v[212:215], v[232:235], v[64:67]
	v_mfma_f32_16x16x32_bf16 v[120:123], v[56:59], v[228:231], v[92:95]
	v_mfma_f32_16x16x32_bf16 v[112:115], v[56:59], v[154:157], v[24:27]
	v_mfma_f32_16x16x32_bf16 v[108:111], v[200:203], v[228:231], v[88:91]
	v_mfma_f32_16x16x32_bf16 v[104:107], v[200:203], v[154:157], v[104:107]
	v_mfma_f32_16x16x32_bf16 v[92:95], v[208:211], v[228:231], v[76:79]
	v_mfma_f32_16x16x32_bf16 v[88:91], v[208:211], v[154:157], v[72:75]
	v_mfma_f32_16x16x32_bf16 v[68:71], v[216:219], v[228:231], v[68:71]
	v_mfma_f32_16x16x32_bf16 v[56:59], v[216:219], v[154:157], v[64:67]
	s_barrier
	s_nop 0
	ds_read_b128 v[64:67], v153 offset:49152
	ds_read_b128 v[178:181], v153 offset:50176
	ds_read_b128 v[76:79], v152 offset:49152
	ds_read_b128 v[182:185], v152 offset:50176
	ds_read_b128 v[196:199], v151 offset:49152
	ds_read_b128 v[200:203], v151 offset:50176
	ds_read_b128 v[204:207], v150 offset:49152
	ds_read_b128 v[150:153], v150 offset:50176
	s_barrier
	s_waitcnt lgkmcnt(0)
	s_waitcnt lgkmcnt(0)
	v_mfma_f32_16x16x32_bf16 v[24:27], v[64:67], v[0:3], v[60:63]
	v_mfma_f32_16x16x32_bf16 v[60:63], v[64:67], v[16:19], v[134:137]
	v_mfma_f32_16x16x32_bf16 v[134:137], v[76:79], v[0:3], v[170:173]
	v_mfma_f32_16x16x32_bf16 v[170:173], v[76:79], v[16:19], v[224:227]
	v_mfma_f32_16x16x32_bf16 v[44:47], v[196:199], v[0:3], v[44:47]
	v_mfma_f32_16x16x32_bf16 v[208:211], v[196:199], v[16:19], v[40:43]
	v_mfma_f32_16x16x32_bf16 v[0:3], v[204:207], v[0:3], v[36:39]
	v_mfma_f32_16x16x32_bf16 v[36:39], v[204:207], v[16:19], v[32:35]
	v_mfma_f32_16x16x32_bf16 v[72:75], v[178:181], v[8:11], v[24:27]
	v_mfma_f32_16x16x32_bf16 v[60:63], v[178:181], v[192:195], v[60:63]
	v_mfma_f32_16x16x32_bf16 v[40:43], v[182:185], v[8:11], v[134:137]
	v_mfma_f32_16x16x32_bf16 v[32:35], v[182:185], v[192:195], v[170:173]
	v_mfma_f32_16x16x32_bf16 v[24:27], v[200:203], v[8:11], v[44:47]
	v_mfma_f32_16x16x32_bf16 v[16:19], v[200:203], v[192:195], v[208:211]
	v_mfma_f32_16x16x32_bf16 v[8:11], v[150:153], v[8:11], v[0:3]
	v_mfma_f32_16x16x32_bf16 v[0:3], v[150:153], v[192:195], v[36:39]
	v_mfma_f32_16x16x32_bf16 v[28:31], v[64:67], v[220:223], v[28:31]
	v_mfma_f32_16x16x32_bf16 v[36:39], v[64:67], v[232:235], v[138:141]
	v_mfma_f32_16x16x32_bf16 v[20:23], v[76:79], v[220:223], v[20:23]
	v_mfma_f32_16x16x32_bf16 v[134:137], v[76:79], v[232:235], v[174:177]
	v_mfma_f32_16x16x32_bf16 v[12:15], v[196:199], v[220:223], v[12:15]
	v_mfma_f32_16x16x32_bf16 v[138:141], v[196:199], v[232:235], v[188:191]
	v_mfma_f32_16x16x32_bf16 v[4:7], v[204:207], v[220:223], v[4:7]
	v_mfma_f32_16x16x32_bf16 v[158:161], v[204:207], v[232:235], v[158:161]
	v_mfma_f32_16x16x32_bf16 v[76:79], v[178:181], v[228:231], v[28:31]
	v_mfma_f32_16x16x32_bf16 v[64:67], v[178:181], v[154:157], v[36:39]
	v_mfma_f32_16x16x32_bf16 v[44:47], v[182:185], v[228:231], v[20:23]
	v_mfma_f32_16x16x32_bf16 v[36:39], v[182:185], v[154:157], v[134:137]
	v_mfma_f32_16x16x32_bf16 v[28:31], v[200:203], v[228:231], v[12:15]
	v_mfma_f32_16x16x32_bf16 v[20:23], v[200:203], v[154:157], v[138:141]
	v_mfma_f32_16x16x32_bf16 v[12:15], v[150:153], v[228:231], v[4:7]
	v_mfma_f32_16x16x32_bf16 v[4:7], v[150:153], v[154:157], v[158:161]
	v_cmp_gt_u32_e32 vcc, s64, v130
	s_barrier
	s_and_saveexec_b64 s[48:49], vcc
	s_cbranch_execz .LBB0_343
	s_barrier

; #define STAGE(P, BASE, LD, br, kt) do { const char* _g = (const char*)((BASE) + (size_t)(br) * (LD) + (size_t)(kt) * 64); \
;     for (int _i = 0; _i < 2; ++_i) { int _b = tidx * 16 + _i * 8192; int _r, _c; stage_rc(_b, _r, _c); \
;       __builtin_amdgcn_global_load_lds((const unsigned*)(_g + (unsigned)((_r * (LD) + _c) * 2)), (unsigned*)((char*)(P) + _b), 16, 0, 0); } } while (0)
; #define LDA(dst, b, h) for (int m = 0; m < 4; ++m) for (int k = 0; k < 2; ++k) \
;     dst[m][k] = *reinterpret_cast<const bf16x8*>((char*)SA(b, h) + lds_byte(wr * 64 + m * 16 + fr, k * 32 + fq * 8))
; #define LDB(dst, b, h) for (int n = 0; n < 2; ++n) for (int k = 0; k < 2; ++k) \
;     dst[n][k] = *reinterpret_cast<const bf16x8*>((char*)SB(b, h) + lds_byte(wc * 32 + n * 16 + fr, k * 32 + fq * 8))
; #define MMA(ai, bj, At_, Bt_) do { __builtin_amdgcn_s_setprio(1); \
;     for (int k = 0; k < 2; ++k) for (int m = 0; m < 4; ++m) for (int n = 0; n < 2; ++n) \
;       acc[ai][bj][m][n] = __builtin_amdgcn_mfma_f32_16x16x32_bf16(At_[m][k], Bt_[n][k], acc[ai][bj][m][n], 0, 0, 0); \
;     __builtin_amdgcn_s_setprio(0); } while (0)
; #define WAIT_L(n) asm volatile("s_waitcnt lgkmcnt(" #n ")" ::: "memory")
; #define BAR __builtin_amdgcn_s_barrier()
; #define SCHED __builtin_amdgcn_sched_barrier(0)
; template <int EPI, int lda, int ldb, int N, int K>
; __device__ __forceinline__ void gemm_phase(const u16* __restrict__ A, const u16* __restrict__ Bt, const GemmEpi ep, int wv) {
;     ...
;       LDB(B0, 0, 0); SCHED; LDA(At, 0, 0); STAGE(SA(1, 1), Ab, lda, brow + HALF, t + 1);
;       WAIT_L(8); BAR; WAIT_L(0); MMA(0, 0, At, B0); BAR; SCHED;
;       LDB(B1, 0, 1); STAGE(SB(0, 0), Bt, ldb, bcol, t + 2);
;       BAR; WAIT_L(0); MMA(0, 1, At, B1); BAR;
;       LDA(At, 0, 1); STAGE(SA(0, 0), Ab, lda, brow, t + 2);
;       BAR; WAIT_L(0); MMA(1, 0, At, B0); BAR; SCHED;
.LBB0_654:
	ds_read_b128 v[164:167], v160
	ds_read_b128 v[170:173], v160 offset:1024
	ds_read_b128 v[174:177], v160 offset:2048
	ds_read_b128 v[178:181], v160 offset:3072
	v_add_u32_e32 v168, 0xc000, v143
	v_lshl_add_u64 v[234:235], v[138:139], 0, s[52:53]
	v_readfirstlane_b32 s55, v168
	v_add_u32_e32 v169, 0xe000, v143
	v_lshl_add_u64 v[162:163], v[234:235], 0, s[20:21]
	s_mov_b32 m0, s55
	v_lshl_add_u64 v[236:237], v[140:141], 0, s[52:53]
	v_readfirstlane_b32 s55, v169
	ds_read_b128 v[182:185], v151
	ds_read_b128 v[186:189], v151 offset:1024
	ds_read_b128 v[190:193], v150
	ds_read_b128 v[194:197], v150 offset:1024
	ds_read_b128 v[198:201], v149
	ds_read_b128 v[202:205], v149 offset:1024
	ds_read_b128 v[206:209], v148
	ds_read_b128 v[210:213], v148 offset:1024
	global_load_lds_dwordx4 v[162:163], off
	v_lshl_add_u64 v[162:163], v[236:237], 0, s[20:21]
	s_mov_b32 m0, s55
	s_nop 0
	global_load_lds_dwordx4 v[162:163], off
	s_waitcnt lgkmcnt(8)
	s_barrier
	s_waitcnt lgkmcnt(0)
	s_waitcnt lgkmcnt(0)
	v_mfma_f32_16x16x32_bf16 v[124:127], v[164:167], v[182:185], v[124:127]
	v_mfma_f32_16x16x32_bf16 v[120:123], v[174:177], v[182:185], v[120:123]
	v_mfma_f32_16x16x32_bf16 v[116:119], v[164:167], v[190:193], v[116:119]
	v_mfma_f32_16x16x32_bf16 v[112:115], v[174:177], v[190:193], v[112:115]
	v_mfma_f32_16x16x32_bf16 v[108:111], v[164:167], v[198:201], v[108:111]
	v_mfma_f32_16x16x32_bf16 v[104:107], v[174:177], v[198:201], v[104:107]
	v_mfma_f32_16x16x32_bf16 v[100:103], v[164:167], v[206:209], v[100:103]
	v_mfma_f32_16x16x32_bf16 v[96:99], v[174:177], v[206:209], v[96:99]
	v_mfma_f32_16x16x32_bf16 v[124:127], v[170:173], v[186:189], v[124:127]
	v_mfma_f32_16x16x32_bf16 v[120:123], v[178:181], v[186:189], v[120:123]
	v_mfma_f32_16x16x32_bf16 v[116:119], v[170:173], v[194:197], v[116:119]
	v_mfma_f32_16x16x32_bf16 v[112:115], v[178:181], v[194:197], v[112:115]
	v_mfma_f32_16x16x32_bf16 v[108:111], v[170:173], v[202:205], v[108:111]
	v_mfma_f32_16x16x32_bf16 v[104:107], v[178:181], v[202:205], v[104:107]
	v_mfma_f32_16x16x32_bf16 v[100:103], v[170:173], v[210:213], v[100:103]
	v_mfma_f32_16x16x32_bf16 v[96:99], v[178:181], v[210:213], v[96:99]
	s_barrier
	v_add_u32_e32 v161, s65, v153
	v_lshl_add_u64 v[238:239], v[134:135], 0, s[52:53]
	v_readfirstlane_b32 s55, v161
	v_lshl_add_u64 v[162:163], v[238:239], 0, s[22:23]
	s_mov_b32 m0, s55
	ds_read_b128 v[214:217], v159
	ds_read_b128 v[218:221], v159 offset:1024
	ds_read_b128 v[222:225], v159 offset:2048
	ds_read_b128 v[226:229], v159 offset:3072
	global_load_lds_dwordx4 v[162:163], off
	v_add_u32_e32 v162, 0x2000, v161
	v_lshl_add_u64 v[240:241], v[136:137], 0, s[52:53]
	v_readfirstlane_b32 s55, v162
	v_lshl_add_u64 v[230:231], v[240:241], 0, s[22:23]
	s_mov_b32 m0, s55
	s_nop 0
	global_load_lds_dwordx4 v[230:231], off
	s_waitcnt vmcnt(10)
	s_barrier
	s_waitcnt lgkmcnt(0)
	s_waitcnt lgkmcnt(0)
	v_mfma_f32_16x16x32_bf16 v[92:95], v[214:217], v[182:185], v[92:95]
	v_mfma_f32_16x16x32_bf16 v[88:91], v[222:225], v[182:185], v[88:91]
	v_mfma_f32_16x16x32_bf16 v[84:87], v[214:217], v[190:193], v[84:87]
	v_mfma_f32_16x16x32_bf16 v[80:83], v[222:225], v[190:193], v[80:83]
	v_mfma_f32_16x16x32_bf16 v[76:79], v[214:217], v[198:201], v[76:79]
	v_mfma_f32_16x16x32_bf16 v[72:75], v[222:225], v[198:201], v[72:75]
	v_mfma_f32_16x16x32_bf16 v[68:71], v[214:217], v[206:209], v[68:71]
	v_mfma_f32_16x16x32_bf16 v[64:67], v[222:225], v[206:209], v[64:67]
	v_mfma_f32_16x16x32_bf16 v[92:95], v[218:221], v[186:189], v[92:95]
	v_mfma_f32_16x16x32_bf16 v[88:91], v[226:229], v[186:189], v[88:91]
	v_mfma_f32_16x16x32_bf16 v[84:87], v[218:221], v[194:197], v[84:87]
	v_mfma_f32_16x16x32_bf16 v[80:83], v[226:229], v[194:197], v[80:83]
	v_mfma_f32_16x16x32_bf16 v[76:79], v[218:221], v[202:205], v[76:79]
	v_mfma_f32_16x16x32_bf16 v[72:75], v[226:229], v[202:205], v[72:75]
	v_mfma_f32_16x16x32_bf16 v[68:71], v[218:221], v[210:213], v[68:71]
	v_mfma_f32_16x16x32_bf16 v[64:67], v[226:229], v[210:213], v[64:67]
	v_readfirstlane_b32 s55, v143
	v_add_u32_e32 v163, 0x2000, v143
	v_lshl_add_u64 v[230:231], v[234:235], 0, s[24:25]
	s_mov_b32 m0, s55
	v_readfirstlane_b32 s55, v163
	s_barrier
	ds_read_b128 v[182:185], v151 offset:16384
	ds_read_b128 v[186:189], v151 offset:17408
	ds_read_b128 v[190:193], v150 offset:16384
	ds_read_b128 v[194:197], v150 offset:17408
	ds_read_b128 v[198:201], v149 offset:16384
	ds_read_b128 v[202:205], v149 offset:17408
	ds_read_b128 v[206:209], v148 offset:16384
	ds_read_b128 v[210:213], v148 offset:17408
	global_load_lds_dwordx4 v[230:231], off
	v_lshl_add_u64 v[230:231], v[236:237], 0, s[24:25]
	s_mov_b32 m0, s55
	s_nop 0
	global_load_lds_dwordx4 v[230:231], off
	s_barrier
	s_waitcnt lgkmcnt(0)
	s_waitcnt lgkmcnt(0)
	v_mfma_f32_16x16x32_bf16 v[60:63], v[164:167], v[182:185], v[60:63]
	v_mfma_f32_16x16x32_bf16 v[56:59], v[174:177], v[182:185], v[56:59]
	v_mfma_f32_16x16x32_bf16 v[52:55], v[164:167], v[190:193], v[52:55]
	v_mfma_f32_16x16x32_bf16 v[48:51], v[174:177], v[190:193], v[48:51]
	v_mfma_f32_16x16x32_bf16 v[44:47], v[164:167], v[198:201], v[44:47]
	v_mfma_f32_16x16x32_bf16 v[40:43], v[174:177], v[198:201], v[40:43]
	v_mfma_f32_16x16x32_bf16 v[36:39], v[164:167], v[206:209], v[36:39]
	v_mfma_f32_16x16x32_bf16 v[32:35], v[174:177], v[206:209], v[32:35]
	v_mfma_f32_16x16x32_bf16 v[60:63], v[170:173], v[186:189], v[60:63]
	v_mfma_f32_16x16x32_bf16 v[56:59], v[178:181], v[186:189], v[56:59]
	v_mfma_f32_16x16x32_bf16 v[52:55], v[170:173], v[194:197], v[52:55]
	v_mfma_f32_16x16x32_bf16 v[48:51], v[178:181], v[194:197], v[48:51]
	v_mfma_f32_16x16x32_bf16 v[44:47], v[170:173], v[202:205], v[44:47]
	v_mfma_f32_16x16x32_bf16 v[40:43], v[178:181], v[202:205], v[40:43]
	v_mfma_f32_16x16x32_bf16 v[36:39], v[170:173], v[210:213], v[36:39]
	v_mfma_f32_16x16x32_bf16 v[32:35], v[178:181], v[210:213], v[32:35]
	s_barrier
; #define STAGE(P, BASE, LD, br, kt) do { const char* _g = (const char*)((BASE) + (size_t)(br) * (LD) + (size_t)(kt) * 64); \
;     for (int _i = 0; _i < 2; ++_i) { int _b = tidx * 16 + _i * 8192; int _r, _c; stage_rc(_b, _r, _c); \
;       __builtin_amdgcn_global_load_lds((const unsigned*)(_g + (unsigned)((_r * (LD) + _c) * 2)), (unsigned*)((char*)(P) + _b), 16, 0, 0); } } while (0)
; #define LDA(dst, b, h) for (int m = 0; m < 4; ++m) for (int k = 0; k < 2; ++k) \
;     dst[m][k] = *reinterpret_cast<const bf16x8*>((char*)SA(b, h) + lds_byte(wr * 64 + m * 16 + fr, k * 32 + fq * 8))
; #define LDB(dst, b, h) for (int n = 0; n < 2; ++n) for (int k = 0; k < 2; ++k) \
;     dst[n][k] = *reinterpret_cast<const bf16x8*>((char*)SB(b, h) + lds_byte(wc * 32 + n * 16 + fr, k * 32 + fq * 8))
; #define MMA(ai, bj, At_, Bt_) do { __builtin_amdgcn_s_setprio(1); \
;     for (int k = 0; k < 2; ++k) for (int m = 0; m < 4; ++m) for (int n = 0; n < 2; ++n) \
;       acc[ai][bj][m][n] = __builtin_amdgcn_mfma_f32_16x16x32_bf16(At_[m][k], Bt_[n][k], acc[ai][bj][m][n], 0, 0, 0); \
;     __builtin_amdgcn_s_setprio(0); } while (0)
; #define WAIT_V(n) asm volatile("s_waitcnt vmcnt(" #n ")" ::: "memory")
; #define WAIT_L(n) asm volatile("s_waitcnt lgkmcnt(" #n ")" ::: "memory")
; #define BAR __builtin_amdgcn_s_barrier()
; #define SCHED __builtin_amdgcn_sched_barrier(0)
; template <int EPI, int lda, int ldb, int N, int K>
; __device__ __forceinline__ void gemm_phase(const u16* __restrict__ A, const u16* __restrict__ Bt, const GemmEpi ep, int wv) {
;     ...
;       STAGE(SB(0, 1), Bt, ldb, bcol + HALF, t + 2);
;       WAIT_V(6); BAR; MMA(1, 1, At, B1); BAR;
;       LDB(B0, 1, 0); SCHED; LDA(At, 1, 0); STAGE(SA(0, 1), Ab, lda, brow + HALF, t + 2);
;       WAIT_L(8); BAR; WAIT_L(0); MMA(0, 0, At, B0); BAR; SCHED;
;       LDB(B1, 1, 1); STAGE(SB(1, 0), Bt, ldb, bcol, t + 3);
;       BAR; WAIT_L(0); MMA(0, 1, At, B1); BAR;
	v_add_u32_e32 v164, s66, v153
	v_add_u32_e32 v165, 0x2000, v164
	v_readfirstlane_b32 s55, v164
	v_lshl_add_u64 v[166:167], v[238:239], 0, s[26:27]
	s_mov_b32 m0, s55
	v_readfirstlane_b32 s55, v165
	global_load_lds_dwordx4 v[166:167], off
	v_lshl_add_u64 v[166:167], v[240:241], 0, s[26:27]
	s_mov_b32 m0, s55
	s_nop 0
	global_load_lds_dwordx4 v[166:167], off
	s_waitcnt vmcnt(8)
	s_barrier
	v_mfma_f32_16x16x32_bf16 v[28:31], v[214:217], v[182:185], v[28:31]
	v_mfma_f32_16x16x32_bf16 v[24:27], v[222:225], v[182:185], v[24:27]
	v_mfma_f32_16x16x32_bf16 v[20:23], v[214:217], v[190:193], v[20:23]
	v_mfma_f32_16x16x32_bf16 v[16:19], v[222:225], v[190:193], v[16:19]
	v_mfma_f32_16x16x32_bf16 v[12:15], v[214:217], v[198:201], v[12:15]
	v_mfma_f32_16x16x32_bf16 v[8:11], v[222:225], v[198:201], v[8:11]
	v_mfma_f32_16x16x32_bf16 v[4:7], v[214:217], v[206:209], v[4:7]
	v_mfma_f32_16x16x32_bf16 v[0:3], v[222:225], v[206:209], v[0:3]
	v_mfma_f32_16x16x32_bf16 v[28:31], v[218:221], v[186:189], v[28:31]
	v_mfma_f32_16x16x32_bf16 v[24:27], v[226:229], v[186:189], v[24:27]
	v_mfma_f32_16x16x32_bf16 v[20:23], v[218:221], v[194:197], v[20:23]
	v_mfma_f32_16x16x32_bf16 v[16:19], v[226:229], v[194:197], v[16:19]
	v_mfma_f32_16x16x32_bf16 v[12:15], v[218:221], v[202:205], v[12:15]
	v_mfma_f32_16x16x32_bf16 v[8:11], v[226:229], v[202:205], v[8:11]
	v_mfma_f32_16x16x32_bf16 v[4:7], v[218:221], v[210:213], v[4:7]
	v_mfma_f32_16x16x32_bf16 v[0:3], v[226:229], v[210:213], v[0:3]
	s_barrier
	ds_read_b128 v[170:173], v154
	ds_read_b128 v[174:177], v154 offset:1024
	ds_read_b128 v[178:181], v154 offset:2048
	ds_read_b128 v[182:185], v154 offset:3072
	v_add_u32_e32 v166, 0x4000, v143
	v_add_u32_e32 v167, 0x6000, v143
	v_readfirstlane_b32 s55, v166
	v_lshl_add_u64 v[218:219], v[234:235], 0, s[42:43]
	s_mov_b32 m0, s55
	v_readfirstlane_b32 s55, v167
	ds_read_b128 v[186:189], v151 offset:32768
	ds_read_b128 v[190:193], v151 offset:33792
	ds_read_b128 v[194:197], v150 offset:32768
	ds_read_b128 v[198:201], v150 offset:33792
	ds_read_b128 v[202:205], v149 offset:32768
	ds_read_b128 v[206:209], v149 offset:33792
	ds_read_b128 v[210:213], v148 offset:32768
	ds_read_b128 v[214:217], v148 offset:33792
	global_load_lds_dwordx4 v[218:219], off
	v_lshl_add_u64 v[218:219], v[236:237], 0, s[42:43]
	s_mov_b32 m0, s55
	s_nop 0
	global_load_lds_dwordx4 v[218:219], off
	s_waitcnt lgkmcnt(8)
	s_barrier
	s_waitcnt lgkmcnt(0)
	s_waitcnt lgkmcnt(0)
	v_mfma_f32_16x16x32_bf16 v[124:127], v[170:173], v[186:189], v[124:127]
	v_mfma_f32_16x16x32_bf16 v[120:123], v[178:181], v[186:189], v[120:123]
	v_mfma_f32_16x16x32_bf16 v[116:119], v[170:173], v[194:197], v[116:119]
	v_mfma_f32_16x16x32_bf16 v[112:115], v[178:181], v[194:197], v[112:115]
	v_mfma_f32_16x16x32_bf16 v[108:111], v[170:173], v[202:205], v[108:111]
	v_mfma_f32_16x16x32_bf16 v[104:107], v[178:181], v[202:205], v[104:107]
	v_mfma_f32_16x16x32_bf16 v[100:103], v[170:173], v[210:213], v[100:103]
	v_mfma_f32_16x16x32_bf16 v[96:99], v[178:181], v[210:213], v[96:99]
	v_mfma_f32_16x16x32_bf16 v[124:127], v[174:177], v[190:193], v[124:127]
	v_mfma_f32_16x16x32_bf16 v[120:123], v[182:185], v[190:193], v[120:123]
	v_mfma_f32_16x16x32_bf16 v[116:119], v[174:177], v[198:201], v[116:119]
	v_mfma_f32_16x16x32_bf16 v[112:115], v[182:185], v[198:201], v[112:115]
	v_mfma_f32_16x16x32_bf16 v[108:111], v[174:177], v[206:209], v[108:111]
	v_mfma_f32_16x16x32_bf16 v[104:107], v[182:185], v[206:209], v[104:107]
	v_mfma_f32_16x16x32_bf16 v[100:103], v[174:177], v[214:217], v[100:103]
	v_mfma_f32_16x16x32_bf16 v[96:99], v[182:185], v[214:217], v[96:99]
	s_barrier
	v_readfirstlane_b32 s55, v155
	v_add_u32_e32 v244, 0x2000, v155
	v_lshl_add_u64 v[242:243], v[238:239], 0, s[44:45]
	s_mov_b32 m0, s55
	v_readfirstlane_b32 s55, v244
	ds_read_b128 v[218:221], v152
	ds_read_b128 v[222:225], v152 offset:1024
	ds_read_b128 v[226:229], v152 offset:2048
	ds_read_b128 v[230:233], v152 offset:3072
	global_load_lds_dwordx4 v[242:243], off
	v_lshl_add_u64 v[242:243], v[240:241], 0, s[44:45]
	s_mov_b32 m0, s55
	s_nop 0
	global_load_lds_dwordx4 v[242:243], off
	s_waitcnt vmcnt(10)
	s_barrier
	s_waitcnt lgkmcnt(0)
	s_waitcnt lgkmcnt(0)
	v_mfma_f32_16x16x32_bf16 v[92:95], v[218:221], v[186:189], v[92:95]
	v_mfma_f32_16x16x32_bf16 v[88:91], v[226:229], v[186:189], v[88:91]
	v_mfma_f32_16x16x32_bf16 v[84:87], v[218:221], v[194:197], v[84:87]
	v_mfma_f32_16x16x32_bf16 v[80:83], v[226:229], v[194:197], v[80:83]
	v_mfma_f32_16x16x32_bf16 v[76:79], v[218:221], v[202:205], v[76:79]
	v_mfma_f32_16x16x32_bf16 v[72:75], v[226:229], v[202:205], v[72:75]
	v_mfma_f32_16x16x32_bf16 v[68:71], v[218:221], v[210:213], v[68:71]
	v_mfma_f32_16x16x32_bf16 v[64:67], v[226:229], v[210:213], v[64:67]
	v_mfma_f32_16x16x32_bf16 v[92:95], v[222:225], v[190:193], v[92:95]
	v_mfma_f32_16x16x32_bf16 v[88:91], v[230:233], v[190:193], v[88:91]
	v_mfma_f32_16x16x32_bf16 v[84:87], v[222:225], v[198:201], v[84:87]
	v_mfma_f32_16x16x32_bf16 v[80:83], v[230:233], v[198:201], v[80:83]
	v_mfma_f32_16x16x32_bf16 v[76:79], v[222:225], v[206:209], v[76:79]
	v_mfma_f32_16x16x32_bf16 v[72:75], v[230:233], v[206:209], v[72:75]
	v_mfma_f32_16x16x32_bf16 v[68:71], v[222:225], v[214:217], v[68:71]
	v_mfma_f32_16x16x32_bf16 v[64:67], v[230:233], v[214:217], v[64:67]
	v_readfirstlane_b32 s55, v156
	v_lshl_add_u64 v[234:235], v[234:235], 0, s[46:47]
	s_mov_b32 m0, s55
	v_readfirstlane_b32 s55, v157
	s_barrier
; #define STAGE(P, BASE, LD, br, kt) do { const char* _g = (const char*)((BASE) + (size_t)(br) * (LD) + (size_t)(kt) * 64); \
;     for (int _i = 0; _i < 2; ++_i) { int _b = tidx * 16 + _i * 8192; int _r, _c; stage_rc(_b, _r, _c); \
;       __builtin_amdgcn_global_load_lds((const unsigned*)(_g + (unsigned)((_r * (LD) + _c) * 2)), (unsigned*)((char*)(P) + _b), 16, 0, 0); } } while (0)
; #define LDA(dst, b, h) for (int m = 0; m < 4; ++m) for (int k = 0; k < 2; ++k) \
;     dst[m][k] = *reinterpret_cast<const bf16x8*>((char*)SA(b, h) + lds_byte(wr * 64 + m * 16 + fr, k * 32 + fq * 8))
; #define LDB(dst, b, h) for (int n = 0; n < 2; ++n) for (int k = 0; k < 2; ++k) \
;     dst[n][k] = *reinterpret_cast<const bf16x8*>((char*)SB(b, h) + lds_byte(wc * 32 + n * 16 + fr, k * 32 + fq * 8))
; #define MMA(ai, bj, At_, Bt_) do { __builtin_amdgcn_s_setprio(1); \
;     for (int k = 0; k < 2; ++k) for (int m = 0; m < 4; ++m) for (int n = 0; n < 2; ++n) \
;       acc[ai][bj][m][n] = __builtin_amdgcn_mfma_f32_16x16x32_bf16(At_[m][k], Bt_[n][k], acc[ai][bj][m][n], 0, 0, 0); \
;     __builtin_amdgcn_s_setprio(0); } while (0)
; #define WAIT_V(n) asm volatile("s_waitcnt vmcnt(" #n ")" ::: "memory")
; #define WAIT_L(n) asm volatile("s_waitcnt lgkmcnt(" #n ")" ::: "memory")
; #define BAR __builtin_amdgcn_s_barrier()
; #define SCHED __builtin_amdgcn_sched_barrier(0)
; template <int EPI, int lda, int ldb, int N, int K>
; __device__ __forceinline__ void gemm_phase(const u16* __restrict__ A, const u16* __restrict__ Bt, const GemmEpi ep, int wv) {
;     ...
;       LDA(At, 1, 1); STAGE(SA(1, 0), Ab, lda, brow, t + 3);
;       BAR; WAIT_L(0); MMA(1, 0, At, B0); BAR; SCHED;
;       STAGE(SB(1, 1), Bt, ldb, bcol + HALF, t + 3);
;       WAIT_V(6); BAR; MMA(1, 1, At, B1); BAR;
;     }
;     { LDB(B0, 0, 0); LDA(At, 0, 0); STAGE(SA(1, 1), Ab, lda, brow + HALF, nt - 1);
;       BAR; WAIT_L(0); MMA(0, 0, At, B0); BAR;
;       LDB(B1, 0, 1); BAR; WAIT_L(0); MMA(0, 1, At, B1); BAR;
	ds_read_b128 v[186:189], v151 offset:49152
	ds_read_b128 v[190:193], v151 offset:50176
	ds_read_b128 v[194:197], v150 offset:49152
	ds_read_b128 v[198:201], v150 offset:50176
	ds_read_b128 v[202:205], v149 offset:49152
	ds_read_b128 v[206:209], v149 offset:50176
	ds_read_b128 v[210:213], v148 offset:49152
	ds_read_b128 v[214:217], v148 offset:50176
	global_load_lds_dwordx4 v[234:235], off
	v_lshl_add_u64 v[234:235], v[236:237], 0, s[46:47]
	s_mov_b32 m0, s55
	s_nop 0
	global_load_lds_dwordx4 v[234:235], off
	s_barrier
	s_waitcnt lgkmcnt(0)
	s_waitcnt lgkmcnt(0)
	v_mfma_f32_16x16x32_bf16 v[60:63], v[170:173], v[186:189], v[60:63]
	v_mfma_f32_16x16x32_bf16 v[56:59], v[178:181], v[186:189], v[56:59]
	v_mfma_f32_16x16x32_bf16 v[52:55], v[170:173], v[194:197], v[52:55]
	v_mfma_f32_16x16x32_bf16 v[48:51], v[178:181], v[194:197], v[48:51]
	v_mfma_f32_16x16x32_bf16 v[44:47], v[170:173], v[202:205], v[44:47]
	v_mfma_f32_16x16x32_bf16 v[40:43], v[178:181], v[202:205], v[40:43]
	v_mfma_f32_16x16x32_bf16 v[36:39], v[170:173], v[210:213], v[36:39]
	v_mfma_f32_16x16x32_bf16 v[32:35], v[178:181], v[210:213], v[32:35]
	v_mfma_f32_16x16x32_bf16 v[60:63], v[174:177], v[190:193], v[60:63]
	v_mfma_f32_16x16x32_bf16 v[56:59], v[182:185], v[190:193], v[56:59]
	v_mfma_f32_16x16x32_bf16 v[52:55], v[174:177], v[198:201], v[52:55]
	v_mfma_f32_16x16x32_bf16 v[48:51], v[182:185], v[198:201], v[48:51]
	v_mfma_f32_16x16x32_bf16 v[44:47], v[174:177], v[206:209], v[44:47]
	v_mfma_f32_16x16x32_bf16 v[40:43], v[182:185], v[206:209], v[40:43]
	v_mfma_f32_16x16x32_bf16 v[36:39], v[174:177], v[214:217], v[36:39]
	v_mfma_f32_16x16x32_bf16 v[32:35], v[182:185], v[214:217], v[32:35]
	s_barrier
	v_readfirstlane_b32 s55, v158
	v_add_u32_e32 v172, 0x2000, v158
	v_lshl_add_u64 v[170:171], v[238:239], 0, s[48:49]
	s_mov_b32 m0, s55
	v_readfirstlane_b32 s55, v172
	global_load_lds_dwordx4 v[170:171], off
	v_lshl_add_u64 v[170:171], v[240:241], 0, s[48:49]
	s_mov_b32 m0, s55
	s_nop 0
	global_load_lds_dwordx4 v[170:171], off
	s_waitcnt vmcnt(8)
	s_barrier
	v_mfma_f32_16x16x32_bf16 v[28:31], v[218:221], v[186:189], v[28:31]
	v_mfma_f32_16x16x32_bf16 v[24:27], v[226:229], v[186:189], v[24:27]
	v_mfma_f32_16x16x32_bf16 v[20:23], v[218:221], v[194:197], v[20:23]
	v_mfma_f32_16x16x32_bf16 v[16:19], v[226:229], v[194:197], v[16:19]
	v_mfma_f32_16x16x32_bf16 v[12:15], v[218:221], v[202:205], v[12:15]
	v_mfma_f32_16x16x32_bf16 v[8:11], v[226:229], v[202:205], v[8:11]
	v_mfma_f32_16x16x32_bf16 v[4:7], v[218:221], v[210:213], v[4:7]
	v_mfma_f32_16x16x32_bf16 v[0:3], v[226:229], v[210:213], v[0:3]
	v_mfma_f32_16x16x32_bf16 v[28:31], v[222:225], v[190:193], v[28:31]
	v_mfma_f32_16x16x32_bf16 v[24:27], v[230:233], v[190:193], v[24:27]
	v_mfma_f32_16x16x32_bf16 v[20:23], v[222:225], v[198:201], v[20:23]
	v_mfma_f32_16x16x32_bf16 v[16:19], v[230:233], v[198:201], v[16:19]
	v_mfma_f32_16x16x32_bf16 v[12:15], v[222:225], v[206:209], v[12:15]
	v_mfma_f32_16x16x32_bf16 v[8:11], v[230:233], v[206:209], v[8:11]
	v_mfma_f32_16x16x32_bf16 v[4:7], v[222:225], v[214:217], v[4:7]
	v_mfma_f32_16x16x32_bf16 v[0:3], v[230:233], v[214:217], v[0:3]
	s_add_i32 s54, s54, 2
	s_add_u32 s52, s52, 0x100
	s_addc_u32 s53, s53, 0
	s_cmp_gt_u32 s54, 27
	s_barrier
	s_cbranch_scc0 .LBB0_654
	s_lshl_b64 s[52:53], s[16:17], 12
	s_add_u32 s52, s14, s52
	s_addc_u32 s53, s15, s53
	s_add_u32 s52, s52, 0x80000
	s_addc_u32 s53, s53, 0
	v_lshl_add_u64 v[156:157], s[52:53], 0, v[128:129]
	v_readfirstlane_b32 s54, v168
	v_lshl_add_u64 v[156:157], v[156:157], 0, s[50:51]
	s_mov_b32 m0, s54
	ds_read_b128 v[134:137], v160
	ds_read_b128 v[138:141], v160 offset:1024
	ds_read_b128 v[170:173], v160 offset:2048
	ds_read_b128 v[174:177], v160 offset:3072
	ds_read_b128 v[178:181], v151
	ds_read_b128 v[182:185], v151 offset:1024
	ds_read_b128 v[186:189], v150
	ds_read_b128 v[190:193], v150 offset:1024
	ds_read_b128 v[194:197], v149
	ds_read_b128 v[198:201], v149 offset:1024
	ds_read_b128 v[202:205], v148
	ds_read_b128 v[206:209], v148 offset:1024
	global_load_lds_dwordx4 v[156:157], off
	v_lshl_add_u64 v[156:157], s[52:53], 0, v[132:133]
	v_readfirstlane_b32 s52, v169
	v_lshl_add_u64 v[156:157], v[156:157], 0, s[50:51]
	s_mov_b32 m0, s52
	s_nop 0
	global_load_lds_dwordx4 v[156:157], off
	s_barrier
	s_waitcnt lgkmcnt(0)
	s_waitcnt lgkmcnt(0)
	v_mfma_f32_16x16x32_bf16 v[124:127], v[134:137], v[178:181], v[124:127]
	v_mfma_f32_16x16x32_bf16 v[120:123], v[170:173], v[178:181], v[120:123]
	v_mfma_f32_16x16x32_bf16 v[116:119], v[134:137], v[186:189], v[116:119]
	v_mfma_f32_16x16x32_bf16 v[112:115], v[170:173], v[186:189], v[112:115]
	v_mfma_f32_16x16x32_bf16 v[108:111], v[134:137], v[194:197], v[108:111]
	v_mfma_f32_16x16x32_bf16 v[104:107], v[170:173], v[194:197], v[104:107]
	v_mfma_f32_16x16x32_bf16 v[100:103], v[134:137], v[202:205], v[100:103]
	v_mfma_f32_16x16x32_bf16 v[96:99], v[170:173], v[202:205], v[96:99]
	v_mfma_f32_16x16x32_bf16 v[124:127], v[138:141], v[182:185], v[124:127]
	v_mfma_f32_16x16x32_bf16 v[120:123], v[174:177], v[182:185], v[120:123]
	v_mfma_f32_16x16x32_bf16 v[116:119], v[138:141], v[190:193], v[116:119]
	v_mfma_f32_16x16x32_bf16 v[112:115], v[174:177], v[190:193], v[112:115]
	v_mfma_f32_16x16x32_bf16 v[108:111], v[138:141], v[198:201], v[108:111]
	v_mfma_f32_16x16x32_bf16 v[104:107], v[174:177], v[198:201], v[104:107]
	v_mfma_f32_16x16x32_bf16 v[100:103], v[138:141], v[206:209], v[100:103]
	v_mfma_f32_16x16x32_bf16 v[96:99], v[174:177], v[206:209], v[96:99]
	s_barrier
	ds_read_b128 v[210:213], v159
	ds_read_b128 v[214:217], v159 offset:1024
	ds_read_b128 v[218:221], v159 offset:2048
	ds_read_b128 v[156:159], v159 offset:3072
	s_waitcnt vmcnt(8)
	s_barrier
; #define LDA(dst, b, h) for (int m = 0; m < 4; ++m) for (int k = 0; k < 2; ++k) \
;     dst[m][k] = *reinterpret_cast<const bf16x8*>((char*)SA(b, h) + lds_byte(wr * 64 + m * 16 + fr, k * 32 + fq * 8))
; #define LDB(dst, b, h) for (int n = 0; n < 2; ++n) for (int k = 0; k < 2; ++k) \
;     dst[n][k] = *reinterpret_cast<const bf16x8*>((char*)SB(b, h) + lds_byte(wc * 32 + n * 16 + fr, k * 32 + fq * 8))
; #define MMA(ai, bj, At_, Bt_) do { __builtin_amdgcn_s_setprio(1); \
;     for (int k = 0; k < 2; ++k) for (int m = 0; m < 4; ++m) for (int n = 0; n < 2; ++n) \
;       acc[ai][bj][m][n] = __builtin_amdgcn_mfma_f32_16x16x32_bf16(At_[m][k], Bt_[n][k], acc[ai][bj][m][n], 0, 0, 0); \
;     __builtin_amdgcn_s_setprio(0); } while (0)
; #define WAIT_V(n) asm volatile("s_waitcnt vmcnt(" #n ")" ::: "memory")
; #define WAIT_L(n) asm volatile("s_waitcnt lgkmcnt(" #n ")" ::: "memory")
; #define BAR __builtin_amdgcn_s_barrier()
; template <int EPI, int lda, int ldb, int N, int K>
; __device__ __forceinline__ void gemm_phase(const u16* __restrict__ A, const u16* __restrict__ Bt, const GemmEpi ep, int wv) {
;     ...
;       LDB(B1, 0, 1); BAR; WAIT_L(0); MMA(0, 1, At, B1); BAR;
;       LDA(At, 0, 1); WAIT_V(4); BAR; WAIT_L(0); MMA(1, 0, At, B0); MMA(1, 1, At, B1); BAR; }
;     { LDB(B0, 1, 0); LDA(At, 1, 0); WAIT_V(2); BAR; WAIT_L(0); MMA(0, 0, At, B0); BAR;
	s_waitcnt lgkmcnt(0)
	s_waitcnt lgkmcnt(0)
	v_mfma_f32_16x16x32_bf16 v[92:95], v[210:213], v[178:181], v[92:95]
	v_mfma_f32_16x16x32_bf16 v[88:91], v[218:221], v[178:181], v[88:91]
	v_mfma_f32_16x16x32_bf16 v[76:79], v[210:213], v[194:197], v[76:79]
	v_mfma_f32_16x16x32_bf16 v[72:75], v[218:221], v[194:197], v[72:75]
	v_mfma_f32_16x16x32_bf16 v[84:87], v[210:213], v[186:189], v[84:87]
	v_mfma_f32_16x16x32_bf16 v[80:83], v[218:221], v[186:189], v[80:83]
	v_mfma_f32_16x16x32_bf16 v[68:71], v[210:213], v[202:205], v[68:71]
	v_mfma_f32_16x16x32_bf16 v[64:67], v[218:221], v[202:205], v[64:67]
	v_mfma_f32_16x16x32_bf16 v[92:95], v[214:217], v[182:185], v[92:95]
	v_mfma_f32_16x16x32_bf16 v[88:91], v[156:159], v[182:185], v[88:91]
	v_mfma_f32_16x16x32_bf16 v[76:79], v[214:217], v[198:201], v[76:79]
	v_mfma_f32_16x16x32_bf16 v[72:75], v[156:159], v[198:201], v[72:75]
	v_mfma_f32_16x16x32_bf16 v[178:181], v[214:217], v[190:193], v[84:87]
	v_mfma_f32_16x16x32_bf16 v[182:185], v[156:159], v[190:193], v[80:83]
	v_mfma_f32_16x16x32_bf16 v[186:189], v[214:217], v[206:209], v[68:71]
	v_mfma_f32_16x16x32_bf16 v[190:193], v[156:159], v[206:209], v[64:67]
	s_barrier
	s_nop 0
	ds_read_b128 v[64:67], v151 offset:16384
	ds_read_b128 v[68:71], v151 offset:17408
	ds_read_b128 v[80:83], v150 offset:16384
	ds_read_b128 v[84:87], v150 offset:17408
	ds_read_b128 v[194:197], v149 offset:16384
	ds_read_b128 v[198:201], v149 offset:17408
	ds_read_b128 v[202:205], v148 offset:16384
	ds_read_b128 v[206:209], v148 offset:17408
	s_waitcnt vmcnt(4)
	s_barrier
	s_waitcnt lgkmcnt(0)
	s_waitcnt lgkmcnt(0)
	v_mfma_f32_16x16x32_bf16 v[60:63], v[134:137], v[64:67], v[60:63]
	v_mfma_f32_16x16x32_bf16 v[56:59], v[170:173], v[64:67], v[56:59]
	v_mfma_f32_16x16x32_bf16 v[52:55], v[134:137], v[80:83], v[52:55]
	v_mfma_f32_16x16x32_bf16 v[48:51], v[170:173], v[80:83], v[48:51]
	v_mfma_f32_16x16x32_bf16 v[44:47], v[134:137], v[194:197], v[44:47]
	v_mfma_f32_16x16x32_bf16 v[40:43], v[170:173], v[194:197], v[40:43]
	v_mfma_f32_16x16x32_bf16 v[36:39], v[134:137], v[202:205], v[36:39]
	v_mfma_f32_16x16x32_bf16 v[32:35], v[170:173], v[202:205], v[32:35]
	v_mfma_f32_16x16x32_bf16 v[60:63], v[138:141], v[68:71], v[60:63]
	v_mfma_f32_16x16x32_bf16 v[56:59], v[174:177], v[68:71], v[56:59]
	v_mfma_f32_16x16x32_bf16 v[52:55], v[138:141], v[84:87], v[52:55]
	v_mfma_f32_16x16x32_bf16 v[48:51], v[174:177], v[84:87], v[48:51]
	v_mfma_f32_16x16x32_bf16 v[44:47], v[138:141], v[198:201], v[44:47]
	v_mfma_f32_16x16x32_bf16 v[40:43], v[174:177], v[198:201], v[40:43]
	v_mfma_f32_16x16x32_bf16 v[36:39], v[138:141], v[206:209], v[36:39]
	v_mfma_f32_16x16x32_bf16 v[32:35], v[174:177], v[206:209], v[32:35]
	v_mfma_f32_16x16x32_bf16 v[28:31], v[210:213], v[64:67], v[28:31]
	v_mfma_f32_16x16x32_bf16 v[20:23], v[210:213], v[80:83], v[20:23]
	v_mfma_f32_16x16x32_bf16 v[12:15], v[210:213], v[194:197], v[12:15]
	v_mfma_f32_16x16x32_bf16 v[4:7], v[210:213], v[202:205], v[4:7]
	v_mfma_f32_16x16x32_bf16 v[24:27], v[218:221], v[64:67], v[24:27]
	v_mfma_f32_16x16x32_bf16 v[16:19], v[218:221], v[80:83], v[16:19]
	v_mfma_f32_16x16x32_bf16 v[8:11], v[218:221], v[194:197], v[8:11]
	v_mfma_f32_16x16x32_bf16 v[0:3], v[218:221], v[202:205], v[0:3]
	v_mfma_f32_16x16x32_bf16 v[28:31], v[214:217], v[68:71], v[28:31]
	v_mfma_f32_16x16x32_bf16 v[20:23], v[214:217], v[84:87], v[20:23]
	v_mfma_f32_16x16x32_bf16 v[12:15], v[214:217], v[198:201], v[12:15]
	v_mfma_f32_16x16x32_bf16 v[4:7], v[214:217], v[206:209], v[4:7]
	v_mfma_f32_16x16x32_bf16 v[134:137], v[156:159], v[68:71], v[24:27]
	v_mfma_f32_16x16x32_bf16 v[138:141], v[156:159], v[84:87], v[16:19]
	v_mfma_f32_16x16x32_bf16 v[168:171], v[156:159], v[198:201], v[8:11]
	v_mfma_f32_16x16x32_bf16 v[156:159], v[156:159], v[206:209], v[0:3]
	s_barrier
	s_nop 0
	ds_read_b128 v[0:3], v154
	ds_read_b128 v[8:11], v154 offset:1024
	ds_read_b128 v[16:19], v154 offset:2048
	ds_read_b128 v[172:175], v154 offset:3072
	ds_read_b128 v[24:27], v151 offset:32768
	ds_read_b128 v[194:197], v151 offset:33792
	ds_read_b128 v[198:201], v150 offset:32768
	ds_read_b128 v[202:205], v150 offset:33792
	ds_read_b128 v[206:209], v149 offset:32768
	ds_read_b128 v[210:213], v149 offset:33792
	ds_read_b128 v[214:217], v148 offset:32768
	ds_read_b128 v[218:221], v148 offset:33792
	s_waitcnt vmcnt(2)
	s_barrier
; #define LDA(dst, b, h) for (int m = 0; m < 4; ++m) for (int k = 0; k < 2; ++k) \
;     dst[m][k] = *reinterpret_cast<const bf16x8*>((char*)SA(b, h) + lds_byte(wr * 64 + m * 16 + fr, k * 32 + fq * 8))
; #define LDB(dst, b, h) for (int n = 0; n < 2; ++n) for (int k = 0; k < 2; ++k) \
;     dst[n][k] = *reinterpret_cast<const bf16x8*>((char*)SB(b, h) + lds_byte(wc * 32 + n * 16 + fr, k * 32 + fq * 8))
; #define MMA(ai, bj, At_, Bt_) do { __builtin_amdgcn_s_setprio(1); \
;     for (int k = 0; k < 2; ++k) for (int m = 0; m < 4; ++m) for (int n = 0; n < 2; ++n) \
;       acc[ai][bj][m][n] = __builtin_amdgcn_mfma_f32_16x16x32_bf16(At_[m][k], Bt_[n][k], acc[ai][bj][m][n], 0, 0, 0); \
;     __builtin_amdgcn_s_setprio(0); } while (0)
; #define WAIT_V(n) asm volatile("s_waitcnt vmcnt(" #n ")" ::: "memory")
; #define WAIT_L(n) asm volatile("s_waitcnt lgkmcnt(" #n ")" ::: "memory")
; #define BAR __builtin_amdgcn_s_barrier()
; template <int EPI, int lda, int ldb, int N, int K>
; __device__ __forceinline__ void gemm_phase(const u16* __restrict__ A, const u16* __restrict__ Bt, const GemmEpi ep, int wv) {
;     ...
;     { LDB(B0, 1, 0); LDA(At, 1, 0); WAIT_V(2); BAR; WAIT_L(0); MMA(0, 0, At, B0); BAR;
;       LDB(B1, 1, 1); WAIT_V(0); BAR; WAIT_L(0); MMA(0, 1, At, B1); BAR;
;       LDA(At, 1, 1); BAR; WAIT_L(0); MMA(1, 0, At, B0); MMA(1, 1, At, B1); BAR; }
;     if (wr == 0) BAR;
	s_waitcnt lgkmcnt(0)
	s_waitcnt lgkmcnt(0)
	v_mfma_f32_16x16x32_bf16 v[64:67], v[0:3], v[24:27], v[124:127]
	v_mfma_f32_16x16x32_bf16 v[68:71], v[16:19], v[24:27], v[120:123]
	v_mfma_f32_16x16x32_bf16 v[80:83], v[0:3], v[198:201], v[116:119]
	v_mfma_f32_16x16x32_bf16 v[84:87], v[16:19], v[198:201], v[112:115]
	v_mfma_f32_16x16x32_bf16 v[108:111], v[0:3], v[206:209], v[108:111]
	v_mfma_f32_16x16x32_bf16 v[104:107], v[16:19], v[206:209], v[104:107]
	v_mfma_f32_16x16x32_bf16 v[120:123], v[0:3], v[214:217], v[100:103]
	v_mfma_f32_16x16x32_bf16 v[124:127], v[16:19], v[214:217], v[96:99]
	v_mfma_f32_16x16x32_bf16 v[116:119], v[8:11], v[194:197], v[64:67]
	v_mfma_f32_16x16x32_bf16 v[112:115], v[172:175], v[194:197], v[68:71]
	v_mfma_f32_16x16x32_bf16 v[100:103], v[8:11], v[202:205], v[80:83]
	v_mfma_f32_16x16x32_bf16 v[96:99], v[172:175], v[202:205], v[84:87]
	v_mfma_f32_16x16x32_bf16 v[84:87], v[8:11], v[210:213], v[108:111]
	v_mfma_f32_16x16x32_bf16 v[80:83], v[172:175], v[210:213], v[104:107]
	v_mfma_f32_16x16x32_bf16 v[68:71], v[8:11], v[218:221], v[120:123]
	v_mfma_f32_16x16x32_bf16 v[64:67], v[172:175], v[218:221], v[124:127]
	s_barrier
	ds_read_b128 v[222:225], v152
	ds_read_b128 v[226:229], v152 offset:1024
	ds_read_b128 v[230:233], v152 offset:2048
	ds_read_b128 v[152:155], v152 offset:3072
	s_waitcnt vmcnt(0)
	s_barrier
	s_waitcnt lgkmcnt(0)
	s_waitcnt lgkmcnt(0)
	v_mfma_f32_16x16x32_bf16 v[92:95], v[222:225], v[24:27], v[92:95]
	v_mfma_f32_16x16x32_bf16 v[24:27], v[230:233], v[24:27], v[88:91]
	v_mfma_f32_16x16x32_bf16 v[88:91], v[222:225], v[198:201], v[178:181]
	v_mfma_f32_16x16x32_bf16 v[104:107], v[230:233], v[198:201], v[182:185]
	v_mfma_f32_16x16x32_bf16 v[76:79], v[222:225], v[206:209], v[76:79]
	v_mfma_f32_16x16x32_bf16 v[72:75], v[230:233], v[206:209], v[72:75]
	v_mfma_f32_16x16x32_bf16 v[176:179], v[222:225], v[214:217], v[186:189]
	v_mfma_f32_16x16x32_bf16 v[180:183], v[230:233], v[214:217], v[190:193]
	v_mfma_f32_16x16x32_bf16 v[124:127], v[226:229], v[194:197], v[92:95]
	v_mfma_f32_16x16x32_bf16 v[120:123], v[152:155], v[194:197], v[24:27]
	v_mfma_f32_16x16x32_bf16 v[108:111], v[226:229], v[202:205], v[88:91]
	v_mfma_f32_16x16x32_bf16 v[104:107], v[152:155], v[202:205], v[104:107]
	v_mfma_f32_16x16x32_bf16 v[92:95], v[226:229], v[210:213], v[76:79]
	v_mfma_f32_16x16x32_bf16 v[88:91], v[152:155], v[210:213], v[72:75]
	v_mfma_f32_16x16x32_bf16 v[76:79], v[226:229], v[218:221], v[176:179]
	v_mfma_f32_16x16x32_bf16 v[72:75], v[152:155], v[218:221], v[180:183]
	s_barrier
	ds_read_b128 v[176:179], v151 offset:49152
	ds_read_b128 v[180:183], v151 offset:50176
	ds_read_b128 v[184:187], v150 offset:49152
	ds_read_b128 v[188:191], v150 offset:50176
	ds_read_b128 v[192:195], v149 offset:49152
	ds_read_b128 v[196:199], v149 offset:50176
	ds_read_b128 v[200:203], v148 offset:49152
	ds_read_b128 v[148:151], v148 offset:50176
	s_barrier
	s_waitcnt lgkmcnt(0)
	s_waitcnt lgkmcnt(0)
	v_mfma_f32_16x16x32_bf16 v[24:27], v[0:3], v[176:179], v[60:63]
	v_mfma_f32_16x16x32_bf16 v[60:63], v[16:19], v[176:179], v[56:59]
	v_mfma_f32_16x16x32_bf16 v[52:55], v[0:3], v[184:187], v[52:55]
	v_mfma_f32_16x16x32_bf16 v[204:207], v[16:19], v[184:187], v[48:51]
	v_mfma_f32_16x16x32_bf16 v[44:47], v[0:3], v[192:195], v[44:47]
	v_mfma_f32_16x16x32_bf16 v[208:211], v[16:19], v[192:195], v[40:43]
	v_mfma_f32_16x16x32_bf16 v[0:3], v[0:3], v[200:203], v[36:39]
	v_mfma_f32_16x16x32_bf16 v[36:39], v[16:19], v[200:203], v[32:35]
	v_mfma_f32_16x16x32_bf16 v[56:59], v[8:11], v[180:183], v[24:27]
	v_mfma_f32_16x16x32_bf16 v[48:51], v[172:175], v[180:183], v[60:63]
	v_mfma_f32_16x16x32_bf16 v[40:43], v[8:11], v[188:191], v[52:55]
	v_mfma_f32_16x16x32_bf16 v[32:35], v[172:175], v[188:191], v[204:207]
	v_mfma_f32_16x16x32_bf16 v[24:27], v[8:11], v[196:199], v[44:47]
	v_mfma_f32_16x16x32_bf16 v[16:19], v[172:175], v[196:199], v[208:211]
	v_mfma_f32_16x16x32_bf16 v[8:11], v[8:11], v[148:151], v[0:3]
	v_mfma_f32_16x16x32_bf16 v[0:3], v[172:175], v[148:151], v[36:39]
	v_mfma_f32_16x16x32_bf16 v[28:31], v[222:225], v[176:179], v[28:31]
	v_mfma_f32_16x16x32_bf16 v[36:39], v[230:233], v[176:179], v[134:137]
	v_mfma_f32_16x16x32_bf16 v[20:23], v[222:225], v[184:187], v[20:23]
	v_mfma_f32_16x16x32_bf16 v[134:137], v[230:233], v[184:187], v[138:141]
	v_mfma_f32_16x16x32_bf16 v[12:15], v[222:225], v[192:195], v[12:15]
	v_mfma_f32_16x16x32_bf16 v[138:141], v[230:233], v[192:195], v[168:171]
	v_mfma_f32_16x16x32_bf16 v[4:7], v[222:225], v[200:203], v[4:7]
	v_mfma_f32_16x16x32_bf16 v[156:159], v[230:233], v[200:203], v[156:159]
	v_mfma_f32_16x16x32_bf16 v[60:63], v[226:229], v[180:183], v[28:31]
	v_mfma_f32_16x16x32_bf16 v[52:55], v[152:155], v[180:183], v[36:39]
	v_mfma_f32_16x16x32_bf16 v[44:47], v[226:229], v[188:191], v[20:23]
	v_mfma_f32_16x16x32_bf16 v[36:39], v[152:155], v[188:191], v[134:137]
	v_mfma_f32_16x16x32_bf16 v[28:31], v[226:229], v[196:199], v[12:15]
	v_mfma_f32_16x16x32_bf16 v[20:23], v[152:155], v[196:199], v[138:141]
	v_mfma_f32_16x16x32_bf16 v[12:15], v[226:229], v[148:151], v[4:7]
	v_mfma_f32_16x16x32_bf16 v[4:7], v[152:155], v[148:151], v[156:159]
	v_cmp_gt_u32_e32 vcc, s70, v130
	s_barrier
	s_and_saveexec_b64 s[52:53], vcc
	s_cbranch_execz .LBB0_657
	s_barrier

; #define STAGE(P, BASE, LD, br, kt) do { const char* _g = (const char*)((BASE) + (size_t)(br) * (LD) + (size_t)(kt) * 64); \
;     for (int _i = 0; _i < 2; ++_i) { int _b = tidx * 16 + _i * 8192; int _r, _c; stage_rc(_b, _r, _c); \
;       __builtin_amdgcn_global_load_lds((const unsigned*)(_g + (unsigned)((_r * (LD) + _c) * 2)), (unsigned*)((char*)(P) + _b), 16, 0, 0); } } while (0)
; #define LDA(dst, b, h) for (int m = 0; m < 4; ++m) for (int k = 0; k < 2; ++k) \
;     dst[m][k] = *reinterpret_cast<const bf16x8*>((char*)SA(b, h) + lds_byte(wr * 64 + m * 16 + fr, k * 32 + fq * 8))
; #define LDB(dst, b, h) for (int n = 0; n < 2; ++n) for (int k = 0; k < 2; ++k) \
;     dst[n][k] = *reinterpret_cast<const bf16x8*>((char*)SB(b, h) + lds_byte(wc * 32 + n * 16 + fr, k * 32 + fq * 8))
; #define MMA(ai, bj, At_, Bt_) do { __builtin_amdgcn_s_setprio(1); \
;     for (int k = 0; k < 2; ++k) for (int m = 0; m < 4; ++m) for (int n = 0; n < 2; ++n) \
;       acc[ai][bj][m][n] = __builtin_amdgcn_mfma_f32_16x16x32_bf16(At_[m][k], Bt_[n][k], acc[ai][bj][m][n], 0, 0, 0); \
;     __builtin_amdgcn_s_setprio(0); } while (0)
; #define WAIT_L(n) asm volatile("s_waitcnt lgkmcnt(" #n ")" ::: "memory")
; #define BAR __builtin_amdgcn_s_barrier()
; #define SCHED __builtin_amdgcn_sched_barrier(0)
; template <int EPI, int lda, int ldb, int N, int K>
; __device__ __forceinline__ void gemm_phase(const u16* __restrict__ A, const u16* __restrict__ Bt, const GemmEpi ep, int wv) {
;     ...
;       LDB(B0, 0, 0); SCHED; LDA(At, 0, 0); STAGE(SA(1, 1), Ab, lda, brow + HALF, t + 1);
;       WAIT_L(8); BAR; WAIT_L(0); MMA(0, 0, At, B0); BAR; SCHED;
;       LDB(B1, 0, 1); STAGE(SB(0, 0), Bt, ldb, bcol, t + 2);
;       BAR; WAIT_L(0); MMA(0, 1, At, B1); BAR;
;       LDA(At, 0, 1); STAGE(SA(0, 0), Ab, lda, brow, t + 2);
;       BAR; WAIT_L(0); MMA(1, 0, At, B0); BAR; SCHED;
.LBB0_770:
	ds_read_b128 v[172:175], v161
	ds_read_b128 v[176:179], v161 offset:1024
	ds_read_b128 v[180:183], v161 offset:2048
	ds_read_b128 v[184:187], v161 offset:3072
	v_add_u32_e32 v169, 0xc000, v148
	v_lshl_add_u64 v[236:237], v[136:137], 0, s[50:51]
	v_readfirstlane_b32 s53, v169
	v_add_u32_e32 v170, 0xe000, v148
	v_lshl_add_u64 v[162:163], v[236:237], 0, s[18:19]
	s_mov_b32 m0, s53
	v_lshl_add_u64 v[238:239], v[134:135], 0, s[50:51]
	v_readfirstlane_b32 s53, v170
	ds_read_b128 v[164:167], v152
	ds_read_b128 v[188:191], v152 offset:1024
	ds_read_b128 v[192:195], v151
	ds_read_b128 v[196:199], v151 offset:1024
	ds_read_b128 v[200:203], v150
	ds_read_b128 v[204:207], v150 offset:1024
	ds_read_b128 v[208:211], v149
	ds_read_b128 v[212:215], v149 offset:1024
	global_load_lds_dwordx4 v[162:163], off
	v_lshl_add_u64 v[162:163], v[238:239], 0, s[18:19]
	s_mov_b32 m0, s53
	s_nop 0
	global_load_lds_dwordx4 v[162:163], off
	s_waitcnt lgkmcnt(8)
	s_barrier
	s_waitcnt lgkmcnt(0)
	s_waitcnt lgkmcnt(0)
	v_mfma_f32_16x16x32_bf16 v[124:127], v[172:175], v[164:167], v[124:127]
	v_mfma_f32_16x16x32_bf16 v[120:123], v[180:183], v[164:167], v[120:123]
	v_mfma_f32_16x16x32_bf16 v[116:119], v[172:175], v[192:195], v[116:119]
	v_mfma_f32_16x16x32_bf16 v[112:115], v[180:183], v[192:195], v[112:115]
	v_mfma_f32_16x16x32_bf16 v[108:111], v[172:175], v[200:203], v[108:111]
	v_mfma_f32_16x16x32_bf16 v[104:107], v[180:183], v[200:203], v[104:107]
	v_mfma_f32_16x16x32_bf16 v[100:103], v[172:175], v[208:211], v[100:103]
	v_mfma_f32_16x16x32_bf16 v[96:99], v[180:183], v[208:211], v[96:99]
	v_mfma_f32_16x16x32_bf16 v[124:127], v[176:179], v[188:191], v[124:127]
	v_mfma_f32_16x16x32_bf16 v[120:123], v[184:187], v[188:191], v[120:123]
	v_mfma_f32_16x16x32_bf16 v[116:119], v[176:179], v[196:199], v[116:119]
	v_mfma_f32_16x16x32_bf16 v[112:115], v[184:187], v[196:199], v[112:115]
	v_mfma_f32_16x16x32_bf16 v[108:111], v[176:179], v[204:207], v[108:111]
	v_mfma_f32_16x16x32_bf16 v[104:107], v[184:187], v[204:207], v[104:107]
	v_mfma_f32_16x16x32_bf16 v[100:103], v[176:179], v[212:215], v[100:103]
	v_mfma_f32_16x16x32_bf16 v[96:99], v[184:187], v[212:215], v[96:99]
	s_barrier
	v_add_u32_e32 v162, s64, v153
	v_lshl_add_u64 v[240:241], v[140:141], 0, s[50:51]
	v_readfirstlane_b32 s53, v162
	v_add_u32_e32 v163, 0x2000, v162
	v_lshl_add_u64 v[232:233], v[240:241], 0, s[20:21]
	s_mov_b32 m0, s53
	v_lshl_add_u64 v[242:243], v[138:139], 0, s[50:51]
	v_readfirstlane_b32 s53, v163
	ds_read_b128 v[216:219], v160
	ds_read_b128 v[220:223], v160 offset:1024
	ds_read_b128 v[224:227], v160 offset:2048
	ds_read_b128 v[228:231], v160 offset:3072
	global_load_lds_dwordx4 v[232:233], off
	v_lshl_add_u64 v[232:233], v[242:243], 0, s[20:21]
	s_mov_b32 m0, s53
	s_nop 0
	global_load_lds_dwordx4 v[232:233], off
	s_waitcnt vmcnt(10)
	s_barrier
	s_waitcnt lgkmcnt(0)
	s_waitcnt lgkmcnt(0)
	v_mfma_f32_16x16x32_bf16 v[92:95], v[216:219], v[164:167], v[92:95]
	v_mfma_f32_16x16x32_bf16 v[88:91], v[224:227], v[164:167], v[88:91]
	v_mfma_f32_16x16x32_bf16 v[84:87], v[216:219], v[192:195], v[84:87]
	v_mfma_f32_16x16x32_bf16 v[80:83], v[224:227], v[192:195], v[80:83]
	v_mfma_f32_16x16x32_bf16 v[76:79], v[216:219], v[200:203], v[76:79]
	v_mfma_f32_16x16x32_bf16 v[72:75], v[224:227], v[200:203], v[72:75]
	v_mfma_f32_16x16x32_bf16 v[68:71], v[216:219], v[208:211], v[68:71]
	v_mfma_f32_16x16x32_bf16 v[64:67], v[224:227], v[208:211], v[64:67]
	v_mfma_f32_16x16x32_bf16 v[92:95], v[220:223], v[188:191], v[92:95]
	v_mfma_f32_16x16x32_bf16 v[88:91], v[228:231], v[188:191], v[88:91]
	v_mfma_f32_16x16x32_bf16 v[84:87], v[220:223], v[196:199], v[84:87]
	v_mfma_f32_16x16x32_bf16 v[80:83], v[228:231], v[196:199], v[80:83]
	v_mfma_f32_16x16x32_bf16 v[76:79], v[220:223], v[204:207], v[76:79]
	v_mfma_f32_16x16x32_bf16 v[72:75], v[228:231], v[204:207], v[72:75]
	v_mfma_f32_16x16x32_bf16 v[68:71], v[220:223], v[212:215], v[68:71]
	v_mfma_f32_16x16x32_bf16 v[64:67], v[228:231], v[212:215], v[64:67]
	v_readfirstlane_b32 s53, v148
	v_lshl_add_u64 v[164:165], v[236:237], 0, s[22:23]
	s_mov_b32 m0, s53
	s_barrier
	ds_read_b128 v[188:191], v152 offset:16384
	ds_read_b128 v[192:195], v152 offset:17408
	ds_read_b128 v[196:199], v151 offset:16384
	ds_read_b128 v[200:203], v151 offset:17408
	ds_read_b128 v[204:207], v150 offset:16384
	ds_read_b128 v[208:211], v150 offset:17408
	ds_read_b128 v[212:215], v149 offset:16384
	ds_read_b128 v[232:235], v149 offset:17408
	global_load_lds_dwordx4 v[164:165], off
	v_add_u32_e32 v164, 0x2000, v148
	v_lshl_add_u64 v[166:167], v[238:239], 0, s[22:23]
	v_readfirstlane_b32 s53, v164
	s_mov_b32 m0, s53
	s_nop 0
	global_load_lds_dwordx4 v[166:167], off
	s_barrier
	s_waitcnt lgkmcnt(0)
	s_waitcnt lgkmcnt(0)
	v_mfma_f32_16x16x32_bf16 v[60:63], v[172:175], v[188:191], v[60:63]
	v_mfma_f32_16x16x32_bf16 v[56:59], v[180:183], v[188:191], v[56:59]
	v_mfma_f32_16x16x32_bf16 v[52:55], v[172:175], v[196:199], v[52:55]
	v_mfma_f32_16x16x32_bf16 v[48:51], v[180:183], v[196:199], v[48:51]
	v_mfma_f32_16x16x32_bf16 v[44:47], v[172:175], v[204:207], v[44:47]
	v_mfma_f32_16x16x32_bf16 v[40:43], v[180:183], v[204:207], v[40:43]
	v_mfma_f32_16x16x32_bf16 v[36:39], v[172:175], v[212:215], v[36:39]
	v_mfma_f32_16x16x32_bf16 v[32:35], v[180:183], v[212:215], v[32:35]
	v_mfma_f32_16x16x32_bf16 v[60:63], v[176:179], v[192:195], v[60:63]
	v_mfma_f32_16x16x32_bf16 v[56:59], v[184:187], v[192:195], v[56:59]
	v_mfma_f32_16x16x32_bf16 v[52:55], v[176:179], v[200:203], v[52:55]
	v_mfma_f32_16x16x32_bf16 v[48:51], v[184:187], v[200:203], v[48:51]
	v_mfma_f32_16x16x32_bf16 v[44:47], v[176:179], v[208:211], v[44:47]
	v_mfma_f32_16x16x32_bf16 v[40:43], v[184:187], v[208:211], v[40:43]
	v_mfma_f32_16x16x32_bf16 v[36:39], v[176:179], v[232:235], v[36:39]
	v_mfma_f32_16x16x32_bf16 v[32:35], v[184:187], v[232:235], v[32:35]
	s_barrier
; #define STAGE(P, BASE, LD, br, kt) do { const char* _g = (const char*)((BASE) + (size_t)(br) * (LD) + (size_t)(kt) * 64); \
;     for (int _i = 0; _i < 2; ++_i) { int _b = tidx * 16 + _i * 8192; int _r, _c; stage_rc(_b, _r, _c); \
;       __builtin_amdgcn_global_load_lds((const unsigned*)(_g + (unsigned)((_r * (LD) + _c) * 2)), (unsigned*)((char*)(P) + _b), 16, 0, 0); } } while (0)
; #define LDA(dst, b, h) for (int m = 0; m < 4; ++m) for (int k = 0; k < 2; ++k) \
;     dst[m][k] = *reinterpret_cast<const bf16x8*>((char*)SA(b, h) + lds_byte(wr * 64 + m * 16 + fr, k * 32 + fq * 8))
; #define LDB(dst, b, h) for (int n = 0; n < 2; ++n) for (int k = 0; k < 2; ++k) \
;     dst[n][k] = *reinterpret_cast<const bf16x8*>((char*)SB(b, h) + lds_byte(wc * 32 + n * 16 + fr, k * 32 + fq * 8))
; #define MMA(ai, bj, At_, Bt_) do { __builtin_amdgcn_s_setprio(1); \
;     for (int k = 0; k < 2; ++k) for (int m = 0; m < 4; ++m) for (int n = 0; n < 2; ++n) \
;       acc[ai][bj][m][n] = __builtin_amdgcn_mfma_f32_16x16x32_bf16(At_[m][k], Bt_[n][k], acc[ai][bj][m][n], 0, 0, 0); \
;     __builtin_amdgcn_s_setprio(0); } while (0)
; #define WAIT_V(n) asm volatile("s_waitcnt vmcnt(" #n ")" ::: "memory")
; #define WAIT_L(n) asm volatile("s_waitcnt lgkmcnt(" #n ")" ::: "memory")
; #define BAR __builtin_amdgcn_s_barrier()
; #define SCHED __builtin_amdgcn_sched_barrier(0)
; template <int EPI, int lda, int ldb, int N, int K>
; __device__ __forceinline__ void gemm_phase(const u16* __restrict__ A, const u16* __restrict__ Bt, const GemmEpi ep, int wv) {
;     ...
;       STAGE(SB(0, 1), Bt, ldb, bcol + HALF, t + 2);
;       WAIT_V(6); BAR; MMA(1, 1, At, B1); BAR;
;       LDB(B0, 1, 0); SCHED; LDA(At, 1, 0); STAGE(SA(0, 1), Ab, lda, brow + HALF, t + 2);
;       WAIT_L(8); BAR; WAIT_L(0); MMA(0, 0, At, B0); BAR; SCHED;
;       LDB(B1, 1, 1); STAGE(SB(1, 0), Bt, ldb, bcol, t + 3);
;       BAR; WAIT_L(0); MMA(0, 1, At, B1); BAR;
	v_add_u32_e32 v165, s65, v153
	v_lshl_add_u64 v[166:167], v[240:241], 0, s[24:25]
	v_readfirstlane_b32 s53, v165
	s_mov_b32 m0, s53
	v_lshl_add_u64 v[172:173], v[242:243], 0, s[24:25]
	global_load_lds_dwordx4 v[166:167], off
	v_add_u32_e32 v166, 0x2000, v165
	s_nop 0
	v_readfirstlane_b32 s53, v166
	s_mov_b32 m0, s53
	s_nop 0
	global_load_lds_dwordx4 v[172:173], off
	s_waitcnt vmcnt(8)
	s_barrier
	v_mfma_f32_16x16x32_bf16 v[28:31], v[216:219], v[188:191], v[28:31]
	v_mfma_f32_16x16x32_bf16 v[24:27], v[224:227], v[188:191], v[24:27]
	v_mfma_f32_16x16x32_bf16 v[20:23], v[216:219], v[196:199], v[20:23]
	v_mfma_f32_16x16x32_bf16 v[16:19], v[224:227], v[196:199], v[16:19]
	v_mfma_f32_16x16x32_bf16 v[12:15], v[216:219], v[204:207], v[12:15]
	v_mfma_f32_16x16x32_bf16 v[8:11], v[224:227], v[204:207], v[8:11]
	v_mfma_f32_16x16x32_bf16 v[4:7], v[216:219], v[212:215], v[4:7]
	v_mfma_f32_16x16x32_bf16 v[0:3], v[224:227], v[212:215], v[0:3]
	v_mfma_f32_16x16x32_bf16 v[28:31], v[220:223], v[192:195], v[28:31]
	v_mfma_f32_16x16x32_bf16 v[24:27], v[228:231], v[192:195], v[24:27]
	v_mfma_f32_16x16x32_bf16 v[20:23], v[220:223], v[200:203], v[20:23]
	v_mfma_f32_16x16x32_bf16 v[16:19], v[228:231], v[200:203], v[16:19]
	v_mfma_f32_16x16x32_bf16 v[12:15], v[220:223], v[208:211], v[12:15]
	v_mfma_f32_16x16x32_bf16 v[8:11], v[228:231], v[208:211], v[8:11]
	v_mfma_f32_16x16x32_bf16 v[4:7], v[220:223], v[232:235], v[4:7]
	v_mfma_f32_16x16x32_bf16 v[0:3], v[228:231], v[232:235], v[0:3]
	s_barrier
	ds_read_b128 v[172:175], v156
	ds_read_b128 v[176:179], v156 offset:1024
	ds_read_b128 v[180:183], v156 offset:2048
	ds_read_b128 v[184:187], v156 offset:3072
	v_add_u32_e32 v167, 0x4000, v148
	v_add_u32_e32 v168, 0x6000, v148
	v_readfirstlane_b32 s53, v167
	v_lshl_add_u64 v[220:221], v[236:237], 0, s[26:27]
	s_mov_b32 m0, s53
	v_readfirstlane_b32 s53, v168
	ds_read_b128 v[188:191], v152 offset:32768
	ds_read_b128 v[192:195], v152 offset:33792
	ds_read_b128 v[196:199], v151 offset:32768
	ds_read_b128 v[200:203], v151 offset:33792
	ds_read_b128 v[204:207], v150 offset:32768
	ds_read_b128 v[208:211], v150 offset:33792
	ds_read_b128 v[212:215], v149 offset:32768
	ds_read_b128 v[216:219], v149 offset:33792
	global_load_lds_dwordx4 v[220:221], off
	v_lshl_add_u64 v[220:221], v[238:239], 0, s[26:27]
	s_mov_b32 m0, s53
	s_nop 0
	global_load_lds_dwordx4 v[220:221], off
	s_waitcnt lgkmcnt(8)
	s_barrier
	s_waitcnt lgkmcnt(0)
	s_waitcnt lgkmcnt(0)
	v_mfma_f32_16x16x32_bf16 v[124:127], v[172:175], v[188:191], v[124:127]
	v_mfma_f32_16x16x32_bf16 v[120:123], v[180:183], v[188:191], v[120:123]
	v_mfma_f32_16x16x32_bf16 v[116:119], v[172:175], v[196:199], v[116:119]
	v_mfma_f32_16x16x32_bf16 v[112:115], v[180:183], v[196:199], v[112:115]
	v_mfma_f32_16x16x32_bf16 v[108:111], v[172:175], v[204:207], v[108:111]
	v_mfma_f32_16x16x32_bf16 v[104:107], v[180:183], v[204:207], v[104:107]
	v_mfma_f32_16x16x32_bf16 v[100:103], v[172:175], v[212:215], v[100:103]
	v_mfma_f32_16x16x32_bf16 v[96:99], v[180:183], v[212:215], v[96:99]
	v_mfma_f32_16x16x32_bf16 v[124:127], v[176:179], v[192:195], v[124:127]
	v_mfma_f32_16x16x32_bf16 v[120:123], v[184:187], v[192:195], v[120:123]
	v_mfma_f32_16x16x32_bf16 v[116:119], v[176:179], v[200:203], v[116:119]
	v_mfma_f32_16x16x32_bf16 v[112:115], v[184:187], v[200:203], v[112:115]
	v_mfma_f32_16x16x32_bf16 v[108:111], v[176:179], v[208:211], v[108:111]
	v_mfma_f32_16x16x32_bf16 v[104:107], v[184:187], v[208:211], v[104:107]
	v_mfma_f32_16x16x32_bf16 v[100:103], v[176:179], v[216:219], v[100:103]
	v_mfma_f32_16x16x32_bf16 v[96:99], v[184:187], v[216:219], v[96:99]
	s_barrier
	v_readfirstlane_b32 s53, v155
	v_add_u32_e32 v171, 0x2000, v155
	v_lshl_add_u64 v[244:245], v[240:241], 0, s[40:41]
	s_mov_b32 m0, s53
	v_readfirstlane_b32 s53, v171
	ds_read_b128 v[220:223], v154
	ds_read_b128 v[224:227], v154 offset:1024
	ds_read_b128 v[228:231], v154 offset:2048
	ds_read_b128 v[232:235], v154 offset:3072
	global_load_lds_dwordx4 v[244:245], off
	v_lshl_add_u64 v[244:245], v[242:243], 0, s[40:41]
	s_mov_b32 m0, s53
	s_nop 0
	global_load_lds_dwordx4 v[244:245], off
	s_waitcnt vmcnt(10)
	s_barrier
	s_waitcnt lgkmcnt(0)
	s_waitcnt lgkmcnt(0)
	v_mfma_f32_16x16x32_bf16 v[92:95], v[220:223], v[188:191], v[92:95]
	v_mfma_f32_16x16x32_bf16 v[88:91], v[228:231], v[188:191], v[88:91]
	v_mfma_f32_16x16x32_bf16 v[84:87], v[220:223], v[196:199], v[84:87]
	v_mfma_f32_16x16x32_bf16 v[80:83], v[228:231], v[196:199], v[80:83]
	v_mfma_f32_16x16x32_bf16 v[76:79], v[220:223], v[204:207], v[76:79]
	v_mfma_f32_16x16x32_bf16 v[72:75], v[228:231], v[204:207], v[72:75]
	v_mfma_f32_16x16x32_bf16 v[68:71], v[220:223], v[212:215], v[68:71]
	v_mfma_f32_16x16x32_bf16 v[64:67], v[228:231], v[212:215], v[64:67]
	v_mfma_f32_16x16x32_bf16 v[92:95], v[224:227], v[192:195], v[92:95]
	v_mfma_f32_16x16x32_bf16 v[88:91], v[232:235], v[192:195], v[88:91]
	v_mfma_f32_16x16x32_bf16 v[84:87], v[224:227], v[200:203], v[84:87]
	v_mfma_f32_16x16x32_bf16 v[80:83], v[232:235], v[200:203], v[80:83]
	v_mfma_f32_16x16x32_bf16 v[76:79], v[224:227], v[208:211], v[76:79]
	v_mfma_f32_16x16x32_bf16 v[72:75], v[232:235], v[208:211], v[72:75]
	v_mfma_f32_16x16x32_bf16 v[68:71], v[224:227], v[216:219], v[68:71]
	v_mfma_f32_16x16x32_bf16 v[64:67], v[232:235], v[216:219], v[64:67]
	v_readfirstlane_b32 s53, v157
	v_lshl_add_u64 v[236:237], v[236:237], 0, s[42:43]
	s_mov_b32 m0, s53
	v_readfirstlane_b32 s53, v158
	s_barrier
; #define STAGE(P, BASE, LD, br, kt) do { const char* _g = (const char*)((BASE) + (size_t)(br) * (LD) + (size_t)(kt) * 64); \
;     for (int _i = 0; _i < 2; ++_i) { int _b = tidx * 16 + _i * 8192; int _r, _c; stage_rc(_b, _r, _c); \
;       __builtin_amdgcn_global_load_lds((const unsigned*)(_g + (unsigned)((_r * (LD) + _c) * 2)), (unsigned*)((char*)(P) + _b), 16, 0, 0); } } while (0)
; #define LDA(dst, b, h) for (int m = 0; m < 4; ++m) for (int k = 0; k < 2; ++k) \
;     dst[m][k] = *reinterpret_cast<const bf16x8*>((char*)SA(b, h) + lds_byte(wr * 64 + m * 16 + fr, k * 32 + fq * 8))
; #define LDB(dst, b, h) for (int n = 0; n < 2; ++n) for (int k = 0; k < 2; ++k) \
;     dst[n][k] = *reinterpret_cast<const bf16x8*>((char*)SB(b, h) + lds_byte(wc * 32 + n * 16 + fr, k * 32 + fq * 8))
; #define MMA(ai, bj, At_, Bt_) do { __builtin_amdgcn_s_setprio(1); \
;     for (int k = 0; k < 2; ++k) for (int m = 0; m < 4; ++m) for (int n = 0; n < 2; ++n) \
;       acc[ai][bj][m][n] = __builtin_amdgcn_mfma_f32_16x16x32_bf16(At_[m][k], Bt_[n][k], acc[ai][bj][m][n], 0, 0, 0); \
;     __builtin_amdgcn_s_setprio(0); } while (0)
; #define WAIT_V(n) asm volatile("s_waitcnt vmcnt(" #n ")" ::: "memory")
; #define WAIT_L(n) asm volatile("s_waitcnt lgkmcnt(" #n ")" ::: "memory")
; #define BAR __builtin_amdgcn_s_barrier()
; #define SCHED __builtin_amdgcn_sched_barrier(0)
; template <int EPI, int lda, int ldb, int N, int K>
; __device__ __forceinline__ void gemm_phase(const u16* __restrict__ A, const u16* __restrict__ Bt, const GemmEpi ep, int wv) {
;     ...
;       LDA(At, 1, 1); STAGE(SA(1, 0), Ab, lda, brow, t + 3);
;       BAR; WAIT_L(0); MMA(1, 0, At, B0); BAR; SCHED;
;       STAGE(SB(1, 1), Bt, ldb, bcol + HALF, t + 3);
;       WAIT_V(6); BAR; MMA(1, 1, At, B1); BAR;
;     }
;     { LDB(B0, 0, 0); LDA(At, 0, 0); STAGE(SA(1, 1), Ab, lda, brow + HALF, nt - 1);
;       BAR; WAIT_L(0); MMA(0, 0, At, B0); BAR;
;       LDB(B1, 0, 1); BAR; WAIT_L(0); MMA(0, 1, At, B1); BAR;
	ds_read_b128 v[188:191], v152 offset:49152
	ds_read_b128 v[192:195], v152 offset:50176
	ds_read_b128 v[196:199], v151 offset:49152
	ds_read_b128 v[200:203], v151 offset:50176
	ds_read_b128 v[204:207], v150 offset:49152
	ds_read_b128 v[208:211], v150 offset:50176
	ds_read_b128 v[212:215], v149 offset:49152
	ds_read_b128 v[216:219], v149 offset:50176
	global_load_lds_dwordx4 v[236:237], off
	v_lshl_add_u64 v[236:237], v[238:239], 0, s[42:43]
	s_mov_b32 m0, s53
	s_nop 0
	global_load_lds_dwordx4 v[236:237], off
	s_barrier
	s_waitcnt lgkmcnt(0)
	s_waitcnt lgkmcnt(0)
	v_mfma_f32_16x16x32_bf16 v[60:63], v[172:175], v[188:191], v[60:63]
	v_mfma_f32_16x16x32_bf16 v[56:59], v[180:183], v[188:191], v[56:59]
	v_mfma_f32_16x16x32_bf16 v[52:55], v[172:175], v[196:199], v[52:55]
	v_mfma_f32_16x16x32_bf16 v[48:51], v[180:183], v[196:199], v[48:51]
	v_mfma_f32_16x16x32_bf16 v[44:47], v[172:175], v[204:207], v[44:47]
	v_mfma_f32_16x16x32_bf16 v[40:43], v[180:183], v[204:207], v[40:43]
	v_mfma_f32_16x16x32_bf16 v[36:39], v[172:175], v[212:215], v[36:39]
	v_mfma_f32_16x16x32_bf16 v[32:35], v[180:183], v[212:215], v[32:35]
	v_mfma_f32_16x16x32_bf16 v[60:63], v[176:179], v[192:195], v[60:63]
	v_mfma_f32_16x16x32_bf16 v[56:59], v[184:187], v[192:195], v[56:59]
	v_mfma_f32_16x16x32_bf16 v[52:55], v[176:179], v[200:203], v[52:55]
	v_mfma_f32_16x16x32_bf16 v[48:51], v[184:187], v[200:203], v[48:51]
	v_mfma_f32_16x16x32_bf16 v[44:47], v[176:179], v[208:211], v[44:47]
	v_mfma_f32_16x16x32_bf16 v[40:43], v[184:187], v[208:211], v[40:43]
	v_mfma_f32_16x16x32_bf16 v[36:39], v[176:179], v[216:219], v[36:39]
	v_mfma_f32_16x16x32_bf16 v[32:35], v[184:187], v[216:219], v[32:35]
	s_barrier
	v_readfirstlane_b32 s53, v159
	v_add_u32_e32 v171, 0x2000, v159
	v_lshl_add_u64 v[172:173], v[240:241], 0, s[44:45]
	s_mov_b32 m0, s53
	v_readfirstlane_b32 s53, v171
	global_load_lds_dwordx4 v[172:173], off
	v_lshl_add_u64 v[172:173], v[242:243], 0, s[44:45]
	s_mov_b32 m0, s53
	s_nop 0
	global_load_lds_dwordx4 v[172:173], off
	s_waitcnt vmcnt(8)
	s_barrier
	v_mfma_f32_16x16x32_bf16 v[28:31], v[220:223], v[188:191], v[28:31]
	v_mfma_f32_16x16x32_bf16 v[24:27], v[228:231], v[188:191], v[24:27]
	v_mfma_f32_16x16x32_bf16 v[20:23], v[220:223], v[196:199], v[20:23]
	v_mfma_f32_16x16x32_bf16 v[16:19], v[228:231], v[196:199], v[16:19]
	v_mfma_f32_16x16x32_bf16 v[12:15], v[220:223], v[204:207], v[12:15]
	v_mfma_f32_16x16x32_bf16 v[8:11], v[228:231], v[204:207], v[8:11]
	v_mfma_f32_16x16x32_bf16 v[4:7], v[220:223], v[212:215], v[4:7]
	v_mfma_f32_16x16x32_bf16 v[0:3], v[228:231], v[212:215], v[0:3]
	v_mfma_f32_16x16x32_bf16 v[28:31], v[224:227], v[192:195], v[28:31]
	v_mfma_f32_16x16x32_bf16 v[24:27], v[232:235], v[192:195], v[24:27]
	v_mfma_f32_16x16x32_bf16 v[20:23], v[224:227], v[200:203], v[20:23]
	v_mfma_f32_16x16x32_bf16 v[16:19], v[232:235], v[200:203], v[16:19]
	v_mfma_f32_16x16x32_bf16 v[12:15], v[224:227], v[208:211], v[12:15]
	v_mfma_f32_16x16x32_bf16 v[8:11], v[232:235], v[208:211], v[8:11]
	v_mfma_f32_16x16x32_bf16 v[4:7], v[224:227], v[216:219], v[4:7]
	v_mfma_f32_16x16x32_bf16 v[0:3], v[232:235], v[216:219], v[0:3]
	s_add_i32 s52, s52, 2
	s_add_u32 s50, s50, 0x100
	s_addc_u32 s51, s51, 0
	s_cmp_gt_u32 s52, 27
	s_barrier
	s_cbranch_scc0 .LBB0_770
	s_add_i32 s50, s48, 0x80
	s_mul_hi_i32 s51, s50, 0x1080
	s_mulk_i32 s50, 0x1080
	s_add_u32 s50, s61, s50
	s_addc_u32 s51, s62, s51
	v_lshl_add_u64 v[158:159], s[50:51], 0, v[128:129]
	v_readfirstlane_b32 s52, v169
	v_lshl_add_u64 v[158:159], v[158:159], 0, s[46:47]
	s_mov_b32 m0, s52
	ds_read_b128 v[134:137], v161
	ds_read_b128 v[138:141], v161 offset:1024
	ds_read_b128 v[172:175], v161 offset:2048
	ds_read_b128 v[176:179], v161 offset:3072
	ds_read_b128 v[180:183], v152
	ds_read_b128 v[184:187], v152 offset:1024
	ds_read_b128 v[188:191], v151
	ds_read_b128 v[192:195], v151 offset:1024
	ds_read_b128 v[196:199], v150
	ds_read_b128 v[200:203], v150 offset:1024
	ds_read_b128 v[204:207], v149
	ds_read_b128 v[208:211], v149 offset:1024
	global_load_lds_dwordx4 v[158:159], off
	v_lshl_add_u64 v[158:159], s[50:51], 0, v[132:133]
	v_readfirstlane_b32 s50, v170
	v_lshl_add_u64 v[158:159], v[158:159], 0, s[46:47]
	s_mov_b32 m0, s50
	s_nop 0
	global_load_lds_dwordx4 v[158:159], off
	s_barrier
	s_waitcnt lgkmcnt(0)
	s_waitcnt lgkmcnt(0)
	v_mfma_f32_16x16x32_bf16 v[124:127], v[134:137], v[180:183], v[124:127]
	v_mfma_f32_16x16x32_bf16 v[120:123], v[172:175], v[180:183], v[120:123]
	v_mfma_f32_16x16x32_bf16 v[116:119], v[134:137], v[188:191], v[116:119]
	v_mfma_f32_16x16x32_bf16 v[112:115], v[172:175], v[188:191], v[112:115]
	v_mfma_f32_16x16x32_bf16 v[108:111], v[134:137], v[196:199], v[108:111]
	v_mfma_f32_16x16x32_bf16 v[104:107], v[172:175], v[196:199], v[104:107]
	v_mfma_f32_16x16x32_bf16 v[100:103], v[134:137], v[204:207], v[100:103]
	v_mfma_f32_16x16x32_bf16 v[96:99], v[172:175], v[204:207], v[96:99]
	v_mfma_f32_16x16x32_bf16 v[124:127], v[138:141], v[184:187], v[124:127]
	v_mfma_f32_16x16x32_bf16 v[120:123], v[176:179], v[184:187], v[120:123]
	v_mfma_f32_16x16x32_bf16 v[116:119], v[138:141], v[192:195], v[116:119]
	v_mfma_f32_16x16x32_bf16 v[112:115], v[176:179], v[192:195], v[112:115]
	v_mfma_f32_16x16x32_bf16 v[108:111], v[138:141], v[200:203], v[108:111]
	v_mfma_f32_16x16x32_bf16 v[104:107], v[176:179], v[200:203], v[104:107]
	v_mfma_f32_16x16x32_bf16 v[100:103], v[138:141], v[208:211], v[100:103]
	v_mfma_f32_16x16x32_bf16 v[96:99], v[176:179], v[208:211], v[96:99]
	s_barrier
	ds_read_b128 v[212:215], v160
	ds_read_b128 v[216:219], v160 offset:1024
	ds_read_b128 v[220:223], v160 offset:2048
	ds_read_b128 v[158:161], v160 offset:3072
	s_waitcnt vmcnt(8)
	s_barrier
; #define LDA(dst, b, h) for (int m = 0; m < 4; ++m) for (int k = 0; k < 2; ++k) \
;     dst[m][k] = *reinterpret_cast<const bf16x8*>((char*)SA(b, h) + lds_byte(wr * 64 + m * 16 + fr, k * 32 + fq * 8))
; #define LDB(dst, b, h) for (int n = 0; n < 2; ++n) for (int k = 0; k < 2; ++k) \
;     dst[n][k] = *reinterpret_cast<const bf16x8*>((char*)SB(b, h) + lds_byte(wc * 32 + n * 16 + fr, k * 32 + fq * 8))
; #define MMA(ai, bj, At_, Bt_) do { __builtin_amdgcn_s_setprio(1); \
;     for (int k = 0; k < 2; ++k) for (int m = 0; m < 4; ++m) for (int n = 0; n < 2; ++n) \
;       acc[ai][bj][m][n] = __builtin_amdgcn_mfma_f32_16x16x32_bf16(At_[m][k], Bt_[n][k], acc[ai][bj][m][n], 0, 0, 0); \
;     __builtin_amdgcn_s_setprio(0); } while (0)
; #define WAIT_V(n) asm volatile("s_waitcnt vmcnt(" #n ")" ::: "memory")
; #define WAIT_L(n) asm volatile("s_waitcnt lgkmcnt(" #n ")" ::: "memory")
; #define BAR __builtin_amdgcn_s_barrier()
; template <int EPI, int lda, int ldb, int N, int K>
; __device__ __forceinline__ void gemm_phase(const u16* __restrict__ A, const u16* __restrict__ Bt, const GemmEpi ep, int wv) {
;     ...
;       LDB(B1, 0, 1); BAR; WAIT_L(0); MMA(0, 1, At, B1); BAR;
;       LDA(At, 0, 1); WAIT_V(4); BAR; WAIT_L(0); MMA(1, 0, At, B0); MMA(1, 1, At, B1); BAR; }
;     { LDB(B0, 1, 0); LDA(At, 1, 0); WAIT_V(2); BAR; WAIT_L(0); MMA(0, 0, At, B0); BAR;
	s_waitcnt lgkmcnt(0)
	s_waitcnt lgkmcnt(0)
	v_mfma_f32_16x16x32_bf16 v[92:95], v[212:215], v[180:183], v[92:95]
	v_mfma_f32_16x16x32_bf16 v[88:91], v[220:223], v[180:183], v[88:91]
	v_mfma_f32_16x16x32_bf16 v[76:79], v[212:215], v[196:199], v[76:79]
	v_mfma_f32_16x16x32_bf16 v[72:75], v[220:223], v[196:199], v[72:75]
	v_mfma_f32_16x16x32_bf16 v[84:87], v[212:215], v[188:191], v[84:87]
	v_mfma_f32_16x16x32_bf16 v[80:83], v[220:223], v[188:191], v[80:83]
	v_mfma_f32_16x16x32_bf16 v[68:71], v[212:215], v[204:207], v[68:71]
	v_mfma_f32_16x16x32_bf16 v[64:67], v[220:223], v[204:207], v[64:67]
	v_mfma_f32_16x16x32_bf16 v[92:95], v[216:219], v[184:187], v[92:95]
	v_mfma_f32_16x16x32_bf16 v[88:91], v[158:161], v[184:187], v[88:91]
	v_mfma_f32_16x16x32_bf16 v[76:79], v[216:219], v[200:203], v[76:79]
	v_mfma_f32_16x16x32_bf16 v[72:75], v[158:161], v[200:203], v[72:75]
	v_mfma_f32_16x16x32_bf16 v[180:183], v[216:219], v[192:195], v[84:87]
	v_mfma_f32_16x16x32_bf16 v[184:187], v[158:161], v[192:195], v[80:83]
	v_mfma_f32_16x16x32_bf16 v[188:191], v[216:219], v[208:211], v[68:71]
	v_mfma_f32_16x16x32_bf16 v[192:195], v[158:161], v[208:211], v[64:67]
	s_barrier
	s_nop 0
	ds_read_b128 v[64:67], v152 offset:16384
	ds_read_b128 v[68:71], v152 offset:17408
	ds_read_b128 v[80:83], v151 offset:16384
	ds_read_b128 v[84:87], v151 offset:17408
	ds_read_b128 v[196:199], v150 offset:16384
	ds_read_b128 v[200:203], v150 offset:17408
	ds_read_b128 v[204:207], v149 offset:16384
	ds_read_b128 v[208:211], v149 offset:17408
	s_waitcnt vmcnt(4)
	s_barrier
	s_waitcnt lgkmcnt(0)
	s_waitcnt lgkmcnt(0)
	v_mfma_f32_16x16x32_bf16 v[60:63], v[134:137], v[64:67], v[60:63]
	v_mfma_f32_16x16x32_bf16 v[56:59], v[172:175], v[64:67], v[56:59]
	v_mfma_f32_16x16x32_bf16 v[52:55], v[134:137], v[80:83], v[52:55]
	v_mfma_f32_16x16x32_bf16 v[48:51], v[172:175], v[80:83], v[48:51]
	v_mfma_f32_16x16x32_bf16 v[44:47], v[134:137], v[196:199], v[44:47]
	v_mfma_f32_16x16x32_bf16 v[40:43], v[172:175], v[196:199], v[40:43]
	v_mfma_f32_16x16x32_bf16 v[36:39], v[134:137], v[204:207], v[36:39]
	v_mfma_f32_16x16x32_bf16 v[32:35], v[172:175], v[204:207], v[32:35]
	v_mfma_f32_16x16x32_bf16 v[60:63], v[138:141], v[68:71], v[60:63]
	v_mfma_f32_16x16x32_bf16 v[56:59], v[176:179], v[68:71], v[56:59]
	v_mfma_f32_16x16x32_bf16 v[52:55], v[138:141], v[84:87], v[52:55]
	v_mfma_f32_16x16x32_bf16 v[48:51], v[176:179], v[84:87], v[48:51]
	v_mfma_f32_16x16x32_bf16 v[44:47], v[138:141], v[200:203], v[44:47]
	v_mfma_f32_16x16x32_bf16 v[40:43], v[176:179], v[200:203], v[40:43]
	v_mfma_f32_16x16x32_bf16 v[36:39], v[138:141], v[208:211], v[36:39]
	v_mfma_f32_16x16x32_bf16 v[32:35], v[176:179], v[208:211], v[32:35]
	v_mfma_f32_16x16x32_bf16 v[28:31], v[212:215], v[64:67], v[28:31]
	v_mfma_f32_16x16x32_bf16 v[24:27], v[220:223], v[64:67], v[24:27]
	v_mfma_f32_16x16x32_bf16 v[12:15], v[212:215], v[196:199], v[12:15]
	v_mfma_f32_16x16x32_bf16 v[8:11], v[220:223], v[196:199], v[8:11]
	v_mfma_f32_16x16x32_bf16 v[20:23], v[212:215], v[80:83], v[20:23]
	v_mfma_f32_16x16x32_bf16 v[16:19], v[220:223], v[80:83], v[16:19]
	v_mfma_f32_16x16x32_bf16 v[4:7], v[212:215], v[204:207], v[4:7]
	v_mfma_f32_16x16x32_bf16 v[0:3], v[220:223], v[204:207], v[0:3]
	v_mfma_f32_16x16x32_bf16 v[28:31], v[216:219], v[68:71], v[28:31]
	v_mfma_f32_16x16x32_bf16 v[24:27], v[158:161], v[68:71], v[24:27]
	v_mfma_f32_16x16x32_bf16 v[12:15], v[216:219], v[200:203], v[12:15]
	v_mfma_f32_16x16x32_bf16 v[8:11], v[158:161], v[200:203], v[8:11]
	v_mfma_f32_16x16x32_bf16 v[134:137], v[216:219], v[84:87], v[20:23]
	v_mfma_f32_16x16x32_bf16 v[138:141], v[158:161], v[84:87], v[16:19]
	v_mfma_f32_16x16x32_bf16 v[170:173], v[216:219], v[208:211], v[4:7]
	v_mfma_f32_16x16x32_bf16 v[158:161], v[158:161], v[208:211], v[0:3]
	s_barrier
	s_nop 0
	ds_read_b128 v[0:3], v156
	ds_read_b128 v[4:7], v156 offset:1024
	ds_read_b128 v[16:19], v156 offset:2048
	ds_read_b128 v[174:177], v156 offset:3072
	ds_read_b128 v[20:23], v152 offset:32768
	ds_read_b128 v[196:199], v152 offset:33792
	ds_read_b128 v[200:203], v151 offset:32768
	ds_read_b128 v[204:207], v151 offset:33792
	ds_read_b128 v[208:211], v150 offset:32768
	ds_read_b128 v[212:215], v150 offset:33792
	ds_read_b128 v[216:219], v149 offset:32768
	ds_read_b128 v[220:223], v149 offset:33792
	s_waitcnt vmcnt(2)
	s_barrier
; #define LDA(dst, b, h) for (int m = 0; m < 4; ++m) for (int k = 0; k < 2; ++k) \
;     dst[m][k] = *reinterpret_cast<const bf16x8*>((char*)SA(b, h) + lds_byte(wr * 64 + m * 16 + fr, k * 32 + fq * 8))
; #define LDB(dst, b, h) for (int n = 0; n < 2; ++n) for (int k = 0; k < 2; ++k) \
;     dst[n][k] = *reinterpret_cast<const bf16x8*>((char*)SB(b, h) + lds_byte(wc * 32 + n * 16 + fr, k * 32 + fq * 8))
; #define MMA(ai, bj, At_, Bt_) do { __builtin_amdgcn_s_setprio(1); \
;     for (int k = 0; k < 2; ++k) for (int m = 0; m < 4; ++m) for (int n = 0; n < 2; ++n) \
;       acc[ai][bj][m][n] = __builtin_amdgcn_mfma_f32_16x16x32_bf16(At_[m][k], Bt_[n][k], acc[ai][bj][m][n], 0, 0, 0); \
;     __builtin_amdgcn_s_setprio(0); } while (0)
; #define WAIT_V(n) asm volatile("s_waitcnt vmcnt(" #n ")" ::: "memory")
; #define WAIT_L(n) asm volatile("s_waitcnt lgkmcnt(" #n ")" ::: "memory")
; #define BAR __builtin_amdgcn_s_barrier()
; template <int EPI, int lda, int ldb, int N, int K>
; __device__ __forceinline__ void gemm_phase(const u16* __restrict__ A, const u16* __restrict__ Bt, const GemmEpi ep, int wv) {
;     ...
;     { LDB(B0, 1, 0); LDA(At, 1, 0); WAIT_V(2); BAR; WAIT_L(0); MMA(0, 0, At, B0); BAR;
;       LDB(B1, 1, 1); WAIT_V(0); BAR; WAIT_L(0); MMA(0, 1, At, B1); BAR;
;       LDA(At, 1, 1); BAR; WAIT_L(0); MMA(1, 0, At, B0); MMA(1, 1, At, B1); BAR; }
;     if (wr == 0) BAR;
	s_waitcnt lgkmcnt(0)
	s_waitcnt lgkmcnt(0)
	v_mfma_f32_16x16x32_bf16 v[64:67], v[0:3], v[20:23], v[124:127]
	v_mfma_f32_16x16x32_bf16 v[68:71], v[16:19], v[20:23], v[120:123]
	v_mfma_f32_16x16x32_bf16 v[80:83], v[0:3], v[200:203], v[116:119]
	v_mfma_f32_16x16x32_bf16 v[84:87], v[16:19], v[200:203], v[112:115]
	v_mfma_f32_16x16x32_bf16 v[108:111], v[0:3], v[208:211], v[108:111]
	v_mfma_f32_16x16x32_bf16 v[104:107], v[16:19], v[208:211], v[104:107]
	v_mfma_f32_16x16x32_bf16 v[120:123], v[0:3], v[216:219], v[100:103]
	v_mfma_f32_16x16x32_bf16 v[124:127], v[16:19], v[216:219], v[96:99]
	v_mfma_f32_16x16x32_bf16 v[116:119], v[4:7], v[196:199], v[64:67]
	v_mfma_f32_16x16x32_bf16 v[112:115], v[174:177], v[196:199], v[68:71]
	v_mfma_f32_16x16x32_bf16 v[100:103], v[4:7], v[204:207], v[80:83]
	v_mfma_f32_16x16x32_bf16 v[96:99], v[174:177], v[204:207], v[84:87]
	v_mfma_f32_16x16x32_bf16 v[84:87], v[4:7], v[212:215], v[108:111]
	v_mfma_f32_16x16x32_bf16 v[80:83], v[174:177], v[212:215], v[104:107]
	v_mfma_f32_16x16x32_bf16 v[68:71], v[4:7], v[220:223], v[120:123]
	v_mfma_f32_16x16x32_bf16 v[64:67], v[174:177], v[220:223], v[124:127]
	s_barrier
	ds_read_b128 v[224:227], v154
	ds_read_b128 v[228:231], v154 offset:1024
	ds_read_b128 v[232:235], v154 offset:2048
	ds_read_b128 v[154:157], v154 offset:3072
	s_waitcnt vmcnt(0)
	s_barrier
	s_waitcnt lgkmcnt(0)
	s_waitcnt lgkmcnt(0)
	v_mfma_f32_16x16x32_bf16 v[92:95], v[224:227], v[20:23], v[92:95]
	v_mfma_f32_16x16x32_bf16 v[20:23], v[232:235], v[20:23], v[88:91]
	v_mfma_f32_16x16x32_bf16 v[88:91], v[224:227], v[200:203], v[180:183]
	v_mfma_f32_16x16x32_bf16 v[104:107], v[232:235], v[200:203], v[184:187]
	v_mfma_f32_16x16x32_bf16 v[76:79], v[224:227], v[208:211], v[76:79]
	v_mfma_f32_16x16x32_bf16 v[72:75], v[232:235], v[208:211], v[72:75]
	v_mfma_f32_16x16x32_bf16 v[178:181], v[224:227], v[216:219], v[188:191]
	v_mfma_f32_16x16x32_bf16 v[182:185], v[232:235], v[216:219], v[192:195]
	v_mfma_f32_16x16x32_bf16 v[124:127], v[228:231], v[196:199], v[92:95]
	v_mfma_f32_16x16x32_bf16 v[120:123], v[154:157], v[196:199], v[20:23]
	v_mfma_f32_16x16x32_bf16 v[108:111], v[228:231], v[204:207], v[88:91]
	v_mfma_f32_16x16x32_bf16 v[104:107], v[154:157], v[204:207], v[104:107]
	v_mfma_f32_16x16x32_bf16 v[92:95], v[228:231], v[212:215], v[76:79]
	v_mfma_f32_16x16x32_bf16 v[88:91], v[154:157], v[212:215], v[72:75]
	v_mfma_f32_16x16x32_bf16 v[76:79], v[228:231], v[220:223], v[178:181]
	v_mfma_f32_16x16x32_bf16 v[72:75], v[154:157], v[220:223], v[182:185]
	s_barrier
	ds_read_b128 v[178:181], v152 offset:49152
	ds_read_b128 v[182:185], v152 offset:50176
	ds_read_b128 v[186:189], v151 offset:49152
	ds_read_b128 v[190:193], v151 offset:50176
	ds_read_b128 v[194:197], v150 offset:49152
	ds_read_b128 v[150:153], v150 offset:50176
	ds_read_b128 v[198:201], v149 offset:49152
	ds_read_b128 v[202:205], v149 offset:50176
	s_barrier
	s_waitcnt lgkmcnt(0)
	s_waitcnt lgkmcnt(0)
	v_mfma_f32_16x16x32_bf16 v[20:23], v[0:3], v[178:181], v[60:63]
	v_mfma_f32_16x16x32_bf16 v[56:59], v[16:19], v[178:181], v[56:59]
	v_mfma_f32_16x16x32_bf16 v[60:63], v[0:3], v[186:189], v[52:55]
	v_mfma_f32_16x16x32_bf16 v[206:209], v[16:19], v[186:189], v[48:51]
	v_mfma_f32_16x16x32_bf16 v[44:47], v[0:3], v[194:197], v[44:47]
	v_mfma_f32_16x16x32_bf16 v[40:43], v[16:19], v[194:197], v[40:43]
	v_mfma_f32_16x16x32_bf16 v[0:3], v[0:3], v[198:201], v[36:39]
	v_mfma_f32_16x16x32_bf16 v[210:213], v[16:19], v[198:201], v[32:35]
	v_mfma_f32_16x16x32_bf16 v[52:55], v[4:7], v[182:185], v[20:23]
	v_mfma_f32_16x16x32_bf16 v[48:51], v[174:177], v[182:185], v[56:59]
	v_mfma_f32_16x16x32_bf16 v[36:39], v[4:7], v[190:193], v[60:63]
	v_mfma_f32_16x16x32_bf16 v[32:35], v[174:177], v[190:193], v[206:209]
	v_mfma_f32_16x16x32_bf16 v[20:23], v[4:7], v[150:153], v[44:47]
	v_mfma_f32_16x16x32_bf16 v[16:19], v[174:177], v[150:153], v[40:43]
	v_mfma_f32_16x16x32_bf16 v[4:7], v[4:7], v[202:205], v[0:3]
	v_mfma_f32_16x16x32_bf16 v[0:3], v[174:177], v[202:205], v[210:213]
	v_mfma_f32_16x16x32_bf16 v[28:31], v[224:227], v[178:181], v[28:31]
	v_mfma_f32_16x16x32_bf16 v[24:27], v[232:235], v[178:181], v[24:27]
	v_mfma_f32_16x16x32_bf16 v[40:43], v[224:227], v[186:189], v[134:137]
	v_mfma_f32_16x16x32_bf16 v[134:137], v[232:235], v[186:189], v[138:141]
	v_mfma_f32_16x16x32_bf16 v[12:15], v[224:227], v[194:197], v[12:15]
	v_mfma_f32_16x16x32_bf16 v[8:11], v[232:235], v[194:197], v[8:11]
	v_mfma_f32_16x16x32_bf16 v[138:141], v[224:227], v[198:201], v[170:173]
	v_mfma_f32_16x16x32_bf16 v[158:161], v[232:235], v[198:201], v[158:161]
	v_mfma_f32_16x16x32_bf16 v[60:63], v[228:231], v[182:185], v[28:31]
	v_mfma_f32_16x16x32_bf16 v[56:59], v[154:157], v[182:185], v[24:27]
	v_mfma_f32_16x16x32_bf16 v[44:47], v[228:231], v[190:193], v[40:43]
	v_mfma_f32_16x16x32_bf16 v[40:43], v[154:157], v[190:193], v[134:137]
	v_mfma_f32_16x16x32_bf16 v[28:31], v[228:231], v[150:153], v[12:15]
	v_mfma_f32_16x16x32_bf16 v[24:27], v[154:157], v[150:153], v[8:11]
	v_mfma_f32_16x16x32_bf16 v[12:15], v[228:231], v[202:205], v[138:141]
	v_mfma_f32_16x16x32_bf16 v[8:11], v[154:157], v[202:205], v[158:161]
	v_cmp_gt_u32_e32 vcc, s66, v130
	s_barrier
	s_and_saveexec_b64 s[50:51], vcc
	s_cbranch_execz .LBB0_773
	s_barrier

; #define STAGE(P, BASE, LD, br, kt) do { const char* _g = (const char*)((BASE) + (size_t)(br) * (LD) + (size_t)(kt) * 64); \
;     for (int _i = 0; _i < 2; ++_i) { int _b = tidx * 16 + _i * 8192; int _r, _c; stage_rc(_b, _r, _c); \
;       __builtin_amdgcn_global_load_lds((const unsigned*)(_g + (unsigned)((_r * (LD) + _c) * 2)), (unsigned*)((char*)(P) + _b), 16, 0, 0); } } while (0)
; #define LDA(dst, b, h) for (int m = 0; m < 4; ++m) for (int k = 0; k < 2; ++k) \
;     dst[m][k] = *reinterpret_cast<const bf16x8*>((char*)SA(b, h) + lds_byte(wr * 64 + m * 16 + fr, k * 32 + fq * 8))
; #define LDB(dst, b, h) for (int n = 0; n < 2; ++n) for (int k = 0; k < 2; ++k) \
;     dst[n][k] = *reinterpret_cast<const bf16x8*>((char*)SB(b, h) + lds_byte(wc * 32 + n * 16 + fr, k * 32 + fq * 8))
; #define MMA(ai, bj, At_, Bt_) do { __builtin_amdgcn_s_setprio(1); \
;     for (int k = 0; k < 2; ++k) for (int m = 0; m < 4; ++m) for (int n = 0; n < 2; ++n) \
;       acc[ai][bj][m][n] = __builtin_amdgcn_mfma_f32_16x16x32_bf16(At_[m][k], Bt_[n][k], acc[ai][bj][m][n], 0, 0, 0); \
;     __builtin_amdgcn_s_setprio(0); } while (0)
; #define WAIT_L(n) asm volatile("s_waitcnt lgkmcnt(" #n ")" ::: "memory")
; #define BAR __builtin_amdgcn_s_barrier()
; #define SCHED __builtin_amdgcn_sched_barrier(0)
; template <int EPI, int lda, int ldb, int N, int K>
; __device__ __forceinline__ void gemm_phase(const u16* __restrict__ A, const u16* __restrict__ Bt, const GemmEpi ep, int wv) {
;     ...
;       LDB(B0, 0, 0); SCHED; LDA(At, 0, 0); STAGE(SA(1, 1), Ab, lda, brow + HALF, t + 1);
;       WAIT_L(8); BAR; WAIT_L(0); MMA(0, 0, At, B0); BAR; SCHED;
;       LDB(B1, 0, 1); STAGE(SB(0, 0), Bt, ldb, bcol, t + 2);
;       BAR; WAIT_L(0); MMA(0, 1, At, B1); BAR;
;       LDA(At, 0, 1); STAGE(SA(0, 0), Ab, lda, brow, t + 2);
;       BAR; WAIT_L(0); MMA(1, 0, At, B0); BAR; SCHED;
.LBB0_838:
	ds_read_b128 v[168:171], v164
	ds_read_b128 v[174:177], v164 offset:1024
	ds_read_b128 v[178:181], v164 offset:2048
	ds_read_b128 v[182:185], v164 offset:3072
	v_add_u32_e32 v172, 0xc000, v147
	v_lshl_add_u64 v[238:239], v[136:137], 0, s[50:51]
	v_readfirstlane_b32 s73, v172
	v_add_u32_e32 v173, 0xe000, v147
	v_lshl_add_u64 v[166:167], v[238:239], 0, s[22:23]
	s_mov_b32 m0, s73
	v_lshl_add_u64 v[240:241], v[134:135], 0, s[50:51]
	v_readfirstlane_b32 s73, v173
	ds_read_b128 v[186:189], v155
	ds_read_b128 v[190:193], v155 offset:1024
	ds_read_b128 v[194:197], v154
	ds_read_b128 v[198:201], v154 offset:1024
	ds_read_b128 v[202:205], v153
	ds_read_b128 v[206:209], v153 offset:1024
	ds_read_b128 v[210:213], v152
	ds_read_b128 v[214:217], v152 offset:1024
	global_load_lds_dwordx4 v[166:167], off
	v_lshl_add_u64 v[166:167], v[240:241], 0, s[22:23]
	s_mov_b32 m0, s73
	s_nop 0
	global_load_lds_dwordx4 v[166:167], off
	s_waitcnt lgkmcnt(8)
	s_barrier
	s_waitcnt lgkmcnt(0)
	s_waitcnt lgkmcnt(0)
	v_mfma_f32_16x16x32_bf16 v[124:127], v[168:171], v[186:189], v[124:127]
	v_mfma_f32_16x16x32_bf16 v[120:123], v[178:181], v[186:189], v[120:123]
	v_mfma_f32_16x16x32_bf16 v[116:119], v[168:171], v[194:197], v[116:119]
	v_mfma_f32_16x16x32_bf16 v[112:115], v[178:181], v[194:197], v[112:115]
	v_mfma_f32_16x16x32_bf16 v[108:111], v[168:171], v[202:205], v[108:111]
	v_mfma_f32_16x16x32_bf16 v[104:107], v[178:181], v[202:205], v[104:107]
	v_mfma_f32_16x16x32_bf16 v[100:103], v[168:171], v[210:213], v[100:103]
	v_mfma_f32_16x16x32_bf16 v[96:99], v[178:181], v[210:213], v[96:99]
	v_mfma_f32_16x16x32_bf16 v[124:127], v[174:177], v[190:193], v[124:127]
	v_mfma_f32_16x16x32_bf16 v[120:123], v[182:185], v[190:193], v[120:123]
	v_mfma_f32_16x16x32_bf16 v[116:119], v[174:177], v[198:201], v[116:119]
	v_mfma_f32_16x16x32_bf16 v[112:115], v[182:185], v[198:201], v[112:115]
	v_mfma_f32_16x16x32_bf16 v[108:111], v[174:177], v[206:209], v[108:111]
	v_mfma_f32_16x16x32_bf16 v[104:107], v[182:185], v[206:209], v[104:107]
	v_mfma_f32_16x16x32_bf16 v[100:103], v[174:177], v[214:217], v[100:103]
	v_mfma_f32_16x16x32_bf16 v[96:99], v[182:185], v[214:217], v[96:99]
	s_barrier
	v_add_u32_e32 v165, s63, v156
	v_lshl_add_u64 v[242:243], v[144:145], 0, s[50:51]
	v_readfirstlane_b32 s73, v165
	v_lshl_add_u64 v[166:167], v[242:243], 0, s[24:25]
	s_mov_b32 m0, s73
	ds_read_b128 v[218:221], v163
	ds_read_b128 v[222:225], v163 offset:1024
	ds_read_b128 v[226:229], v163 offset:2048
	ds_read_b128 v[230:233], v163 offset:3072
	global_load_lds_dwordx4 v[166:167], off
	v_add_u32_e32 v166, 0x2000, v165
	v_lshl_add_u64 v[244:245], v[142:143], 0, s[50:51]
	v_readfirstlane_b32 s73, v166
	v_lshl_add_u64 v[234:235], v[244:245], 0, s[24:25]
	s_mov_b32 m0, s73
	s_nop 0
	global_load_lds_dwordx4 v[234:235], off
	s_waitcnt vmcnt(10)
	s_barrier
	s_waitcnt lgkmcnt(0)
	s_waitcnt lgkmcnt(0)
	v_mfma_f32_16x16x32_bf16 v[92:95], v[218:221], v[186:189], v[92:95]
	v_mfma_f32_16x16x32_bf16 v[88:91], v[226:229], v[186:189], v[88:91]
	v_mfma_f32_16x16x32_bf16 v[84:87], v[218:221], v[194:197], v[84:87]
	v_mfma_f32_16x16x32_bf16 v[80:83], v[226:229], v[194:197], v[80:83]
	v_mfma_f32_16x16x32_bf16 v[76:79], v[218:221], v[202:205], v[76:79]
	v_mfma_f32_16x16x32_bf16 v[72:75], v[226:229], v[202:205], v[72:75]
	v_mfma_f32_16x16x32_bf16 v[68:71], v[218:221], v[210:213], v[68:71]
	v_mfma_f32_16x16x32_bf16 v[64:67], v[226:229], v[210:213], v[64:67]
	v_mfma_f32_16x16x32_bf16 v[92:95], v[222:225], v[190:193], v[92:95]
	v_mfma_f32_16x16x32_bf16 v[88:91], v[230:233], v[190:193], v[88:91]
	v_mfma_f32_16x16x32_bf16 v[84:87], v[222:225], v[198:201], v[84:87]
	v_mfma_f32_16x16x32_bf16 v[80:83], v[230:233], v[198:201], v[80:83]
	v_mfma_f32_16x16x32_bf16 v[76:79], v[222:225], v[206:209], v[76:79]
	v_mfma_f32_16x16x32_bf16 v[72:75], v[230:233], v[206:209], v[72:75]
	v_mfma_f32_16x16x32_bf16 v[68:71], v[222:225], v[214:217], v[68:71]
	v_mfma_f32_16x16x32_bf16 v[64:67], v[230:233], v[214:217], v[64:67]
	v_readfirstlane_b32 s73, v147
	v_add_u32_e32 v167, 0x2000, v147
	v_lshl_add_u64 v[234:235], v[238:239], 0, s[26:27]
	s_mov_b32 m0, s73
	v_readfirstlane_b32 s73, v167
	s_barrier
	ds_read_b128 v[186:189], v155 offset:16384
	ds_read_b128 v[190:193], v155 offset:17408
	ds_read_b128 v[194:197], v154 offset:16384
	ds_read_b128 v[198:201], v154 offset:17408
	ds_read_b128 v[202:205], v153 offset:16384
	ds_read_b128 v[206:209], v153 offset:17408
	ds_read_b128 v[210:213], v152 offset:16384
	ds_read_b128 v[214:217], v152 offset:17408
	global_load_lds_dwordx4 v[234:235], off
	v_lshl_add_u64 v[234:235], v[240:241], 0, s[26:27]
	s_mov_b32 m0, s73
	s_nop 0
	global_load_lds_dwordx4 v[234:235], off
	s_barrier
	s_waitcnt lgkmcnt(0)
	s_waitcnt lgkmcnt(0)
	v_mfma_f32_16x16x32_bf16 v[60:63], v[168:171], v[186:189], v[60:63]
	v_mfma_f32_16x16x32_bf16 v[56:59], v[178:181], v[186:189], v[56:59]
	v_mfma_f32_16x16x32_bf16 v[52:55], v[168:171], v[194:197], v[52:55]
	v_mfma_f32_16x16x32_bf16 v[48:51], v[178:181], v[194:197], v[48:51]
	v_mfma_f32_16x16x32_bf16 v[44:47], v[168:171], v[202:205], v[44:47]
	v_mfma_f32_16x16x32_bf16 v[40:43], v[178:181], v[202:205], v[40:43]
	v_mfma_f32_16x16x32_bf16 v[36:39], v[168:171], v[210:213], v[36:39]
	v_mfma_f32_16x16x32_bf16 v[32:35], v[178:181], v[210:213], v[32:35]
	v_mfma_f32_16x16x32_bf16 v[60:63], v[174:177], v[190:193], v[60:63]
	v_mfma_f32_16x16x32_bf16 v[56:59], v[182:185], v[190:193], v[56:59]
	v_mfma_f32_16x16x32_bf16 v[52:55], v[174:177], v[198:201], v[52:55]
	v_mfma_f32_16x16x32_bf16 v[48:51], v[182:185], v[198:201], v[48:51]
	v_mfma_f32_16x16x32_bf16 v[44:47], v[174:177], v[206:209], v[44:47]
	v_mfma_f32_16x16x32_bf16 v[40:43], v[182:185], v[206:209], v[40:43]
	v_mfma_f32_16x16x32_bf16 v[36:39], v[174:177], v[214:217], v[36:39]
	v_mfma_f32_16x16x32_bf16 v[32:35], v[182:185], v[214:217], v[32:35]
	s_barrier
; #define STAGE(P, BASE, LD, br, kt) do { const char* _g = (const char*)((BASE) + (size_t)(br) * (LD) + (size_t)(kt) * 64); \
;     for (int _i = 0; _i < 2; ++_i) { int _b = tidx * 16 + _i * 8192; int _r, _c; stage_rc(_b, _r, _c); \
;       __builtin_amdgcn_global_load_lds((const unsigned*)(_g + (unsigned)((_r * (LD) + _c) * 2)), (unsigned*)((char*)(P) + _b), 16, 0, 0); } } while (0)
; #define LDA(dst, b, h) for (int m = 0; m < 4; ++m) for (int k = 0; k < 2; ++k) \
;     dst[m][k] = *reinterpret_cast<const bf16x8*>((char*)SA(b, h) + lds_byte(wr * 64 + m * 16 + fr, k * 32 + fq * 8))
; #define LDB(dst, b, h) for (int n = 0; n < 2; ++n) for (int k = 0; k < 2; ++k) \
;     dst[n][k] = *reinterpret_cast<const bf16x8*>((char*)SB(b, h) + lds_byte(wc * 32 + n * 16 + fr, k * 32 + fq * 8))
; #define MMA(ai, bj, At_, Bt_) do { __builtin_amdgcn_s_setprio(1); \
;     for (int k = 0; k < 2; ++k) for (int m = 0; m < 4; ++m) for (int n = 0; n < 2; ++n) \
;       acc[ai][bj][m][n] = __builtin_amdgcn_mfma_f32_16x16x32_bf16(At_[m][k], Bt_[n][k], acc[ai][bj][m][n], 0, 0, 0); \
;     __builtin_amdgcn_s_setprio(0); } while (0)
; #define WAIT_V(n) asm volatile("s_waitcnt vmcnt(" #n ")" ::: "memory")
; #define WAIT_L(n) asm volatile("s_waitcnt lgkmcnt(" #n ")" ::: "memory")
; #define BAR __builtin_amdgcn_s_barrier()
; #define SCHED __builtin_amdgcn_sched_barrier(0)
; template <int EPI, int lda, int ldb, int N, int K>
; __device__ __forceinline__ void gemm_phase(const u16* __restrict__ A, const u16* __restrict__ Bt, const GemmEpi ep, int wv) {
;     ...
;       STAGE(SB(0, 1), Bt, ldb, bcol + HALF, t + 2);
;       WAIT_V(6); BAR; MMA(1, 1, At, B1); BAR;
;       LDB(B0, 1, 0); SCHED; LDA(At, 1, 0); STAGE(SA(0, 1), Ab, lda, brow + HALF, t + 2);
;       WAIT_L(8); BAR; WAIT_L(0); MMA(0, 0, At, B0); BAR; SCHED;
;       LDB(B1, 1, 1); STAGE(SB(1, 0), Bt, ldb, bcol, t + 3);
;       BAR; WAIT_L(0); MMA(0, 1, At, B1); BAR;
	v_add_u32_e32 v168, s64, v156
	v_lshl_add_u64 v[246:247], v[140:141], 0, s[50:51]
	v_readfirstlane_b32 s73, v168
	v_add_u32_e32 v169, 0x2000, v168
	v_lshl_add_u64 v[170:171], v[246:247], 0, s[40:41]
	s_mov_b32 m0, s73
	v_lshl_add_u64 v[248:249], v[138:139], 0, s[50:51]
	v_readfirstlane_b32 s73, v169
	global_load_lds_dwordx4 v[170:171], off
	v_lshl_add_u64 v[170:171], v[248:249], 0, s[40:41]
	s_mov_b32 m0, s73
	s_nop 0
	global_load_lds_dwordx4 v[170:171], off
	s_waitcnt vmcnt(8)
	s_barrier
	v_mfma_f32_16x16x32_bf16 v[28:31], v[218:221], v[186:189], v[28:31]
	v_mfma_f32_16x16x32_bf16 v[24:27], v[226:229], v[186:189], v[24:27]
	v_mfma_f32_16x16x32_bf16 v[20:23], v[218:221], v[194:197], v[20:23]
	v_mfma_f32_16x16x32_bf16 v[16:19], v[226:229], v[194:197], v[16:19]
	v_mfma_f32_16x16x32_bf16 v[12:15], v[218:221], v[202:205], v[12:15]
	v_mfma_f32_16x16x32_bf16 v[8:11], v[226:229], v[202:205], v[8:11]
	v_mfma_f32_16x16x32_bf16 v[4:7], v[218:221], v[210:213], v[4:7]
	v_mfma_f32_16x16x32_bf16 v[0:3], v[226:229], v[210:213], v[0:3]
	v_mfma_f32_16x16x32_bf16 v[28:31], v[222:225], v[190:193], v[28:31]
	v_mfma_f32_16x16x32_bf16 v[24:27], v[230:233], v[190:193], v[24:27]
	v_mfma_f32_16x16x32_bf16 v[20:23], v[222:225], v[198:201], v[20:23]
	v_mfma_f32_16x16x32_bf16 v[16:19], v[230:233], v[198:201], v[16:19]
	v_mfma_f32_16x16x32_bf16 v[12:15], v[222:225], v[206:209], v[12:15]
	v_mfma_f32_16x16x32_bf16 v[8:11], v[230:233], v[206:209], v[8:11]
	v_mfma_f32_16x16x32_bf16 v[4:7], v[222:225], v[214:217], v[4:7]
	v_mfma_f32_16x16x32_bf16 v[0:3], v[230:233], v[214:217], v[0:3]
	s_barrier
	ds_read_b128 v[174:177], v159
	ds_read_b128 v[178:181], v159 offset:1024
	ds_read_b128 v[182:185], v159 offset:2048
	ds_read_b128 v[186:189], v159 offset:3072
	v_add_u32_e32 v170, 0x4000, v147
	v_add_u32_e32 v171, 0x6000, v147
	v_readfirstlane_b32 s73, v170
	v_lshl_add_u64 v[222:223], v[238:239], 0, s[42:43]
	s_mov_b32 m0, s73
	v_readfirstlane_b32 s73, v171
	ds_read_b128 v[190:193], v155 offset:32768
	ds_read_b128 v[194:197], v155 offset:33792
	ds_read_b128 v[198:201], v154 offset:32768
	ds_read_b128 v[202:205], v154 offset:33792
	ds_read_b128 v[206:209], v153 offset:32768
	ds_read_b128 v[210:213], v153 offset:33792
	ds_read_b128 v[214:217], v152 offset:32768
	ds_read_b128 v[218:221], v152 offset:33792
	global_load_lds_dwordx4 v[222:223], off
	v_lshl_add_u64 v[222:223], v[240:241], 0, s[42:43]
	s_mov_b32 m0, s73
	s_nop 0
	global_load_lds_dwordx4 v[222:223], off
	s_waitcnt lgkmcnt(8)
	s_barrier
	s_waitcnt lgkmcnt(0)
	s_waitcnt lgkmcnt(0)
	v_mfma_f32_16x16x32_bf16 v[124:127], v[174:177], v[190:193], v[124:127]
	v_mfma_f32_16x16x32_bf16 v[120:123], v[182:185], v[190:193], v[120:123]
	v_mfma_f32_16x16x32_bf16 v[116:119], v[174:177], v[198:201], v[116:119]
	v_mfma_f32_16x16x32_bf16 v[112:115], v[182:185], v[198:201], v[112:115]
	v_mfma_f32_16x16x32_bf16 v[108:111], v[174:177], v[206:209], v[108:111]
	v_mfma_f32_16x16x32_bf16 v[104:107], v[182:185], v[206:209], v[104:107]
	v_mfma_f32_16x16x32_bf16 v[100:103], v[174:177], v[214:217], v[100:103]
	v_mfma_f32_16x16x32_bf16 v[96:99], v[182:185], v[214:217], v[96:99]
	v_mfma_f32_16x16x32_bf16 v[124:127], v[178:181], v[194:197], v[124:127]
	v_mfma_f32_16x16x32_bf16 v[120:123], v[186:189], v[194:197], v[120:123]
	v_mfma_f32_16x16x32_bf16 v[116:119], v[178:181], v[202:205], v[116:119]
	v_mfma_f32_16x16x32_bf16 v[112:115], v[186:189], v[202:205], v[112:115]
	v_mfma_f32_16x16x32_bf16 v[108:111], v[178:181], v[210:213], v[108:111]
	v_mfma_f32_16x16x32_bf16 v[104:107], v[186:189], v[210:213], v[104:107]
	v_mfma_f32_16x16x32_bf16 v[100:103], v[178:181], v[218:221], v[100:103]
	v_mfma_f32_16x16x32_bf16 v[96:99], v[186:189], v[218:221], v[96:99]
	s_barrier
	v_readfirstlane_b32 s73, v158
	v_lshl_add_u64 v[242:243], v[242:243], 0, s[44:45]
	s_mov_b32 m0, s73
	ds_read_b128 v[222:225], v157
	ds_read_b128 v[226:229], v157 offset:1024
	ds_read_b128 v[230:233], v157 offset:2048
	ds_read_b128 v[234:237], v157 offset:3072
	global_load_lds_dwordx4 v[242:243], off
	v_lshl_add_u64 v[242:243], v[244:245], 0, s[44:45]
	v_add_u32_e32 v244, 0x2000, v158
	s_nop 0
	v_readfirstlane_b32 s73, v244
	s_mov_b32 m0, s73
	s_nop 0
	global_load_lds_dwordx4 v[242:243], off
	s_waitcnt vmcnt(10)
	s_barrier
	s_waitcnt lgkmcnt(0)
	s_waitcnt lgkmcnt(0)
	v_mfma_f32_16x16x32_bf16 v[92:95], v[222:225], v[190:193], v[92:95]
	v_mfma_f32_16x16x32_bf16 v[88:91], v[230:233], v[190:193], v[88:91]
	v_mfma_f32_16x16x32_bf16 v[84:87], v[222:225], v[198:201], v[84:87]
	v_mfma_f32_16x16x32_bf16 v[80:83], v[230:233], v[198:201], v[80:83]
	v_mfma_f32_16x16x32_bf16 v[76:79], v[222:225], v[206:209], v[76:79]
	v_mfma_f32_16x16x32_bf16 v[72:75], v[230:233], v[206:209], v[72:75]
	v_mfma_f32_16x16x32_bf16 v[68:71], v[222:225], v[214:217], v[68:71]
	v_mfma_f32_16x16x32_bf16 v[64:67], v[230:233], v[214:217], v[64:67]
	v_mfma_f32_16x16x32_bf16 v[92:95], v[226:229], v[194:197], v[92:95]
	v_mfma_f32_16x16x32_bf16 v[88:91], v[234:237], v[194:197], v[88:91]
	v_mfma_f32_16x16x32_bf16 v[84:87], v[226:229], v[202:205], v[84:87]
	v_mfma_f32_16x16x32_bf16 v[80:83], v[234:237], v[202:205], v[80:83]
	v_mfma_f32_16x16x32_bf16 v[76:79], v[226:229], v[210:213], v[76:79]
	v_mfma_f32_16x16x32_bf16 v[72:75], v[234:237], v[210:213], v[72:75]
	v_mfma_f32_16x16x32_bf16 v[68:71], v[226:229], v[218:221], v[68:71]
	v_mfma_f32_16x16x32_bf16 v[64:67], v[234:237], v[218:221], v[64:67]
	v_readfirstlane_b32 s73, v160
	v_lshl_add_u64 v[238:239], v[238:239], 0, s[46:47]
	s_mov_b32 m0, s73
	v_readfirstlane_b32 s73, v161
	s_barrier
; #define STAGE(P, BASE, LD, br, kt) do { const char* _g = (const char*)((BASE) + (size_t)(br) * (LD) + (size_t)(kt) * 64); \
;     for (int _i = 0; _i < 2; ++_i) { int _b = tidx * 16 + _i * 8192; int _r, _c; stage_rc(_b, _r, _c); \
;       __builtin_amdgcn_global_load_lds((const unsigned*)(_g + (unsigned)((_r * (LD) + _c) * 2)), (unsigned*)((char*)(P) + _b), 16, 0, 0); } } while (0)
; #define LDA(dst, b, h) for (int m = 0; m < 4; ++m) for (int k = 0; k < 2; ++k) \
;     dst[m][k] = *reinterpret_cast<const bf16x8*>((char*)SA(b, h) + lds_byte(wr * 64 + m * 16 + fr, k * 32 + fq * 8))
; #define LDB(dst, b, h) for (int n = 0; n < 2; ++n) for (int k = 0; k < 2; ++k) \
;     dst[n][k] = *reinterpret_cast<const bf16x8*>((char*)SB(b, h) + lds_byte(wc * 32 + n * 16 + fr, k * 32 + fq * 8))
; #define MMA(ai, bj, At_, Bt_) do { __builtin_amdgcn_s_setprio(1); \
;     for (int k = 0; k < 2; ++k) for (int m = 0; m < 4; ++m) for (int n = 0; n < 2; ++n) \
;       acc[ai][bj][m][n] = __builtin_amdgcn_mfma_f32_16x16x32_bf16(At_[m][k], Bt_[n][k], acc[ai][bj][m][n], 0, 0, 0); \
;     __builtin_amdgcn_s_setprio(0); } while (0)
; #define WAIT_V(n) asm volatile("s_waitcnt vmcnt(" #n ")" ::: "memory")
; #define WAIT_L(n) asm volatile("s_waitcnt lgkmcnt(" #n ")" ::: "memory")
; #define BAR __builtin_amdgcn_s_barrier()
; #define SCHED __builtin_amdgcn_sched_barrier(0)
; template <int EPI, int lda, int ldb, int N, int K>
; __device__ __forceinline__ void gemm_phase(const u16* __restrict__ A, const u16* __restrict__ Bt, const GemmEpi ep, int wv) {
;     ...
;       LDA(At, 1, 1); STAGE(SA(1, 0), Ab, lda, brow, t + 3);
;       BAR; WAIT_L(0); MMA(1, 0, At, B0); BAR; SCHED;
;       STAGE(SB(1, 1), Bt, ldb, bcol + HALF, t + 3);
;       WAIT_V(6); BAR; MMA(1, 1, At, B1); BAR;
;     }
;     { LDB(B0, 0, 0); LDA(At, 0, 0); STAGE(SA(1, 1), Ab, lda, brow + HALF, nt - 1);
;       BAR; WAIT_L(0); MMA(0, 0, At, B0); BAR;
;       LDB(B1, 0, 1); BAR; WAIT_L(0); MMA(0, 1, At, B1); BAR;
	ds_read_b128 v[190:193], v155 offset:49152
	ds_read_b128 v[194:197], v155 offset:50176
	ds_read_b128 v[198:201], v154 offset:49152
	ds_read_b128 v[202:205], v154 offset:50176
	ds_read_b128 v[206:209], v153 offset:49152
	ds_read_b128 v[210:213], v153 offset:50176
	ds_read_b128 v[214:217], v152 offset:49152
	ds_read_b128 v[218:221], v152 offset:50176
	global_load_lds_dwordx4 v[238:239], off
	v_lshl_add_u64 v[238:239], v[240:241], 0, s[46:47]
	s_mov_b32 m0, s73
	s_nop 0
	global_load_lds_dwordx4 v[238:239], off
	s_barrier
	s_waitcnt lgkmcnt(0)
	s_waitcnt lgkmcnt(0)
	v_mfma_f32_16x16x32_bf16 v[60:63], v[174:177], v[190:193], v[60:63]
	v_mfma_f32_16x16x32_bf16 v[56:59], v[182:185], v[190:193], v[56:59]
	v_mfma_f32_16x16x32_bf16 v[52:55], v[174:177], v[198:201], v[52:55]
	v_mfma_f32_16x16x32_bf16 v[48:51], v[182:185], v[198:201], v[48:51]
	v_mfma_f32_16x16x32_bf16 v[44:47], v[174:177], v[206:209], v[44:47]
	v_mfma_f32_16x16x32_bf16 v[40:43], v[182:185], v[206:209], v[40:43]
	v_mfma_f32_16x16x32_bf16 v[36:39], v[174:177], v[214:217], v[36:39]
	v_mfma_f32_16x16x32_bf16 v[32:35], v[182:185], v[214:217], v[32:35]
	v_mfma_f32_16x16x32_bf16 v[60:63], v[178:181], v[194:197], v[60:63]
	v_mfma_f32_16x16x32_bf16 v[56:59], v[186:189], v[194:197], v[56:59]
	v_mfma_f32_16x16x32_bf16 v[52:55], v[178:181], v[202:205], v[52:55]
	v_mfma_f32_16x16x32_bf16 v[48:51], v[186:189], v[202:205], v[48:51]
	v_mfma_f32_16x16x32_bf16 v[44:47], v[178:181], v[210:213], v[44:47]
	v_mfma_f32_16x16x32_bf16 v[40:43], v[186:189], v[210:213], v[40:43]
	v_mfma_f32_16x16x32_bf16 v[36:39], v[178:181], v[218:221], v[36:39]
	v_mfma_f32_16x16x32_bf16 v[32:35], v[186:189], v[218:221], v[32:35]
	s_barrier
	v_readfirstlane_b32 s73, v162
	v_add_u32_e32 v176, 0x2000, v162
	v_lshl_add_u64 v[174:175], v[246:247], 0, s[48:49]
	s_mov_b32 m0, s73
	v_readfirstlane_b32 s73, v176
	global_load_lds_dwordx4 v[174:175], off
	v_lshl_add_u64 v[174:175], v[248:249], 0, s[48:49]
	s_mov_b32 m0, s73
	s_nop 0
	global_load_lds_dwordx4 v[174:175], off
	s_waitcnt vmcnt(8)
	s_barrier
	v_mfma_f32_16x16x32_bf16 v[28:31], v[222:225], v[190:193], v[28:31]
	v_mfma_f32_16x16x32_bf16 v[24:27], v[230:233], v[190:193], v[24:27]
	v_mfma_f32_16x16x32_bf16 v[20:23], v[222:225], v[198:201], v[20:23]
	v_mfma_f32_16x16x32_bf16 v[16:19], v[230:233], v[198:201], v[16:19]
	v_mfma_f32_16x16x32_bf16 v[12:15], v[222:225], v[206:209], v[12:15]
	v_mfma_f32_16x16x32_bf16 v[8:11], v[230:233], v[206:209], v[8:11]
	v_mfma_f32_16x16x32_bf16 v[4:7], v[222:225], v[214:217], v[4:7]
	v_mfma_f32_16x16x32_bf16 v[0:3], v[230:233], v[214:217], v[0:3]
	v_mfma_f32_16x16x32_bf16 v[28:31], v[226:229], v[194:197], v[28:31]
	v_mfma_f32_16x16x32_bf16 v[24:27], v[234:237], v[194:197], v[24:27]
	v_mfma_f32_16x16x32_bf16 v[20:23], v[226:229], v[202:205], v[20:23]
	v_mfma_f32_16x16x32_bf16 v[16:19], v[234:237], v[202:205], v[16:19]
	v_mfma_f32_16x16x32_bf16 v[12:15], v[226:229], v[210:213], v[12:15]
	v_mfma_f32_16x16x32_bf16 v[8:11], v[234:237], v[210:213], v[8:11]
	v_mfma_f32_16x16x32_bf16 v[4:7], v[226:229], v[218:221], v[4:7]
	v_mfma_f32_16x16x32_bf16 v[0:3], v[234:237], v[218:221], v[0:3]
	s_add_i32 s72, s72, 2
	s_add_u32 s50, s50, 0x100
	s_addc_u32 s51, s51, 0
	s_cmpk_gt_u32 s72, 0x51
	s_barrier
	s_cbranch_scc0 .LBB0_838
	s_add_i32 s50, s18, 0x80
	s_mul_hi_i32 s51, s50, 0x2b00
	s_mulk_i32 s50, 0x2b00
	s_add_u32 s50, s56, s50
	s_addc_u32 s51, s57, s51
	s_add_u32 s50, s50, 0x2a80
	s_addc_u32 s51, s51, 0
	v_readfirstlane_b32 s72, v172
	v_lshl_add_u64 v[160:161], s[50:51], 0, v[128:129]
	s_mov_b32 m0, s72
	ds_read_b128 v[134:137], v164
	ds_read_b128 v[138:141], v164 offset:1024
	ds_read_b128 v[142:145], v164 offset:2048
	ds_read_b128 v[174:177], v164 offset:3072
	ds_read_b128 v[178:181], v155
	ds_read_b128 v[182:185], v155 offset:1024
	ds_read_b128 v[186:189], v154
	ds_read_b128 v[190:193], v154 offset:1024
	ds_read_b128 v[194:197], v153
	ds_read_b128 v[198:201], v153 offset:1024
	ds_read_b128 v[202:205], v152
	ds_read_b128 v[206:209], v152 offset:1024
	global_load_lds_dwordx4 v[160:161], off
	v_lshl_add_u64 v[160:161], s[50:51], 0, v[132:133]
	v_readfirstlane_b32 s50, v173
	s_mov_b32 m0, s50
	s_nop 0
	global_load_lds_dwordx4 v[160:161], off
	s_barrier
	s_waitcnt lgkmcnt(0)
	s_waitcnt lgkmcnt(0)
	v_mfma_f32_16x16x32_bf16 v[124:127], v[134:137], v[178:181], v[124:127]
	v_mfma_f32_16x16x32_bf16 v[120:123], v[142:145], v[178:181], v[120:123]
	v_mfma_f32_16x16x32_bf16 v[116:119], v[134:137], v[186:189], v[116:119]
	v_mfma_f32_16x16x32_bf16 v[112:115], v[142:145], v[186:189], v[112:115]
	v_mfma_f32_16x16x32_bf16 v[108:111], v[134:137], v[194:197], v[108:111]
	v_mfma_f32_16x16x32_bf16 v[104:107], v[142:145], v[194:197], v[104:107]
	v_mfma_f32_16x16x32_bf16 v[100:103], v[134:137], v[202:205], v[100:103]
	v_mfma_f32_16x16x32_bf16 v[96:99], v[142:145], v[202:205], v[96:99]
	v_mfma_f32_16x16x32_bf16 v[124:127], v[138:141], v[182:185], v[124:127]
	v_mfma_f32_16x16x32_bf16 v[120:123], v[174:177], v[182:185], v[120:123]
	v_mfma_f32_16x16x32_bf16 v[116:119], v[138:141], v[190:193], v[116:119]
	v_mfma_f32_16x16x32_bf16 v[112:115], v[174:177], v[190:193], v[112:115]
	v_mfma_f32_16x16x32_bf16 v[108:111], v[138:141], v[198:201], v[108:111]
	v_mfma_f32_16x16x32_bf16 v[104:107], v[174:177], v[198:201], v[104:107]
	v_mfma_f32_16x16x32_bf16 v[100:103], v[138:141], v[206:209], v[100:103]
	v_mfma_f32_16x16x32_bf16 v[96:99], v[174:177], v[206:209], v[96:99]
	s_barrier
	ds_read_b128 v[210:213], v163
	ds_read_b128 v[214:217], v163 offset:1024
	ds_read_b128 v[218:221], v163 offset:2048
	ds_read_b128 v[160:163], v163 offset:3072
	s_waitcnt vmcnt(8)
	s_barrier
; #define LDA(dst, b, h) for (int m = 0; m < 4; ++m) for (int k = 0; k < 2; ++k) \
;     dst[m][k] = *reinterpret_cast<const bf16x8*>((char*)SA(b, h) + lds_byte(wr * 64 + m * 16 + fr, k * 32 + fq * 8))
; #define LDB(dst, b, h) for (int n = 0; n < 2; ++n) for (int k = 0; k < 2; ++k) \
;     dst[n][k] = *reinterpret_cast<const bf16x8*>((char*)SB(b, h) + lds_byte(wc * 32 + n * 16 + fr, k * 32 + fq * 8))
; #define MMA(ai, bj, At_, Bt_) do { __builtin_amdgcn_s_setprio(1); \
;     for (int k = 0; k < 2; ++k) for (int m = 0; m < 4; ++m) for (int n = 0; n < 2; ++n) \
;       acc[ai][bj][m][n] = __builtin_amdgcn_mfma_f32_16x16x32_bf16(At_[m][k], Bt_[n][k], acc[ai][bj][m][n], 0, 0, 0); \
;     __builtin_amdgcn_s_setprio(0); } while (0)
; #define WAIT_V(n) asm volatile("s_waitcnt vmcnt(" #n ")" ::: "memory")
; #define WAIT_L(n) asm volatile("s_waitcnt lgkmcnt(" #n ")" ::: "memory")
; #define BAR __builtin_amdgcn_s_barrier()
; template <int EPI, int lda, int ldb, int N, int K>
; __device__ __forceinline__ void gemm_phase(const u16* __restrict__ A, const u16* __restrict__ Bt, const GemmEpi ep, int wv) {
;     ...
;       LDB(B1, 0, 1); BAR; WAIT_L(0); MMA(0, 1, At, B1); BAR;
;       LDA(At, 0, 1); WAIT_V(4); BAR; WAIT_L(0); MMA(1, 0, At, B0); MMA(1, 1, At, B1); BAR; }
;     { LDB(B0, 1, 0); LDA(At, 1, 0); WAIT_V(2); BAR; WAIT_L(0); MMA(0, 0, At, B0); BAR;
	s_waitcnt lgkmcnt(0)
	s_waitcnt lgkmcnt(0)
	v_mfma_f32_16x16x32_bf16 v[92:95], v[210:213], v[178:181], v[92:95]
	v_mfma_f32_16x16x32_bf16 v[88:91], v[218:221], v[178:181], v[88:91]
	v_mfma_f32_16x16x32_bf16 v[76:79], v[210:213], v[194:197], v[76:79]
	v_mfma_f32_16x16x32_bf16 v[72:75], v[218:221], v[194:197], v[72:75]
	v_mfma_f32_16x16x32_bf16 v[84:87], v[210:213], v[186:189], v[84:87]
	v_mfma_f32_16x16x32_bf16 v[80:83], v[218:221], v[186:189], v[80:83]
	v_mfma_f32_16x16x32_bf16 v[68:71], v[210:213], v[202:205], v[68:71]
	v_mfma_f32_16x16x32_bf16 v[64:67], v[218:221], v[202:205], v[64:67]
	v_mfma_f32_16x16x32_bf16 v[92:95], v[214:217], v[182:185], v[92:95]
	v_mfma_f32_16x16x32_bf16 v[88:91], v[160:163], v[182:185], v[88:91]
	v_mfma_f32_16x16x32_bf16 v[76:79], v[214:217], v[198:201], v[76:79]
	v_mfma_f32_16x16x32_bf16 v[72:75], v[160:163], v[198:201], v[72:75]
	v_mfma_f32_16x16x32_bf16 v[178:181], v[214:217], v[190:193], v[84:87]
	v_mfma_f32_16x16x32_bf16 v[182:185], v[160:163], v[190:193], v[80:83]
	v_mfma_f32_16x16x32_bf16 v[186:189], v[214:217], v[206:209], v[68:71]
	v_mfma_f32_16x16x32_bf16 v[190:193], v[160:163], v[206:209], v[64:67]
	s_barrier
	s_nop 0
	ds_read_b128 v[64:67], v155 offset:16384
	ds_read_b128 v[68:71], v155 offset:17408
	ds_read_b128 v[80:83], v154 offset:16384
	ds_read_b128 v[84:87], v154 offset:17408
	ds_read_b128 v[194:197], v153 offset:16384
	ds_read_b128 v[198:201], v153 offset:17408
	ds_read_b128 v[202:205], v152 offset:16384
	ds_read_b128 v[206:209], v152 offset:17408
	s_waitcnt vmcnt(4)
	s_barrier
	s_waitcnt lgkmcnt(0)
	s_waitcnt lgkmcnt(0)
	v_mfma_f32_16x16x32_bf16 v[60:63], v[134:137], v[64:67], v[60:63]
	v_mfma_f32_16x16x32_bf16 v[56:59], v[142:145], v[64:67], v[56:59]
	v_mfma_f32_16x16x32_bf16 v[52:55], v[134:137], v[80:83], v[52:55]
	v_mfma_f32_16x16x32_bf16 v[48:51], v[142:145], v[80:83], v[48:51]
	v_mfma_f32_16x16x32_bf16 v[44:47], v[134:137], v[194:197], v[44:47]
	v_mfma_f32_16x16x32_bf16 v[40:43], v[142:145], v[194:197], v[40:43]
	v_mfma_f32_16x16x32_bf16 v[36:39], v[134:137], v[202:205], v[36:39]
	v_mfma_f32_16x16x32_bf16 v[32:35], v[142:145], v[202:205], v[32:35]
	v_mfma_f32_16x16x32_bf16 v[60:63], v[138:141], v[68:71], v[60:63]
	v_mfma_f32_16x16x32_bf16 v[56:59], v[174:177], v[68:71], v[56:59]
	v_mfma_f32_16x16x32_bf16 v[52:55], v[138:141], v[84:87], v[52:55]
	v_mfma_f32_16x16x32_bf16 v[48:51], v[174:177], v[84:87], v[48:51]
	v_mfma_f32_16x16x32_bf16 v[44:47], v[138:141], v[198:201], v[44:47]
	v_mfma_f32_16x16x32_bf16 v[40:43], v[174:177], v[198:201], v[40:43]
	v_mfma_f32_16x16x32_bf16 v[36:39], v[138:141], v[206:209], v[36:39]
	v_mfma_f32_16x16x32_bf16 v[32:35], v[174:177], v[206:209], v[32:35]
	v_mfma_f32_16x16x32_bf16 v[28:31], v[210:213], v[64:67], v[28:31]
	v_mfma_f32_16x16x32_bf16 v[16:19], v[218:221], v[80:83], v[16:19]
	v_mfma_f32_16x16x32_bf16 v[12:15], v[210:213], v[194:197], v[12:15]
	v_mfma_f32_16x16x32_bf16 v[0:3], v[218:221], v[202:205], v[0:3]
	v_mfma_f32_16x16x32_bf16 v[24:27], v[218:221], v[64:67], v[24:27]
	v_mfma_f32_16x16x32_bf16 v[20:23], v[210:213], v[80:83], v[20:23]
	v_mfma_f32_16x16x32_bf16 v[8:11], v[218:221], v[194:197], v[8:11]
	v_mfma_f32_16x16x32_bf16 v[4:7], v[210:213], v[202:205], v[4:7]
	v_mfma_f32_16x16x32_bf16 v[28:31], v[214:217], v[68:71], v[28:31]
	v_mfma_f32_16x16x32_bf16 v[16:19], v[160:163], v[84:87], v[16:19]
	v_mfma_f32_16x16x32_bf16 v[12:15], v[214:217], v[198:201], v[12:15]
	v_mfma_f32_16x16x32_bf16 v[0:3], v[160:163], v[206:209], v[0:3]
	v_mfma_f32_16x16x32_bf16 v[134:137], v[160:163], v[68:71], v[24:27]
	v_mfma_f32_16x16x32_bf16 v[138:141], v[214:217], v[84:87], v[20:23]
	v_mfma_f32_16x16x32_bf16 v[142:145], v[160:163], v[198:201], v[8:11]
	v_mfma_f32_16x16x32_bf16 v[172:175], v[214:217], v[206:209], v[4:7]
	s_barrier
	s_nop 0
	ds_read_b128 v[4:7], v159
	ds_read_b128 v[8:11], v159 offset:1024
	ds_read_b128 v[20:23], v159 offset:2048
	ds_read_b128 v[158:161], v159 offset:3072
	ds_read_b128 v[24:27], v155 offset:32768
	ds_read_b128 v[194:197], v155 offset:33792
	ds_read_b128 v[198:201], v154 offset:32768
	ds_read_b128 v[202:205], v154 offset:33792
	ds_read_b128 v[206:209], v153 offset:32768
	ds_read_b128 v[210:213], v153 offset:33792
	ds_read_b128 v[214:217], v152 offset:32768
	ds_read_b128 v[218:221], v152 offset:33792
	s_waitcnt vmcnt(2)
	s_barrier
; #define LDA(dst, b, h) for (int m = 0; m < 4; ++m) for (int k = 0; k < 2; ++k) \
;     dst[m][k] = *reinterpret_cast<const bf16x8*>((char*)SA(b, h) + lds_byte(wr * 64 + m * 16 + fr, k * 32 + fq * 8))
; #define LDB(dst, b, h) for (int n = 0; n < 2; ++n) for (int k = 0; k < 2; ++k) \
;     dst[n][k] = *reinterpret_cast<const bf16x8*>((char*)SB(b, h) + lds_byte(wc * 32 + n * 16 + fr, k * 32 + fq * 8))
; #define MMA(ai, bj, At_, Bt_) do { __builtin_amdgcn_s_setprio(1); \
;     for (int k = 0; k < 2; ++k) for (int m = 0; m < 4; ++m) for (int n = 0; n < 2; ++n) \
;       acc[ai][bj][m][n] = __builtin_amdgcn_mfma_f32_16x16x32_bf16(At_[m][k], Bt_[n][k], acc[ai][bj][m][n], 0, 0, 0); \
;     __builtin_amdgcn_s_setprio(0); } while (0)
; #define WAIT_V(n) asm volatile("s_waitcnt vmcnt(" #n ")" ::: "memory")
; #define WAIT_L(n) asm volatile("s_waitcnt lgkmcnt(" #n ")" ::: "memory")
; #define BAR __builtin_amdgcn_s_barrier()
; template <int EPI, int lda, int ldb, int N, int K>
; __device__ __forceinline__ void gemm_phase(const u16* __restrict__ A, const u16* __restrict__ Bt, const GemmEpi ep, int wv) {
;     ...
;     { LDB(B0, 1, 0); LDA(At, 1, 0); WAIT_V(2); BAR; WAIT_L(0); MMA(0, 0, At, B0); BAR;
;       LDB(B1, 1, 1); WAIT_V(0); BAR; WAIT_L(0); MMA(0, 1, At, B1); BAR;
;       LDA(At, 1, 1); BAR; WAIT_L(0); MMA(1, 0, At, B0); MMA(1, 1, At, B1); BAR; }
;     if (wr == 0) BAR;
	s_waitcnt lgkmcnt(0)
	s_waitcnt lgkmcnt(0)
	v_mfma_f32_16x16x32_bf16 v[64:67], v[4:7], v[24:27], v[124:127]
	v_mfma_f32_16x16x32_bf16 v[68:71], v[20:23], v[24:27], v[120:123]
	v_mfma_f32_16x16x32_bf16 v[80:83], v[4:7], v[198:201], v[116:119]
	v_mfma_f32_16x16x32_bf16 v[84:87], v[20:23], v[198:201], v[112:115]
	v_mfma_f32_16x16x32_bf16 v[108:111], v[4:7], v[206:209], v[108:111]
	v_mfma_f32_16x16x32_bf16 v[104:107], v[20:23], v[206:209], v[104:107]
	v_mfma_f32_16x16x32_bf16 v[120:123], v[4:7], v[214:217], v[100:103]
	v_mfma_f32_16x16x32_bf16 v[124:127], v[20:23], v[214:217], v[96:99]
	v_mfma_f32_16x16x32_bf16 v[116:119], v[8:11], v[194:197], v[64:67]
	v_mfma_f32_16x16x32_bf16 v[112:115], v[158:161], v[194:197], v[68:71]
	v_mfma_f32_16x16x32_bf16 v[100:103], v[8:11], v[202:205], v[80:83]
	v_mfma_f32_16x16x32_bf16 v[96:99], v[158:161], v[202:205], v[84:87]
	v_mfma_f32_16x16x32_bf16 v[84:87], v[8:11], v[210:213], v[108:111]
	v_mfma_f32_16x16x32_bf16 v[80:83], v[158:161], v[210:213], v[104:107]
	v_mfma_f32_16x16x32_bf16 v[68:71], v[8:11], v[218:221], v[120:123]
	v_mfma_f32_16x16x32_bf16 v[64:67], v[158:161], v[218:221], v[124:127]
	s_barrier
	ds_read_b128 v[222:225], v157
	ds_read_b128 v[226:229], v157 offset:1024
	ds_read_b128 v[230:233], v157 offset:2048
	ds_read_b128 v[234:237], v157 offset:3072
	s_waitcnt vmcnt(0)
	s_barrier
	s_waitcnt lgkmcnt(0)
	s_waitcnt lgkmcnt(0)
	v_mfma_f32_16x16x32_bf16 v[92:95], v[222:225], v[24:27], v[92:95]
	v_mfma_f32_16x16x32_bf16 v[24:27], v[230:233], v[24:27], v[88:91]
	v_mfma_f32_16x16x32_bf16 v[88:91], v[222:225], v[198:201], v[178:181]
	v_mfma_f32_16x16x32_bf16 v[104:107], v[230:233], v[198:201], v[182:185]
	v_mfma_f32_16x16x32_bf16 v[76:79], v[222:225], v[206:209], v[76:79]
	v_mfma_f32_16x16x32_bf16 v[72:75], v[230:233], v[206:209], v[72:75]
	v_mfma_f32_16x16x32_bf16 v[176:179], v[222:225], v[214:217], v[186:189]
	v_mfma_f32_16x16x32_bf16 v[180:183], v[230:233], v[214:217], v[190:193]
	v_mfma_f32_16x16x32_bf16 v[124:127], v[226:229], v[194:197], v[92:95]
	v_mfma_f32_16x16x32_bf16 v[120:123], v[234:237], v[194:197], v[24:27]
	v_mfma_f32_16x16x32_bf16 v[108:111], v[226:229], v[202:205], v[88:91]
	v_mfma_f32_16x16x32_bf16 v[104:107], v[234:237], v[202:205], v[104:107]
	v_mfma_f32_16x16x32_bf16 v[92:95], v[226:229], v[210:213], v[76:79]
	v_mfma_f32_16x16x32_bf16 v[88:91], v[234:237], v[210:213], v[72:75]
	v_mfma_f32_16x16x32_bf16 v[76:79], v[226:229], v[218:221], v[176:179]
	v_mfma_f32_16x16x32_bf16 v[72:75], v[234:237], v[218:221], v[180:183]
	s_barrier
	ds_read_b128 v[176:179], v155 offset:49152
	ds_read_b128 v[180:183], v155 offset:50176
	ds_read_b128 v[184:187], v154 offset:49152
	ds_read_b128 v[154:157], v154 offset:50176
	ds_read_b128 v[188:191], v153 offset:49152
	ds_read_b128 v[192:195], v153 offset:50176
	ds_read_b128 v[196:199], v152 offset:49152
	ds_read_b128 v[200:203], v152 offset:50176
	s_barrier
	s_waitcnt lgkmcnt(0)
	s_waitcnt lgkmcnt(0)
	v_mfma_f32_16x16x32_bf16 v[24:27], v[4:7], v[176:179], v[60:63]
	v_mfma_f32_16x16x32_bf16 v[60:63], v[20:23], v[176:179], v[56:59]
	v_mfma_f32_16x16x32_bf16 v[204:207], v[4:7], v[184:187], v[52:55]
	v_mfma_f32_16x16x32_bf16 v[48:51], v[20:23], v[184:187], v[48:51]
	v_mfma_f32_16x16x32_bf16 v[44:47], v[4:7], v[188:191], v[44:47]
	v_mfma_f32_16x16x32_bf16 v[208:211], v[20:23], v[188:191], v[40:43]
	v_mfma_f32_16x16x32_bf16 v[4:7], v[4:7], v[196:199], v[36:39]
	v_mfma_f32_16x16x32_bf16 v[32:35], v[20:23], v[196:199], v[32:35]
	v_mfma_f32_16x16x32_bf16 v[56:59], v[8:11], v[180:183], v[24:27]
	v_mfma_f32_16x16x32_bf16 v[52:55], v[158:161], v[180:183], v[60:63]
	v_mfma_f32_16x16x32_bf16 v[40:43], v[8:11], v[154:157], v[204:207]
	v_mfma_f32_16x16x32_bf16 v[36:39], v[158:161], v[154:157], v[48:51]
	v_mfma_f32_16x16x32_bf16 v[24:27], v[8:11], v[192:195], v[44:47]
	v_mfma_f32_16x16x32_bf16 v[20:23], v[158:161], v[192:195], v[208:211]
	v_mfma_f32_16x16x32_bf16 v[8:11], v[8:11], v[200:203], v[4:7]
	v_mfma_f32_16x16x32_bf16 v[4:7], v[158:161], v[200:203], v[32:35]
	v_mfma_f32_16x16x32_bf16 v[28:31], v[222:225], v[176:179], v[28:31]
	v_mfma_f32_16x16x32_bf16 v[32:35], v[230:233], v[176:179], v[134:137]
	v_mfma_f32_16x16x32_bf16 v[44:47], v[222:225], v[184:187], v[138:141]
	v_mfma_f32_16x16x32_bf16 v[16:19], v[230:233], v[184:187], v[16:19]
	v_mfma_f32_16x16x32_bf16 v[12:15], v[222:225], v[188:191], v[12:15]
	v_mfma_f32_16x16x32_bf16 v[134:137], v[230:233], v[188:191], v[142:145]
	v_mfma_f32_16x16x32_bf16 v[138:141], v[222:225], v[196:199], v[172:175]
	v_mfma_f32_16x16x32_bf16 v[0:3], v[230:233], v[196:199], v[0:3]
	v_mfma_f32_16x16x32_bf16 v[60:63], v[226:229], v[180:183], v[28:31]
	v_mfma_f32_16x16x32_bf16 v[48:51], v[234:237], v[180:183], v[32:35]
	v_mfma_f32_16x16x32_bf16 v[44:47], v[226:229], v[154:157], v[44:47]
	v_mfma_f32_16x16x32_bf16 v[32:35], v[234:237], v[154:157], v[16:19]
	v_mfma_f32_16x16x32_bf16 v[28:31], v[226:229], v[192:195], v[12:15]
	v_mfma_f32_16x16x32_bf16 v[16:19], v[234:237], v[192:195], v[134:137]
	v_mfma_f32_16x16x32_bf16 v[12:15], v[226:229], v[200:203], v[138:141]
	v_mfma_f32_16x16x32_bf16 v[0:3], v[234:237], v[200:203], v[0:3]
	v_cmp_gt_u32_e32 vcc, s69, v130
	s_barrier
	s_and_saveexec_b64 s[50:51], vcc
	s_cbranch_execz .LBB0_841
	s_barrier

; #define STAGE(P, BASE, LD, br, kt) do { const char* _g = (const char*)((BASE) + (size_t)(br) * (LD) + (size_t)(kt) * 64); \
;     for (int _i = 0; _i < 2; ++_i) { int _b = tidx * 16 + _i * 8192; int _r, _c; stage_rc(_b, _r, _c); \
;       __builtin_amdgcn_global_load_lds((const unsigned*)(_g + (unsigned)((_r * (LD) + _c) * 2)), (unsigned*)((char*)(P) + _b), 16, 0, 0); } } while (0)
; #define LDA(dst, b, h) for (int m = 0; m < 4; ++m) for (int k = 0; k < 2; ++k) \
;     dst[m][k] = *reinterpret_cast<const bf16x8*>((char*)SA(b, h) + lds_byte(wr * 64 + m * 16 + fr, k * 32 + fq * 8))
; #define LDB(dst, b, h) for (int n = 0; n < 2; ++n) for (int k = 0; k < 2; ++k) \
;     dst[n][k] = *reinterpret_cast<const bf16x8*>((char*)SB(b, h) + lds_byte(wc * 32 + n * 16 + fr, k * 32 + fq * 8))
; #define MMA(ai, bj, At_, Bt_) do { __builtin_amdgcn_s_setprio(1); \
;     for (int k = 0; k < 2; ++k) for (int m = 0; m < 4; ++m) for (int n = 0; n < 2; ++n) \
;       acc[ai][bj][m][n] = __builtin_amdgcn_mfma_f32_16x16x32_bf16(At_[m][k], Bt_[n][k], acc[ai][bj][m][n], 0, 0, 0); \
;     __builtin_amdgcn_s_setprio(0); } while (0)
; #define WAIT_L(n) asm volatile("s_waitcnt lgkmcnt(" #n ")" ::: "memory")
; #define BAR __builtin_amdgcn_s_barrier()
; #define SCHED __builtin_amdgcn_sched_barrier(0)
; template <int EPI, int lda, int ldb, int N, int K>
; __device__ __forceinline__ void gemm_phase(const u16* __restrict__ A, const u16* __restrict__ Bt, const GemmEpi ep, int wv) {
;     ...
;       LDB(B0, 0, 0); SCHED; LDA(At, 0, 0); STAGE(SA(1, 1), Ab, lda, brow + HALF, t + 1);
;       WAIT_L(8); BAR; WAIT_L(0); MMA(0, 0, At, B0); BAR; SCHED;
;       LDB(B1, 0, 1); STAGE(SB(0, 0), Bt, ldb, bcol, t + 2);
;       BAR; WAIT_L(0); MMA(0, 1, At, B1); BAR;
;       LDA(At, 0, 1); STAGE(SA(0, 0), Ab, lda, brow, t + 2);
;       BAR; WAIT_L(0); MMA(1, 0, At, B0); BAR; SCHED;
.LBB0_1147:
	ds_read_b128 v[172:175], v161
	ds_read_b128 v[176:179], v161 offset:1024
	ds_read_b128 v[180:183], v161 offset:2048
	ds_read_b128 v[184:187], v161 offset:3072
	v_add_u32_e32 v169, 0xc000, v148
	v_lshl_add_u64 v[236:237], v[138:139], 0, s[60:61]
	v_readfirstlane_b32 s63, v169
	v_add_u32_e32 v170, 0xe000, v148
	v_lshl_add_u64 v[162:163], v[236:237], 0, s[22:23]
	s_mov_b32 m0, s63
	v_lshl_add_u64 v[238:239], v[140:141], 0, s[60:61]
	v_readfirstlane_b32 s63, v170
	ds_read_b128 v[164:167], v152
	ds_read_b128 v[188:191], v152 offset:1024
	ds_read_b128 v[192:195], v151
	ds_read_b128 v[196:199], v151 offset:1024
	ds_read_b128 v[200:203], v150
	ds_read_b128 v[204:207], v150 offset:1024
	ds_read_b128 v[208:211], v149
	ds_read_b128 v[212:215], v149 offset:1024
	global_load_lds_dwordx4 v[162:163], off
	v_lshl_add_u64 v[162:163], v[238:239], 0, s[22:23]
	s_mov_b32 m0, s63
	s_nop 0
	global_load_lds_dwordx4 v[162:163], off
	s_waitcnt lgkmcnt(8)
	s_barrier
	s_waitcnt lgkmcnt(0)
	s_waitcnt lgkmcnt(0)
	v_mfma_f32_16x16x32_bf16 v[124:127], v[164:167], v[172:175], v[124:127]
	v_mfma_f32_16x16x32_bf16 v[120:123], v[164:167], v[180:183], v[120:123]
	v_mfma_f32_16x16x32_bf16 v[116:119], v[192:195], v[172:175], v[116:119]
	v_mfma_f32_16x16x32_bf16 v[112:115], v[192:195], v[180:183], v[112:115]
	v_mfma_f32_16x16x32_bf16 v[108:111], v[200:203], v[172:175], v[108:111]
	v_mfma_f32_16x16x32_bf16 v[104:107], v[200:203], v[180:183], v[104:107]
	v_mfma_f32_16x16x32_bf16 v[100:103], v[208:211], v[172:175], v[100:103]
	v_mfma_f32_16x16x32_bf16 v[96:99], v[208:211], v[180:183], v[96:99]
	v_mfma_f32_16x16x32_bf16 v[124:127], v[188:191], v[176:179], v[124:127]
	v_mfma_f32_16x16x32_bf16 v[120:123], v[188:191], v[184:187], v[120:123]
	v_mfma_f32_16x16x32_bf16 v[116:119], v[196:199], v[176:179], v[116:119]
	v_mfma_f32_16x16x32_bf16 v[112:115], v[196:199], v[184:187], v[112:115]
	v_mfma_f32_16x16x32_bf16 v[108:111], v[204:207], v[176:179], v[108:111]
	v_mfma_f32_16x16x32_bf16 v[104:107], v[204:207], v[184:187], v[104:107]
	v_mfma_f32_16x16x32_bf16 v[100:103], v[212:215], v[176:179], v[100:103]
	v_mfma_f32_16x16x32_bf16 v[96:99], v[212:215], v[184:187], v[96:99]
	s_barrier
	v_add_u32_e32 v162, s75, v154
	v_lshl_add_u64 v[240:241], v[134:135], 0, s[60:61]
	v_readfirstlane_b32 s63, v162
	v_add_u32_e32 v163, 0x2000, v162
	v_lshl_add_u64 v[232:233], v[240:241], 0, s[24:25]
	s_mov_b32 m0, s63
	v_lshl_add_u64 v[242:243], v[136:137], 0, s[60:61]
	v_readfirstlane_b32 s63, v163
	ds_read_b128 v[216:219], v160
	ds_read_b128 v[220:223], v160 offset:1024
	ds_read_b128 v[224:227], v160 offset:2048
	ds_read_b128 v[228:231], v160 offset:3072
	global_load_lds_dwordx4 v[232:233], off
	v_lshl_add_u64 v[232:233], v[242:243], 0, s[24:25]
	s_mov_b32 m0, s63
	s_nop 0
	global_load_lds_dwordx4 v[232:233], off
	s_waitcnt vmcnt(10)
	s_barrier
	s_waitcnt lgkmcnt(0)
	s_waitcnt lgkmcnt(0)
	v_mfma_f32_16x16x32_bf16 v[92:95], v[164:167], v[216:219], v[92:95]
	v_mfma_f32_16x16x32_bf16 v[88:91], v[164:167], v[224:227], v[88:91]
	v_mfma_f32_16x16x32_bf16 v[84:87], v[192:195], v[216:219], v[84:87]
	v_mfma_f32_16x16x32_bf16 v[80:83], v[192:195], v[224:227], v[80:83]
	v_mfma_f32_16x16x32_bf16 v[76:79], v[200:203], v[216:219], v[76:79]
	v_mfma_f32_16x16x32_bf16 v[72:75], v[200:203], v[224:227], v[72:75]
	v_mfma_f32_16x16x32_bf16 v[68:71], v[208:211], v[216:219], v[68:71]
	v_mfma_f32_16x16x32_bf16 v[64:67], v[208:211], v[224:227], v[64:67]
	v_mfma_f32_16x16x32_bf16 v[92:95], v[188:191], v[220:223], v[92:95]
	v_mfma_f32_16x16x32_bf16 v[88:91], v[188:191], v[228:231], v[88:91]
	v_mfma_f32_16x16x32_bf16 v[84:87], v[196:199], v[220:223], v[84:87]
	v_mfma_f32_16x16x32_bf16 v[80:83], v[196:199], v[228:231], v[80:83]
	v_mfma_f32_16x16x32_bf16 v[76:79], v[204:207], v[220:223], v[76:79]
	v_mfma_f32_16x16x32_bf16 v[72:75], v[204:207], v[228:231], v[72:75]
	v_mfma_f32_16x16x32_bf16 v[68:71], v[212:215], v[220:223], v[68:71]
	v_mfma_f32_16x16x32_bf16 v[64:67], v[212:215], v[228:231], v[64:67]
	v_readfirstlane_b32 s63, v148
	v_lshl_add_u64 v[164:165], v[236:237], 0, s[26:27]
	s_mov_b32 m0, s63
	s_barrier
	ds_read_b128 v[188:191], v152 offset:16384
	ds_read_b128 v[192:195], v152 offset:17408
	ds_read_b128 v[196:199], v151 offset:16384
	ds_read_b128 v[200:203], v151 offset:17408
	ds_read_b128 v[204:207], v150 offset:16384
	ds_read_b128 v[208:211], v150 offset:17408
	ds_read_b128 v[212:215], v149 offset:16384
	ds_read_b128 v[232:235], v149 offset:17408
	global_load_lds_dwordx4 v[164:165], off
	v_add_u32_e32 v164, 0x2000, v148
	v_lshl_add_u64 v[166:167], v[238:239], 0, s[26:27]
	v_readfirstlane_b32 s63, v164
	s_mov_b32 m0, s63
	s_nop 0
	global_load_lds_dwordx4 v[166:167], off
	s_barrier
	s_waitcnt lgkmcnt(0)
	s_waitcnt lgkmcnt(0)
	v_mfma_f32_16x16x32_bf16 v[60:63], v[188:191], v[172:175], v[60:63]
	v_mfma_f32_16x16x32_bf16 v[56:59], v[188:191], v[180:183], v[56:59]
	v_mfma_f32_16x16x32_bf16 v[52:55], v[196:199], v[172:175], v[52:55]
	v_mfma_f32_16x16x32_bf16 v[48:51], v[196:199], v[180:183], v[48:51]
	v_mfma_f32_16x16x32_bf16 v[44:47], v[204:207], v[172:175], v[44:47]
	v_mfma_f32_16x16x32_bf16 v[40:43], v[204:207], v[180:183], v[40:43]
	v_mfma_f32_16x16x32_bf16 v[36:39], v[212:215], v[172:175], v[36:39]
	v_mfma_f32_16x16x32_bf16 v[32:35], v[212:215], v[180:183], v[32:35]
	v_mfma_f32_16x16x32_bf16 v[60:63], v[192:195], v[176:179], v[60:63]
	v_mfma_f32_16x16x32_bf16 v[56:59], v[192:195], v[184:187], v[56:59]
	v_mfma_f32_16x16x32_bf16 v[52:55], v[200:203], v[176:179], v[52:55]
	v_mfma_f32_16x16x32_bf16 v[48:51], v[200:203], v[184:187], v[48:51]
	v_mfma_f32_16x16x32_bf16 v[44:47], v[208:211], v[176:179], v[44:47]
	v_mfma_f32_16x16x32_bf16 v[40:43], v[208:211], v[184:187], v[40:43]
	v_mfma_f32_16x16x32_bf16 v[36:39], v[232:235], v[176:179], v[36:39]
	v_mfma_f32_16x16x32_bf16 v[32:35], v[232:235], v[184:187], v[32:35]
	s_barrier
; #define STAGE(P, BASE, LD, br, kt) do { const char* _g = (const char*)((BASE) + (size_t)(br) * (LD) + (size_t)(kt) * 64); \
;     for (int _i = 0; _i < 2; ++_i) { int _b = tidx * 16 + _i * 8192; int _r, _c; stage_rc(_b, _r, _c); \
;       __builtin_amdgcn_global_load_lds((const unsigned*)(_g + (unsigned)((_r * (LD) + _c) * 2)), (unsigned*)((char*)(P) + _b), 16, 0, 0); } } while (0)
; #define LDA(dst, b, h) for (int m = 0; m < 4; ++m) for (int k = 0; k < 2; ++k) \
;     dst[m][k] = *reinterpret_cast<const bf16x8*>((char*)SA(b, h) + lds_byte(wr * 64 + m * 16 + fr, k * 32 + fq * 8))
; #define LDB(dst, b, h) for (int n = 0; n < 2; ++n) for (int k = 0; k < 2; ++k) \
;     dst[n][k] = *reinterpret_cast<const bf16x8*>((char*)SB(b, h) + lds_byte(wc * 32 + n * 16 + fr, k * 32 + fq * 8))
; #define MMA(ai, bj, At_, Bt_) do { __builtin_amdgcn_s_setprio(1); \
;     for (int k = 0; k < 2; ++k) for (int m = 0; m < 4; ++m) for (int n = 0; n < 2; ++n) \
;       acc[ai][bj][m][n] = __builtin_amdgcn_mfma_f32_16x16x32_bf16(At_[m][k], Bt_[n][k], acc[ai][bj][m][n], 0, 0, 0); \
;     __builtin_amdgcn_s_setprio(0); } while (0)
; #define WAIT_V(n) asm volatile("s_waitcnt vmcnt(" #n ")" ::: "memory")
; #define WAIT_L(n) asm volatile("s_waitcnt lgkmcnt(" #n ")" ::: "memory")
; #define BAR __builtin_amdgcn_s_barrier()
; #define SCHED __builtin_amdgcn_sched_barrier(0)
; template <int EPI, int lda, int ldb, int N, int K>
; __device__ __forceinline__ void gemm_phase(const u16* __restrict__ A, const u16* __restrict__ Bt, const GemmEpi ep, int wv) {
;     ...
;       STAGE(SB(0, 1), Bt, ldb, bcol + HALF, t + 2);
;       WAIT_V(6); BAR; MMA(1, 1, At, B1); BAR;
;       LDB(B0, 1, 0); SCHED; LDA(At, 1, 0); STAGE(SA(0, 1), Ab, lda, brow + HALF, t + 2);
;       WAIT_L(8); BAR; WAIT_L(0); MMA(0, 0, At, B0); BAR; SCHED;
;       LDB(B1, 1, 1); STAGE(SB(1, 0), Bt, ldb, bcol, t + 3);
;       BAR; WAIT_L(0); MMA(0, 1, At, B1); BAR;
	v_add_u32_e32 v165, s76, v154
	v_lshl_add_u64 v[166:167], v[240:241], 0, s[40:41]
	v_readfirstlane_b32 s63, v165
	s_mov_b32 m0, s63
	v_lshl_add_u64 v[172:173], v[242:243], 0, s[40:41]
	global_load_lds_dwordx4 v[166:167], off
	v_add_u32_e32 v166, 0x2000, v165
	s_nop 0
	v_readfirstlane_b32 s63, v166
	s_mov_b32 m0, s63
	s_nop 0
	global_load_lds_dwordx4 v[172:173], off
	s_waitcnt vmcnt(8)
	s_barrier
	v_mfma_f32_16x16x32_bf16 v[28:31], v[188:191], v[216:219], v[28:31]
	v_mfma_f32_16x16x32_bf16 v[24:27], v[188:191], v[224:227], v[24:27]
	v_mfma_f32_16x16x32_bf16 v[20:23], v[196:199], v[216:219], v[20:23]
	v_mfma_f32_16x16x32_bf16 v[16:19], v[196:199], v[224:227], v[16:19]
	v_mfma_f32_16x16x32_bf16 v[12:15], v[204:207], v[216:219], v[12:15]
	v_mfma_f32_16x16x32_bf16 v[8:11], v[204:207], v[224:227], v[8:11]
	v_mfma_f32_16x16x32_bf16 v[4:7], v[212:215], v[216:219], v[4:7]
	v_mfma_f32_16x16x32_bf16 v[0:3], v[212:215], v[224:227], v[0:3]
	v_mfma_f32_16x16x32_bf16 v[28:31], v[192:195], v[220:223], v[28:31]
	v_mfma_f32_16x16x32_bf16 v[24:27], v[192:195], v[228:231], v[24:27]
	v_mfma_f32_16x16x32_bf16 v[20:23], v[200:203], v[220:223], v[20:23]
	v_mfma_f32_16x16x32_bf16 v[16:19], v[200:203], v[228:231], v[16:19]
	v_mfma_f32_16x16x32_bf16 v[12:15], v[208:211], v[220:223], v[12:15]
	v_mfma_f32_16x16x32_bf16 v[8:11], v[208:211], v[228:231], v[8:11]
	v_mfma_f32_16x16x32_bf16 v[4:7], v[232:235], v[220:223], v[4:7]
	v_mfma_f32_16x16x32_bf16 v[0:3], v[232:235], v[228:231], v[0:3]
	s_barrier
	ds_read_b128 v[172:175], v155
	ds_read_b128 v[176:179], v155 offset:1024
	ds_read_b128 v[180:183], v155 offset:2048
	ds_read_b128 v[184:187], v155 offset:3072
	v_add_u32_e32 v167, 0x4000, v148
	v_add_u32_e32 v168, 0x6000, v148
	v_readfirstlane_b32 s63, v167
	v_lshl_add_u64 v[220:221], v[236:237], 0, s[42:43]
	s_mov_b32 m0, s63
	v_readfirstlane_b32 s63, v168
	ds_read_b128 v[188:191], v152 offset:32768
	ds_read_b128 v[192:195], v152 offset:33792
	ds_read_b128 v[196:199], v151 offset:32768
	ds_read_b128 v[200:203], v151 offset:33792
	ds_read_b128 v[204:207], v150 offset:32768
	ds_read_b128 v[208:211], v150 offset:33792
	ds_read_b128 v[212:215], v149 offset:32768
	ds_read_b128 v[216:219], v149 offset:33792
	global_load_lds_dwordx4 v[220:221], off
	v_lshl_add_u64 v[220:221], v[238:239], 0, s[42:43]
	s_mov_b32 m0, s63
	s_nop 0
	global_load_lds_dwordx4 v[220:221], off
	s_waitcnt lgkmcnt(8)
	s_barrier
	s_waitcnt lgkmcnt(0)
	s_waitcnt lgkmcnt(0)
	v_mfma_f32_16x16x32_bf16 v[124:127], v[188:191], v[172:175], v[124:127]
	v_mfma_f32_16x16x32_bf16 v[120:123], v[188:191], v[180:183], v[120:123]
	v_mfma_f32_16x16x32_bf16 v[116:119], v[196:199], v[172:175], v[116:119]
	v_mfma_f32_16x16x32_bf16 v[112:115], v[196:199], v[180:183], v[112:115]
	v_mfma_f32_16x16x32_bf16 v[108:111], v[204:207], v[172:175], v[108:111]
	v_mfma_f32_16x16x32_bf16 v[104:107], v[204:207], v[180:183], v[104:107]
	v_mfma_f32_16x16x32_bf16 v[100:103], v[212:215], v[172:175], v[100:103]
	v_mfma_f32_16x16x32_bf16 v[96:99], v[212:215], v[180:183], v[96:99]
	v_mfma_f32_16x16x32_bf16 v[124:127], v[192:195], v[176:179], v[124:127]
	v_mfma_f32_16x16x32_bf16 v[120:123], v[192:195], v[184:187], v[120:123]
	v_mfma_f32_16x16x32_bf16 v[116:119], v[200:203], v[176:179], v[116:119]
	v_mfma_f32_16x16x32_bf16 v[112:115], v[200:203], v[184:187], v[112:115]
	v_mfma_f32_16x16x32_bf16 v[108:111], v[208:211], v[176:179], v[108:111]
	v_mfma_f32_16x16x32_bf16 v[104:107], v[208:211], v[184:187], v[104:107]
	v_mfma_f32_16x16x32_bf16 v[100:103], v[216:219], v[176:179], v[100:103]
	v_mfma_f32_16x16x32_bf16 v[96:99], v[216:219], v[184:187], v[96:99]
	s_barrier
	v_readfirstlane_b32 s63, v156
	v_add_u32_e32 v171, 0x2000, v156
	v_lshl_add_u64 v[244:245], v[240:241], 0, s[44:45]
	s_mov_b32 m0, s63
	v_readfirstlane_b32 s63, v171
	ds_read_b128 v[220:223], v153
	ds_read_b128 v[224:227], v153 offset:1024
	ds_read_b128 v[228:231], v153 offset:2048
	ds_read_b128 v[232:235], v153 offset:3072
	global_load_lds_dwordx4 v[244:245], off
	v_lshl_add_u64 v[244:245], v[242:243], 0, s[44:45]
	s_mov_b32 m0, s63
	s_nop 0
	global_load_lds_dwordx4 v[244:245], off
	s_waitcnt vmcnt(10)
	s_barrier
	s_waitcnt lgkmcnt(0)
	s_waitcnt lgkmcnt(0)
	v_mfma_f32_16x16x32_bf16 v[92:95], v[188:191], v[220:223], v[92:95]
	v_mfma_f32_16x16x32_bf16 v[88:91], v[188:191], v[228:231], v[88:91]
	v_mfma_f32_16x16x32_bf16 v[84:87], v[196:199], v[220:223], v[84:87]
	v_mfma_f32_16x16x32_bf16 v[80:83], v[196:199], v[228:231], v[80:83]
	v_mfma_f32_16x16x32_bf16 v[76:79], v[204:207], v[220:223], v[76:79]
	v_mfma_f32_16x16x32_bf16 v[72:75], v[204:207], v[228:231], v[72:75]
	v_mfma_f32_16x16x32_bf16 v[68:71], v[212:215], v[220:223], v[68:71]
	v_mfma_f32_16x16x32_bf16 v[64:67], v[212:215], v[228:231], v[64:67]
	v_mfma_f32_16x16x32_bf16 v[92:95], v[192:195], v[224:227], v[92:95]
	v_mfma_f32_16x16x32_bf16 v[88:91], v[192:195], v[232:235], v[88:91]
	v_mfma_f32_16x16x32_bf16 v[84:87], v[200:203], v[224:227], v[84:87]
	v_mfma_f32_16x16x32_bf16 v[80:83], v[200:203], v[232:235], v[80:83]
	v_mfma_f32_16x16x32_bf16 v[76:79], v[208:211], v[224:227], v[76:79]
	v_mfma_f32_16x16x32_bf16 v[72:75], v[208:211], v[232:235], v[72:75]
	v_mfma_f32_16x16x32_bf16 v[68:71], v[216:219], v[224:227], v[68:71]
	v_mfma_f32_16x16x32_bf16 v[64:67], v[216:219], v[232:235], v[64:67]
	v_readfirstlane_b32 s63, v157
	v_lshl_add_u64 v[236:237], v[236:237], 0, s[46:47]
	s_mov_b32 m0, s63
	v_readfirstlane_b32 s63, v158
	s_barrier
; #define STAGE(P, BASE, LD, br, kt) do { const char* _g = (const char*)((BASE) + (size_t)(br) * (LD) + (size_t)(kt) * 64); \
;     for (int _i = 0; _i < 2; ++_i) { int _b = tidx * 16 + _i * 8192; int _r, _c; stage_rc(_b, _r, _c); \
;       __builtin_amdgcn_global_load_lds((const unsigned*)(_g + (unsigned)((_r * (LD) + _c) * 2)), (unsigned*)((char*)(P) + _b), 16, 0, 0); } } while (0)
; #define LDA(dst, b, h) for (int m = 0; m < 4; ++m) for (int k = 0; k < 2; ++k) \
;     dst[m][k] = *reinterpret_cast<const bf16x8*>((char*)SA(b, h) + lds_byte(wr * 64 + m * 16 + fr, k * 32 + fq * 8))
; #define LDB(dst, b, h) for (int n = 0; n < 2; ++n) for (int k = 0; k < 2; ++k) \
;     dst[n][k] = *reinterpret_cast<const bf16x8*>((char*)SB(b, h) + lds_byte(wc * 32 + n * 16 + fr, k * 32 + fq * 8))
; #define MMA(ai, bj, At_, Bt_) do { __builtin_amdgcn_s_setprio(1); \
;     for (int k = 0; k < 2; ++k) for (int m = 0; m < 4; ++m) for (int n = 0; n < 2; ++n) \
;       acc[ai][bj][m][n] = __builtin_amdgcn_mfma_f32_16x16x32_bf16(At_[m][k], Bt_[n][k], acc[ai][bj][m][n], 0, 0, 0); \
;     __builtin_amdgcn_s_setprio(0); } while (0)
; #define WAIT_V(n) asm volatile("s_waitcnt vmcnt(" #n ")" ::: "memory")
; #define WAIT_L(n) asm volatile("s_waitcnt lgkmcnt(" #n ")" ::: "memory")
; #define BAR __builtin_amdgcn_s_barrier()
; #define SCHED __builtin_amdgcn_sched_barrier(0)
; template <int EPI, int lda, int ldb, int N, int K>
; __device__ __forceinline__ void gemm_phase(const u16* __restrict__ A, const u16* __restrict__ Bt, const GemmEpi ep, int wv) {
;     ...
;       LDA(At, 1, 1); STAGE(SA(1, 0), Ab, lda, brow, t + 3);
;       BAR; WAIT_L(0); MMA(1, 0, At, B0); BAR; SCHED;
;       STAGE(SB(1, 1), Bt, ldb, bcol + HALF, t + 3);
;       WAIT_V(6); BAR; MMA(1, 1, At, B1); BAR;
;     }
;     { LDB(B0, 0, 0); LDA(At, 0, 0); STAGE(SA(1, 1), Ab, lda, brow + HALF, nt - 1);
;       BAR; WAIT_L(0); MMA(0, 0, At, B0); BAR;
;       LDB(B1, 0, 1); BAR; WAIT_L(0); MMA(0, 1, At, B1); BAR;
	ds_read_b128 v[188:191], v152 offset:49152
	ds_read_b128 v[192:195], v152 offset:50176
	ds_read_b128 v[196:199], v151 offset:49152
	ds_read_b128 v[200:203], v151 offset:50176
	ds_read_b128 v[204:207], v150 offset:49152
	ds_read_b128 v[208:211], v150 offset:50176
	ds_read_b128 v[212:215], v149 offset:49152
	ds_read_b128 v[216:219], v149 offset:50176
	global_load_lds_dwordx4 v[236:237], off
	v_lshl_add_u64 v[236:237], v[238:239], 0, s[46:47]
	s_mov_b32 m0, s63
	s_nop 0
	global_load_lds_dwordx4 v[236:237], off
	s_barrier
	s_waitcnt lgkmcnt(0)
	s_waitcnt lgkmcnt(0)
	v_mfma_f32_16x16x32_bf16 v[60:63], v[188:191], v[172:175], v[60:63]
	v_mfma_f32_16x16x32_bf16 v[56:59], v[188:191], v[180:183], v[56:59]
	v_mfma_f32_16x16x32_bf16 v[52:55], v[196:199], v[172:175], v[52:55]
	v_mfma_f32_16x16x32_bf16 v[48:51], v[196:199], v[180:183], v[48:51]
	v_mfma_f32_16x16x32_bf16 v[44:47], v[204:207], v[172:175], v[44:47]
	v_mfma_f32_16x16x32_bf16 v[40:43], v[204:207], v[180:183], v[40:43]
	v_mfma_f32_16x16x32_bf16 v[36:39], v[212:215], v[172:175], v[36:39]
	v_mfma_f32_16x16x32_bf16 v[32:35], v[212:215], v[180:183], v[32:35]
	v_mfma_f32_16x16x32_bf16 v[60:63], v[192:195], v[176:179], v[60:63]
	v_mfma_f32_16x16x32_bf16 v[56:59], v[192:195], v[184:187], v[56:59]
	v_mfma_f32_16x16x32_bf16 v[52:55], v[200:203], v[176:179], v[52:55]
	v_mfma_f32_16x16x32_bf16 v[48:51], v[200:203], v[184:187], v[48:51]
	v_mfma_f32_16x16x32_bf16 v[44:47], v[208:211], v[176:179], v[44:47]
	v_mfma_f32_16x16x32_bf16 v[40:43], v[208:211], v[184:187], v[40:43]
	v_mfma_f32_16x16x32_bf16 v[36:39], v[216:219], v[176:179], v[36:39]
	v_mfma_f32_16x16x32_bf16 v[32:35], v[216:219], v[184:187], v[32:35]
	s_barrier
	v_readfirstlane_b32 s63, v159
	v_add_u32_e32 v171, 0x2000, v159
	v_lshl_add_u64 v[172:173], v[240:241], 0, s[48:49]
	s_mov_b32 m0, s63
	v_readfirstlane_b32 s63, v171
	global_load_lds_dwordx4 v[172:173], off
	v_lshl_add_u64 v[172:173], v[242:243], 0, s[48:49]
	s_mov_b32 m0, s63
	s_nop 0
	global_load_lds_dwordx4 v[172:173], off
	s_waitcnt vmcnt(8)
	s_barrier
	v_mfma_f32_16x16x32_bf16 v[28:31], v[188:191], v[220:223], v[28:31]
	v_mfma_f32_16x16x32_bf16 v[24:27], v[188:191], v[228:231], v[24:27]
	v_mfma_f32_16x16x32_bf16 v[20:23], v[196:199], v[220:223], v[20:23]
	v_mfma_f32_16x16x32_bf16 v[16:19], v[196:199], v[228:231], v[16:19]
	v_mfma_f32_16x16x32_bf16 v[12:15], v[204:207], v[220:223], v[12:15]
	v_mfma_f32_16x16x32_bf16 v[8:11], v[204:207], v[228:231], v[8:11]
	v_mfma_f32_16x16x32_bf16 v[4:7], v[212:215], v[220:223], v[4:7]
	v_mfma_f32_16x16x32_bf16 v[0:3], v[212:215], v[228:231], v[0:3]
	v_mfma_f32_16x16x32_bf16 v[28:31], v[192:195], v[224:227], v[28:31]
	v_mfma_f32_16x16x32_bf16 v[24:27], v[192:195], v[232:235], v[24:27]
	v_mfma_f32_16x16x32_bf16 v[20:23], v[200:203], v[224:227], v[20:23]
	v_mfma_f32_16x16x32_bf16 v[16:19], v[200:203], v[232:235], v[16:19]
	v_mfma_f32_16x16x32_bf16 v[12:15], v[208:211], v[224:227], v[12:15]
	v_mfma_f32_16x16x32_bf16 v[8:11], v[208:211], v[232:235], v[8:11]
	v_mfma_f32_16x16x32_bf16 v[4:7], v[216:219], v[224:227], v[4:7]
	v_mfma_f32_16x16x32_bf16 v[0:3], v[216:219], v[232:235], v[0:3]
	s_add_i32 s62, s62, 2
	s_add_u32 s60, s60, 0x100
	s_addc_u32 s61, s61, 0
	s_cmp_gt_u32 s62, 27
	s_barrier
	s_cbranch_scc0 .LBB0_1147
	s_add_i32 s60, s58, 0x80
	s_mul_hi_i32 s61, s60, 0x1080
	s_mulk_i32 s60, 0x1080
	s_add_u32 s60, s69, s60
	s_addc_u32 s61, s70, s61
	v_lshl_add_u64 v[208:209], s[60:61], 0, v[128:129]
	v_readfirstlane_b32 s62, v169
	v_lshl_add_u64 v[208:209], v[208:209], 0, s[50:51]
	s_mov_b32 m0, s62
	ds_read_b128 v[134:137], v161
	ds_read_b128 v[138:141], v161 offset:1024
	ds_read_b128 v[156:159], v161 offset:2048
	ds_read_b128 v[172:175], v161 offset:3072
	ds_read_b128 v[176:179], v152
	ds_read_b128 v[180:183], v152 offset:1024
	ds_read_b128 v[184:187], v151
	ds_read_b128 v[188:191], v151 offset:1024
	ds_read_b128 v[192:195], v150
	ds_read_b128 v[196:199], v150 offset:1024
	ds_read_b128 v[200:203], v149
	ds_read_b128 v[204:207], v149 offset:1024
	global_load_lds_dwordx4 v[208:209], off
	v_lshl_add_u64 v[208:209], s[60:61], 0, v[132:133]
	v_readfirstlane_b32 s60, v170
	v_lshl_add_u64 v[208:209], v[208:209], 0, s[50:51]
	s_mov_b32 m0, s60
	s_nop 0
	global_load_lds_dwordx4 v[208:209], off
	s_barrier
	s_waitcnt lgkmcnt(0)
	s_waitcnt lgkmcnt(0)
	v_mfma_f32_16x16x32_bf16 v[124:127], v[176:179], v[134:137], v[124:127]
	v_mfma_f32_16x16x32_bf16 v[120:123], v[176:179], v[156:159], v[120:123]
	v_mfma_f32_16x16x32_bf16 v[116:119], v[184:187], v[134:137], v[116:119]
	v_mfma_f32_16x16x32_bf16 v[112:115], v[184:187], v[156:159], v[112:115]
	v_mfma_f32_16x16x32_bf16 v[108:111], v[192:195], v[134:137], v[108:111]
	v_mfma_f32_16x16x32_bf16 v[104:107], v[192:195], v[156:159], v[104:107]
	v_mfma_f32_16x16x32_bf16 v[100:103], v[200:203], v[134:137], v[100:103]
	v_mfma_f32_16x16x32_bf16 v[96:99], v[200:203], v[156:159], v[96:99]
	v_mfma_f32_16x16x32_bf16 v[124:127], v[180:183], v[138:141], v[124:127]
	v_mfma_f32_16x16x32_bf16 v[120:123], v[180:183], v[172:175], v[120:123]
	v_mfma_f32_16x16x32_bf16 v[116:119], v[188:191], v[138:141], v[116:119]
	v_mfma_f32_16x16x32_bf16 v[112:115], v[188:191], v[172:175], v[112:115]
	v_mfma_f32_16x16x32_bf16 v[108:111], v[196:199], v[138:141], v[108:111]
	v_mfma_f32_16x16x32_bf16 v[104:107], v[196:199], v[172:175], v[104:107]
	v_mfma_f32_16x16x32_bf16 v[100:103], v[204:207], v[138:141], v[100:103]
	v_mfma_f32_16x16x32_bf16 v[96:99], v[204:207], v[172:175], v[96:99]
	s_barrier
	ds_read_b128 v[208:211], v160
	ds_read_b128 v[212:215], v160 offset:1024
	ds_read_b128 v[216:219], v160 offset:2048
	ds_read_b128 v[220:223], v160 offset:3072
	s_waitcnt vmcnt(8)
	s_barrier
; #define LDA(dst, b, h) for (int m = 0; m < 4; ++m) for (int k = 0; k < 2; ++k) \
;     dst[m][k] = *reinterpret_cast<const bf16x8*>((char*)SA(b, h) + lds_byte(wr * 64 + m * 16 + fr, k * 32 + fq * 8))
; #define LDB(dst, b, h) for (int n = 0; n < 2; ++n) for (int k = 0; k < 2; ++k) \
;     dst[n][k] = *reinterpret_cast<const bf16x8*>((char*)SB(b, h) + lds_byte(wc * 32 + n * 16 + fr, k * 32 + fq * 8))
; #define MMA(ai, bj, At_, Bt_) do { __builtin_amdgcn_s_setprio(1); \
;     for (int k = 0; k < 2; ++k) for (int m = 0; m < 4; ++m) for (int n = 0; n < 2; ++n) \
;       acc[ai][bj][m][n] = __builtin_amdgcn_mfma_f32_16x16x32_bf16(At_[m][k], Bt_[n][k], acc[ai][bj][m][n], 0, 0, 0); \
;     __builtin_amdgcn_s_setprio(0); } while (0)
; #define WAIT_V(n) asm volatile("s_waitcnt vmcnt(" #n ")" ::: "memory")
; #define WAIT_L(n) asm volatile("s_waitcnt lgkmcnt(" #n ")" ::: "memory")
; #define BAR __builtin_amdgcn_s_barrier()
; template <int EPI, int lda, int ldb, int N, int K>
; __device__ __forceinline__ void gemm_phase(const u16* __restrict__ A, const u16* __restrict__ Bt, const GemmEpi ep, int wv) {
;     ...
;       LDB(B1, 0, 1); BAR; WAIT_L(0); MMA(0, 1, At, B1); BAR;
;       LDA(At, 0, 1); WAIT_V(4); BAR; WAIT_L(0); MMA(1, 0, At, B0); MMA(1, 1, At, B1); BAR; }
;     { LDB(B0, 1, 0); LDA(At, 1, 0); WAIT_V(2); BAR; WAIT_L(0); MMA(0, 0, At, B0); BAR;
	s_waitcnt lgkmcnt(0)
	s_waitcnt lgkmcnt(0)
	v_mfma_f32_16x16x32_bf16 v[92:95], v[176:179], v[208:211], v[92:95]
	v_mfma_f32_16x16x32_bf16 v[88:91], v[176:179], v[216:219], v[88:91]
	v_mfma_f32_16x16x32_bf16 v[76:79], v[192:195], v[208:211], v[76:79]
	v_mfma_f32_16x16x32_bf16 v[72:75], v[192:195], v[216:219], v[72:75]
	v_mfma_f32_16x16x32_bf16 v[84:87], v[184:187], v[208:211], v[84:87]
	v_mfma_f32_16x16x32_bf16 v[80:83], v[184:187], v[216:219], v[80:83]
	v_mfma_f32_16x16x32_bf16 v[68:71], v[200:203], v[208:211], v[68:71]
	v_mfma_f32_16x16x32_bf16 v[64:67], v[200:203], v[216:219], v[64:67]
	v_mfma_f32_16x16x32_bf16 v[92:95], v[180:183], v[212:215], v[92:95]
	v_mfma_f32_16x16x32_bf16 v[88:91], v[180:183], v[220:223], v[88:91]
	v_mfma_f32_16x16x32_bf16 v[76:79], v[196:199], v[212:215], v[76:79]
	v_mfma_f32_16x16x32_bf16 v[72:75], v[196:199], v[220:223], v[72:75]
	v_mfma_f32_16x16x32_bf16 v[176:179], v[188:191], v[212:215], v[84:87]
	v_mfma_f32_16x16x32_bf16 v[180:183], v[188:191], v[220:223], v[80:83]
	v_mfma_f32_16x16x32_bf16 v[184:187], v[204:207], v[212:215], v[68:71]
	v_mfma_f32_16x16x32_bf16 v[188:191], v[204:207], v[220:223], v[64:67]
	s_barrier
	s_nop 0
	ds_read_b128 v[64:67], v152 offset:16384
	ds_read_b128 v[68:71], v152 offset:17408
	ds_read_b128 v[80:83], v151 offset:16384
	ds_read_b128 v[84:87], v151 offset:17408
	ds_read_b128 v[192:195], v150 offset:16384
	ds_read_b128 v[196:199], v150 offset:17408
	ds_read_b128 v[200:203], v149 offset:16384
	ds_read_b128 v[204:207], v149 offset:17408
	s_waitcnt vmcnt(4)
	s_barrier
	s_waitcnt lgkmcnt(0)
	s_waitcnt lgkmcnt(0)
	v_mfma_f32_16x16x32_bf16 v[60:63], v[64:67], v[134:137], v[60:63]
	v_mfma_f32_16x16x32_bf16 v[56:59], v[64:67], v[156:159], v[56:59]
	v_mfma_f32_16x16x32_bf16 v[52:55], v[80:83], v[134:137], v[52:55]
	v_mfma_f32_16x16x32_bf16 v[48:51], v[80:83], v[156:159], v[48:51]
	v_mfma_f32_16x16x32_bf16 v[44:47], v[192:195], v[134:137], v[44:47]
	v_mfma_f32_16x16x32_bf16 v[40:43], v[192:195], v[156:159], v[40:43]
	v_mfma_f32_16x16x32_bf16 v[36:39], v[200:203], v[134:137], v[36:39]
	v_mfma_f32_16x16x32_bf16 v[32:35], v[200:203], v[156:159], v[32:35]
	v_mfma_f32_16x16x32_bf16 v[60:63], v[68:71], v[138:141], v[60:63]
	v_mfma_f32_16x16x32_bf16 v[56:59], v[68:71], v[172:175], v[56:59]
	v_mfma_f32_16x16x32_bf16 v[52:55], v[84:87], v[138:141], v[52:55]
	v_mfma_f32_16x16x32_bf16 v[48:51], v[84:87], v[172:175], v[48:51]
	v_mfma_f32_16x16x32_bf16 v[44:47], v[196:199], v[138:141], v[44:47]
	v_mfma_f32_16x16x32_bf16 v[40:43], v[196:199], v[172:175], v[40:43]
	v_mfma_f32_16x16x32_bf16 v[36:39], v[204:207], v[138:141], v[36:39]
	v_mfma_f32_16x16x32_bf16 v[32:35], v[204:207], v[172:175], v[32:35]
	v_mfma_f32_16x16x32_bf16 v[28:31], v[64:67], v[208:211], v[28:31]
	v_mfma_f32_16x16x32_bf16 v[24:27], v[64:67], v[216:219], v[24:27]
	v_mfma_f32_16x16x32_bf16 v[12:15], v[192:195], v[208:211], v[12:15]
	v_mfma_f32_16x16x32_bf16 v[8:11], v[192:195], v[216:219], v[8:11]
	v_mfma_f32_16x16x32_bf16 v[20:23], v[80:83], v[208:211], v[20:23]
	v_mfma_f32_16x16x32_bf16 v[16:19], v[80:83], v[216:219], v[16:19]
	v_mfma_f32_16x16x32_bf16 v[4:7], v[200:203], v[208:211], v[4:7]
	v_mfma_f32_16x16x32_bf16 v[0:3], v[200:203], v[216:219], v[0:3]
	v_mfma_f32_16x16x32_bf16 v[28:31], v[68:71], v[212:215], v[28:31]
	v_mfma_f32_16x16x32_bf16 v[24:27], v[68:71], v[220:223], v[24:27]
	v_mfma_f32_16x16x32_bf16 v[12:15], v[196:199], v[212:215], v[12:15]
	v_mfma_f32_16x16x32_bf16 v[8:11], v[196:199], v[220:223], v[8:11]
	v_mfma_f32_16x16x32_bf16 v[134:137], v[84:87], v[212:215], v[20:23]
	v_mfma_f32_16x16x32_bf16 v[138:141], v[84:87], v[220:223], v[16:19]
	v_mfma_f32_16x16x32_bf16 v[156:159], v[204:207], v[212:215], v[4:7]
	v_mfma_f32_16x16x32_bf16 v[170:173], v[204:207], v[220:223], v[0:3]
	s_barrier
	s_nop 0
	ds_read_b128 v[0:3], v155
	ds_read_b128 v[4:7], v155 offset:1024
	ds_read_b128 v[16:19], v155 offset:2048
	ds_read_b128 v[192:195], v155 offset:3072
	ds_read_b128 v[20:23], v152 offset:32768
	ds_read_b128 v[196:199], v152 offset:33792
	ds_read_b128 v[200:203], v151 offset:32768
	ds_read_b128 v[204:207], v151 offset:33792
	ds_read_b128 v[208:211], v150 offset:32768
	ds_read_b128 v[212:215], v150 offset:33792
	ds_read_b128 v[216:219], v149 offset:32768
	ds_read_b128 v[220:223], v149 offset:33792
	s_waitcnt vmcnt(2)
	s_barrier
; #define LDA(dst, b, h) for (int m = 0; m < 4; ++m) for (int k = 0; k < 2; ++k) \
;     dst[m][k] = *reinterpret_cast<const bf16x8*>((char*)SA(b, h) + lds_byte(wr * 64 + m * 16 + fr, k * 32 + fq * 8))
; #define LDB(dst, b, h) for (int n = 0; n < 2; ++n) for (int k = 0; k < 2; ++k) \
;     dst[n][k] = *reinterpret_cast<const bf16x8*>((char*)SB(b, h) + lds_byte(wc * 32 + n * 16 + fr, k * 32 + fq * 8))
; #define MMA(ai, bj, At_, Bt_) do { __builtin_amdgcn_s_setprio(1); \
;     for (int k = 0; k < 2; ++k) for (int m = 0; m < 4; ++m) for (int n = 0; n < 2; ++n) \
;       acc[ai][bj][m][n] = __builtin_amdgcn_mfma_f32_16x16x32_bf16(At_[m][k], Bt_[n][k], acc[ai][bj][m][n], 0, 0, 0); \
;     __builtin_amdgcn_s_setprio(0); } while (0)
; #define WAIT_V(n) asm volatile("s_waitcnt vmcnt(" #n ")" ::: "memory")
; #define WAIT_L(n) asm volatile("s_waitcnt lgkmcnt(" #n ")" ::: "memory")
; #define BAR __builtin_amdgcn_s_barrier()
; template <int EPI, int lda, int ldb, int N, int K>
; __device__ __forceinline__ void gemm_phase(const u16* __restrict__ A, const u16* __restrict__ Bt, const GemmEpi ep, int wv) {
;     ...
;     { LDB(B0, 1, 0); LDA(At, 1, 0); WAIT_V(2); BAR; WAIT_L(0); MMA(0, 0, At, B0); BAR;
;       LDB(B1, 1, 1); WAIT_V(0); BAR; WAIT_L(0); MMA(0, 1, At, B1); BAR;
;       LDA(At, 1, 1); BAR; WAIT_L(0); MMA(1, 0, At, B0); MMA(1, 1, At, B1); BAR; }
;     if (wr == 0) BAR;
	s_waitcnt lgkmcnt(0)
	s_waitcnt lgkmcnt(0)
	v_mfma_f32_16x16x32_bf16 v[64:67], v[20:23], v[0:3], v[124:127]
	v_mfma_f32_16x16x32_bf16 v[68:71], v[20:23], v[16:19], v[120:123]
	v_mfma_f32_16x16x32_bf16 v[80:83], v[200:203], v[0:3], v[116:119]
	v_mfma_f32_16x16x32_bf16 v[84:87], v[200:203], v[16:19], v[112:115]
	v_mfma_f32_16x16x32_bf16 v[108:111], v[208:211], v[0:3], v[108:111]
	v_mfma_f32_16x16x32_bf16 v[104:107], v[208:211], v[16:19], v[104:107]
	v_mfma_f32_16x16x32_bf16 v[120:123], v[216:219], v[0:3], v[100:103]
	v_mfma_f32_16x16x32_bf16 v[124:127], v[216:219], v[16:19], v[96:99]
	v_mfma_f32_16x16x32_bf16 v[116:119], v[196:199], v[4:7], v[64:67]
	v_mfma_f32_16x16x32_bf16 v[112:115], v[196:199], v[192:195], v[68:71]
	v_mfma_f32_16x16x32_bf16 v[100:103], v[204:207], v[4:7], v[80:83]
	v_mfma_f32_16x16x32_bf16 v[96:99], v[204:207], v[192:195], v[84:87]
	v_mfma_f32_16x16x32_bf16 v[84:87], v[212:215], v[4:7], v[108:111]
	v_mfma_f32_16x16x32_bf16 v[80:83], v[212:215], v[192:195], v[104:107]
	v_mfma_f32_16x16x32_bf16 v[68:71], v[220:223], v[4:7], v[120:123]
	v_mfma_f32_16x16x32_bf16 v[64:67], v[220:223], v[192:195], v[124:127]
	s_barrier
	ds_read_b128 v[224:227], v153
	ds_read_b128 v[228:231], v153 offset:1024
	ds_read_b128 v[232:235], v153 offset:2048
	ds_read_b128 v[236:239], v153 offset:3072
	s_waitcnt vmcnt(0)
	s_barrier
	s_waitcnt lgkmcnt(0)
	s_waitcnt lgkmcnt(0)
	v_mfma_f32_16x16x32_bf16 v[92:95], v[20:23], v[224:227], v[92:95]
	v_mfma_f32_16x16x32_bf16 v[20:23], v[20:23], v[232:235], v[88:91]
	v_mfma_f32_16x16x32_bf16 v[88:91], v[200:203], v[224:227], v[176:179]
	v_mfma_f32_16x16x32_bf16 v[104:107], v[200:203], v[232:235], v[180:183]
	v_mfma_f32_16x16x32_bf16 v[76:79], v[208:211], v[224:227], v[76:79]
	v_mfma_f32_16x16x32_bf16 v[72:75], v[208:211], v[232:235], v[72:75]
	v_mfma_f32_16x16x32_bf16 v[174:177], v[216:219], v[224:227], v[184:187]
	v_mfma_f32_16x16x32_bf16 v[178:181], v[216:219], v[232:235], v[188:191]
	v_mfma_f32_16x16x32_bf16 v[124:127], v[196:199], v[228:231], v[92:95]
	v_mfma_f32_16x16x32_bf16 v[120:123], v[196:199], v[236:239], v[20:23]
	v_mfma_f32_16x16x32_bf16 v[108:111], v[204:207], v[228:231], v[88:91]
	v_mfma_f32_16x16x32_bf16 v[104:107], v[204:207], v[236:239], v[104:107]
	v_mfma_f32_16x16x32_bf16 v[92:95], v[212:215], v[228:231], v[76:79]
	v_mfma_f32_16x16x32_bf16 v[88:91], v[212:215], v[236:239], v[72:75]
	v_mfma_f32_16x16x32_bf16 v[76:79], v[220:223], v[228:231], v[174:177]
	v_mfma_f32_16x16x32_bf16 v[72:75], v[220:223], v[236:239], v[178:181]
	s_barrier
	ds_read_b128 v[174:177], v152 offset:49152
	ds_read_b128 v[152:155], v152 offset:50176
	ds_read_b128 v[178:181], v151 offset:49152
	ds_read_b128 v[182:185], v151 offset:50176
	ds_read_b128 v[186:189], v150 offset:49152
	ds_read_b128 v[196:199], v150 offset:50176
	ds_read_b128 v[200:203], v149 offset:49152
	ds_read_b128 v[204:207], v149 offset:50176
	s_barrier
	s_waitcnt lgkmcnt(0)
	s_waitcnt lgkmcnt(0)
	v_mfma_f32_16x16x32_bf16 v[20:23], v[174:177], v[0:3], v[60:63]
	v_mfma_f32_16x16x32_bf16 v[56:59], v[174:177], v[16:19], v[56:59]
	v_mfma_f32_16x16x32_bf16 v[60:63], v[178:181], v[0:3], v[52:55]
	v_mfma_f32_16x16x32_bf16 v[208:211], v[178:181], v[16:19], v[48:51]
	v_mfma_f32_16x16x32_bf16 v[44:47], v[186:189], v[0:3], v[44:47]
	v_mfma_f32_16x16x32_bf16 v[40:43], v[186:189], v[16:19], v[40:43]
	v_mfma_f32_16x16x32_bf16 v[0:3], v[200:203], v[0:3], v[36:39]
	v_mfma_f32_16x16x32_bf16 v[212:215], v[200:203], v[16:19], v[32:35]
	v_mfma_f32_16x16x32_bf16 v[52:55], v[152:155], v[4:7], v[20:23]
	v_mfma_f32_16x16x32_bf16 v[48:51], v[152:155], v[192:195], v[56:59]
	v_mfma_f32_16x16x32_bf16 v[36:39], v[182:185], v[4:7], v[60:63]
	v_mfma_f32_16x16x32_bf16 v[32:35], v[182:185], v[192:195], v[208:211]
	v_mfma_f32_16x16x32_bf16 v[20:23], v[196:199], v[4:7], v[44:47]
	v_mfma_f32_16x16x32_bf16 v[16:19], v[196:199], v[192:195], v[40:43]
	v_mfma_f32_16x16x32_bf16 v[4:7], v[204:207], v[4:7], v[0:3]
	v_mfma_f32_16x16x32_bf16 v[0:3], v[204:207], v[192:195], v[212:215]
	v_mfma_f32_16x16x32_bf16 v[28:31], v[174:177], v[224:227], v[28:31]
	v_mfma_f32_16x16x32_bf16 v[24:27], v[174:177], v[232:235], v[24:27]
	v_mfma_f32_16x16x32_bf16 v[40:43], v[178:181], v[224:227], v[134:137]
	v_mfma_f32_16x16x32_bf16 v[134:137], v[178:181], v[232:235], v[138:141]
	v_mfma_f32_16x16x32_bf16 v[12:15], v[186:189], v[224:227], v[12:15]
	v_mfma_f32_16x16x32_bf16 v[8:11], v[186:189], v[232:235], v[8:11]
	v_mfma_f32_16x16x32_bf16 v[138:141], v[200:203], v[224:227], v[156:159]
	v_mfma_f32_16x16x32_bf16 v[156:159], v[200:203], v[232:235], v[170:173]
	v_mfma_f32_16x16x32_bf16 v[60:63], v[152:155], v[228:231], v[28:31]
	v_mfma_f32_16x16x32_bf16 v[56:59], v[152:155], v[236:239], v[24:27]
	v_mfma_f32_16x16x32_bf16 v[44:47], v[182:185], v[228:231], v[40:43]
	v_mfma_f32_16x16x32_bf16 v[40:43], v[182:185], v[236:239], v[134:137]
	v_mfma_f32_16x16x32_bf16 v[28:31], v[196:199], v[228:231], v[12:15]
	v_mfma_f32_16x16x32_bf16 v[24:27], v[196:199], v[236:239], v[8:11]
	v_mfma_f32_16x16x32_bf16 v[12:15], v[204:207], v[228:231], v[138:141]
	v_mfma_f32_16x16x32_bf16 v[8:11], v[204:207], v[236:239], v[156:159]
	v_cmp_gt_u32_e32 vcc, s80, v130
	s_barrier
	s_and_saveexec_b64 s[60:61], vcc
	s_cbranch_execz .LBB0_1150
	s_barrier

; #define STAGE(P, BASE, LD, br, kt) do { const char* _g = (const char*)((BASE) + (size_t)(br) * (LD) + (size_t)(kt) * 64); \
;     for (int _i = 0; _i < 2; ++_i) { int _b = tidx * 16 + _i * 8192; int _r, _c; stage_rc(_b, _r, _c); \
;       __builtin_amdgcn_global_load_lds((const unsigned*)(_g + (unsigned)((_r * (LD) + _c) * 2)), (unsigned*)((char*)(P) + _b), 16, 0, 0); } } while (0)
; #define LDA(dst, b, h) for (int m = 0; m < 4; ++m) for (int k = 0; k < 2; ++k) \
;     dst[m][k] = *reinterpret_cast<const bf16x8*>((char*)SA(b, h) + lds_byte(wr * 64 + m * 16 + fr, k * 32 + fq * 8))
; #define LDB(dst, b, h) for (int n = 0; n < 2; ++n) for (int k = 0; k < 2; ++k) \
;     dst[n][k] = *reinterpret_cast<const bf16x8*>((char*)SB(b, h) + lds_byte(wc * 32 + n * 16 + fr, k * 32 + fq * 8))
; #define MMA(ai, bj, At_, Bt_) do { __builtin_amdgcn_s_setprio(1); \
;     for (int k = 0; k < 2; ++k) for (int m = 0; m < 4; ++m) for (int n = 0; n < 2; ++n) \
;       acc[ai][bj][m][n] = __builtin_amdgcn_mfma_f32_16x16x32_bf16(At_[m][k], Bt_[n][k], acc[ai][bj][m][n], 0, 0, 0); \
;     __builtin_amdgcn_s_setprio(0); } while (0)
; #define WAIT_V(n) asm volatile("s_waitcnt vmcnt(" #n ")" ::: "memory")
; #define WAIT_L(n) asm volatile("s_waitcnt lgkmcnt(" #n ")" ::: "memory")
; #define BAR __builtin_amdgcn_s_barrier()
; #define SCHED __builtin_amdgcn_sched_barrier(0)
; template <int EPI, int lda, int ldb, int N, int K>
; __device__ __forceinline__ void gemm_phase(const u16* __restrict__ A, const u16* __restrict__ Bt, const GemmEpi ep, int wv) {
;     ...
;     const int wid = tidx >> 6, lane = tidx & 63, wr = wid >> 2, wc = wid & 3, fr = lane & 15, fq = lane >> 4;
;     const u16* Ab = A + (EPI == EPI_RG ? (pn >> 1) * 256 : 0);
;     f32x4 acc[2][2][4][2] = {};
;     bf16x8 At[4][2], B0[2][2], B1[2][2];
;     constexpr int nt = K / 64;
;     if (wr == 1) BAR;
;     WAIT_V(4); BAR;
;     STAGE(SB(1, 0), Bt, ldb, bcol, 1); STAGE(SA(1, 0), Ab, lda, brow, 1); STAGE(SB(1, 1), Bt, ldb, bcol + HALF, 1);
;     WAIT_V(6); BAR;
;     for (int t = 0; t < nt - 2; t += 2) {
;       LDB(B0, 0, 0); SCHED; LDA(At, 0, 0); STAGE(SA(1, 1), Ab, lda, brow + HALF, t + 1);
;       WAIT_L(8); BAR; WAIT_L(0); MMA(0, 0, At, B0); BAR; SCHED;
;       LDB(B1, 0, 1); STAGE(SB(0, 0), Bt, ldb, bcol, t + 2);
;       BAR; WAIT_L(0); MMA(0, 1, At, B1); BAR;
.LBB0_1248:
	s_or_b64 exec, exec, s[54:55]
	v_mov_b32_e32 v1, v129
	v_add_u32_e32 v7, s60, v6
	v_lshl_add_u64 v[12:13], s[46:47], 0, v[128:129]
	v_lshl_add_u64 v[14:15], s[46:47], 0, v[0:1]
	v_lshl_add_u64 v[2:3], s[52:53], 0, v[128:129]
	v_lshl_add_u64 v[0:1], s[52:53], 0, v[0:1]
	v_readfirstlane_b32 s53, v7
	v_add_u32_e32 v7, 0x2000, v7
	v_mov_b32_e32 v5, v129
	v_mov_b32_e32 v17, v129
	v_lshl_add_u64 v[26:27], v[12:13], 0, s[40:41]
	s_mov_b32 m0, s53
	v_readfirstlane_b32 s52, v7
	v_add_u32_e32 v7, 0x8000, v23
	v_lshl_add_u64 v[8:9], s[50:51], 0, v[4:5]
	v_lshl_add_u64 v[10:11], s[50:51], 0, v[16:17]
	s_waitcnt vmcnt(4)
	s_barrier
	global_load_lds_dwordx4 v[26:27], off
	v_lshl_add_u64 v[26:27], v[14:15], 0, s[40:41]
	s_mov_b32 m0, s52
	v_readfirstlane_b32 s51, v7
	v_add_u32_e32 v7, 0xa000, v23
	global_load_lds_dwordx4 v[26:27], off
	v_lshl_add_u64 v[26:27], v[8:9], 0, s[40:41]
	s_mov_b32 m0, s51
	v_readfirstlane_b32 s50, v7
	v_add_u32_e32 v25, s61, v6
	global_load_lds_dwordx4 v[26:27], off
	v_lshl_add_u64 v[26:27], v[10:11], 0, s[40:41]
	s_mov_b32 m0, s50
	v_readfirstlane_b32 s13, v25
	v_add_u32_e32 v25, 0x2000, v25
	global_load_lds_dwordx4 v[26:27], off
	v_lshl_add_u64 v[26:27], v[2:3], 0, s[40:41]
	s_mov_b32 m0, s13
	v_readfirstlane_b32 s11, v25
	global_load_lds_dwordx4 v[26:27], off
	v_lshl_add_u64 v[6:7], v[0:1], 0, s[40:41]
	s_mov_b32 m0, s11
	v_and_b32_e32 v132, 15, v20
	global_load_lds_dwordx4 v[6:7], off
	v_bfe_u32 v128, v20, 4, 2
	v_lshlrev_b32_e32 v7, 2, v20
	v_bfe_u32 v131, v130, 6, 2
	v_lshlrev_b32_e32 v25, 4, v128
	v_lshlrev_b32_e32 v6, 6, v132
	v_and_b32_e32 v50, 32, v7
	v_lshlrev_b32_e32 v126, 12, v131
	v_bitop3_b32 v127, v25, v50, v6 bitop3:0x36
	v_add3_u32 v133, s58, v127, v126
	s_waitcnt vmcnt(6)
	s_barrier
	ds_read_b128 v[26:29], v133
	ds_read_b128 v[30:33], v133 offset:1024
	ds_read_b128 v[34:37], v133 offset:2048
	ds_read_b128 v[38:41], v133 offset:3072
	v_lshl_add_u64 v[6:7], s[48:49], 0, v[4:5]
	v_lshl_add_u64 v[4:5], s[48:49], 0, v[16:17]
	v_lshlrev_b32_e32 v17, 6, v20
	v_and_b32_e32 v17, 0x3c0, v17
	v_add_u32_e32 v20, 0xc000, v23
	v_lshlrev_b32_e32 v16, 13, v143
	v_bitop3_b32 v17, v17, v50, v25 bitop3:0x36
	v_readfirstlane_b32 s47, v20
	v_add_u32_e32 v20, 0xe000, v23
	v_add3_u32 v228, 0, v127, v16
	v_add3_u32 v229, 0, v17, v16
	v_lshl_add_u64 v[16:17], v[6:7], 0, s[40:41]
	s_mov_b32 m0, s47
	v_readfirstlane_b32 s46, v20
	ds_read_b128 v[42:45], v228
	ds_read_b128 v[46:49], v228 offset:1024
	ds_read_b128 v[50:53], v229 offset:2048
	ds_read_b128 v[54:57], v229 offset:3072
	ds_read_b128 v[58:61], v229 offset:4096
	ds_read_b128 v[62:65], v229 offset:5120
	ds_read_b128 v[66:69], v229 offset:6144
	ds_read_b128 v[70:73], v229 offset:7168
	global_load_lds_dwordx4 v[16:17], off
	v_lshl_add_u64 v[16:17], v[4:5], 0, s[40:41]
	s_mov_b32 m0, s46
	s_nop 0
	global_load_lds_dwordx4 v[16:17], off
	s_waitcnt lgkmcnt(8)
	s_barrier
	s_waitcnt lgkmcnt(0)
	s_waitcnt lgkmcnt(0)
	v_mfma_f32_16x16x32_bf16 v[74:77], v[42:45], v[26:29], 0
	v_mfma_f32_16x16x32_bf16 v[78:81], v[42:45], v[34:37], 0
	v_mfma_f32_16x16x32_bf16 v[82:85], v[50:53], v[26:29], 0
	v_mfma_f32_16x16x32_bf16 v[86:89], v[50:53], v[34:37], 0
	v_mfma_f32_16x16x32_bf16 v[90:93], v[58:61], v[26:29], 0
	v_mfma_f32_16x16x32_bf16 v[94:97], v[58:61], v[34:37], 0
	v_mfma_f32_16x16x32_bf16 v[98:101], v[66:69], v[26:29], 0
	v_mfma_f32_16x16x32_bf16 v[102:105], v[66:69], v[34:37], 0
	v_mfma_f32_16x16x32_bf16 v[74:77], v[46:49], v[30:33], v[74:77]
	v_mfma_f32_16x16x32_bf16 v[78:81], v[46:49], v[38:41], v[78:81]
	v_mfma_f32_16x16x32_bf16 v[82:85], v[54:57], v[30:33], v[82:85]
	v_mfma_f32_16x16x32_bf16 v[86:89], v[54:57], v[38:41], v[86:89]
	v_mfma_f32_16x16x32_bf16 v[90:93], v[62:65], v[30:33], v[90:93]
	v_mfma_f32_16x16x32_bf16 v[94:97], v[62:65], v[38:41], v[94:97]
	v_mfma_f32_16x16x32_bf16 v[98:101], v[70:73], v[30:33], v[98:101]
	v_mfma_f32_16x16x32_bf16 v[102:105], v[70:73], v[38:41], v[102:105]
	s_barrier
	v_readfirstlane_b32 s48, v21
	v_add_u32_e32 v20, 0x2000, v21
	v_add3_u32 v224, s59, v127, v126
	v_lshl_add_u64 v[16:17], v[12:13], 0, s[42:43]
	s_mov_b32 m0, s48
	v_readfirstlane_b32 s48, v20
	ds_read_b128 v[106:109], v224
	ds_read_b128 v[110:113], v224 offset:1024
	ds_read_b128 v[114:117], v224 offset:2048
	ds_read_b128 v[118:121], v224 offset:3072
	global_load_lds_dwordx4 v[16:17], off
	v_lshl_add_u64 v[16:17], v[14:15], 0, s[42:43]
	s_mov_b32 m0, s48
	s_nop 0
	global_load_lds_dwordx4 v[16:17], off
	s_waitcnt vmcnt(10)
	s_barrier
	s_waitcnt lgkmcnt(0)
	s_waitcnt lgkmcnt(0)
	v_mfma_f32_16x16x32_bf16 v[122:125], v[42:45], v[106:109], 0
	v_mfma_f32_16x16x32_bf16 v[42:45], v[42:45], v[114:117], 0
	v_mfma_f32_16x16x32_bf16 v[134:137], v[50:53], v[106:109], 0
	v_mfma_f32_16x16x32_bf16 v[50:53], v[50:53], v[114:117], 0
	v_mfma_f32_16x16x32_bf16 v[144:147], v[58:61], v[106:109], 0
	v_mfma_f32_16x16x32_bf16 v[58:61], v[58:61], v[114:117], 0
	v_mfma_f32_16x16x32_bf16 v[148:151], v[66:69], v[106:109], 0
	v_mfma_f32_16x16x32_bf16 v[66:69], v[66:69], v[114:117], 0
	v_mfma_f32_16x16x32_bf16 v[122:125], v[46:49], v[110:113], v[122:125]
	v_mfma_f32_16x16x32_bf16 v[42:45], v[46:49], v[118:121], v[42:45]
	v_mfma_f32_16x16x32_bf16 v[46:49], v[54:57], v[110:113], v[134:137]
	v_mfma_f32_16x16x32_bf16 v[50:53], v[54:57], v[118:121], v[50:53]
	v_mfma_f32_16x16x32_bf16 v[54:57], v[62:65], v[110:113], v[144:147]
	v_mfma_f32_16x16x32_bf16 v[58:61], v[62:65], v[118:121], v[58:61]
	v_mfma_f32_16x16x32_bf16 v[62:65], v[70:73], v[110:113], v[148:151]
	v_mfma_f32_16x16x32_bf16 v[66:69], v[70:73], v[118:121], v[66:69]
	v_readfirstlane_b32 s48, v23
	v_lshl_add_u64 v[16:17], v[8:9], 0, s[42:43]
	s_mov_b32 m0, s48
	v_readfirstlane_b32 s48, v24
	s_barrier
; #define STAGE(P, BASE, LD, br, kt) do { const char* _g = (const char*)((BASE) + (size_t)(br) * (LD) + (size_t)(kt) * 64); \
;     for (int _i = 0; _i < 2; ++_i) { int _b = tidx * 16 + _i * 8192; int _r, _c; stage_rc(_b, _r, _c); \
;       __builtin_amdgcn_global_load_lds((const unsigned*)(_g + (unsigned)((_r * (LD) + _c) * 2)), (unsigned*)((char*)(P) + _b), 16, 0, 0); } } while (0)
; #define LDA(dst, b, h) for (int m = 0; m < 4; ++m) for (int k = 0; k < 2; ++k) \
;     dst[m][k] = *reinterpret_cast<const bf16x8*>((char*)SA(b, h) + lds_byte(wr * 64 + m * 16 + fr, k * 32 + fq * 8))
; #define LDB(dst, b, h) for (int n = 0; n < 2; ++n) for (int k = 0; k < 2; ++k) \
;     dst[n][k] = *reinterpret_cast<const bf16x8*>((char*)SB(b, h) + lds_byte(wc * 32 + n * 16 + fr, k * 32 + fq * 8))
; #define MMA(ai, bj, At_, Bt_) do { __builtin_amdgcn_s_setprio(1); \
;     for (int k = 0; k < 2; ++k) for (int m = 0; m < 4; ++m) for (int n = 0; n < 2; ++n) \
;       acc[ai][bj][m][n] = __builtin_amdgcn_mfma_f32_16x16x32_bf16(At_[m][k], Bt_[n][k], acc[ai][bj][m][n], 0, 0, 0); \
;     __builtin_amdgcn_s_setprio(0); } while (0)
; #define WAIT_V(n) asm volatile("s_waitcnt vmcnt(" #n ")" ::: "memory")
; #define WAIT_L(n) asm volatile("s_waitcnt lgkmcnt(" #n ")" ::: "memory")
; #define BAR __builtin_amdgcn_s_barrier()
; #define SCHED __builtin_amdgcn_sched_barrier(0)
; template <int EPI, int lda, int ldb, int N, int K>
; __device__ __forceinline__ void gemm_phase(const u16* __restrict__ A, const u16* __restrict__ Bt, const GemmEpi ep, int wv) {
;     ...
;       LDA(At, 0, 1); STAGE(SA(0, 0), Ab, lda, brow, t + 2);
;       BAR; WAIT_L(0); MMA(1, 0, At, B0); BAR; SCHED;
;       STAGE(SB(0, 1), Bt, ldb, bcol + HALF, t + 2);
;       WAIT_V(6); BAR; MMA(1, 1, At, B1); BAR;
;       LDB(B0, 1, 0); SCHED; LDA(At, 1, 0); STAGE(SA(0, 1), Ab, lda, brow + HALF, t + 2);
;       WAIT_L(8); BAR; WAIT_L(0); MMA(0, 0, At, B0); BAR; SCHED;
;       LDB(B1, 1, 1); STAGE(SB(1, 0), Bt, ldb, bcol, t + 3);
	ds_read_b128 v[70:73], v228 offset:16384
	ds_read_b128 v[134:137], v228 offset:17408
	ds_read_b128 v[144:147], v229 offset:18432
	ds_read_b128 v[148:151], v229 offset:19456
	ds_read_b128 v[152:155], v229 offset:20480
	ds_read_b128 v[156:159], v229 offset:21504
	ds_read_b128 v[160:163], v229 offset:22528
	ds_read_b128 v[164:167], v229 offset:23552
	global_load_lds_dwordx4 v[16:17], off
	v_lshl_add_u64 v[16:17], v[10:11], 0, s[42:43]
	s_mov_b32 m0, s48
	s_nop 0
	global_load_lds_dwordx4 v[16:17], off
	s_barrier
	s_waitcnt lgkmcnt(0)
	s_waitcnt lgkmcnt(0)
	v_mfma_f32_16x16x32_bf16 v[168:171], v[70:73], v[26:29], 0
	v_mfma_f32_16x16x32_bf16 v[172:175], v[70:73], v[34:37], 0
	v_mfma_f32_16x16x32_bf16 v[176:179], v[144:147], v[26:29], 0
	v_mfma_f32_16x16x32_bf16 v[180:183], v[144:147], v[34:37], 0
	v_mfma_f32_16x16x32_bf16 v[184:187], v[152:155], v[26:29], 0
	v_mfma_f32_16x16x32_bf16 v[188:191], v[152:155], v[34:37], 0
	v_mfma_f32_16x16x32_bf16 v[24:27], v[160:163], v[26:29], 0
	v_mfma_f32_16x16x32_bf16 v[34:37], v[160:163], v[34:37], 0
	v_mfma_f32_16x16x32_bf16 v[168:171], v[134:137], v[30:33], v[168:171]
	v_mfma_f32_16x16x32_bf16 v[176:179], v[148:151], v[30:33], v[176:179]
	v_mfma_f32_16x16x32_bf16 v[184:187], v[156:159], v[30:33], v[184:187]
	v_mfma_f32_16x16x32_bf16 v[24:27], v[164:167], v[30:33], v[24:27]
	v_mfma_f32_16x16x32_bf16 v[28:31], v[164:167], v[38:41], v[34:37]
	v_mfma_f32_16x16x32_bf16 v[172:175], v[134:137], v[38:41], v[172:175]
	v_mfma_f32_16x16x32_bf16 v[180:183], v[148:151], v[38:41], v[180:183]
	v_mfma_f32_16x16x32_bf16 v[188:191], v[156:159], v[38:41], v[188:191]
	s_barrier
	v_readfirstlane_b32 s48, v22
	v_add_u32_e32 v20, 0x2000, v22
	v_lshl_add_u64 v[16:17], v[2:3], 0, s[42:43]
	s_mov_b32 m0, s48
	v_readfirstlane_b32 s48, v20
	global_load_lds_dwordx4 v[16:17], off
	v_lshl_add_u64 v[16:17], v[0:1], 0, s[42:43]
	s_mov_b32 m0, s48
	s_nop 0
	global_load_lds_dwordx4 v[16:17], off
	s_waitcnt vmcnt(8)
	s_barrier
	v_mfma_f32_16x16x32_bf16 v[20:23], v[70:73], v[106:109], 0
	v_mfma_f32_16x16x32_bf16 v[32:35], v[70:73], v[114:117], 0
	v_mfma_f32_16x16x32_bf16 v[36:39], v[144:147], v[106:109], 0
	v_mfma_f32_16x16x32_bf16 v[70:73], v[144:147], v[114:117], 0
	v_mfma_f32_16x16x32_bf16 v[144:147], v[152:155], v[106:109], 0
	v_mfma_f32_16x16x32_bf16 v[152:155], v[152:155], v[114:117], 0
	v_mfma_f32_16x16x32_bf16 v[106:109], v[160:163], v[106:109], 0
	v_mfma_f32_16x16x32_bf16 v[114:117], v[160:163], v[114:117], 0
	v_mfma_f32_16x16x32_bf16 v[20:23], v[134:137], v[110:113], v[20:23]
	v_mfma_f32_16x16x32_bf16 v[32:35], v[134:137], v[118:121], v[32:35]
	v_mfma_f32_16x16x32_bf16 v[36:39], v[148:151], v[110:113], v[36:39]
	v_mfma_f32_16x16x32_bf16 v[70:73], v[148:151], v[118:121], v[70:73]
	v_mfma_f32_16x16x32_bf16 v[134:137], v[156:159], v[110:113], v[144:147]
	v_mfma_f32_16x16x32_bf16 v[106:109], v[164:167], v[110:113], v[106:109]
	v_mfma_f32_16x16x32_bf16 v[110:113], v[164:167], v[118:121], v[114:117]
	v_mfma_f32_16x16x32_bf16 v[144:147], v[156:159], v[118:121], v[152:155]
	v_add3_u32 v225, s60, v127, v126
	s_barrier
	ds_read_b128 v[114:117], v225
	ds_read_b128 v[118:121], v225 offset:1024
	ds_read_b128 v[148:151], v225 offset:2048
	ds_read_b128 v[152:155], v225 offset:3072
	v_readfirstlane_b32 s48, v18
	v_lshl_add_u64 v[16:17], v[6:7], 0, s[42:43]
	s_mov_b32 m0, s48
	v_readfirstlane_b32 s48, v19
	ds_read_b128 v[156:159], v228 offset:32768
	ds_read_b128 v[160:163], v228 offset:33792
	ds_read_b128 v[164:167], v229 offset:34816
	ds_read_b128 v[192:195], v229 offset:35840
	ds_read_b128 v[196:199], v229 offset:36864
	ds_read_b128 v[200:203], v229 offset:37888
	ds_read_b128 v[204:207], v229 offset:38912
	ds_read_b128 v[208:211], v229 offset:39936
	global_load_lds_dwordx4 v[16:17], off
	v_lshl_add_u64 v[16:17], v[4:5], 0, s[42:43]
	s_mov_b32 m0, s48
	s_nop 0
	global_load_lds_dwordx4 v[16:17], off
	s_waitcnt lgkmcnt(8)
	s_barrier
	s_waitcnt lgkmcnt(0)
	s_waitcnt lgkmcnt(0)
	v_mfma_f32_16x16x32_bf16 v[16:19], v[156:159], v[114:117], v[74:77]
	v_mfma_f32_16x16x32_bf16 v[74:77], v[156:159], v[148:151], v[78:81]
	v_mfma_f32_16x16x32_bf16 v[78:81], v[164:167], v[114:117], v[82:85]
	v_mfma_f32_16x16x32_bf16 v[82:85], v[164:167], v[148:151], v[86:89]
	v_mfma_f32_16x16x32_bf16 v[86:89], v[196:199], v[114:117], v[90:93]
	v_mfma_f32_16x16x32_bf16 v[90:93], v[196:199], v[148:151], v[94:97]
	v_mfma_f32_16x16x32_bf16 v[94:97], v[204:207], v[114:117], v[98:101]
	v_mfma_f32_16x16x32_bf16 v[98:101], v[204:207], v[148:151], v[102:105]
	v_mfma_f32_16x16x32_bf16 v[16:19], v[160:163], v[118:121], v[16:19]
	v_mfma_f32_16x16x32_bf16 v[74:77], v[160:163], v[152:155], v[74:77]
	v_mfma_f32_16x16x32_bf16 v[78:81], v[192:195], v[118:121], v[78:81]
	v_mfma_f32_16x16x32_bf16 v[82:85], v[192:195], v[152:155], v[82:85]
	v_mfma_f32_16x16x32_bf16 v[86:89], v[200:203], v[118:121], v[86:89]
	v_mfma_f32_16x16x32_bf16 v[90:93], v[200:203], v[152:155], v[90:93]
	v_mfma_f32_16x16x32_bf16 v[94:97], v[208:211], v[118:121], v[94:97]
	v_mfma_f32_16x16x32_bf16 v[98:101], v[208:211], v[152:155], v[98:101]
	s_barrier
	s_mov_b32 m0, s53
	v_add3_u32 v226, s61, v127, v126
	v_lshl_add_u64 v[12:13], v[12:13], 0, s[44:45]
	ds_read_b128 v[102:105], v226
	ds_read_b128 v[212:215], v226 offset:1024
	ds_read_b128 v[216:219], v226 offset:2048
	ds_read_b128 v[220:223], v226 offset:3072
	global_load_lds_dwordx4 v[12:13], off
	v_lshl_add_u64 v[12:13], v[14:15], 0, s[44:45]
	s_mov_b32 m0, s52
	s_nop 0
	global_load_lds_dwordx4 v[12:13], off
	s_waitcnt vmcnt(10)
	s_barrier
; #define STAGE(P, BASE, LD, br, kt) do { const char* _g = (const char*)((BASE) + (size_t)(br) * (LD) + (size_t)(kt) * 64); \
;     for (int _i = 0; _i < 2; ++_i) { int _b = tidx * 16 + _i * 8192; int _r, _c; stage_rc(_b, _r, _c); \
;       __builtin_amdgcn_global_load_lds((const unsigned*)(_g + (unsigned)((_r * (LD) + _c) * 2)), (unsigned*)((char*)(P) + _b), 16, 0, 0); } } while (0)
; #define LDA(dst, b, h) for (int m = 0; m < 4; ++m) for (int k = 0; k < 2; ++k) \
;     dst[m][k] = *reinterpret_cast<const bf16x8*>((char*)SA(b, h) + lds_byte(wr * 64 + m * 16 + fr, k * 32 + fq * 8))
; #define LDB(dst, b, h) for (int n = 0; n < 2; ++n) for (int k = 0; k < 2; ++k) \
;     dst[n][k] = *reinterpret_cast<const bf16x8*>((char*)SB(b, h) + lds_byte(wc * 32 + n * 16 + fr, k * 32 + fq * 8))
; #define MMA(ai, bj, At_, Bt_) do { __builtin_amdgcn_s_setprio(1); \
;     for (int k = 0; k < 2; ++k) for (int m = 0; m < 4; ++m) for (int n = 0; n < 2; ++n) \
;       acc[ai][bj][m][n] = __builtin_amdgcn_mfma_f32_16x16x32_bf16(At_[m][k], Bt_[n][k], acc[ai][bj][m][n], 0, 0, 0); \
;     __builtin_amdgcn_s_setprio(0); } while (0)
; #define WAIT_V(n) asm volatile("s_waitcnt vmcnt(" #n ")" ::: "memory")
; #define WAIT_L(n) asm volatile("s_waitcnt lgkmcnt(" #n ")" ::: "memory")
; #define BAR __builtin_amdgcn_s_barrier()
; #define SCHED __builtin_amdgcn_sched_barrier(0)
; template <int EPI, int lda, int ldb, int N, int K>
; __device__ __forceinline__ void gemm_phase(const u16* __restrict__ A, const u16* __restrict__ Bt, const GemmEpi ep, int wv) {
;     ...
;       BAR; WAIT_L(0); MMA(0, 1, At, B1); BAR;
;       LDA(At, 1, 1); STAGE(SA(1, 0), Ab, lda, brow, t + 3);
;       BAR; WAIT_L(0); MMA(1, 0, At, B0); BAR; SCHED;
;       STAGE(SB(1, 1), Bt, ldb, bcol + HALF, t + 3);
;       WAIT_V(6); BAR; MMA(1, 1, At, B1); BAR;
;     }
;     { LDB(B0, 0, 0); LDA(At, 0, 0); STAGE(SA(1, 1), Ab, lda, brow + HALF, nt - 1);
;       BAR; WAIT_L(0); MMA(0, 0, At, B0); BAR;
	s_waitcnt lgkmcnt(0)
	s_waitcnt lgkmcnt(0)
	v_mfma_f32_16x16x32_bf16 v[12:15], v[156:159], v[102:105], v[122:125]
	v_mfma_f32_16x16x32_bf16 v[40:43], v[156:159], v[216:219], v[42:45]
	v_mfma_f32_16x16x32_bf16 v[44:47], v[164:167], v[102:105], v[46:49]
	v_mfma_f32_16x16x32_bf16 v[48:51], v[164:167], v[216:219], v[50:53]
	v_mfma_f32_16x16x32_bf16 v[52:55], v[196:199], v[102:105], v[54:57]
	v_mfma_f32_16x16x32_bf16 v[56:59], v[196:199], v[216:219], v[58:61]
	v_mfma_f32_16x16x32_bf16 v[60:63], v[204:207], v[102:105], v[62:65]
	v_mfma_f32_16x16x32_bf16 v[64:67], v[204:207], v[216:219], v[66:69]
	v_mfma_f32_16x16x32_bf16 v[12:15], v[160:163], v[212:215], v[12:15]
	v_mfma_f32_16x16x32_bf16 v[40:43], v[160:163], v[220:223], v[40:43]
	v_mfma_f32_16x16x32_bf16 v[44:47], v[192:195], v[212:215], v[44:47]
	v_mfma_f32_16x16x32_bf16 v[48:51], v[192:195], v[220:223], v[48:51]
	v_mfma_f32_16x16x32_bf16 v[52:55], v[200:203], v[212:215], v[52:55]
	v_mfma_f32_16x16x32_bf16 v[56:59], v[200:203], v[220:223], v[56:59]
	v_mfma_f32_16x16x32_bf16 v[60:63], v[208:211], v[212:215], v[60:63]
	v_mfma_f32_16x16x32_bf16 v[64:67], v[208:211], v[220:223], v[64:67]
	s_mov_b32 m0, s51
	v_lshl_add_u64 v[8:9], v[8:9], 0, s[44:45]
	s_barrier
	ds_read_b128 v[122:125], v228 offset:49152
	ds_read_b128 v[156:159], v228 offset:50176
	ds_read_b128 v[160:163], v229 offset:51200
	ds_read_b128 v[164:167], v229 offset:52224
	ds_read_b128 v[192:195], v229 offset:53248
	ds_read_b128 v[196:199], v229 offset:54272
	ds_read_b128 v[200:203], v229 offset:55296
	ds_read_b128 v[204:207], v229 offset:56320
	global_load_lds_dwordx4 v[8:9], off
	v_lshl_add_u64 v[8:9], v[10:11], 0, s[44:45]
	s_mov_b32 m0, s50
	s_nop 0
	global_load_lds_dwordx4 v[8:9], off
	s_barrier
	s_waitcnt lgkmcnt(0)
	s_waitcnt lgkmcnt(0)
	v_mfma_f32_16x16x32_bf16 v[8:11], v[122:125], v[114:117], v[168:171]
	v_mfma_f32_16x16x32_bf16 v[168:171], v[122:125], v[148:151], v[172:175]
	v_mfma_f32_16x16x32_bf16 v[24:27], v[200:203], v[114:117], v[24:27]
	v_mfma_f32_16x16x32_bf16 v[28:31], v[200:203], v[148:151], v[28:31]
	v_mfma_f32_16x16x32_bf16 v[172:175], v[160:163], v[114:117], v[176:179]
	v_mfma_f32_16x16x32_bf16 v[176:179], v[160:163], v[148:151], v[180:183]
	v_mfma_f32_16x16x32_bf16 v[180:183], v[192:195], v[114:117], v[184:187]
	v_mfma_f32_16x16x32_bf16 v[184:187], v[192:195], v[148:151], v[188:191]
	v_mfma_f32_16x16x32_bf16 v[8:11], v[156:159], v[118:121], v[8:11]
	v_mfma_f32_16x16x32_bf16 v[114:117], v[156:159], v[152:155], v[168:171]
	v_mfma_f32_16x16x32_bf16 v[24:27], v[204:207], v[118:121], v[24:27]
	v_mfma_f32_16x16x32_bf16 v[28:31], v[204:207], v[152:155], v[28:31]
	v_mfma_f32_16x16x32_bf16 v[148:151], v[164:167], v[118:121], v[172:175]
	v_mfma_f32_16x16x32_bf16 v[168:171], v[164:167], v[152:155], v[176:179]
	v_mfma_f32_16x16x32_bf16 v[172:175], v[196:199], v[118:121], v[180:183]
	v_mfma_f32_16x16x32_bf16 v[176:179], v[196:199], v[152:155], v[184:187]
	s_barrier
	s_mov_b32 m0, s13
	v_lshl_add_u64 v[2:3], v[2:3], 0, s[44:45]
	global_load_lds_dwordx4 v[2:3], off
	v_lshl_add_u64 v[0:1], v[0:1], 0, s[44:45]
	s_mov_b32 m0, s11
	s_nop 0
	global_load_lds_dwordx4 v[0:1], off
	s_waitcnt vmcnt(8)
	s_barrier
	v_mfma_f32_16x16x32_bf16 v[0:3], v[122:125], v[102:105], v[20:23]
	v_mfma_f32_16x16x32_bf16 v[20:23], v[122:125], v[216:219], v[32:35]
	v_mfma_f32_16x16x32_bf16 v[32:35], v[160:163], v[102:105], v[36:39]
	v_mfma_f32_16x16x32_bf16 v[36:39], v[160:163], v[216:219], v[70:73]
	v_mfma_f32_16x16x32_bf16 v[68:71], v[192:195], v[102:105], v[134:137]
	v_mfma_f32_16x16x32_bf16 v[118:121], v[192:195], v[216:219], v[144:147]
	v_mfma_f32_16x16x32_bf16 v[102:105], v[200:203], v[102:105], v[106:109]
	v_mfma_f32_16x16x32_bf16 v[106:109], v[200:203], v[216:219], v[110:113]
	v_mfma_f32_16x16x32_bf16 v[0:3], v[156:159], v[212:215], v[0:3]
	v_mfma_f32_16x16x32_bf16 v[20:23], v[156:159], v[220:223], v[20:23]
	v_mfma_f32_16x16x32_bf16 v[32:35], v[164:167], v[212:215], v[32:35]
	v_mfma_f32_16x16x32_bf16 v[36:39], v[164:167], v[220:223], v[36:39]
	v_mfma_f32_16x16x32_bf16 v[68:71], v[196:199], v[212:215], v[68:71]
	v_mfma_f32_16x16x32_bf16 v[110:113], v[196:199], v[220:223], v[118:121]
	v_mfma_f32_16x16x32_bf16 v[102:105], v[204:207], v[212:215], v[102:105]
	v_mfma_f32_16x16x32_bf16 v[106:109], v[204:207], v[220:223], v[106:109]
	s_mov_b32 m0, s47
	v_lshl_add_u64 v[6:7], v[6:7], 0, s[44:45]
	s_barrier
	ds_read_b128 v[118:121], v133
	ds_read_b128 v[122:125], v133 offset:1024
	ds_read_b128 v[134:137], v133 offset:2048
	ds_read_b128 v[144:147], v133 offset:3072
	ds_read_b128 v[152:155], v228
	ds_read_b128 v[156:159], v228 offset:1024
	ds_read_b128 v[160:163], v229 offset:2048
	ds_read_b128 v[164:167], v229 offset:3072
	ds_read_b128 v[180:183], v229 offset:4096
	ds_read_b128 v[184:187], v229 offset:5120
	ds_read_b128 v[188:191], v229 offset:6144
	ds_read_b128 v[192:195], v229 offset:7168
	global_load_lds_dwordx4 v[6:7], off
	v_lshl_add_u64 v[4:5], v[4:5], 0, s[44:45]
	s_mov_b32 m0, s46
	s_nop 0
	global_load_lds_dwordx4 v[4:5], off
	s_barrier
	s_waitcnt lgkmcnt(0)
	s_waitcnt lgkmcnt(0)
	v_mfma_f32_16x16x32_bf16 v[4:7], v[152:155], v[118:121], v[16:19]
	v_mfma_f32_16x16x32_bf16 v[16:19], v[152:155], v[134:137], v[74:77]
	v_mfma_f32_16x16x32_bf16 v[72:75], v[160:163], v[118:121], v[78:81]
	v_mfma_f32_16x16x32_bf16 v[76:79], v[160:163], v[134:137], v[82:85]
	v_mfma_f32_16x16x32_bf16 v[80:83], v[180:183], v[118:121], v[86:89]
	v_mfma_f32_16x16x32_bf16 v[84:87], v[180:183], v[134:137], v[90:93]
	v_mfma_f32_16x16x32_bf16 v[88:91], v[188:191], v[118:121], v[94:97]
	v_mfma_f32_16x16x32_bf16 v[92:95], v[188:191], v[134:137], v[98:101]
	v_mfma_f32_16x16x32_bf16 v[4:7], v[156:159], v[122:125], v[4:7]
	v_mfma_f32_16x16x32_bf16 v[16:19], v[156:159], v[144:147], v[16:19]
	v_mfma_f32_16x16x32_bf16 v[72:75], v[164:167], v[122:125], v[72:75]
	v_mfma_f32_16x16x32_bf16 v[76:79], v[164:167], v[144:147], v[76:79]
	v_mfma_f32_16x16x32_bf16 v[80:83], v[184:187], v[122:125], v[80:83]
	v_mfma_f32_16x16x32_bf16 v[84:87], v[184:187], v[144:147], v[84:87]
	v_mfma_f32_16x16x32_bf16 v[88:91], v[192:195], v[122:125], v[88:91]
	v_mfma_f32_16x16x32_bf16 v[92:95], v[192:195], v[144:147], v[92:95]
	s_barrier
; #define LDA(dst, b, h) for (int m = 0; m < 4; ++m) for (int k = 0; k < 2; ++k) \
;     dst[m][k] = *reinterpret_cast<const bf16x8*>((char*)SA(b, h) + lds_byte(wr * 64 + m * 16 + fr, k * 32 + fq * 8))
; #define LDB(dst, b, h) for (int n = 0; n < 2; ++n) for (int k = 0; k < 2; ++k) \
;     dst[n][k] = *reinterpret_cast<const bf16x8*>((char*)SB(b, h) + lds_byte(wc * 32 + n * 16 + fr, k * 32 + fq * 8))
; #define MMA(ai, bj, At_, Bt_) do { __builtin_amdgcn_s_setprio(1); \
;     for (int k = 0; k < 2; ++k) for (int m = 0; m < 4; ++m) for (int n = 0; n < 2; ++n) \
;       acc[ai][bj][m][n] = __builtin_amdgcn_mfma_f32_16x16x32_bf16(At_[m][k], Bt_[n][k], acc[ai][bj][m][n], 0, 0, 0); \
;     __builtin_amdgcn_s_setprio(0); } while (0)
; #define WAIT_V(n) asm volatile("s_waitcnt vmcnt(" #n ")" ::: "memory")
; #define WAIT_L(n) asm volatile("s_waitcnt lgkmcnt(" #n ")" ::: "memory")
; #define BAR __builtin_amdgcn_s_barrier()
; template <int EPI, int lda, int ldb, int N, int K>
; __device__ __forceinline__ void gemm_phase(const u16* __restrict__ A, const u16* __restrict__ Bt, const GemmEpi ep, int wv) {
;     ...
;       LDB(B1, 0, 1); BAR; WAIT_L(0); MMA(0, 1, At, B1); BAR;
;       LDA(At, 0, 1); WAIT_V(4); BAR; WAIT_L(0); MMA(1, 0, At, B0); MMA(1, 1, At, B1); BAR; }
;     { LDB(B0, 1, 0); LDA(At, 1, 0); WAIT_V(2); BAR; WAIT_L(0); MMA(0, 0, At, B0); BAR;
	ds_read_b128 v[96:99], v224
	ds_read_b128 v[196:199], v224 offset:1024
	ds_read_b128 v[200:203], v224 offset:2048
	ds_read_b128 v[204:207], v224 offset:3072
	s_waitcnt vmcnt(8)
	s_barrier
	s_waitcnt lgkmcnt(0)
	s_waitcnt lgkmcnt(0)
	v_mfma_f32_16x16x32_bf16 v[12:15], v[152:155], v[96:99], v[12:15]
	v_mfma_f32_16x16x32_bf16 v[40:43], v[152:155], v[200:203], v[40:43]
	v_mfma_f32_16x16x32_bf16 v[52:55], v[180:183], v[96:99], v[52:55]
	v_mfma_f32_16x16x32_bf16 v[56:59], v[180:183], v[200:203], v[56:59]
	v_mfma_f32_16x16x32_bf16 v[64:67], v[188:191], v[200:203], v[64:67]
	v_mfma_f32_16x16x32_bf16 v[44:47], v[160:163], v[96:99], v[44:47]
	v_mfma_f32_16x16x32_bf16 v[48:51], v[160:163], v[200:203], v[48:51]
	v_mfma_f32_16x16x32_bf16 v[60:63], v[188:191], v[96:99], v[60:63]
	v_mfma_f32_16x16x32_bf16 v[12:15], v[156:159], v[196:199], v[12:15]
	v_mfma_f32_16x16x32_bf16 v[40:43], v[156:159], v[204:207], v[40:43]
	v_mfma_f32_16x16x32_bf16 v[52:55], v[184:187], v[196:199], v[52:55]
	v_mfma_f32_16x16x32_bf16 v[56:59], v[184:187], v[204:207], v[56:59]
	v_mfma_f32_16x16x32_bf16 v[64:67], v[192:195], v[204:207], v[64:67]
	v_mfma_f32_16x16x32_bf16 v[152:155], v[164:167], v[196:199], v[44:47]
	v_mfma_f32_16x16x32_bf16 v[156:159], v[164:167], v[204:207], v[48:51]
	v_mfma_f32_16x16x32_bf16 v[160:163], v[192:195], v[196:199], v[60:63]
	s_barrier
	ds_read_b128 v[44:47], v228 offset:16384
	ds_read_b128 v[48:51], v228 offset:17408
	ds_read_b128 v[60:63], v229 offset:18432
	ds_read_b128 v[164:167], v229 offset:19456
	ds_read_b128 v[180:183], v229 offset:20480
	ds_read_b128 v[184:187], v229 offset:21504
	ds_read_b128 v[188:191], v229 offset:22528
	ds_read_b128 v[192:195], v229 offset:23552
	s_waitcnt vmcnt(4)
	s_barrier
	s_waitcnt lgkmcnt(0)
	s_waitcnt lgkmcnt(0)
	v_mfma_f32_16x16x32_bf16 v[8:11], v[44:47], v[118:121], v[8:11]
	v_mfma_f32_16x16x32_bf16 v[24:27], v[188:191], v[118:121], v[24:27]
	v_mfma_f32_16x16x32_bf16 v[28:31], v[188:191], v[134:137], v[28:31]
	v_mfma_f32_16x16x32_bf16 v[114:117], v[44:47], v[134:137], v[114:117]
	v_mfma_f32_16x16x32_bf16 v[148:151], v[60:63], v[118:121], v[148:151]
	v_mfma_f32_16x16x32_bf16 v[168:171], v[60:63], v[134:137], v[168:171]
	v_mfma_f32_16x16x32_bf16 v[172:175], v[180:183], v[118:121], v[172:175]
	v_mfma_f32_16x16x32_bf16 v[176:179], v[180:183], v[134:137], v[176:179]
	v_mfma_f32_16x16x32_bf16 v[8:11], v[48:51], v[122:125], v[8:11]
	v_mfma_f32_16x16x32_bf16 v[24:27], v[192:195], v[122:125], v[24:27]
	v_mfma_f32_16x16x32_bf16 v[28:31], v[192:195], v[144:147], v[28:31]
	v_mfma_f32_16x16x32_bf16 v[134:137], v[48:51], v[144:147], v[114:117]
	v_mfma_f32_16x16x32_bf16 v[148:151], v[164:167], v[122:125], v[148:151]
	v_mfma_f32_16x16x32_bf16 v[168:171], v[164:167], v[144:147], v[168:171]
	v_mfma_f32_16x16x32_bf16 v[172:175], v[184:187], v[122:125], v[172:175]
	v_mfma_f32_16x16x32_bf16 v[176:179], v[184:187], v[144:147], v[176:179]
	v_mfma_f32_16x16x32_bf16 v[0:3], v[44:47], v[96:99], v[0:3]
	v_mfma_f32_16x16x32_bf16 v[20:23], v[44:47], v[200:203], v[20:23]
	v_mfma_f32_16x16x32_bf16 v[44:47], v[180:183], v[96:99], v[68:71]
	v_mfma_f32_16x16x32_bf16 v[68:71], v[188:191], v[96:99], v[102:105]
	v_mfma_f32_16x16x32_bf16 v[32:35], v[60:63], v[96:99], v[32:35]
	v_mfma_f32_16x16x32_bf16 v[36:39], v[60:63], v[200:203], v[36:39]
	v_mfma_f32_16x16x32_bf16 v[60:63], v[180:183], v[200:203], v[110:113]
	v_mfma_f32_16x16x32_bf16 v[96:99], v[188:191], v[200:203], v[106:109]
	v_mfma_f32_16x16x32_bf16 v[20:23], v[48:51], v[204:207], v[20:23]
	v_mfma_f32_16x16x32_bf16 v[68:71], v[192:195], v[196:199], v[68:71]
	v_mfma_f32_16x16x32_bf16 v[144:147], v[48:51], v[196:199], v[0:3]
	v_mfma_f32_16x16x32_bf16 v[180:183], v[164:167], v[196:199], v[32:35]
	v_mfma_f32_16x16x32_bf16 v[164:167], v[164:167], v[204:207], v[36:39]
	v_mfma_f32_16x16x32_bf16 v[188:191], v[184:187], v[196:199], v[44:47]
	v_mfma_f32_16x16x32_bf16 v[184:187], v[184:187], v[204:207], v[60:63]
	v_mfma_f32_16x16x32_bf16 v[192:195], v[192:195], v[204:207], v[96:99]
	s_barrier
	ds_read_b128 v[0:3], v225
	ds_read_b128 v[196:199], v225 offset:1024
	ds_read_b128 v[200:203], v225 offset:2048
	ds_read_b128 v[204:207], v225 offset:3072
	ds_read_b128 v[36:39], v228 offset:32768
	ds_read_b128 v[100:103], v228 offset:33792
	ds_read_b128 v[108:111], v229 offset:34816
	ds_read_b128 v[208:211], v229 offset:35840
	ds_read_b128 v[116:119], v229 offset:36864
	ds_read_b128 v[212:215], v229 offset:37888
	ds_read_b128 v[124:127], v229 offset:38912
	ds_read_b128 v[216:219], v229 offset:39936
	s_waitcnt vmcnt(2)
	s_barrier
; #define LDA(dst, b, h) for (int m = 0; m < 4; ++m) for (int k = 0; k < 2; ++k) \
;     dst[m][k] = *reinterpret_cast<const bf16x8*>((char*)SA(b, h) + lds_byte(wr * 64 + m * 16 + fr, k * 32 + fq * 8))
; #define LDB(dst, b, h) for (int n = 0; n < 2; ++n) for (int k = 0; k < 2; ++k) \
;     dst[n][k] = *reinterpret_cast<const bf16x8*>((char*)SB(b, h) + lds_byte(wc * 32 + n * 16 + fr, k * 32 + fq * 8))
; #define MMA(ai, bj, At_, Bt_) do { __builtin_amdgcn_s_setprio(1); \
;     for (int k = 0; k < 2; ++k) for (int m = 0; m < 4; ++m) for (int n = 0; n < 2; ++n) \
;       acc[ai][bj][m][n] = __builtin_amdgcn_mfma_f32_16x16x32_bf16(At_[m][k], Bt_[n][k], acc[ai][bj][m][n], 0, 0, 0); \
;     __builtin_amdgcn_s_setprio(0); } while (0)
; #define WAIT_V(n) asm volatile("s_waitcnt vmcnt(" #n ")" ::: "memory")
; #define WAIT_L(n) asm volatile("s_waitcnt lgkmcnt(" #n ")" ::: "memory")
; #define BAR __builtin_amdgcn_s_barrier()
; template <int EPI, int lda, int ldb, int N, int K>
; __device__ __forceinline__ void gemm_phase(const u16* __restrict__ A, const u16* __restrict__ Bt, const GemmEpi ep, int wv) {
;     ...
;     { LDB(B0, 1, 0); LDA(At, 1, 0); WAIT_V(2); BAR; WAIT_L(0); MMA(0, 0, At, B0); BAR;
;       LDB(B1, 1, 1); WAIT_V(0); BAR; WAIT_L(0); MMA(0, 1, At, B1); BAR;
;       LDA(At, 1, 1); BAR; WAIT_L(0); MMA(1, 0, At, B0); MMA(1, 1, At, B1); BAR; }
;     if (wr == 0) BAR;
	s_waitcnt lgkmcnt(0)
	s_waitcnt lgkmcnt(0)
	v_mfma_f32_16x16x32_bf16 v[4:7], v[36:39], v[0:3], v[4:7]
	v_mfma_f32_16x16x32_bf16 v[16:19], v[36:39], v[200:203], v[16:19]
	v_mfma_f32_16x16x32_bf16 v[32:35], v[108:111], v[0:3], v[72:75]
	v_mfma_f32_16x16x32_bf16 v[44:47], v[108:111], v[200:203], v[76:79]
	v_mfma_f32_16x16x32_bf16 v[72:75], v[116:119], v[0:3], v[80:83]
	v_mfma_f32_16x16x32_bf16 v[76:79], v[116:119], v[200:203], v[84:87]
	v_mfma_f32_16x16x32_bf16 v[80:83], v[124:127], v[0:3], v[88:91]
	v_mfma_f32_16x16x32_bf16 v[84:87], v[124:127], v[200:203], v[92:95]
	v_mfma_f32_16x16x32_bf16 v[120:123], v[100:103], v[196:199], v[4:7]
	v_mfma_f32_16x16x32_bf16 v[60:63], v[100:103], v[204:207], v[16:19]
	v_mfma_f32_16x16x32_bf16 v[112:115], v[208:211], v[196:199], v[32:35]
	v_mfma_f32_16x16x32_bf16 v[48:51], v[208:211], v[204:207], v[44:47]
	v_mfma_f32_16x16x32_bf16 v[104:107], v[212:215], v[196:199], v[72:75]
	v_mfma_f32_16x16x32_bf16 v[44:47], v[212:215], v[204:207], v[76:79]
	v_mfma_f32_16x16x32_bf16 v[96:99], v[216:219], v[196:199], v[80:83]
	v_mfma_f32_16x16x32_bf16 v[32:35], v[216:219], v[204:207], v[84:87]
	s_barrier
	ds_read_b128 v[4:7], v226
	ds_read_b128 v[220:223], v226 offset:1024
	ds_read_b128 v[76:79], v226 offset:2048
	ds_read_b128 v[224:227], v226 offset:3072
	s_waitcnt vmcnt(0)
	s_barrier
	s_waitcnt lgkmcnt(0)
	s_waitcnt lgkmcnt(0)
	v_mfma_f32_16x16x32_bf16 v[12:15], v[36:39], v[4:7], v[12:15]
	v_mfma_f32_16x16x32_bf16 v[16:19], v[36:39], v[76:79], v[40:43]
	v_mfma_f32_16x16x32_bf16 v[36:39], v[108:111], v[4:7], v[152:155]
	v_mfma_f32_16x16x32_bf16 v[40:43], v[108:111], v[76:79], v[156:159]
	v_mfma_f32_16x16x32_bf16 v[72:75], v[116:119], v[4:7], v[52:55]
	v_mfma_f32_16x16x32_bf16 v[80:83], v[116:119], v[76:79], v[56:59]
	v_mfma_f32_16x16x32_bf16 v[84:87], v[124:127], v[4:7], v[160:163]
	v_mfma_f32_16x16x32_bf16 v[64:67], v[124:127], v[76:79], v[64:67]
	v_mfma_f32_16x16x32_bf16 v[124:127], v[100:103], v[220:223], v[12:15]
	v_mfma_f32_16x16x32_bf16 v[56:59], v[100:103], v[224:227], v[16:19]
	v_mfma_f32_16x16x32_bf16 v[116:119], v[208:211], v[220:223], v[36:39]
	v_mfma_f32_16x16x32_bf16 v[52:55], v[208:211], v[224:227], v[40:43]
	v_mfma_f32_16x16x32_bf16 v[108:111], v[212:215], v[220:223], v[72:75]
	v_mfma_f32_16x16x32_bf16 v[40:43], v[212:215], v[224:227], v[80:83]
	v_mfma_f32_16x16x32_bf16 v[100:103], v[216:219], v[220:223], v[84:87]
	v_mfma_f32_16x16x32_bf16 v[36:39], v[216:219], v[224:227], v[64:67]
	s_barrier
	ds_read_b128 v[84:87], v228 offset:49152
	ds_read_b128 v[152:155], v228 offset:50176
	ds_read_b128 v[92:95], v229 offset:51200
	ds_read_b128 v[156:159], v229 offset:52224
	ds_read_b128 v[160:163], v229 offset:53248
	ds_read_b128 v[208:211], v229 offset:54272
	ds_read_b128 v[212:215], v229 offset:55296
	ds_read_b128 v[216:219], v229 offset:56320
	s_barrier
	s_waitcnt lgkmcnt(0)
	s_waitcnt lgkmcnt(0)
	v_mfma_f32_16x16x32_bf16 v[8:11], v[84:87], v[0:3], v[8:11]
	v_mfma_f32_16x16x32_bf16 v[12:15], v[84:87], v[200:203], v[134:137]
	v_mfma_f32_16x16x32_bf16 v[16:19], v[92:95], v[0:3], v[148:151]
	v_mfma_f32_16x16x32_bf16 v[64:67], v[92:95], v[200:203], v[168:171]
	v_mfma_f32_16x16x32_bf16 v[72:75], v[160:163], v[0:3], v[172:175]
	v_mfma_f32_16x16x32_bf16 v[134:137], v[160:163], v[200:203], v[176:179]
	v_mfma_f32_16x16x32_bf16 v[0:3], v[212:215], v[0:3], v[24:27]
	v_mfma_f32_16x16x32_bf16 v[24:27], v[212:215], v[200:203], v[28:31]
	v_mfma_f32_16x16x32_bf16 v[88:91], v[152:155], v[196:199], v[8:11]
	v_mfma_f32_16x16x32_bf16 v[28:31], v[152:155], v[204:207], v[12:15]
	v_mfma_f32_16x16x32_bf16 v[80:83], v[156:159], v[196:199], v[16:19]
	v_mfma_f32_16x16x32_bf16 v[16:19], v[156:159], v[204:207], v[64:67]
	v_mfma_f32_16x16x32_bf16 v[72:75], v[208:211], v[196:199], v[72:75]
	v_mfma_f32_16x16x32_bf16 v[12:15], v[208:211], v[204:207], v[134:137]
	v_mfma_f32_16x16x32_bf16 v[64:67], v[216:219], v[196:199], v[0:3]
	v_mfma_f32_16x16x32_bf16 v[0:3], v[216:219], v[204:207], v[24:27]
	v_mfma_f32_16x16x32_bf16 v[8:11], v[84:87], v[4:7], v[144:147]
	v_mfma_f32_16x16x32_bf16 v[20:23], v[84:87], v[76:79], v[20:23]
	v_mfma_f32_16x16x32_bf16 v[84:87], v[92:95], v[4:7], v[180:183]
	v_mfma_f32_16x16x32_bf16 v[134:137], v[92:95], v[76:79], v[164:167]
	v_mfma_f32_16x16x32_bf16 v[144:147], v[160:163], v[4:7], v[188:191]
	v_mfma_f32_16x16x32_bf16 v[148:151], v[160:163], v[76:79], v[184:187]
	v_mfma_f32_16x16x32_bf16 v[4:7], v[212:215], v[4:7], v[68:71]
	v_mfma_f32_16x16x32_bf16 v[160:163], v[212:215], v[76:79], v[192:195]
	v_mfma_f32_16x16x32_bf16 v[92:95], v[152:155], v[220:223], v[8:11]
	v_mfma_f32_16x16x32_bf16 v[24:27], v[152:155], v[224:227], v[20:23]
	v_mfma_f32_16x16x32_bf16 v[84:87], v[156:159], v[220:223], v[84:87]
	v_mfma_f32_16x16x32_bf16 v[20:23], v[156:159], v[224:227], v[134:137]
	v_mfma_f32_16x16x32_bf16 v[76:79], v[208:211], v[220:223], v[144:147]
	v_mfma_f32_16x16x32_bf16 v[8:11], v[208:211], v[224:227], v[148:151]
	v_mfma_f32_16x16x32_bf16 v[68:71], v[216:219], v[220:223], v[4:7]
	v_mfma_f32_16x16x32_bf16 v[4:7], v[216:219], v[224:227], v[160:163]
	v_cmp_gt_u32_e32 vcc, s62, v130
	s_barrier
	s_and_saveexec_b64 s[46:47], vcc
	s_cbranch_execz .LBB0_1245
	s_barrier
	s_branch .LBB0_1245

; #define STAGE(P, BASE, LD, br, kt) do { const char* _g = (const char*)((BASE) + (size_t)(br) * (LD) + (size_t)(kt) * 64); \
;     for (int _i = 0; _i < 2; ++_i) { int _b = tidx * 16 + _i * 8192; int _r, _c; stage_rc(_b, _r, _c); \
;       __builtin_amdgcn_global_load_lds((const unsigned*)(_g + (unsigned)((_r * (LD) + _c) * 2)), (unsigned*)((char*)(P) + _b), 16, 0, 0); } } while (0)
; #define LDA(dst, b, h) for (int m = 0; m < 4; ++m) for (int k = 0; k < 2; ++k) \
;     dst[m][k] = *reinterpret_cast<const bf16x8*>((char*)SA(b, h) + lds_byte(wr * 64 + m * 16 + fr, k * 32 + fq * 8))
; #define LDB(dst, b, h) for (int n = 0; n < 2; ++n) for (int k = 0; k < 2; ++k) \
;     dst[n][k] = *reinterpret_cast<const bf16x8*>((char*)SB(b, h) + lds_byte(wc * 32 + n * 16 + fr, k * 32 + fq * 8))
; #define MMA(ai, bj, At_, Bt_) do { __builtin_amdgcn_s_setprio(1); \
;     for (int k = 0; k < 2; ++k) for (int m = 0; m < 4; ++m) for (int n = 0; n < 2; ++n) \
;       acc[ai][bj][m][n] = __builtin_amdgcn_mfma_f32_16x16x32_bf16(At_[m][k], Bt_[n][k], acc[ai][bj][m][n], 0, 0, 0); \
;     __builtin_amdgcn_s_setprio(0); } while (0)
; #define WAIT_V(n) asm volatile("s_waitcnt vmcnt(" #n ")" ::: "memory")
; #define WAIT_L(n) asm volatile("s_waitcnt lgkmcnt(" #n ")" ::: "memory")
; #define BAR __builtin_amdgcn_s_barrier()
; #define SCHED __builtin_amdgcn_sched_barrier(0)
; template <int EPI, int lda, int ldb, int N, int K>
; __device__ __forceinline__ void gemm_phase(const u16* __restrict__ A, const u16* __restrict__ Bt, const GemmEpi ep, int wv) {
;     ...
;     const int wid = tidx >> 6, lane = tidx & 63, wr = wid >> 2, wc = wid & 3, fr = lane & 15, fq = lane >> 4;
;     const u16* Ab = A + (EPI == EPI_RG ? (pn >> 1) * 256 : 0);
;     f32x4 acc[2][2][4][2] = {};
;     bf16x8 At[4][2], B0[2][2], B1[2][2];
;     constexpr int nt = K / 64;
;     if (wr == 1) BAR;
;     WAIT_V(4); BAR;
;     STAGE(SB(1, 0), Bt, ldb, bcol, 1); STAGE(SA(1, 0), Ab, lda, brow, 1); STAGE(SB(1, 1), Bt, ldb, bcol + HALF, 1);
;     WAIT_V(6); BAR;
;     for (int t = 0; t < nt - 2; t += 2) {
;       LDB(B0, 0, 0); SCHED; LDA(At, 0, 0); STAGE(SA(1, 1), Ab, lda, brow + HALF, t + 1);
;       WAIT_L(8); BAR; WAIT_L(0); MMA(0, 0, At, B0); BAR; SCHED;
;       LDB(B1, 0, 1); STAGE(SB(0, 0), Bt, ldb, bcol, t + 2);
;       BAR; WAIT_L(0); MMA(0, 1, At, B1); BAR;
.LBB0_1349:
	s_or_b64 exec, exec, s[54:55]
	v_mov_b32_e32 v1, v129
	v_add_u32_e32 v7, s58, v6
	v_lshl_add_u64 v[12:13], s[46:47], 0, v[128:129]
	v_lshl_add_u64 v[14:15], s[46:47], 0, v[0:1]
	v_lshl_add_u64 v[2:3], s[52:53], 0, v[128:129]
	v_lshl_add_u64 v[0:1], s[52:53], 0, v[0:1]
	v_readfirstlane_b32 s53, v7
	v_add_u32_e32 v7, 0x2000, v7
	v_mov_b32_e32 v5, v129
	v_mov_b32_e32 v17, v129
	v_lshl_add_u64 v[26:27], v[12:13], 0, s[36:37]
	s_mov_b32 m0, s53
	v_readfirstlane_b32 s52, v7
	v_add_u32_e32 v7, 0x8000, v23
	v_lshl_add_u64 v[8:9], s[50:51], 0, v[4:5]
	v_lshl_add_u64 v[10:11], s[50:51], 0, v[16:17]
	s_waitcnt vmcnt(4)
	s_barrier
	global_load_lds_dwordx4 v[26:27], off
	v_lshl_add_u64 v[26:27], v[14:15], 0, s[36:37]
	s_mov_b32 m0, s52
	v_readfirstlane_b32 s51, v7
	v_add_u32_e32 v7, 0xa000, v23
	global_load_lds_dwordx4 v[26:27], off
	v_lshl_add_u64 v[26:27], v[8:9], 0, s[36:37]
	s_mov_b32 m0, s51
	v_readfirstlane_b32 s50, v7
	v_add_u32_e32 v25, s59, v6
	global_load_lds_dwordx4 v[26:27], off
	v_lshl_add_u64 v[26:27], v[10:11], 0, s[36:37]
	s_mov_b32 m0, s50
	v_readfirstlane_b32 s11, v25
	v_add_u32_e32 v25, 0x2000, v25
	global_load_lds_dwordx4 v[26:27], off
	v_lshl_add_u64 v[26:27], v[2:3], 0, s[36:37]
	s_mov_b32 m0, s11
	v_readfirstlane_b32 s5, v25
	global_load_lds_dwordx4 v[26:27], off
	v_lshl_add_u64 v[6:7], v[0:1], 0, s[36:37]
	s_mov_b32 m0, s5
	v_and_b32_e32 v132, 15, v20
	global_load_lds_dwordx4 v[6:7], off
	v_bfe_u32 v128, v20, 4, 2
	v_lshlrev_b32_e32 v7, 2, v20
	v_bfe_u32 v131, v130, 6, 2
	v_lshlrev_b32_e32 v25, 4, v128
	v_lshlrev_b32_e32 v6, 6, v132
	v_and_b32_e32 v50, 32, v7
	v_lshlrev_b32_e32 v126, 12, v131
	v_bitop3_b32 v127, v25, v50, v6 bitop3:0x36
	v_add3_u32 v133, s56, v127, v126
	s_waitcnt vmcnt(6)
	s_barrier
	ds_read_b128 v[26:29], v133
	ds_read_b128 v[30:33], v133 offset:1024
	ds_read_b128 v[34:37], v133 offset:2048
	ds_read_b128 v[38:41], v133 offset:3072
	v_lshl_add_u64 v[6:7], s[48:49], 0, v[4:5]
	v_lshl_add_u64 v[4:5], s[48:49], 0, v[16:17]
	v_lshlrev_b32_e32 v17, 6, v20
	v_and_b32_e32 v17, 0x3c0, v17
	v_add_u32_e32 v20, 0xc000, v23
	v_lshlrev_b32_e32 v16, 13, v139
	v_bitop3_b32 v17, v17, v50, v25 bitop3:0x36
	v_readfirstlane_b32 s47, v20
	v_add_u32_e32 v20, 0xe000, v23
	v_add3_u32 v228, 0, v127, v16
	v_add3_u32 v229, 0, v17, v16
	v_lshl_add_u64 v[16:17], v[6:7], 0, s[36:37]
	s_mov_b32 m0, s47
	v_readfirstlane_b32 s46, v20
	ds_read_b128 v[42:45], v228
	ds_read_b128 v[46:49], v228 offset:1024
	ds_read_b128 v[50:53], v229 offset:2048
	ds_read_b128 v[54:57], v229 offset:3072
	ds_read_b128 v[58:61], v229 offset:4096
	ds_read_b128 v[62:65], v229 offset:5120
	ds_read_b128 v[66:69], v229 offset:6144
	ds_read_b128 v[70:73], v229 offset:7168
	global_load_lds_dwordx4 v[16:17], off
	v_lshl_add_u64 v[16:17], v[4:5], 0, s[36:37]
	s_mov_b32 m0, s46
	s_nop 0
	global_load_lds_dwordx4 v[16:17], off
	s_waitcnt lgkmcnt(8)
	s_barrier
	s_waitcnt lgkmcnt(0)
	s_waitcnt lgkmcnt(0)
	v_mfma_f32_16x16x32_bf16 v[74:77], v[42:45], v[26:29], 0
	v_mfma_f32_16x16x32_bf16 v[78:81], v[42:45], v[34:37], 0
	v_mfma_f32_16x16x32_bf16 v[82:85], v[50:53], v[26:29], 0
	v_mfma_f32_16x16x32_bf16 v[86:89], v[50:53], v[34:37], 0
	v_mfma_f32_16x16x32_bf16 v[90:93], v[58:61], v[26:29], 0
	v_mfma_f32_16x16x32_bf16 v[94:97], v[58:61], v[34:37], 0
	v_mfma_f32_16x16x32_bf16 v[98:101], v[66:69], v[26:29], 0
	v_mfma_f32_16x16x32_bf16 v[102:105], v[66:69], v[34:37], 0
	v_mfma_f32_16x16x32_bf16 v[74:77], v[46:49], v[30:33], v[74:77]
	v_mfma_f32_16x16x32_bf16 v[78:81], v[46:49], v[38:41], v[78:81]
	v_mfma_f32_16x16x32_bf16 v[82:85], v[54:57], v[30:33], v[82:85]
	v_mfma_f32_16x16x32_bf16 v[86:89], v[54:57], v[38:41], v[86:89]
	v_mfma_f32_16x16x32_bf16 v[90:93], v[62:65], v[30:33], v[90:93]
	v_mfma_f32_16x16x32_bf16 v[94:97], v[62:65], v[38:41], v[94:97]
	v_mfma_f32_16x16x32_bf16 v[98:101], v[70:73], v[30:33], v[98:101]
	v_mfma_f32_16x16x32_bf16 v[102:105], v[70:73], v[38:41], v[102:105]
	s_barrier
	v_readfirstlane_b32 s48, v21
	v_add_u32_e32 v20, 0x2000, v21
	v_add3_u32 v224, s57, v127, v126
	v_lshl_add_u64 v[16:17], v[12:13], 0, s[38:39]
	s_mov_b32 m0, s48
	v_readfirstlane_b32 s48, v20
	ds_read_b128 v[106:109], v224
	ds_read_b128 v[110:113], v224 offset:1024
	ds_read_b128 v[114:117], v224 offset:2048
	ds_read_b128 v[118:121], v224 offset:3072
	global_load_lds_dwordx4 v[16:17], off
	v_lshl_add_u64 v[16:17], v[14:15], 0, s[38:39]
	s_mov_b32 m0, s48
	s_nop 0
	global_load_lds_dwordx4 v[16:17], off
	s_waitcnt vmcnt(10)
	s_barrier
	s_waitcnt lgkmcnt(0)
	s_waitcnt lgkmcnt(0)
	v_mfma_f32_16x16x32_bf16 v[122:125], v[42:45], v[106:109], 0
	v_mfma_f32_16x16x32_bf16 v[42:45], v[42:45], v[114:117], 0
	v_mfma_f32_16x16x32_bf16 v[140:143], v[50:53], v[106:109], 0
	v_mfma_f32_16x16x32_bf16 v[50:53], v[50:53], v[114:117], 0
	v_mfma_f32_16x16x32_bf16 v[144:147], v[58:61], v[106:109], 0
	v_mfma_f32_16x16x32_bf16 v[58:61], v[58:61], v[114:117], 0
	v_mfma_f32_16x16x32_bf16 v[148:151], v[66:69], v[106:109], 0
	v_mfma_f32_16x16x32_bf16 v[66:69], v[66:69], v[114:117], 0
	v_mfma_f32_16x16x32_bf16 v[122:125], v[46:49], v[110:113], v[122:125]
	v_mfma_f32_16x16x32_bf16 v[42:45], v[46:49], v[118:121], v[42:45]
	v_mfma_f32_16x16x32_bf16 v[46:49], v[54:57], v[110:113], v[140:143]
	v_mfma_f32_16x16x32_bf16 v[50:53], v[54:57], v[118:121], v[50:53]
	v_mfma_f32_16x16x32_bf16 v[54:57], v[62:65], v[110:113], v[144:147]
	v_mfma_f32_16x16x32_bf16 v[58:61], v[62:65], v[118:121], v[58:61]
	v_mfma_f32_16x16x32_bf16 v[62:65], v[70:73], v[110:113], v[148:151]
	v_mfma_f32_16x16x32_bf16 v[66:69], v[70:73], v[118:121], v[66:69]
	v_readfirstlane_b32 s48, v23
	v_lshl_add_u64 v[16:17], v[8:9], 0, s[38:39]
	s_mov_b32 m0, s48
	v_readfirstlane_b32 s48, v24
	s_barrier
; #define STAGE(P, BASE, LD, br, kt) do { const char* _g = (const char*)((BASE) + (size_t)(br) * (LD) + (size_t)(kt) * 64); \
;     for (int _i = 0; _i < 2; ++_i) { int _b = tidx * 16 + _i * 8192; int _r, _c; stage_rc(_b, _r, _c); \
;       __builtin_amdgcn_global_load_lds((const unsigned*)(_g + (unsigned)((_r * (LD) + _c) * 2)), (unsigned*)((char*)(P) + _b), 16, 0, 0); } } while (0)
; #define LDA(dst, b, h) for (int m = 0; m < 4; ++m) for (int k = 0; k < 2; ++k) \
;     dst[m][k] = *reinterpret_cast<const bf16x8*>((char*)SA(b, h) + lds_byte(wr * 64 + m * 16 + fr, k * 32 + fq * 8))
; #define LDB(dst, b, h) for (int n = 0; n < 2; ++n) for (int k = 0; k < 2; ++k) \
;     dst[n][k] = *reinterpret_cast<const bf16x8*>((char*)SB(b, h) + lds_byte(wc * 32 + n * 16 + fr, k * 32 + fq * 8))
; #define MMA(ai, bj, At_, Bt_) do { __builtin_amdgcn_s_setprio(1); \
;     for (int k = 0; k < 2; ++k) for (int m = 0; m < 4; ++m) for (int n = 0; n < 2; ++n) \
;       acc[ai][bj][m][n] = __builtin_amdgcn_mfma_f32_16x16x32_bf16(At_[m][k], Bt_[n][k], acc[ai][bj][m][n], 0, 0, 0); \
;     __builtin_amdgcn_s_setprio(0); } while (0)
; #define WAIT_V(n) asm volatile("s_waitcnt vmcnt(" #n ")" ::: "memory")
; #define WAIT_L(n) asm volatile("s_waitcnt lgkmcnt(" #n ")" ::: "memory")
; #define BAR __builtin_amdgcn_s_barrier()
; #define SCHED __builtin_amdgcn_sched_barrier(0)
; template <int EPI, int lda, int ldb, int N, int K>
; __device__ __forceinline__ void gemm_phase(const u16* __restrict__ A, const u16* __restrict__ Bt, const GemmEpi ep, int wv) {
;     ...
;       LDA(At, 0, 1); STAGE(SA(0, 0), Ab, lda, brow, t + 2);
;       BAR; WAIT_L(0); MMA(1, 0, At, B0); BAR; SCHED;
;       STAGE(SB(0, 1), Bt, ldb, bcol + HALF, t + 2);
;       WAIT_V(6); BAR; MMA(1, 1, At, B1); BAR;
;       LDB(B0, 1, 0); SCHED; LDA(At, 1, 0); STAGE(SA(0, 1), Ab, lda, brow + HALF, t + 2);
;       WAIT_L(8); BAR; WAIT_L(0); MMA(0, 0, At, B0); BAR; SCHED;
;       LDB(B1, 1, 1); STAGE(SB(1, 0), Bt, ldb, bcol, t + 3);
	ds_read_b128 v[70:73], v228 offset:16384
	ds_read_b128 v[140:143], v228 offset:17408
	ds_read_b128 v[144:147], v229 offset:18432
	ds_read_b128 v[148:151], v229 offset:19456
	ds_read_b128 v[152:155], v229 offset:20480
	ds_read_b128 v[156:159], v229 offset:21504
	ds_read_b128 v[160:163], v229 offset:22528
	ds_read_b128 v[164:167], v229 offset:23552
	global_load_lds_dwordx4 v[16:17], off
	v_lshl_add_u64 v[16:17], v[10:11], 0, s[38:39]
	s_mov_b32 m0, s48
	s_nop 0
	global_load_lds_dwordx4 v[16:17], off
	s_barrier
	s_waitcnt lgkmcnt(0)
	s_waitcnt lgkmcnt(0)
	v_mfma_f32_16x16x32_bf16 v[168:171], v[70:73], v[26:29], 0
	v_mfma_f32_16x16x32_bf16 v[172:175], v[70:73], v[34:37], 0
	v_mfma_f32_16x16x32_bf16 v[176:179], v[144:147], v[26:29], 0
	v_mfma_f32_16x16x32_bf16 v[180:183], v[144:147], v[34:37], 0
	v_mfma_f32_16x16x32_bf16 v[184:187], v[152:155], v[26:29], 0
	v_mfma_f32_16x16x32_bf16 v[188:191], v[152:155], v[34:37], 0
	v_mfma_f32_16x16x32_bf16 v[24:27], v[160:163], v[26:29], 0
	v_mfma_f32_16x16x32_bf16 v[34:37], v[160:163], v[34:37], 0
	v_mfma_f32_16x16x32_bf16 v[168:171], v[140:143], v[30:33], v[168:171]
	v_mfma_f32_16x16x32_bf16 v[176:179], v[148:151], v[30:33], v[176:179]
	v_mfma_f32_16x16x32_bf16 v[184:187], v[156:159], v[30:33], v[184:187]
	v_mfma_f32_16x16x32_bf16 v[24:27], v[164:167], v[30:33], v[24:27]
	v_mfma_f32_16x16x32_bf16 v[28:31], v[164:167], v[38:41], v[34:37]
	v_mfma_f32_16x16x32_bf16 v[172:175], v[140:143], v[38:41], v[172:175]
	v_mfma_f32_16x16x32_bf16 v[180:183], v[148:151], v[38:41], v[180:183]
	v_mfma_f32_16x16x32_bf16 v[188:191], v[156:159], v[38:41], v[188:191]
	s_barrier
	v_readfirstlane_b32 s48, v22
	v_add_u32_e32 v20, 0x2000, v22
	v_lshl_add_u64 v[16:17], v[2:3], 0, s[38:39]
	s_mov_b32 m0, s48
	v_readfirstlane_b32 s48, v20
	global_load_lds_dwordx4 v[16:17], off
	v_lshl_add_u64 v[16:17], v[0:1], 0, s[38:39]
	s_mov_b32 m0, s48
	s_nop 0
	global_load_lds_dwordx4 v[16:17], off
	s_waitcnt vmcnt(8)
	s_barrier
	v_mfma_f32_16x16x32_bf16 v[20:23], v[70:73], v[106:109], 0
	v_mfma_f32_16x16x32_bf16 v[32:35], v[70:73], v[114:117], 0
	v_mfma_f32_16x16x32_bf16 v[36:39], v[144:147], v[106:109], 0
	v_mfma_f32_16x16x32_bf16 v[70:73], v[144:147], v[114:117], 0
	v_mfma_f32_16x16x32_bf16 v[144:147], v[152:155], v[106:109], 0
	v_mfma_f32_16x16x32_bf16 v[152:155], v[152:155], v[114:117], 0
	v_mfma_f32_16x16x32_bf16 v[106:109], v[160:163], v[106:109], 0
	v_mfma_f32_16x16x32_bf16 v[114:117], v[160:163], v[114:117], 0
	v_mfma_f32_16x16x32_bf16 v[20:23], v[140:143], v[110:113], v[20:23]
	v_mfma_f32_16x16x32_bf16 v[32:35], v[140:143], v[118:121], v[32:35]
	v_mfma_f32_16x16x32_bf16 v[36:39], v[148:151], v[110:113], v[36:39]
	v_mfma_f32_16x16x32_bf16 v[70:73], v[148:151], v[118:121], v[70:73]
	v_mfma_f32_16x16x32_bf16 v[140:143], v[156:159], v[110:113], v[144:147]
	v_mfma_f32_16x16x32_bf16 v[106:109], v[164:167], v[110:113], v[106:109]
	v_mfma_f32_16x16x32_bf16 v[110:113], v[164:167], v[118:121], v[114:117]
	v_mfma_f32_16x16x32_bf16 v[144:147], v[156:159], v[118:121], v[152:155]
	v_add3_u32 v225, s58, v127, v126
	s_barrier
	ds_read_b128 v[114:117], v225
	ds_read_b128 v[118:121], v225 offset:1024
	ds_read_b128 v[148:151], v225 offset:2048
	ds_read_b128 v[152:155], v225 offset:3072
	v_readfirstlane_b32 s48, v18
	v_lshl_add_u64 v[16:17], v[6:7], 0, s[38:39]
	s_mov_b32 m0, s48
	v_readfirstlane_b32 s48, v19
	ds_read_b128 v[156:159], v228 offset:32768
	ds_read_b128 v[160:163], v228 offset:33792
	ds_read_b128 v[164:167], v229 offset:34816
	ds_read_b128 v[192:195], v229 offset:35840
	ds_read_b128 v[196:199], v229 offset:36864
	ds_read_b128 v[200:203], v229 offset:37888
	ds_read_b128 v[204:207], v229 offset:38912
	ds_read_b128 v[208:211], v229 offset:39936
	global_load_lds_dwordx4 v[16:17], off
	v_lshl_add_u64 v[16:17], v[4:5], 0, s[38:39]
	s_mov_b32 m0, s48
	s_nop 0
	global_load_lds_dwordx4 v[16:17], off
	s_waitcnt lgkmcnt(8)
	s_barrier
	s_waitcnt lgkmcnt(0)
	s_waitcnt lgkmcnt(0)
	v_mfma_f32_16x16x32_bf16 v[16:19], v[156:159], v[114:117], v[74:77]
	v_mfma_f32_16x16x32_bf16 v[74:77], v[156:159], v[148:151], v[78:81]
	v_mfma_f32_16x16x32_bf16 v[78:81], v[164:167], v[114:117], v[82:85]
	v_mfma_f32_16x16x32_bf16 v[82:85], v[164:167], v[148:151], v[86:89]
	v_mfma_f32_16x16x32_bf16 v[86:89], v[196:199], v[114:117], v[90:93]
	v_mfma_f32_16x16x32_bf16 v[90:93], v[196:199], v[148:151], v[94:97]
	v_mfma_f32_16x16x32_bf16 v[94:97], v[204:207], v[114:117], v[98:101]
	v_mfma_f32_16x16x32_bf16 v[98:101], v[204:207], v[148:151], v[102:105]
	v_mfma_f32_16x16x32_bf16 v[16:19], v[160:163], v[118:121], v[16:19]
	v_mfma_f32_16x16x32_bf16 v[74:77], v[160:163], v[152:155], v[74:77]
	v_mfma_f32_16x16x32_bf16 v[78:81], v[192:195], v[118:121], v[78:81]
	v_mfma_f32_16x16x32_bf16 v[82:85], v[192:195], v[152:155], v[82:85]
	v_mfma_f32_16x16x32_bf16 v[86:89], v[200:203], v[118:121], v[86:89]
	v_mfma_f32_16x16x32_bf16 v[90:93], v[200:203], v[152:155], v[90:93]
	v_mfma_f32_16x16x32_bf16 v[94:97], v[208:211], v[118:121], v[94:97]
	v_mfma_f32_16x16x32_bf16 v[98:101], v[208:211], v[152:155], v[98:101]
	s_barrier
	s_mov_b32 m0, s53
	v_add3_u32 v226, s59, v127, v126
	v_lshl_add_u64 v[12:13], v[12:13], 0, s[40:41]
	ds_read_b128 v[102:105], v226
	ds_read_b128 v[212:215], v226 offset:1024
	ds_read_b128 v[216:219], v226 offset:2048
	ds_read_b128 v[220:223], v226 offset:3072
	global_load_lds_dwordx4 v[12:13], off
	v_lshl_add_u64 v[12:13], v[14:15], 0, s[40:41]
	s_mov_b32 m0, s52
	s_nop 0
	global_load_lds_dwordx4 v[12:13], off
	s_waitcnt vmcnt(10)
	s_barrier
; #define STAGE(P, BASE, LD, br, kt) do { const char* _g = (const char*)((BASE) + (size_t)(br) * (LD) + (size_t)(kt) * 64); \
;     for (int _i = 0; _i < 2; ++_i) { int _b = tidx * 16 + _i * 8192; int _r, _c; stage_rc(_b, _r, _c); \
;       __builtin_amdgcn_global_load_lds((const unsigned*)(_g + (unsigned)((_r * (LD) + _c) * 2)), (unsigned*)((char*)(P) + _b), 16, 0, 0); } } while (0)
; #define LDA(dst, b, h) for (int m = 0; m < 4; ++m) for (int k = 0; k < 2; ++k) \
;     dst[m][k] = *reinterpret_cast<const bf16x8*>((char*)SA(b, h) + lds_byte(wr * 64 + m * 16 + fr, k * 32 + fq * 8))
; #define LDB(dst, b, h) for (int n = 0; n < 2; ++n) for (int k = 0; k < 2; ++k) \
;     dst[n][k] = *reinterpret_cast<const bf16x8*>((char*)SB(b, h) + lds_byte(wc * 32 + n * 16 + fr, k * 32 + fq * 8))
; #define MMA(ai, bj, At_, Bt_) do { __builtin_amdgcn_s_setprio(1); \
;     for (int k = 0; k < 2; ++k) for (int m = 0; m < 4; ++m) for (int n = 0; n < 2; ++n) \
;       acc[ai][bj][m][n] = __builtin_amdgcn_mfma_f32_16x16x32_bf16(At_[m][k], Bt_[n][k], acc[ai][bj][m][n], 0, 0, 0); \
;     __builtin_amdgcn_s_setprio(0); } while (0)
; #define WAIT_V(n) asm volatile("s_waitcnt vmcnt(" #n ")" ::: "memory")
; #define WAIT_L(n) asm volatile("s_waitcnt lgkmcnt(" #n ")" ::: "memory")
; #define BAR __builtin_amdgcn_s_barrier()
; #define SCHED __builtin_amdgcn_sched_barrier(0)
; template <int EPI, int lda, int ldb, int N, int K>
; __device__ __forceinline__ void gemm_phase(const u16* __restrict__ A, const u16* __restrict__ Bt, const GemmEpi ep, int wv) {
;     ...
;       BAR; WAIT_L(0); MMA(0, 1, At, B1); BAR;
;       LDA(At, 1, 1); STAGE(SA(1, 0), Ab, lda, brow, t + 3);
;       BAR; WAIT_L(0); MMA(1, 0, At, B0); BAR; SCHED;
;       STAGE(SB(1, 1), Bt, ldb, bcol + HALF, t + 3);
;       WAIT_V(6); BAR; MMA(1, 1, At, B1); BAR;
;     }
;     { LDB(B0, 0, 0); LDA(At, 0, 0); STAGE(SA(1, 1), Ab, lda, brow + HALF, nt - 1);
;       BAR; WAIT_L(0); MMA(0, 0, At, B0); BAR;
	s_waitcnt lgkmcnt(0)
	s_waitcnt lgkmcnt(0)
	v_mfma_f32_16x16x32_bf16 v[12:15], v[156:159], v[102:105], v[122:125]
	v_mfma_f32_16x16x32_bf16 v[40:43], v[156:159], v[216:219], v[42:45]
	v_mfma_f32_16x16x32_bf16 v[44:47], v[164:167], v[102:105], v[46:49]
	v_mfma_f32_16x16x32_bf16 v[48:51], v[164:167], v[216:219], v[50:53]
	v_mfma_f32_16x16x32_bf16 v[52:55], v[196:199], v[102:105], v[54:57]
	v_mfma_f32_16x16x32_bf16 v[56:59], v[196:199], v[216:219], v[58:61]
	v_mfma_f32_16x16x32_bf16 v[60:63], v[204:207], v[102:105], v[62:65]
	v_mfma_f32_16x16x32_bf16 v[64:67], v[204:207], v[216:219], v[66:69]
	v_mfma_f32_16x16x32_bf16 v[12:15], v[160:163], v[212:215], v[12:15]
	v_mfma_f32_16x16x32_bf16 v[40:43], v[160:163], v[220:223], v[40:43]
	v_mfma_f32_16x16x32_bf16 v[44:47], v[192:195], v[212:215], v[44:47]
	v_mfma_f32_16x16x32_bf16 v[48:51], v[192:195], v[220:223], v[48:51]
	v_mfma_f32_16x16x32_bf16 v[52:55], v[200:203], v[212:215], v[52:55]
	v_mfma_f32_16x16x32_bf16 v[56:59], v[200:203], v[220:223], v[56:59]
	v_mfma_f32_16x16x32_bf16 v[60:63], v[208:211], v[212:215], v[60:63]
	v_mfma_f32_16x16x32_bf16 v[64:67], v[208:211], v[220:223], v[64:67]
	s_mov_b32 m0, s51
	v_lshl_add_u64 v[8:9], v[8:9], 0, s[40:41]
	s_barrier
	ds_read_b128 v[122:125], v228 offset:49152
	ds_read_b128 v[156:159], v228 offset:50176
	ds_read_b128 v[160:163], v229 offset:51200
	ds_read_b128 v[164:167], v229 offset:52224
	ds_read_b128 v[192:195], v229 offset:53248
	ds_read_b128 v[196:199], v229 offset:54272
	ds_read_b128 v[200:203], v229 offset:55296
	ds_read_b128 v[204:207], v229 offset:56320
	global_load_lds_dwordx4 v[8:9], off
	v_lshl_add_u64 v[8:9], v[10:11], 0, s[40:41]
	s_mov_b32 m0, s50
	s_nop 0
	global_load_lds_dwordx4 v[8:9], off
	s_barrier
	s_waitcnt lgkmcnt(0)
	s_waitcnt lgkmcnt(0)
	v_mfma_f32_16x16x32_bf16 v[8:11], v[122:125], v[114:117], v[168:171]
	v_mfma_f32_16x16x32_bf16 v[168:171], v[122:125], v[148:151], v[172:175]
	v_mfma_f32_16x16x32_bf16 v[24:27], v[200:203], v[114:117], v[24:27]
	v_mfma_f32_16x16x32_bf16 v[28:31], v[200:203], v[148:151], v[28:31]
	v_mfma_f32_16x16x32_bf16 v[172:175], v[160:163], v[114:117], v[176:179]
	v_mfma_f32_16x16x32_bf16 v[176:179], v[160:163], v[148:151], v[180:183]
	v_mfma_f32_16x16x32_bf16 v[180:183], v[192:195], v[114:117], v[184:187]
	v_mfma_f32_16x16x32_bf16 v[184:187], v[192:195], v[148:151], v[188:191]
	v_mfma_f32_16x16x32_bf16 v[8:11], v[156:159], v[118:121], v[8:11]
	v_mfma_f32_16x16x32_bf16 v[114:117], v[156:159], v[152:155], v[168:171]
	v_mfma_f32_16x16x32_bf16 v[24:27], v[204:207], v[118:121], v[24:27]
	v_mfma_f32_16x16x32_bf16 v[28:31], v[204:207], v[152:155], v[28:31]
	v_mfma_f32_16x16x32_bf16 v[148:151], v[164:167], v[118:121], v[172:175]
	v_mfma_f32_16x16x32_bf16 v[168:171], v[164:167], v[152:155], v[176:179]
	v_mfma_f32_16x16x32_bf16 v[172:175], v[196:199], v[118:121], v[180:183]
	v_mfma_f32_16x16x32_bf16 v[176:179], v[196:199], v[152:155], v[184:187]
	s_barrier
	s_mov_b32 m0, s11
	v_lshl_add_u64 v[2:3], v[2:3], 0, s[40:41]
	global_load_lds_dwordx4 v[2:3], off
	v_lshl_add_u64 v[0:1], v[0:1], 0, s[40:41]
	s_mov_b32 m0, s5
	s_nop 0
	global_load_lds_dwordx4 v[0:1], off
	s_waitcnt vmcnt(8)
	s_barrier
	v_mfma_f32_16x16x32_bf16 v[0:3], v[122:125], v[102:105], v[20:23]
	v_mfma_f32_16x16x32_bf16 v[20:23], v[122:125], v[216:219], v[32:35]
	v_mfma_f32_16x16x32_bf16 v[32:35], v[160:163], v[102:105], v[36:39]
	v_mfma_f32_16x16x32_bf16 v[36:39], v[160:163], v[216:219], v[70:73]
	v_mfma_f32_16x16x32_bf16 v[68:71], v[192:195], v[102:105], v[140:143]
	v_mfma_f32_16x16x32_bf16 v[118:121], v[192:195], v[216:219], v[144:147]
	v_mfma_f32_16x16x32_bf16 v[102:105], v[200:203], v[102:105], v[106:109]
	v_mfma_f32_16x16x32_bf16 v[106:109], v[200:203], v[216:219], v[110:113]
	v_mfma_f32_16x16x32_bf16 v[0:3], v[156:159], v[212:215], v[0:3]
	v_mfma_f32_16x16x32_bf16 v[20:23], v[156:159], v[220:223], v[20:23]
	v_mfma_f32_16x16x32_bf16 v[32:35], v[164:167], v[212:215], v[32:35]
	v_mfma_f32_16x16x32_bf16 v[36:39], v[164:167], v[220:223], v[36:39]
	v_mfma_f32_16x16x32_bf16 v[68:71], v[196:199], v[212:215], v[68:71]
	v_mfma_f32_16x16x32_bf16 v[110:113], v[196:199], v[220:223], v[118:121]
	v_mfma_f32_16x16x32_bf16 v[102:105], v[204:207], v[212:215], v[102:105]
	v_mfma_f32_16x16x32_bf16 v[106:109], v[204:207], v[220:223], v[106:109]
	s_mov_b32 m0, s47
	v_lshl_add_u64 v[6:7], v[6:7], 0, s[40:41]
	s_barrier
	ds_read_b128 v[118:121], v133
	ds_read_b128 v[122:125], v133 offset:1024
	ds_read_b128 v[140:143], v133 offset:2048
	ds_read_b128 v[144:147], v133 offset:3072
	ds_read_b128 v[152:155], v228
	ds_read_b128 v[156:159], v228 offset:1024
	ds_read_b128 v[160:163], v229 offset:2048
	ds_read_b128 v[164:167], v229 offset:3072
	ds_read_b128 v[180:183], v229 offset:4096
	ds_read_b128 v[184:187], v229 offset:5120
	ds_read_b128 v[188:191], v229 offset:6144
	ds_read_b128 v[192:195], v229 offset:7168
	global_load_lds_dwordx4 v[6:7], off
	v_lshl_add_u64 v[4:5], v[4:5], 0, s[40:41]
	s_mov_b32 m0, s46
	s_nop 0
	global_load_lds_dwordx4 v[4:5], off
	s_barrier
	s_waitcnt lgkmcnt(0)
	s_waitcnt lgkmcnt(0)
	v_mfma_f32_16x16x32_bf16 v[4:7], v[152:155], v[118:121], v[16:19]
	v_mfma_f32_16x16x32_bf16 v[16:19], v[152:155], v[140:143], v[74:77]
	v_mfma_f32_16x16x32_bf16 v[72:75], v[160:163], v[118:121], v[78:81]
	v_mfma_f32_16x16x32_bf16 v[76:79], v[160:163], v[140:143], v[82:85]
	v_mfma_f32_16x16x32_bf16 v[80:83], v[180:183], v[118:121], v[86:89]
	v_mfma_f32_16x16x32_bf16 v[84:87], v[180:183], v[140:143], v[90:93]
	v_mfma_f32_16x16x32_bf16 v[88:91], v[188:191], v[118:121], v[94:97]
	v_mfma_f32_16x16x32_bf16 v[92:95], v[188:191], v[140:143], v[98:101]
	v_mfma_f32_16x16x32_bf16 v[4:7], v[156:159], v[122:125], v[4:7]
	v_mfma_f32_16x16x32_bf16 v[16:19], v[156:159], v[144:147], v[16:19]
	v_mfma_f32_16x16x32_bf16 v[72:75], v[164:167], v[122:125], v[72:75]
	v_mfma_f32_16x16x32_bf16 v[76:79], v[164:167], v[144:147], v[76:79]
	v_mfma_f32_16x16x32_bf16 v[80:83], v[184:187], v[122:125], v[80:83]
	v_mfma_f32_16x16x32_bf16 v[84:87], v[184:187], v[144:147], v[84:87]
	v_mfma_f32_16x16x32_bf16 v[88:91], v[192:195], v[122:125], v[88:91]
	v_mfma_f32_16x16x32_bf16 v[92:95], v[192:195], v[144:147], v[92:95]
	s_barrier
; #define LDA(dst, b, h) for (int m = 0; m < 4; ++m) for (int k = 0; k < 2; ++k) \
;     dst[m][k] = *reinterpret_cast<const bf16x8*>((char*)SA(b, h) + lds_byte(wr * 64 + m * 16 + fr, k * 32 + fq * 8))
; #define LDB(dst, b, h) for (int n = 0; n < 2; ++n) for (int k = 0; k < 2; ++k) \
;     dst[n][k] = *reinterpret_cast<const bf16x8*>((char*)SB(b, h) + lds_byte(wc * 32 + n * 16 + fr, k * 32 + fq * 8))
; #define MMA(ai, bj, At_, Bt_) do { __builtin_amdgcn_s_setprio(1); \
;     for (int k = 0; k < 2; ++k) for (int m = 0; m < 4; ++m) for (int n = 0; n < 2; ++n) \
;       acc[ai][bj][m][n] = __builtin_amdgcn_mfma_f32_16x16x32_bf16(At_[m][k], Bt_[n][k], acc[ai][bj][m][n], 0, 0, 0); \
;     __builtin_amdgcn_s_setprio(0); } while (0)
; #define WAIT_V(n) asm volatile("s_waitcnt vmcnt(" #n ")" ::: "memory")
; #define WAIT_L(n) asm volatile("s_waitcnt lgkmcnt(" #n ")" ::: "memory")
; #define BAR __builtin_amdgcn_s_barrier()
; template <int EPI, int lda, int ldb, int N, int K>
; __device__ __forceinline__ void gemm_phase(const u16* __restrict__ A, const u16* __restrict__ Bt, const GemmEpi ep, int wv) {
;     ...
;       LDB(B1, 0, 1); BAR; WAIT_L(0); MMA(0, 1, At, B1); BAR;
;       LDA(At, 0, 1); WAIT_V(4); BAR; WAIT_L(0); MMA(1, 0, At, B0); MMA(1, 1, At, B1); BAR; }
;     { LDB(B0, 1, 0); LDA(At, 1, 0); WAIT_V(2); BAR; WAIT_L(0); MMA(0, 0, At, B0); BAR;
	ds_read_b128 v[96:99], v224
	ds_read_b128 v[196:199], v224 offset:1024
	ds_read_b128 v[200:203], v224 offset:2048
	ds_read_b128 v[204:207], v224 offset:3072
	s_waitcnt vmcnt(8)
	s_barrier
	s_waitcnt lgkmcnt(0)
	s_waitcnt lgkmcnt(0)
	v_mfma_f32_16x16x32_bf16 v[12:15], v[152:155], v[96:99], v[12:15]
	v_mfma_f32_16x16x32_bf16 v[40:43], v[152:155], v[200:203], v[40:43]
	v_mfma_f32_16x16x32_bf16 v[52:55], v[180:183], v[96:99], v[52:55]
	v_mfma_f32_16x16x32_bf16 v[56:59], v[180:183], v[200:203], v[56:59]
	v_mfma_f32_16x16x32_bf16 v[64:67], v[188:191], v[200:203], v[64:67]
	v_mfma_f32_16x16x32_bf16 v[44:47], v[160:163], v[96:99], v[44:47]
	v_mfma_f32_16x16x32_bf16 v[48:51], v[160:163], v[200:203], v[48:51]
	v_mfma_f32_16x16x32_bf16 v[60:63], v[188:191], v[96:99], v[60:63]
	v_mfma_f32_16x16x32_bf16 v[12:15], v[156:159], v[196:199], v[12:15]
	v_mfma_f32_16x16x32_bf16 v[40:43], v[156:159], v[204:207], v[40:43]
	v_mfma_f32_16x16x32_bf16 v[52:55], v[184:187], v[196:199], v[52:55]
	v_mfma_f32_16x16x32_bf16 v[56:59], v[184:187], v[204:207], v[56:59]
	v_mfma_f32_16x16x32_bf16 v[64:67], v[192:195], v[204:207], v[64:67]
	v_mfma_f32_16x16x32_bf16 v[152:155], v[164:167], v[196:199], v[44:47]
	v_mfma_f32_16x16x32_bf16 v[156:159], v[164:167], v[204:207], v[48:51]
	v_mfma_f32_16x16x32_bf16 v[160:163], v[192:195], v[196:199], v[60:63]
	s_barrier
	ds_read_b128 v[44:47], v228 offset:16384
	ds_read_b128 v[48:51], v228 offset:17408
	ds_read_b128 v[60:63], v229 offset:18432
	ds_read_b128 v[164:167], v229 offset:19456
	ds_read_b128 v[180:183], v229 offset:20480
	ds_read_b128 v[184:187], v229 offset:21504
	ds_read_b128 v[188:191], v229 offset:22528
	ds_read_b128 v[192:195], v229 offset:23552
	s_waitcnt vmcnt(4)
	s_barrier
	s_waitcnt lgkmcnt(0)
	s_waitcnt lgkmcnt(0)
	v_mfma_f32_16x16x32_bf16 v[8:11], v[44:47], v[118:121], v[8:11]
	v_mfma_f32_16x16x32_bf16 v[24:27], v[188:191], v[118:121], v[24:27]
	v_mfma_f32_16x16x32_bf16 v[28:31], v[188:191], v[140:143], v[28:31]
	v_mfma_f32_16x16x32_bf16 v[114:117], v[44:47], v[140:143], v[114:117]
	v_mfma_f32_16x16x32_bf16 v[148:151], v[60:63], v[118:121], v[148:151]
	v_mfma_f32_16x16x32_bf16 v[168:171], v[60:63], v[140:143], v[168:171]
	v_mfma_f32_16x16x32_bf16 v[172:175], v[180:183], v[118:121], v[172:175]
	v_mfma_f32_16x16x32_bf16 v[176:179], v[180:183], v[140:143], v[176:179]
	v_mfma_f32_16x16x32_bf16 v[8:11], v[48:51], v[122:125], v[8:11]
	v_mfma_f32_16x16x32_bf16 v[24:27], v[192:195], v[122:125], v[24:27]
	v_mfma_f32_16x16x32_bf16 v[28:31], v[192:195], v[144:147], v[28:31]
	v_mfma_f32_16x16x32_bf16 v[140:143], v[48:51], v[144:147], v[114:117]
	v_mfma_f32_16x16x32_bf16 v[148:151], v[164:167], v[122:125], v[148:151]
	v_mfma_f32_16x16x32_bf16 v[168:171], v[164:167], v[144:147], v[168:171]
	v_mfma_f32_16x16x32_bf16 v[172:175], v[184:187], v[122:125], v[172:175]
	v_mfma_f32_16x16x32_bf16 v[176:179], v[184:187], v[144:147], v[176:179]
	v_mfma_f32_16x16x32_bf16 v[0:3], v[44:47], v[96:99], v[0:3]
	v_mfma_f32_16x16x32_bf16 v[20:23], v[44:47], v[200:203], v[20:23]
	v_mfma_f32_16x16x32_bf16 v[44:47], v[180:183], v[96:99], v[68:71]
	v_mfma_f32_16x16x32_bf16 v[68:71], v[188:191], v[96:99], v[102:105]
	v_mfma_f32_16x16x32_bf16 v[32:35], v[60:63], v[96:99], v[32:35]
	v_mfma_f32_16x16x32_bf16 v[36:39], v[60:63], v[200:203], v[36:39]
	v_mfma_f32_16x16x32_bf16 v[60:63], v[180:183], v[200:203], v[110:113]
	v_mfma_f32_16x16x32_bf16 v[96:99], v[188:191], v[200:203], v[106:109]
	v_mfma_f32_16x16x32_bf16 v[20:23], v[48:51], v[204:207], v[20:23]
	v_mfma_f32_16x16x32_bf16 v[68:71], v[192:195], v[196:199], v[68:71]
	v_mfma_f32_16x16x32_bf16 v[144:147], v[48:51], v[196:199], v[0:3]
	v_mfma_f32_16x16x32_bf16 v[180:183], v[164:167], v[196:199], v[32:35]
	v_mfma_f32_16x16x32_bf16 v[164:167], v[164:167], v[204:207], v[36:39]
	v_mfma_f32_16x16x32_bf16 v[188:191], v[184:187], v[196:199], v[44:47]
	v_mfma_f32_16x16x32_bf16 v[184:187], v[184:187], v[204:207], v[60:63]
	v_mfma_f32_16x16x32_bf16 v[192:195], v[192:195], v[204:207], v[96:99]
	s_barrier
	ds_read_b128 v[0:3], v225
	ds_read_b128 v[196:199], v225 offset:1024
	ds_read_b128 v[200:203], v225 offset:2048
	ds_read_b128 v[204:207], v225 offset:3072
	ds_read_b128 v[36:39], v228 offset:32768
	ds_read_b128 v[100:103], v228 offset:33792
	ds_read_b128 v[108:111], v229 offset:34816
	ds_read_b128 v[208:211], v229 offset:35840
	ds_read_b128 v[116:119], v229 offset:36864
	ds_read_b128 v[212:215], v229 offset:37888
	ds_read_b128 v[124:127], v229 offset:38912
	ds_read_b128 v[216:219], v229 offset:39936
	s_waitcnt vmcnt(2)
	s_barrier
; #define LDA(dst, b, h) for (int m = 0; m < 4; ++m) for (int k = 0; k < 2; ++k) \
;     dst[m][k] = *reinterpret_cast<const bf16x8*>((char*)SA(b, h) + lds_byte(wr * 64 + m * 16 + fr, k * 32 + fq * 8))
; #define LDB(dst, b, h) for (int n = 0; n < 2; ++n) for (int k = 0; k < 2; ++k) \
;     dst[n][k] = *reinterpret_cast<const bf16x8*>((char*)SB(b, h) + lds_byte(wc * 32 + n * 16 + fr, k * 32 + fq * 8))
; #define MMA(ai, bj, At_, Bt_) do { __builtin_amdgcn_s_setprio(1); \
;     for (int k = 0; k < 2; ++k) for (int m = 0; m < 4; ++m) for (int n = 0; n < 2; ++n) \
;       acc[ai][bj][m][n] = __builtin_amdgcn_mfma_f32_16x16x32_bf16(At_[m][k], Bt_[n][k], acc[ai][bj][m][n], 0, 0, 0); \
;     __builtin_amdgcn_s_setprio(0); } while (0)
; #define WAIT_V(n) asm volatile("s_waitcnt vmcnt(" #n ")" ::: "memory")
; #define WAIT_L(n) asm volatile("s_waitcnt lgkmcnt(" #n ")" ::: "memory")
; #define BAR __builtin_amdgcn_s_barrier()
; template <int EPI, int lda, int ldb, int N, int K>
; __device__ __forceinline__ void gemm_phase(const u16* __restrict__ A, const u16* __restrict__ Bt, const GemmEpi ep, int wv) {
;     ...
;     { LDB(B0, 1, 0); LDA(At, 1, 0); WAIT_V(2); BAR; WAIT_L(0); MMA(0, 0, At, B0); BAR;
;       LDB(B1, 1, 1); WAIT_V(0); BAR; WAIT_L(0); MMA(0, 1, At, B1); BAR;
;       LDA(At, 1, 1); BAR; WAIT_L(0); MMA(1, 0, At, B0); MMA(1, 1, At, B1); BAR; }
;     if (wr == 0) BAR;
	s_waitcnt lgkmcnt(0)
	s_waitcnt lgkmcnt(0)
	v_mfma_f32_16x16x32_bf16 v[4:7], v[36:39], v[0:3], v[4:7]
	v_mfma_f32_16x16x32_bf16 v[16:19], v[36:39], v[200:203], v[16:19]
	v_mfma_f32_16x16x32_bf16 v[32:35], v[108:111], v[0:3], v[72:75]
	v_mfma_f32_16x16x32_bf16 v[44:47], v[108:111], v[200:203], v[76:79]
	v_mfma_f32_16x16x32_bf16 v[72:75], v[116:119], v[0:3], v[80:83]
	v_mfma_f32_16x16x32_bf16 v[76:79], v[116:119], v[200:203], v[84:87]
	v_mfma_f32_16x16x32_bf16 v[80:83], v[124:127], v[0:3], v[88:91]
	v_mfma_f32_16x16x32_bf16 v[84:87], v[124:127], v[200:203], v[92:95]
	v_mfma_f32_16x16x32_bf16 v[120:123], v[100:103], v[196:199], v[4:7]
	v_mfma_f32_16x16x32_bf16 v[60:63], v[100:103], v[204:207], v[16:19]
	v_mfma_f32_16x16x32_bf16 v[112:115], v[208:211], v[196:199], v[32:35]
	v_mfma_f32_16x16x32_bf16 v[48:51], v[208:211], v[204:207], v[44:47]
	v_mfma_f32_16x16x32_bf16 v[104:107], v[212:215], v[196:199], v[72:75]
	v_mfma_f32_16x16x32_bf16 v[44:47], v[212:215], v[204:207], v[76:79]
	v_mfma_f32_16x16x32_bf16 v[96:99], v[216:219], v[196:199], v[80:83]
	v_mfma_f32_16x16x32_bf16 v[32:35], v[216:219], v[204:207], v[84:87]
	s_barrier
	ds_read_b128 v[4:7], v226
	ds_read_b128 v[220:223], v226 offset:1024
	ds_read_b128 v[76:79], v226 offset:2048
	ds_read_b128 v[224:227], v226 offset:3072
	s_waitcnt vmcnt(0)
	s_barrier
	s_waitcnt lgkmcnt(0)
	s_waitcnt lgkmcnt(0)
	v_mfma_f32_16x16x32_bf16 v[12:15], v[36:39], v[4:7], v[12:15]
	v_mfma_f32_16x16x32_bf16 v[16:19], v[36:39], v[76:79], v[40:43]
	v_mfma_f32_16x16x32_bf16 v[36:39], v[108:111], v[4:7], v[152:155]
	v_mfma_f32_16x16x32_bf16 v[40:43], v[108:111], v[76:79], v[156:159]
	v_mfma_f32_16x16x32_bf16 v[72:75], v[116:119], v[4:7], v[52:55]
	v_mfma_f32_16x16x32_bf16 v[80:83], v[116:119], v[76:79], v[56:59]
	v_mfma_f32_16x16x32_bf16 v[84:87], v[124:127], v[4:7], v[160:163]
	v_mfma_f32_16x16x32_bf16 v[64:67], v[124:127], v[76:79], v[64:67]
	v_mfma_f32_16x16x32_bf16 v[124:127], v[100:103], v[220:223], v[12:15]
	v_mfma_f32_16x16x32_bf16 v[56:59], v[100:103], v[224:227], v[16:19]
	v_mfma_f32_16x16x32_bf16 v[116:119], v[208:211], v[220:223], v[36:39]
	v_mfma_f32_16x16x32_bf16 v[52:55], v[208:211], v[224:227], v[40:43]
	v_mfma_f32_16x16x32_bf16 v[108:111], v[212:215], v[220:223], v[72:75]
	v_mfma_f32_16x16x32_bf16 v[40:43], v[212:215], v[224:227], v[80:83]
	v_mfma_f32_16x16x32_bf16 v[100:103], v[216:219], v[220:223], v[84:87]
	v_mfma_f32_16x16x32_bf16 v[36:39], v[216:219], v[224:227], v[64:67]
	s_barrier
	ds_read_b128 v[84:87], v228 offset:49152
	ds_read_b128 v[152:155], v228 offset:50176
	ds_read_b128 v[92:95], v229 offset:51200
	ds_read_b128 v[156:159], v229 offset:52224
	ds_read_b128 v[160:163], v229 offset:53248
	ds_read_b128 v[208:211], v229 offset:54272
	ds_read_b128 v[212:215], v229 offset:55296
	ds_read_b128 v[216:219], v229 offset:56320
	s_barrier
	s_waitcnt lgkmcnt(0)
	s_waitcnt lgkmcnt(0)
	v_mfma_f32_16x16x32_bf16 v[8:11], v[84:87], v[0:3], v[8:11]
	v_mfma_f32_16x16x32_bf16 v[12:15], v[84:87], v[200:203], v[140:143]
	v_mfma_f32_16x16x32_bf16 v[16:19], v[92:95], v[0:3], v[148:151]
	v_mfma_f32_16x16x32_bf16 v[64:67], v[92:95], v[200:203], v[168:171]
	v_mfma_f32_16x16x32_bf16 v[72:75], v[160:163], v[0:3], v[172:175]
	v_mfma_f32_16x16x32_bf16 v[140:143], v[160:163], v[200:203], v[176:179]
	v_mfma_f32_16x16x32_bf16 v[0:3], v[212:215], v[0:3], v[24:27]
	v_mfma_f32_16x16x32_bf16 v[24:27], v[212:215], v[200:203], v[28:31]
	v_mfma_f32_16x16x32_bf16 v[88:91], v[152:155], v[196:199], v[8:11]
	v_mfma_f32_16x16x32_bf16 v[28:31], v[152:155], v[204:207], v[12:15]
	v_mfma_f32_16x16x32_bf16 v[80:83], v[156:159], v[196:199], v[16:19]
	v_mfma_f32_16x16x32_bf16 v[16:19], v[156:159], v[204:207], v[64:67]
	v_mfma_f32_16x16x32_bf16 v[72:75], v[208:211], v[196:199], v[72:75]
	v_mfma_f32_16x16x32_bf16 v[12:15], v[208:211], v[204:207], v[140:143]
	v_mfma_f32_16x16x32_bf16 v[64:67], v[216:219], v[196:199], v[0:3]
	v_mfma_f32_16x16x32_bf16 v[0:3], v[216:219], v[204:207], v[24:27]
	v_mfma_f32_16x16x32_bf16 v[8:11], v[84:87], v[4:7], v[144:147]
	v_mfma_f32_16x16x32_bf16 v[20:23], v[84:87], v[76:79], v[20:23]
	v_mfma_f32_16x16x32_bf16 v[84:87], v[92:95], v[4:7], v[180:183]
	v_mfma_f32_16x16x32_bf16 v[140:143], v[92:95], v[76:79], v[164:167]
	v_mfma_f32_16x16x32_bf16 v[144:147], v[160:163], v[4:7], v[188:191]
	v_mfma_f32_16x16x32_bf16 v[148:151], v[160:163], v[76:79], v[184:187]
	v_mfma_f32_16x16x32_bf16 v[4:7], v[212:215], v[4:7], v[68:71]
	v_mfma_f32_16x16x32_bf16 v[160:163], v[212:215], v[76:79], v[192:195]
	v_mfma_f32_16x16x32_bf16 v[92:95], v[152:155], v[220:223], v[8:11]
	v_mfma_f32_16x16x32_bf16 v[24:27], v[152:155], v[224:227], v[20:23]
	v_mfma_f32_16x16x32_bf16 v[84:87], v[156:159], v[220:223], v[84:87]
	v_mfma_f32_16x16x32_bf16 v[20:23], v[156:159], v[224:227], v[140:143]
	v_mfma_f32_16x16x32_bf16 v[76:79], v[208:211], v[220:223], v[144:147]
	v_mfma_f32_16x16x32_bf16 v[8:11], v[208:211], v[224:227], v[148:151]
	v_mfma_f32_16x16x32_bf16 v[68:71], v[216:219], v[220:223], v[4:7]
	v_mfma_f32_16x16x32_bf16 v[4:7], v[216:219], v[224:227], v[160:163]
	v_cmp_gt_u32_e32 vcc, s60, v130
	s_barrier
	s_and_saveexec_b64 s[46:47], vcc
	s_cbranch_execz .LBB0_1346
	s_barrier
	s_branch .LBB0_1346

; #define STAGE(P, BASE, LD, br, kt) do { const char* _g = (const char*)((BASE) + (size_t)(br) * (LD) + (size_t)(kt) * 64); \
;     for (int _i = 0; _i < 2; ++_i) { int _b = tidx * 16 + _i * 8192; int _r, _c; stage_rc(_b, _r, _c); \
;       __builtin_amdgcn_global_load_lds((const unsigned*)(_g + (unsigned)((_r * (LD) + _c) * 2)), (unsigned*)((char*)(P) + _b), 16, 0, 0); } } while (0)
; #define LDA(dst, b, h) for (int m = 0; m < 4; ++m) for (int k = 0; k < 2; ++k) \
;     dst[m][k] = *reinterpret_cast<const bf16x8*>((char*)SA(b, h) + lds_byte(wr * 64 + m * 16 + fr, k * 32 + fq * 8))
; #define LDB(dst, b, h) for (int n = 0; n < 2; ++n) for (int k = 0; k < 2; ++k) \
;     dst[n][k] = *reinterpret_cast<const bf16x8*>((char*)SB(b, h) + lds_byte(wc * 32 + n * 16 + fr, k * 32 + fq * 8))
; #define MMA(ai, bj, At_, Bt_) do { __builtin_amdgcn_s_setprio(1); \
;     for (int k = 0; k < 2; ++k) for (int m = 0; m < 4; ++m) for (int n = 0; n < 2; ++n) \
;       acc[ai][bj][m][n] = __builtin_amdgcn_mfma_f32_16x16x32_bf16(At_[m][k], Bt_[n][k], acc[ai][bj][m][n], 0, 0, 0); \
;     __builtin_amdgcn_s_setprio(0); } while (0)
; #define WAIT_L(n) asm volatile("s_waitcnt lgkmcnt(" #n ")" ::: "memory")
; #define BAR __builtin_amdgcn_s_barrier()
; #define SCHED __builtin_amdgcn_sched_barrier(0)
; template <int EPI, int lda, int ldb, int N, int K>
; __device__ __forceinline__ void gemm_phase(const u16* __restrict__ A, const u16* __restrict__ Bt, const GemmEpi ep, int wv) {
;     ...
;       LDB(B0, 0, 0); SCHED; LDA(At, 0, 0); STAGE(SA(1, 1), Ab, lda, brow + HALF, t + 1);
;       WAIT_L(8); BAR; WAIT_L(0); MMA(0, 0, At, B0); BAR; SCHED;
;       LDB(B1, 0, 1); STAGE(SB(0, 0), Bt, ldb, bcol, t + 2);
;       BAR; WAIT_L(0); MMA(0, 1, At, B1); BAR;
;       LDA(At, 0, 1); STAGE(SA(0, 0), Ab, lda, brow, t + 2);
;       BAR; WAIT_L(0); MMA(1, 0, At, B0); BAR; SCHED;
.LBB0_1448:
	ds_read_b128 v[164:167], v160
	ds_read_b128 v[170:173], v160 offset:1024
	ds_read_b128 v[174:177], v160 offset:2048
	ds_read_b128 v[178:181], v160 offset:3072
	v_add_u32_e32 v168, 0xc000, v143
	v_lshl_add_u64 v[234:235], v[138:139], 0, s[44:45]
	v_readfirstlane_b32 s47, v168
	v_add_u32_e32 v169, 0xe000, v143
	v_lshl_add_u64 v[162:163], v[234:235], 0, s[20:21]
	s_mov_b32 m0, s47
	v_lshl_add_u64 v[236:237], v[140:141], 0, s[44:45]
	v_readfirstlane_b32 s47, v169
	ds_read_b128 v[182:185], v151
	ds_read_b128 v[186:189], v151 offset:1024
	ds_read_b128 v[190:193], v150
	ds_read_b128 v[194:197], v150 offset:1024
	ds_read_b128 v[198:201], v149
	ds_read_b128 v[202:205], v149 offset:1024
	ds_read_b128 v[206:209], v148
	ds_read_b128 v[210:213], v148 offset:1024
	global_load_lds_dwordx4 v[162:163], off
	v_lshl_add_u64 v[162:163], v[236:237], 0, s[20:21]
	s_mov_b32 m0, s47
	s_nop 0
	global_load_lds_dwordx4 v[162:163], off
	s_waitcnt lgkmcnt(8)
	s_barrier
	s_waitcnt lgkmcnt(0)
	s_waitcnt lgkmcnt(0)
	v_mfma_f32_16x16x32_bf16 v[124:127], v[164:167], v[182:185], v[124:127]
	v_mfma_f32_16x16x32_bf16 v[120:123], v[174:177], v[182:185], v[120:123]
	v_mfma_f32_16x16x32_bf16 v[116:119], v[164:167], v[190:193], v[116:119]
	v_mfma_f32_16x16x32_bf16 v[112:115], v[174:177], v[190:193], v[112:115]
	v_mfma_f32_16x16x32_bf16 v[108:111], v[164:167], v[198:201], v[108:111]
	v_mfma_f32_16x16x32_bf16 v[104:107], v[174:177], v[198:201], v[104:107]
	v_mfma_f32_16x16x32_bf16 v[100:103], v[164:167], v[206:209], v[100:103]
	v_mfma_f32_16x16x32_bf16 v[96:99], v[174:177], v[206:209], v[96:99]
	v_mfma_f32_16x16x32_bf16 v[124:127], v[170:173], v[186:189], v[124:127]
	v_mfma_f32_16x16x32_bf16 v[120:123], v[178:181], v[186:189], v[120:123]
	v_mfma_f32_16x16x32_bf16 v[116:119], v[170:173], v[194:197], v[116:119]
	v_mfma_f32_16x16x32_bf16 v[112:115], v[178:181], v[194:197], v[112:115]
	v_mfma_f32_16x16x32_bf16 v[108:111], v[170:173], v[202:205], v[108:111]
	v_mfma_f32_16x16x32_bf16 v[104:107], v[178:181], v[202:205], v[104:107]
	v_mfma_f32_16x16x32_bf16 v[100:103], v[170:173], v[210:213], v[100:103]
	v_mfma_f32_16x16x32_bf16 v[96:99], v[178:181], v[210:213], v[96:99]
	s_barrier
	v_add_u32_e32 v161, s55, v153
	v_lshl_add_u64 v[238:239], v[134:135], 0, s[44:45]
	v_readfirstlane_b32 s47, v161
	v_lshl_add_u64 v[162:163], v[238:239], 0, s[22:23]
	s_mov_b32 m0, s47
	ds_read_b128 v[214:217], v159
	ds_read_b128 v[218:221], v159 offset:1024
	ds_read_b128 v[222:225], v159 offset:2048
	ds_read_b128 v[226:229], v159 offset:3072
	global_load_lds_dwordx4 v[162:163], off
	v_add_u32_e32 v162, 0x2000, v161
	v_lshl_add_u64 v[240:241], v[136:137], 0, s[44:45]
	v_readfirstlane_b32 s47, v162
	v_lshl_add_u64 v[230:231], v[240:241], 0, s[22:23]
	s_mov_b32 m0, s47
	s_nop 0
	global_load_lds_dwordx4 v[230:231], off
	s_waitcnt vmcnt(10)
	s_barrier
	s_waitcnt lgkmcnt(0)
	s_waitcnt lgkmcnt(0)
	v_mfma_f32_16x16x32_bf16 v[92:95], v[214:217], v[182:185], v[92:95]
	v_mfma_f32_16x16x32_bf16 v[88:91], v[222:225], v[182:185], v[88:91]
	v_mfma_f32_16x16x32_bf16 v[84:87], v[214:217], v[190:193], v[84:87]
	v_mfma_f32_16x16x32_bf16 v[80:83], v[222:225], v[190:193], v[80:83]
	v_mfma_f32_16x16x32_bf16 v[76:79], v[214:217], v[198:201], v[76:79]
	v_mfma_f32_16x16x32_bf16 v[72:75], v[222:225], v[198:201], v[72:75]
	v_mfma_f32_16x16x32_bf16 v[68:71], v[214:217], v[206:209], v[68:71]
	v_mfma_f32_16x16x32_bf16 v[64:67], v[222:225], v[206:209], v[64:67]
	v_mfma_f32_16x16x32_bf16 v[92:95], v[218:221], v[186:189], v[92:95]
	v_mfma_f32_16x16x32_bf16 v[88:91], v[226:229], v[186:189], v[88:91]
	v_mfma_f32_16x16x32_bf16 v[84:87], v[218:221], v[194:197], v[84:87]
	v_mfma_f32_16x16x32_bf16 v[80:83], v[226:229], v[194:197], v[80:83]
	v_mfma_f32_16x16x32_bf16 v[76:79], v[218:221], v[202:205], v[76:79]
	v_mfma_f32_16x16x32_bf16 v[72:75], v[226:229], v[202:205], v[72:75]
	v_mfma_f32_16x16x32_bf16 v[68:71], v[218:221], v[210:213], v[68:71]
	v_mfma_f32_16x16x32_bf16 v[64:67], v[226:229], v[210:213], v[64:67]
	v_readfirstlane_b32 s47, v143
	v_add_u32_e32 v163, 0x2000, v143
	v_lshl_add_u64 v[230:231], v[234:235], 0, s[24:25]
	s_mov_b32 m0, s47
	v_readfirstlane_b32 s47, v163
	s_barrier
	ds_read_b128 v[182:185], v151 offset:16384
	ds_read_b128 v[186:189], v151 offset:17408
	ds_read_b128 v[190:193], v150 offset:16384
	ds_read_b128 v[194:197], v150 offset:17408
	ds_read_b128 v[198:201], v149 offset:16384
	ds_read_b128 v[202:205], v149 offset:17408
	ds_read_b128 v[206:209], v148 offset:16384
	ds_read_b128 v[210:213], v148 offset:17408
	global_load_lds_dwordx4 v[230:231], off
	v_lshl_add_u64 v[230:231], v[236:237], 0, s[24:25]
	s_mov_b32 m0, s47
	s_nop 0
	global_load_lds_dwordx4 v[230:231], off
	s_barrier
	s_waitcnt lgkmcnt(0)
	s_waitcnt lgkmcnt(0)
	v_mfma_f32_16x16x32_bf16 v[60:63], v[164:167], v[182:185], v[60:63]
	v_mfma_f32_16x16x32_bf16 v[56:59], v[174:177], v[182:185], v[56:59]
	v_mfma_f32_16x16x32_bf16 v[52:55], v[164:167], v[190:193], v[52:55]
	v_mfma_f32_16x16x32_bf16 v[48:51], v[174:177], v[190:193], v[48:51]
	v_mfma_f32_16x16x32_bf16 v[44:47], v[164:167], v[198:201], v[44:47]
	v_mfma_f32_16x16x32_bf16 v[40:43], v[174:177], v[198:201], v[40:43]
	v_mfma_f32_16x16x32_bf16 v[36:39], v[164:167], v[206:209], v[36:39]
	v_mfma_f32_16x16x32_bf16 v[32:35], v[174:177], v[206:209], v[32:35]
	v_mfma_f32_16x16x32_bf16 v[60:63], v[170:173], v[186:189], v[60:63]
	v_mfma_f32_16x16x32_bf16 v[56:59], v[178:181], v[186:189], v[56:59]
	v_mfma_f32_16x16x32_bf16 v[52:55], v[170:173], v[194:197], v[52:55]
	v_mfma_f32_16x16x32_bf16 v[48:51], v[178:181], v[194:197], v[48:51]
	v_mfma_f32_16x16x32_bf16 v[44:47], v[170:173], v[202:205], v[44:47]
	v_mfma_f32_16x16x32_bf16 v[40:43], v[178:181], v[202:205], v[40:43]
	v_mfma_f32_16x16x32_bf16 v[36:39], v[170:173], v[210:213], v[36:39]
	v_mfma_f32_16x16x32_bf16 v[32:35], v[178:181], v[210:213], v[32:35]
	s_barrier
; #define STAGE(P, BASE, LD, br, kt) do { const char* _g = (const char*)((BASE) + (size_t)(br) * (LD) + (size_t)(kt) * 64); \
;     for (int _i = 0; _i < 2; ++_i) { int _b = tidx * 16 + _i * 8192; int _r, _c; stage_rc(_b, _r, _c); \
;       __builtin_amdgcn_global_load_lds((const unsigned*)(_g + (unsigned)((_r * (LD) + _c) * 2)), (unsigned*)((char*)(P) + _b), 16, 0, 0); } } while (0)
; #define LDA(dst, b, h) for (int m = 0; m < 4; ++m) for (int k = 0; k < 2; ++k) \
;     dst[m][k] = *reinterpret_cast<const bf16x8*>((char*)SA(b, h) + lds_byte(wr * 64 + m * 16 + fr, k * 32 + fq * 8))
; #define LDB(dst, b, h) for (int n = 0; n < 2; ++n) for (int k = 0; k < 2; ++k) \
;     dst[n][k] = *reinterpret_cast<const bf16x8*>((char*)SB(b, h) + lds_byte(wc * 32 + n * 16 + fr, k * 32 + fq * 8))
; #define MMA(ai, bj, At_, Bt_) do { __builtin_amdgcn_s_setprio(1); \
;     for (int k = 0; k < 2; ++k) for (int m = 0; m < 4; ++m) for (int n = 0; n < 2; ++n) \
;       acc[ai][bj][m][n] = __builtin_amdgcn_mfma_f32_16x16x32_bf16(At_[m][k], Bt_[n][k], acc[ai][bj][m][n], 0, 0, 0); \
;     __builtin_amdgcn_s_setprio(0); } while (0)
; #define WAIT_V(n) asm volatile("s_waitcnt vmcnt(" #n ")" ::: "memory")
; #define WAIT_L(n) asm volatile("s_waitcnt lgkmcnt(" #n ")" ::: "memory")
; #define BAR __builtin_amdgcn_s_barrier()
; #define SCHED __builtin_amdgcn_sched_barrier(0)
; template <int EPI, int lda, int ldb, int N, int K>
; __device__ __forceinline__ void gemm_phase(const u16* __restrict__ A, const u16* __restrict__ Bt, const GemmEpi ep, int wv) {
;     ...
;       STAGE(SB(0, 1), Bt, ldb, bcol + HALF, t + 2);
;       WAIT_V(6); BAR; MMA(1, 1, At, B1); BAR;
;       LDB(B0, 1, 0); SCHED; LDA(At, 1, 0); STAGE(SA(0, 1), Ab, lda, brow + HALF, t + 2);
;       WAIT_L(8); BAR; WAIT_L(0); MMA(0, 0, At, B0); BAR; SCHED;
;       LDB(B1, 1, 1); STAGE(SB(1, 0), Bt, ldb, bcol, t + 3);
;       BAR; WAIT_L(0); MMA(0, 1, At, B1); BAR;
	v_add_u32_e32 v164, s56, v153
	v_add_u32_e32 v165, 0x2000, v164
	v_readfirstlane_b32 s47, v164
	v_lshl_add_u64 v[166:167], v[238:239], 0, s[26:27]
	s_mov_b32 m0, s47
	v_readfirstlane_b32 s47, v165
	global_load_lds_dwordx4 v[166:167], off
	v_lshl_add_u64 v[166:167], v[240:241], 0, s[26:27]
	s_mov_b32 m0, s47
	s_nop 0
	global_load_lds_dwordx4 v[166:167], off
	s_waitcnt vmcnt(8)
	s_barrier
	v_mfma_f32_16x16x32_bf16 v[28:31], v[214:217], v[182:185], v[28:31]
	v_mfma_f32_16x16x32_bf16 v[24:27], v[222:225], v[182:185], v[24:27]
	v_mfma_f32_16x16x32_bf16 v[20:23], v[214:217], v[190:193], v[20:23]
	v_mfma_f32_16x16x32_bf16 v[16:19], v[222:225], v[190:193], v[16:19]
	v_mfma_f32_16x16x32_bf16 v[12:15], v[214:217], v[198:201], v[12:15]
	v_mfma_f32_16x16x32_bf16 v[8:11], v[222:225], v[198:201], v[8:11]
	v_mfma_f32_16x16x32_bf16 v[4:7], v[214:217], v[206:209], v[4:7]
	v_mfma_f32_16x16x32_bf16 v[0:3], v[222:225], v[206:209], v[0:3]
	v_mfma_f32_16x16x32_bf16 v[28:31], v[218:221], v[186:189], v[28:31]
	v_mfma_f32_16x16x32_bf16 v[24:27], v[226:229], v[186:189], v[24:27]
	v_mfma_f32_16x16x32_bf16 v[20:23], v[218:221], v[194:197], v[20:23]
	v_mfma_f32_16x16x32_bf16 v[16:19], v[226:229], v[194:197], v[16:19]
	v_mfma_f32_16x16x32_bf16 v[12:15], v[218:221], v[202:205], v[12:15]
	v_mfma_f32_16x16x32_bf16 v[8:11], v[226:229], v[202:205], v[8:11]
	v_mfma_f32_16x16x32_bf16 v[4:7], v[218:221], v[210:213], v[4:7]
	v_mfma_f32_16x16x32_bf16 v[0:3], v[226:229], v[210:213], v[0:3]
	s_barrier
	ds_read_b128 v[170:173], v154
	ds_read_b128 v[174:177], v154 offset:1024
	ds_read_b128 v[178:181], v154 offset:2048
	ds_read_b128 v[182:185], v154 offset:3072
	v_add_u32_e32 v166, 0x4000, v143
	v_add_u32_e32 v167, 0x6000, v143
	v_readfirstlane_b32 s47, v166
	v_lshl_add_u64 v[218:219], v[234:235], 0, s[34:35]
	s_mov_b32 m0, s47
	v_readfirstlane_b32 s47, v167
	ds_read_b128 v[186:189], v151 offset:32768
	ds_read_b128 v[190:193], v151 offset:33792
	ds_read_b128 v[194:197], v150 offset:32768
	ds_read_b128 v[198:201], v150 offset:33792
	ds_read_b128 v[202:205], v149 offset:32768
	ds_read_b128 v[206:209], v149 offset:33792
	ds_read_b128 v[210:213], v148 offset:32768
	ds_read_b128 v[214:217], v148 offset:33792
	global_load_lds_dwordx4 v[218:219], off
	v_lshl_add_u64 v[218:219], v[236:237], 0, s[34:35]
	s_mov_b32 m0, s47
	s_nop 0
	global_load_lds_dwordx4 v[218:219], off
	s_waitcnt lgkmcnt(8)
	s_barrier
	s_waitcnt lgkmcnt(0)
	s_waitcnt lgkmcnt(0)
	v_mfma_f32_16x16x32_bf16 v[124:127], v[170:173], v[186:189], v[124:127]
	v_mfma_f32_16x16x32_bf16 v[120:123], v[178:181], v[186:189], v[120:123]
	v_mfma_f32_16x16x32_bf16 v[116:119], v[170:173], v[194:197], v[116:119]
	v_mfma_f32_16x16x32_bf16 v[112:115], v[178:181], v[194:197], v[112:115]
	v_mfma_f32_16x16x32_bf16 v[108:111], v[170:173], v[202:205], v[108:111]
	v_mfma_f32_16x16x32_bf16 v[104:107], v[178:181], v[202:205], v[104:107]
	v_mfma_f32_16x16x32_bf16 v[100:103], v[170:173], v[210:213], v[100:103]
	v_mfma_f32_16x16x32_bf16 v[96:99], v[178:181], v[210:213], v[96:99]
	v_mfma_f32_16x16x32_bf16 v[124:127], v[174:177], v[190:193], v[124:127]
	v_mfma_f32_16x16x32_bf16 v[120:123], v[182:185], v[190:193], v[120:123]
	v_mfma_f32_16x16x32_bf16 v[116:119], v[174:177], v[198:201], v[116:119]
	v_mfma_f32_16x16x32_bf16 v[112:115], v[182:185], v[198:201], v[112:115]
	v_mfma_f32_16x16x32_bf16 v[108:111], v[174:177], v[206:209], v[108:111]
	v_mfma_f32_16x16x32_bf16 v[104:107], v[182:185], v[206:209], v[104:107]
	v_mfma_f32_16x16x32_bf16 v[100:103], v[174:177], v[214:217], v[100:103]
	v_mfma_f32_16x16x32_bf16 v[96:99], v[182:185], v[214:217], v[96:99]
	s_barrier
	v_readfirstlane_b32 s47, v155
	v_add_u32_e32 v244, 0x2000, v155
	v_lshl_add_u64 v[242:243], v[238:239], 0, s[36:37]
	s_mov_b32 m0, s47
	v_readfirstlane_b32 s47, v244
	ds_read_b128 v[218:221], v152
	ds_read_b128 v[222:225], v152 offset:1024
	ds_read_b128 v[226:229], v152 offset:2048
	ds_read_b128 v[230:233], v152 offset:3072
	global_load_lds_dwordx4 v[242:243], off
	v_lshl_add_u64 v[242:243], v[240:241], 0, s[36:37]
	s_mov_b32 m0, s47
	s_nop 0
	global_load_lds_dwordx4 v[242:243], off
	s_waitcnt vmcnt(10)
	s_barrier
	s_waitcnt lgkmcnt(0)
	s_waitcnt lgkmcnt(0)
	v_mfma_f32_16x16x32_bf16 v[92:95], v[218:221], v[186:189], v[92:95]
	v_mfma_f32_16x16x32_bf16 v[88:91], v[226:229], v[186:189], v[88:91]
	v_mfma_f32_16x16x32_bf16 v[84:87], v[218:221], v[194:197], v[84:87]
	v_mfma_f32_16x16x32_bf16 v[80:83], v[226:229], v[194:197], v[80:83]
	v_mfma_f32_16x16x32_bf16 v[76:79], v[218:221], v[202:205], v[76:79]
	v_mfma_f32_16x16x32_bf16 v[72:75], v[226:229], v[202:205], v[72:75]
	v_mfma_f32_16x16x32_bf16 v[68:71], v[218:221], v[210:213], v[68:71]
	v_mfma_f32_16x16x32_bf16 v[64:67], v[226:229], v[210:213], v[64:67]
	v_mfma_f32_16x16x32_bf16 v[92:95], v[222:225], v[190:193], v[92:95]
	v_mfma_f32_16x16x32_bf16 v[88:91], v[230:233], v[190:193], v[88:91]
	v_mfma_f32_16x16x32_bf16 v[84:87], v[222:225], v[198:201], v[84:87]
	v_mfma_f32_16x16x32_bf16 v[80:83], v[230:233], v[198:201], v[80:83]
	v_mfma_f32_16x16x32_bf16 v[76:79], v[222:225], v[206:209], v[76:79]
	v_mfma_f32_16x16x32_bf16 v[72:75], v[230:233], v[206:209], v[72:75]
	v_mfma_f32_16x16x32_bf16 v[68:71], v[222:225], v[214:217], v[68:71]
	v_mfma_f32_16x16x32_bf16 v[64:67], v[230:233], v[214:217], v[64:67]
	v_readfirstlane_b32 s47, v156
	v_lshl_add_u64 v[234:235], v[234:235], 0, s[38:39]
	s_mov_b32 m0, s47
	v_readfirstlane_b32 s47, v157
	s_barrier
; #define STAGE(P, BASE, LD, br, kt) do { const char* _g = (const char*)((BASE) + (size_t)(br) * (LD) + (size_t)(kt) * 64); \
;     for (int _i = 0; _i < 2; ++_i) { int _b = tidx * 16 + _i * 8192; int _r, _c; stage_rc(_b, _r, _c); \
;       __builtin_amdgcn_global_load_lds((const unsigned*)(_g + (unsigned)((_r * (LD) + _c) * 2)), (unsigned*)((char*)(P) + _b), 16, 0, 0); } } while (0)
; #define LDA(dst, b, h) for (int m = 0; m < 4; ++m) for (int k = 0; k < 2; ++k) \
;     dst[m][k] = *reinterpret_cast<const bf16x8*>((char*)SA(b, h) + lds_byte(wr * 64 + m * 16 + fr, k * 32 + fq * 8))
; #define LDB(dst, b, h) for (int n = 0; n < 2; ++n) for (int k = 0; k < 2; ++k) \
;     dst[n][k] = *reinterpret_cast<const bf16x8*>((char*)SB(b, h) + lds_byte(wc * 32 + n * 16 + fr, k * 32 + fq * 8))
; #define MMA(ai, bj, At_, Bt_) do { __builtin_amdgcn_s_setprio(1); \
;     for (int k = 0; k < 2; ++k) for (int m = 0; m < 4; ++m) for (int n = 0; n < 2; ++n) \
;       acc[ai][bj][m][n] = __builtin_amdgcn_mfma_f32_16x16x32_bf16(At_[m][k], Bt_[n][k], acc[ai][bj][m][n], 0, 0, 0); \
;     __builtin_amdgcn_s_setprio(0); } while (0)
; #define WAIT_V(n) asm volatile("s_waitcnt vmcnt(" #n ")" ::: "memory")
; #define WAIT_L(n) asm volatile("s_waitcnt lgkmcnt(" #n ")" ::: "memory")
; #define BAR __builtin_amdgcn_s_barrier()
; #define SCHED __builtin_amdgcn_sched_barrier(0)
; template <int EPI, int lda, int ldb, int N, int K>
; __device__ __forceinline__ void gemm_phase(const u16* __restrict__ A, const u16* __restrict__ Bt, const GemmEpi ep, int wv) {
;     ...
;       LDA(At, 1, 1); STAGE(SA(1, 0), Ab, lda, brow, t + 3);
;       BAR; WAIT_L(0); MMA(1, 0, At, B0); BAR; SCHED;
;       STAGE(SB(1, 1), Bt, ldb, bcol + HALF, t + 3);
;       WAIT_V(6); BAR; MMA(1, 1, At, B1); BAR;
;     }
;     { LDB(B0, 0, 0); LDA(At, 0, 0); STAGE(SA(1, 1), Ab, lda, brow + HALF, nt - 1);
;       BAR; WAIT_L(0); MMA(0, 0, At, B0); BAR;
;       LDB(B1, 0, 1); BAR; WAIT_L(0); MMA(0, 1, At, B1); BAR;
	ds_read_b128 v[186:189], v151 offset:49152
	ds_read_b128 v[190:193], v151 offset:50176
	ds_read_b128 v[194:197], v150 offset:49152
	ds_read_b128 v[198:201], v150 offset:50176
	ds_read_b128 v[202:205], v149 offset:49152
	ds_read_b128 v[206:209], v149 offset:50176
	ds_read_b128 v[210:213], v148 offset:49152
	ds_read_b128 v[214:217], v148 offset:50176
	global_load_lds_dwordx4 v[234:235], off
	v_lshl_add_u64 v[234:235], v[236:237], 0, s[38:39]
	s_mov_b32 m0, s47
	s_nop 0
	global_load_lds_dwordx4 v[234:235], off
	s_barrier
	s_waitcnt lgkmcnt(0)
	s_waitcnt lgkmcnt(0)
	v_mfma_f32_16x16x32_bf16 v[60:63], v[170:173], v[186:189], v[60:63]
	v_mfma_f32_16x16x32_bf16 v[56:59], v[178:181], v[186:189], v[56:59]
	v_mfma_f32_16x16x32_bf16 v[52:55], v[170:173], v[194:197], v[52:55]
	v_mfma_f32_16x16x32_bf16 v[48:51], v[178:181], v[194:197], v[48:51]
	v_mfma_f32_16x16x32_bf16 v[44:47], v[170:173], v[202:205], v[44:47]
	v_mfma_f32_16x16x32_bf16 v[40:43], v[178:181], v[202:205], v[40:43]
	v_mfma_f32_16x16x32_bf16 v[36:39], v[170:173], v[210:213], v[36:39]
	v_mfma_f32_16x16x32_bf16 v[32:35], v[178:181], v[210:213], v[32:35]
	v_mfma_f32_16x16x32_bf16 v[60:63], v[174:177], v[190:193], v[60:63]
	v_mfma_f32_16x16x32_bf16 v[56:59], v[182:185], v[190:193], v[56:59]
	v_mfma_f32_16x16x32_bf16 v[52:55], v[174:177], v[198:201], v[52:55]
	v_mfma_f32_16x16x32_bf16 v[48:51], v[182:185], v[198:201], v[48:51]
	v_mfma_f32_16x16x32_bf16 v[44:47], v[174:177], v[206:209], v[44:47]
	v_mfma_f32_16x16x32_bf16 v[40:43], v[182:185], v[206:209], v[40:43]
	v_mfma_f32_16x16x32_bf16 v[36:39], v[174:177], v[214:217], v[36:39]
	v_mfma_f32_16x16x32_bf16 v[32:35], v[182:185], v[214:217], v[32:35]
	s_barrier
	v_readfirstlane_b32 s47, v158
	v_add_u32_e32 v172, 0x2000, v158
	v_lshl_add_u64 v[170:171], v[238:239], 0, s[40:41]
	s_mov_b32 m0, s47
	v_readfirstlane_b32 s47, v172
	global_load_lds_dwordx4 v[170:171], off
	v_lshl_add_u64 v[170:171], v[240:241], 0, s[40:41]
	s_mov_b32 m0, s47
	s_nop 0
	global_load_lds_dwordx4 v[170:171], off
	s_waitcnt vmcnt(8)
	s_barrier
	v_mfma_f32_16x16x32_bf16 v[28:31], v[218:221], v[186:189], v[28:31]
	v_mfma_f32_16x16x32_bf16 v[24:27], v[226:229], v[186:189], v[24:27]
	v_mfma_f32_16x16x32_bf16 v[20:23], v[218:221], v[194:197], v[20:23]
	v_mfma_f32_16x16x32_bf16 v[16:19], v[226:229], v[194:197], v[16:19]
	v_mfma_f32_16x16x32_bf16 v[12:15], v[218:221], v[202:205], v[12:15]
	v_mfma_f32_16x16x32_bf16 v[8:11], v[226:229], v[202:205], v[8:11]
	v_mfma_f32_16x16x32_bf16 v[4:7], v[218:221], v[210:213], v[4:7]
	v_mfma_f32_16x16x32_bf16 v[0:3], v[226:229], v[210:213], v[0:3]
	v_mfma_f32_16x16x32_bf16 v[28:31], v[222:225], v[190:193], v[28:31]
	v_mfma_f32_16x16x32_bf16 v[24:27], v[230:233], v[190:193], v[24:27]
	v_mfma_f32_16x16x32_bf16 v[20:23], v[222:225], v[198:201], v[20:23]
	v_mfma_f32_16x16x32_bf16 v[16:19], v[230:233], v[198:201], v[16:19]
	v_mfma_f32_16x16x32_bf16 v[12:15], v[222:225], v[206:209], v[12:15]
	v_mfma_f32_16x16x32_bf16 v[8:11], v[230:233], v[206:209], v[8:11]
	v_mfma_f32_16x16x32_bf16 v[4:7], v[222:225], v[214:217], v[4:7]
	v_mfma_f32_16x16x32_bf16 v[0:3], v[230:233], v[214:217], v[0:3]
	s_add_i32 s46, s46, 2
	s_add_u32 s44, s44, 0x100
	s_addc_u32 s45, s45, 0
	s_cmp_gt_u32 s46, 27
	s_barrier
	s_cbranch_scc0 .LBB0_1448
	s_lshl_b64 s[44:45], s[16:17], 12
	s_add_u32 s44, s14, s44
	s_addc_u32 s45, s15, s45
	s_add_u32 s44, s44, 0x80000
	s_addc_u32 s45, s45, 0
	v_lshl_add_u64 v[156:157], s[44:45], 0, v[128:129]
	v_readfirstlane_b32 s46, v168
	v_lshl_add_u64 v[156:157], v[156:157], 0, s[42:43]
	s_mov_b32 m0, s46
	ds_read_b128 v[134:137], v160
	ds_read_b128 v[138:141], v160 offset:1024
	ds_read_b128 v[170:173], v160 offset:2048
	ds_read_b128 v[174:177], v160 offset:3072
	ds_read_b128 v[178:181], v151
	ds_read_b128 v[182:185], v151 offset:1024
	ds_read_b128 v[186:189], v150
	ds_read_b128 v[190:193], v150 offset:1024
	ds_read_b128 v[194:197], v149
	ds_read_b128 v[198:201], v149 offset:1024
	ds_read_b128 v[202:205], v148
	ds_read_b128 v[206:209], v148 offset:1024
	global_load_lds_dwordx4 v[156:157], off
	v_lshl_add_u64 v[156:157], s[44:45], 0, v[132:133]
	v_readfirstlane_b32 s44, v169
	v_lshl_add_u64 v[156:157], v[156:157], 0, s[42:43]
	s_mov_b32 m0, s44
	s_nop 0
	global_load_lds_dwordx4 v[156:157], off
	s_barrier
	s_waitcnt lgkmcnt(0)
	s_waitcnt lgkmcnt(0)
	v_mfma_f32_16x16x32_bf16 v[124:127], v[134:137], v[178:181], v[124:127]
	v_mfma_f32_16x16x32_bf16 v[120:123], v[170:173], v[178:181], v[120:123]
	v_mfma_f32_16x16x32_bf16 v[116:119], v[134:137], v[186:189], v[116:119]
	v_mfma_f32_16x16x32_bf16 v[112:115], v[170:173], v[186:189], v[112:115]
	v_mfma_f32_16x16x32_bf16 v[108:111], v[134:137], v[194:197], v[108:111]
	v_mfma_f32_16x16x32_bf16 v[104:107], v[170:173], v[194:197], v[104:107]
	v_mfma_f32_16x16x32_bf16 v[100:103], v[134:137], v[202:205], v[100:103]
	v_mfma_f32_16x16x32_bf16 v[96:99], v[170:173], v[202:205], v[96:99]
	v_mfma_f32_16x16x32_bf16 v[124:127], v[138:141], v[182:185], v[124:127]
	v_mfma_f32_16x16x32_bf16 v[120:123], v[174:177], v[182:185], v[120:123]
	v_mfma_f32_16x16x32_bf16 v[116:119], v[138:141], v[190:193], v[116:119]
	v_mfma_f32_16x16x32_bf16 v[112:115], v[174:177], v[190:193], v[112:115]
	v_mfma_f32_16x16x32_bf16 v[108:111], v[138:141], v[198:201], v[108:111]
	v_mfma_f32_16x16x32_bf16 v[104:107], v[174:177], v[198:201], v[104:107]
	v_mfma_f32_16x16x32_bf16 v[100:103], v[138:141], v[206:209], v[100:103]
	v_mfma_f32_16x16x32_bf16 v[96:99], v[174:177], v[206:209], v[96:99]
	s_barrier
	ds_read_b128 v[210:213], v159
	ds_read_b128 v[214:217], v159 offset:1024
	ds_read_b128 v[218:221], v159 offset:2048
	ds_read_b128 v[156:159], v159 offset:3072
	s_waitcnt vmcnt(8)
	s_barrier
; #define LDA(dst, b, h) for (int m = 0; m < 4; ++m) for (int k = 0; k < 2; ++k) \
;     dst[m][k] = *reinterpret_cast<const bf16x8*>((char*)SA(b, h) + lds_byte(wr * 64 + m * 16 + fr, k * 32 + fq * 8))
; #define LDB(dst, b, h) for (int n = 0; n < 2; ++n) for (int k = 0; k < 2; ++k) \
;     dst[n][k] = *reinterpret_cast<const bf16x8*>((char*)SB(b, h) + lds_byte(wc * 32 + n * 16 + fr, k * 32 + fq * 8))
; #define MMA(ai, bj, At_, Bt_) do { __builtin_amdgcn_s_setprio(1); \
;     for (int k = 0; k < 2; ++k) for (int m = 0; m < 4; ++m) for (int n = 0; n < 2; ++n) \
;       acc[ai][bj][m][n] = __builtin_amdgcn_mfma_f32_16x16x32_bf16(At_[m][k], Bt_[n][k], acc[ai][bj][m][n], 0, 0, 0); \
;     __builtin_amdgcn_s_setprio(0); } while (0)
; #define WAIT_V(n) asm volatile("s_waitcnt vmcnt(" #n ")" ::: "memory")
; #define WAIT_L(n) asm volatile("s_waitcnt lgkmcnt(" #n ")" ::: "memory")
; #define BAR __builtin_amdgcn_s_barrier()
; template <int EPI, int lda, int ldb, int N, int K>
; __device__ __forceinline__ void gemm_phase(const u16* __restrict__ A, const u16* __restrict__ Bt, const GemmEpi ep, int wv) {
;     ...
;       LDB(B1, 0, 1); BAR; WAIT_L(0); MMA(0, 1, At, B1); BAR;
;       LDA(At, 0, 1); WAIT_V(4); BAR; WAIT_L(0); MMA(1, 0, At, B0); MMA(1, 1, At, B1); BAR; }
;     { LDB(B0, 1, 0); LDA(At, 1, 0); WAIT_V(2); BAR; WAIT_L(0); MMA(0, 0, At, B0); BAR;
	s_waitcnt lgkmcnt(0)
	s_waitcnt lgkmcnt(0)
	v_mfma_f32_16x16x32_bf16 v[92:95], v[210:213], v[178:181], v[92:95]
	v_mfma_f32_16x16x32_bf16 v[88:91], v[218:221], v[178:181], v[88:91]
	v_mfma_f32_16x16x32_bf16 v[76:79], v[210:213], v[194:197], v[76:79]
	v_mfma_f32_16x16x32_bf16 v[72:75], v[218:221], v[194:197], v[72:75]
	v_mfma_f32_16x16x32_bf16 v[84:87], v[210:213], v[186:189], v[84:87]
	v_mfma_f32_16x16x32_bf16 v[80:83], v[218:221], v[186:189], v[80:83]
	v_mfma_f32_16x16x32_bf16 v[68:71], v[210:213], v[202:205], v[68:71]
	v_mfma_f32_16x16x32_bf16 v[64:67], v[218:221], v[202:205], v[64:67]
	v_mfma_f32_16x16x32_bf16 v[92:95], v[214:217], v[182:185], v[92:95]
	v_mfma_f32_16x16x32_bf16 v[88:91], v[156:159], v[182:185], v[88:91]
	v_mfma_f32_16x16x32_bf16 v[76:79], v[214:217], v[198:201], v[76:79]
	v_mfma_f32_16x16x32_bf16 v[72:75], v[156:159], v[198:201], v[72:75]
	v_mfma_f32_16x16x32_bf16 v[178:181], v[214:217], v[190:193], v[84:87]
	v_mfma_f32_16x16x32_bf16 v[182:185], v[156:159], v[190:193], v[80:83]
	v_mfma_f32_16x16x32_bf16 v[186:189], v[214:217], v[206:209], v[68:71]
	v_mfma_f32_16x16x32_bf16 v[190:193], v[156:159], v[206:209], v[64:67]
	s_barrier
	s_nop 0
	ds_read_b128 v[64:67], v151 offset:16384
	ds_read_b128 v[68:71], v151 offset:17408
	ds_read_b128 v[80:83], v150 offset:16384
	ds_read_b128 v[84:87], v150 offset:17408
	ds_read_b128 v[194:197], v149 offset:16384
	ds_read_b128 v[198:201], v149 offset:17408
	ds_read_b128 v[202:205], v148 offset:16384
	ds_read_b128 v[206:209], v148 offset:17408
	s_waitcnt vmcnt(4)
	s_barrier
	s_waitcnt lgkmcnt(0)
	s_waitcnt lgkmcnt(0)
	v_mfma_f32_16x16x32_bf16 v[60:63], v[134:137], v[64:67], v[60:63]
	v_mfma_f32_16x16x32_bf16 v[56:59], v[170:173], v[64:67], v[56:59]
	v_mfma_f32_16x16x32_bf16 v[52:55], v[134:137], v[80:83], v[52:55]
	v_mfma_f32_16x16x32_bf16 v[48:51], v[170:173], v[80:83], v[48:51]
	v_mfma_f32_16x16x32_bf16 v[44:47], v[134:137], v[194:197], v[44:47]
	v_mfma_f32_16x16x32_bf16 v[40:43], v[170:173], v[194:197], v[40:43]
	v_mfma_f32_16x16x32_bf16 v[36:39], v[134:137], v[202:205], v[36:39]
	v_mfma_f32_16x16x32_bf16 v[32:35], v[170:173], v[202:205], v[32:35]
	v_mfma_f32_16x16x32_bf16 v[60:63], v[138:141], v[68:71], v[60:63]
	v_mfma_f32_16x16x32_bf16 v[56:59], v[174:177], v[68:71], v[56:59]
	v_mfma_f32_16x16x32_bf16 v[52:55], v[138:141], v[84:87], v[52:55]
	v_mfma_f32_16x16x32_bf16 v[48:51], v[174:177], v[84:87], v[48:51]
	v_mfma_f32_16x16x32_bf16 v[44:47], v[138:141], v[198:201], v[44:47]
	v_mfma_f32_16x16x32_bf16 v[40:43], v[174:177], v[198:201], v[40:43]
	v_mfma_f32_16x16x32_bf16 v[36:39], v[138:141], v[206:209], v[36:39]
	v_mfma_f32_16x16x32_bf16 v[32:35], v[174:177], v[206:209], v[32:35]
	v_mfma_f32_16x16x32_bf16 v[28:31], v[210:213], v[64:67], v[28:31]
	v_mfma_f32_16x16x32_bf16 v[20:23], v[210:213], v[80:83], v[20:23]
	v_mfma_f32_16x16x32_bf16 v[12:15], v[210:213], v[194:197], v[12:15]
	v_mfma_f32_16x16x32_bf16 v[4:7], v[210:213], v[202:205], v[4:7]
	v_mfma_f32_16x16x32_bf16 v[24:27], v[218:221], v[64:67], v[24:27]
	v_mfma_f32_16x16x32_bf16 v[16:19], v[218:221], v[80:83], v[16:19]
	v_mfma_f32_16x16x32_bf16 v[8:11], v[218:221], v[194:197], v[8:11]
	v_mfma_f32_16x16x32_bf16 v[0:3], v[218:221], v[202:205], v[0:3]
	v_mfma_f32_16x16x32_bf16 v[28:31], v[214:217], v[68:71], v[28:31]
	v_mfma_f32_16x16x32_bf16 v[20:23], v[214:217], v[84:87], v[20:23]
	v_mfma_f32_16x16x32_bf16 v[12:15], v[214:217], v[198:201], v[12:15]
	v_mfma_f32_16x16x32_bf16 v[4:7], v[214:217], v[206:209], v[4:7]
	v_mfma_f32_16x16x32_bf16 v[134:137], v[156:159], v[68:71], v[24:27]
	v_mfma_f32_16x16x32_bf16 v[138:141], v[156:159], v[84:87], v[16:19]
	v_mfma_f32_16x16x32_bf16 v[168:171], v[156:159], v[198:201], v[8:11]
	v_mfma_f32_16x16x32_bf16 v[156:159], v[156:159], v[206:209], v[0:3]
	s_barrier
	s_nop 0
	ds_read_b128 v[0:3], v154
	ds_read_b128 v[8:11], v154 offset:1024
	ds_read_b128 v[16:19], v154 offset:2048
	ds_read_b128 v[172:175], v154 offset:3072
	ds_read_b128 v[24:27], v151 offset:32768
	ds_read_b128 v[194:197], v151 offset:33792
	ds_read_b128 v[198:201], v150 offset:32768
	ds_read_b128 v[202:205], v150 offset:33792
	ds_read_b128 v[206:209], v149 offset:32768
	ds_read_b128 v[210:213], v149 offset:33792
	ds_read_b128 v[214:217], v148 offset:32768
	ds_read_b128 v[218:221], v148 offset:33792
	s_waitcnt vmcnt(2)
	s_barrier
; #define LDA(dst, b, h) for (int m = 0; m < 4; ++m) for (int k = 0; k < 2; ++k) \
;     dst[m][k] = *reinterpret_cast<const bf16x8*>((char*)SA(b, h) + lds_byte(wr * 64 + m * 16 + fr, k * 32 + fq * 8))
; #define LDB(dst, b, h) for (int n = 0; n < 2; ++n) for (int k = 0; k < 2; ++k) \
;     dst[n][k] = *reinterpret_cast<const bf16x8*>((char*)SB(b, h) + lds_byte(wc * 32 + n * 16 + fr, k * 32 + fq * 8))
; #define MMA(ai, bj, At_, Bt_) do { __builtin_amdgcn_s_setprio(1); \
;     for (int k = 0; k < 2; ++k) for (int m = 0; m < 4; ++m) for (int n = 0; n < 2; ++n) \
;       acc[ai][bj][m][n] = __builtin_amdgcn_mfma_f32_16x16x32_bf16(At_[m][k], Bt_[n][k], acc[ai][bj][m][n], 0, 0, 0); \
;     __builtin_amdgcn_s_setprio(0); } while (0)
; #define WAIT_V(n) asm volatile("s_waitcnt vmcnt(" #n ")" ::: "memory")
; #define WAIT_L(n) asm volatile("s_waitcnt lgkmcnt(" #n ")" ::: "memory")
; #define BAR __builtin_amdgcn_s_barrier()
; template <int EPI, int lda, int ldb, int N, int K>
; __device__ __forceinline__ void gemm_phase(const u16* __restrict__ A, const u16* __restrict__ Bt, const GemmEpi ep, int wv) {
;     ...
;     { LDB(B0, 1, 0); LDA(At, 1, 0); WAIT_V(2); BAR; WAIT_L(0); MMA(0, 0, At, B0); BAR;
;       LDB(B1, 1, 1); WAIT_V(0); BAR; WAIT_L(0); MMA(0, 1, At, B1); BAR;
;       LDA(At, 1, 1); BAR; WAIT_L(0); MMA(1, 0, At, B0); MMA(1, 1, At, B1); BAR; }
;     if (wr == 0) BAR;
	s_waitcnt lgkmcnt(0)
	s_waitcnt lgkmcnt(0)
	v_mfma_f32_16x16x32_bf16 v[64:67], v[0:3], v[24:27], v[124:127]
	v_mfma_f32_16x16x32_bf16 v[68:71], v[16:19], v[24:27], v[120:123]
	v_mfma_f32_16x16x32_bf16 v[80:83], v[0:3], v[198:201], v[116:119]
	v_mfma_f32_16x16x32_bf16 v[84:87], v[16:19], v[198:201], v[112:115]
	v_mfma_f32_16x16x32_bf16 v[108:111], v[0:3], v[206:209], v[108:111]
	v_mfma_f32_16x16x32_bf16 v[104:107], v[16:19], v[206:209], v[104:107]
	v_mfma_f32_16x16x32_bf16 v[120:123], v[0:3], v[214:217], v[100:103]
	v_mfma_f32_16x16x32_bf16 v[124:127], v[16:19], v[214:217], v[96:99]
	v_mfma_f32_16x16x32_bf16 v[116:119], v[8:11], v[194:197], v[64:67]
	v_mfma_f32_16x16x32_bf16 v[112:115], v[172:175], v[194:197], v[68:71]
	v_mfma_f32_16x16x32_bf16 v[100:103], v[8:11], v[202:205], v[80:83]
	v_mfma_f32_16x16x32_bf16 v[96:99], v[172:175], v[202:205], v[84:87]
	v_mfma_f32_16x16x32_bf16 v[84:87], v[8:11], v[210:213], v[108:111]
	v_mfma_f32_16x16x32_bf16 v[80:83], v[172:175], v[210:213], v[104:107]
	v_mfma_f32_16x16x32_bf16 v[68:71], v[8:11], v[218:221], v[120:123]
	v_mfma_f32_16x16x32_bf16 v[64:67], v[172:175], v[218:221], v[124:127]
	s_barrier
	ds_read_b128 v[222:225], v152
	ds_read_b128 v[226:229], v152 offset:1024
	ds_read_b128 v[230:233], v152 offset:2048
	ds_read_b128 v[152:155], v152 offset:3072
	s_waitcnt vmcnt(0)
	s_barrier
	s_waitcnt lgkmcnt(0)
	s_waitcnt lgkmcnt(0)
	v_mfma_f32_16x16x32_bf16 v[92:95], v[222:225], v[24:27], v[92:95]
	v_mfma_f32_16x16x32_bf16 v[24:27], v[230:233], v[24:27], v[88:91]
	v_mfma_f32_16x16x32_bf16 v[88:91], v[222:225], v[198:201], v[178:181]
	v_mfma_f32_16x16x32_bf16 v[104:107], v[230:233], v[198:201], v[182:185]
	v_mfma_f32_16x16x32_bf16 v[76:79], v[222:225], v[206:209], v[76:79]
	v_mfma_f32_16x16x32_bf16 v[72:75], v[230:233], v[206:209], v[72:75]
	v_mfma_f32_16x16x32_bf16 v[176:179], v[222:225], v[214:217], v[186:189]
	v_mfma_f32_16x16x32_bf16 v[180:183], v[230:233], v[214:217], v[190:193]
	v_mfma_f32_16x16x32_bf16 v[124:127], v[226:229], v[194:197], v[92:95]
	v_mfma_f32_16x16x32_bf16 v[120:123], v[152:155], v[194:197], v[24:27]
	v_mfma_f32_16x16x32_bf16 v[108:111], v[226:229], v[202:205], v[88:91]
	v_mfma_f32_16x16x32_bf16 v[104:107], v[152:155], v[202:205], v[104:107]
	v_mfma_f32_16x16x32_bf16 v[92:95], v[226:229], v[210:213], v[76:79]
	v_mfma_f32_16x16x32_bf16 v[88:91], v[152:155], v[210:213], v[72:75]
	v_mfma_f32_16x16x32_bf16 v[76:79], v[226:229], v[218:221], v[176:179]
	v_mfma_f32_16x16x32_bf16 v[72:75], v[152:155], v[218:221], v[180:183]
	s_barrier
	ds_read_b128 v[176:179], v151 offset:49152
	ds_read_b128 v[180:183], v151 offset:50176
	ds_read_b128 v[184:187], v150 offset:49152
	ds_read_b128 v[188:191], v150 offset:50176
	ds_read_b128 v[192:195], v149 offset:49152
	ds_read_b128 v[196:199], v149 offset:50176
	ds_read_b128 v[200:203], v148 offset:49152
	ds_read_b128 v[148:151], v148 offset:50176
	s_barrier
	s_waitcnt lgkmcnt(0)
	s_waitcnt lgkmcnt(0)
	v_mfma_f32_16x16x32_bf16 v[24:27], v[0:3], v[176:179], v[60:63]
	v_mfma_f32_16x16x32_bf16 v[60:63], v[16:19], v[176:179], v[56:59]
	v_mfma_f32_16x16x32_bf16 v[52:55], v[0:3], v[184:187], v[52:55]
	v_mfma_f32_16x16x32_bf16 v[204:207], v[16:19], v[184:187], v[48:51]
	v_mfma_f32_16x16x32_bf16 v[44:47], v[0:3], v[192:195], v[44:47]
	v_mfma_f32_16x16x32_bf16 v[208:211], v[16:19], v[192:195], v[40:43]
	v_mfma_f32_16x16x32_bf16 v[0:3], v[0:3], v[200:203], v[36:39]
	v_mfma_f32_16x16x32_bf16 v[36:39], v[16:19], v[200:203], v[32:35]
	v_mfma_f32_16x16x32_bf16 v[56:59], v[8:11], v[180:183], v[24:27]
	v_mfma_f32_16x16x32_bf16 v[48:51], v[172:175], v[180:183], v[60:63]
	v_mfma_f32_16x16x32_bf16 v[40:43], v[8:11], v[188:191], v[52:55]
	v_mfma_f32_16x16x32_bf16 v[32:35], v[172:175], v[188:191], v[204:207]
	v_mfma_f32_16x16x32_bf16 v[24:27], v[8:11], v[196:199], v[44:47]
	v_mfma_f32_16x16x32_bf16 v[16:19], v[172:175], v[196:199], v[208:211]
	v_mfma_f32_16x16x32_bf16 v[8:11], v[8:11], v[148:151], v[0:3]
	v_mfma_f32_16x16x32_bf16 v[0:3], v[172:175], v[148:151], v[36:39]
	v_mfma_f32_16x16x32_bf16 v[28:31], v[222:225], v[176:179], v[28:31]
	v_mfma_f32_16x16x32_bf16 v[36:39], v[230:233], v[176:179], v[134:137]
	v_mfma_f32_16x16x32_bf16 v[20:23], v[222:225], v[184:187], v[20:23]
	v_mfma_f32_16x16x32_bf16 v[134:137], v[230:233], v[184:187], v[138:141]
	v_mfma_f32_16x16x32_bf16 v[12:15], v[222:225], v[192:195], v[12:15]
	v_mfma_f32_16x16x32_bf16 v[138:141], v[230:233], v[192:195], v[168:171]
	v_mfma_f32_16x16x32_bf16 v[4:7], v[222:225], v[200:203], v[4:7]
	v_mfma_f32_16x16x32_bf16 v[156:159], v[230:233], v[200:203], v[156:159]
	v_mfma_f32_16x16x32_bf16 v[60:63], v[226:229], v[180:183], v[28:31]
	v_mfma_f32_16x16x32_bf16 v[52:55], v[152:155], v[180:183], v[36:39]
	v_mfma_f32_16x16x32_bf16 v[44:47], v[226:229], v[188:191], v[20:23]
	v_mfma_f32_16x16x32_bf16 v[36:39], v[152:155], v[188:191], v[134:137]
	v_mfma_f32_16x16x32_bf16 v[28:31], v[226:229], v[196:199], v[12:15]
	v_mfma_f32_16x16x32_bf16 v[20:23], v[152:155], v[196:199], v[138:141]
	v_mfma_f32_16x16x32_bf16 v[12:15], v[226:229], v[148:151], v[4:7]
	v_mfma_f32_16x16x32_bf16 v[4:7], v[152:155], v[148:151], v[156:159]
	v_cmp_gt_u32_e32 vcc, s60, v130
	s_barrier
	s_and_saveexec_b64 s[44:45], vcc
	s_cbranch_execz .LBB0_1451
	s_barrier

; #define STAGE(P, BASE, LD, br, kt) do { const char* _g = (const char*)((BASE) + (size_t)(br) * (LD) + (size_t)(kt) * 64); \
;     for (int _i = 0; _i < 2; ++_i) { int _b = tidx * 16 + _i * 8192; int _r, _c; stage_rc(_b, _r, _c); \
;       __builtin_amdgcn_global_load_lds((const unsigned*)(_g + (unsigned)((_r * (LD) + _c) * 2)), (unsigned*)((char*)(P) + _b), 16, 0, 0); } } while (0)
; #define LDA(dst, b, h) for (int m = 0; m < 4; ++m) for (int k = 0; k < 2; ++k) \
;     dst[m][k] = *reinterpret_cast<const bf16x8*>((char*)SA(b, h) + lds_byte(wr * 64 + m * 16 + fr, k * 32 + fq * 8))
; #define LDB(dst, b, h) for (int n = 0; n < 2; ++n) for (int k = 0; k < 2; ++k) \
;     dst[n][k] = *reinterpret_cast<const bf16x8*>((char*)SB(b, h) + lds_byte(wc * 32 + n * 16 + fr, k * 32 + fq * 8))
; #define MMA(ai, bj, At_, Bt_) do { __builtin_amdgcn_s_setprio(1); \
;     for (int k = 0; k < 2; ++k) for (int m = 0; m < 4; ++m) for (int n = 0; n < 2; ++n) \
;       acc[ai][bj][m][n] = __builtin_amdgcn_mfma_f32_16x16x32_bf16(At_[m][k], Bt_[n][k], acc[ai][bj][m][n], 0, 0, 0); \
;     __builtin_amdgcn_s_setprio(0); } while (0)
; #define WAIT_L(n) asm volatile("s_waitcnt lgkmcnt(" #n ")" ::: "memory")
; #define BAR __builtin_amdgcn_s_barrier()
; #define SCHED __builtin_amdgcn_sched_barrier(0)
; template <int EPI, int lda, int ldb, int N, int K>
; __device__ __forceinline__ void gemm_phase(const u16* __restrict__ A, const u16* __restrict__ Bt, const GemmEpi ep, int wv) {
;     ...
;       LDB(B0, 0, 0); SCHED; LDA(At, 0, 0); STAGE(SA(1, 1), Ab, lda, brow + HALF, t + 1);
;       WAIT_L(8); BAR; WAIT_L(0); MMA(0, 0, At, B0); BAR; SCHED;
;       LDB(B1, 0, 1); STAGE(SB(0, 0), Bt, ldb, bcol, t + 2);
;       BAR; WAIT_L(0); MMA(0, 1, At, B1); BAR;
;       LDA(At, 0, 1); STAGE(SA(0, 0), Ab, lda, brow, t + 2);
;       BAR; WAIT_L(0); MMA(1, 0, At, B0); BAR; SCHED;
.LBB0_1564:
	ds_read_b128 v[172:175], v161
	ds_read_b128 v[176:179], v161 offset:1024
	ds_read_b128 v[180:183], v161 offset:2048
	ds_read_b128 v[184:187], v161 offset:3072
	v_add_u32_e32 v169, 0xc000, v148
	v_lshl_add_u64 v[236:237], v[136:137], 0, s[40:41]
	v_readfirstlane_b32 s43, v169
	v_add_u32_e32 v170, 0xe000, v148
	v_lshl_add_u64 v[162:163], v[236:237], 0, s[14:15]
	s_mov_b32 m0, s43
	v_lshl_add_u64 v[238:239], v[134:135], 0, s[40:41]
	v_readfirstlane_b32 s43, v170
	ds_read_b128 v[164:167], v152
	ds_read_b128 v[188:191], v152 offset:1024
	ds_read_b128 v[192:195], v151
	ds_read_b128 v[196:199], v151 offset:1024
	ds_read_b128 v[200:203], v150
	ds_read_b128 v[204:207], v150 offset:1024
	ds_read_b128 v[208:211], v149
	ds_read_b128 v[212:215], v149 offset:1024
	global_load_lds_dwordx4 v[162:163], off
	v_lshl_add_u64 v[162:163], v[238:239], 0, s[14:15]
	s_mov_b32 m0, s43
	s_nop 0
	global_load_lds_dwordx4 v[162:163], off
	s_waitcnt lgkmcnt(8)
	s_barrier
	s_waitcnt lgkmcnt(0)
	s_waitcnt lgkmcnt(0)
	v_mfma_f32_16x16x32_bf16 v[124:127], v[172:175], v[164:167], v[124:127]
	v_mfma_f32_16x16x32_bf16 v[120:123], v[180:183], v[164:167], v[120:123]
	v_mfma_f32_16x16x32_bf16 v[116:119], v[172:175], v[192:195], v[116:119]
	v_mfma_f32_16x16x32_bf16 v[112:115], v[180:183], v[192:195], v[112:115]
	v_mfma_f32_16x16x32_bf16 v[108:111], v[172:175], v[200:203], v[108:111]
	v_mfma_f32_16x16x32_bf16 v[104:107], v[180:183], v[200:203], v[104:107]
	v_mfma_f32_16x16x32_bf16 v[100:103], v[172:175], v[208:211], v[100:103]
	v_mfma_f32_16x16x32_bf16 v[96:99], v[180:183], v[208:211], v[96:99]
	v_mfma_f32_16x16x32_bf16 v[124:127], v[176:179], v[188:191], v[124:127]
	v_mfma_f32_16x16x32_bf16 v[120:123], v[184:187], v[188:191], v[120:123]
	v_mfma_f32_16x16x32_bf16 v[116:119], v[176:179], v[196:199], v[116:119]
	v_mfma_f32_16x16x32_bf16 v[112:115], v[184:187], v[196:199], v[112:115]
	v_mfma_f32_16x16x32_bf16 v[108:111], v[176:179], v[204:207], v[108:111]
	v_mfma_f32_16x16x32_bf16 v[104:107], v[184:187], v[204:207], v[104:107]
	v_mfma_f32_16x16x32_bf16 v[100:103], v[176:179], v[212:215], v[100:103]
	v_mfma_f32_16x16x32_bf16 v[96:99], v[184:187], v[212:215], v[96:99]
	s_barrier
	v_add_u32_e32 v162, s52, v153
	v_lshl_add_u64 v[240:241], v[140:141], 0, s[40:41]
	v_readfirstlane_b32 s43, v162
	v_add_u32_e32 v163, 0x2000, v162
	v_lshl_add_u64 v[232:233], v[240:241], 0, s[16:17]
	s_mov_b32 m0, s43
	v_lshl_add_u64 v[242:243], v[138:139], 0, s[40:41]
	v_readfirstlane_b32 s43, v163
	ds_read_b128 v[216:219], v160
	ds_read_b128 v[220:223], v160 offset:1024
	ds_read_b128 v[224:227], v160 offset:2048
	ds_read_b128 v[228:231], v160 offset:3072
	global_load_lds_dwordx4 v[232:233], off
	v_lshl_add_u64 v[232:233], v[242:243], 0, s[16:17]
	s_mov_b32 m0, s43
	s_nop 0
	global_load_lds_dwordx4 v[232:233], off
	s_waitcnt vmcnt(10)
	s_barrier
	s_waitcnt lgkmcnt(0)
	s_waitcnt lgkmcnt(0)
	v_mfma_f32_16x16x32_bf16 v[92:95], v[216:219], v[164:167], v[92:95]
	v_mfma_f32_16x16x32_bf16 v[88:91], v[224:227], v[164:167], v[88:91]
	v_mfma_f32_16x16x32_bf16 v[84:87], v[216:219], v[192:195], v[84:87]
	v_mfma_f32_16x16x32_bf16 v[80:83], v[224:227], v[192:195], v[80:83]
	v_mfma_f32_16x16x32_bf16 v[76:79], v[216:219], v[200:203], v[76:79]
	v_mfma_f32_16x16x32_bf16 v[72:75], v[224:227], v[200:203], v[72:75]
	v_mfma_f32_16x16x32_bf16 v[68:71], v[216:219], v[208:211], v[68:71]
	v_mfma_f32_16x16x32_bf16 v[64:67], v[224:227], v[208:211], v[64:67]
	v_mfma_f32_16x16x32_bf16 v[92:95], v[220:223], v[188:191], v[92:95]
	v_mfma_f32_16x16x32_bf16 v[88:91], v[228:231], v[188:191], v[88:91]
	v_mfma_f32_16x16x32_bf16 v[84:87], v[220:223], v[196:199], v[84:87]
	v_mfma_f32_16x16x32_bf16 v[80:83], v[228:231], v[196:199], v[80:83]
	v_mfma_f32_16x16x32_bf16 v[76:79], v[220:223], v[204:207], v[76:79]
	v_mfma_f32_16x16x32_bf16 v[72:75], v[228:231], v[204:207], v[72:75]
	v_mfma_f32_16x16x32_bf16 v[68:71], v[220:223], v[212:215], v[68:71]
	v_mfma_f32_16x16x32_bf16 v[64:67], v[228:231], v[212:215], v[64:67]
	v_readfirstlane_b32 s43, v148
	v_lshl_add_u64 v[164:165], v[236:237], 0, s[18:19]
	s_mov_b32 m0, s43
	s_barrier
	ds_read_b128 v[188:191], v152 offset:16384
	ds_read_b128 v[192:195], v152 offset:17408
	ds_read_b128 v[196:199], v151 offset:16384
	ds_read_b128 v[200:203], v151 offset:17408
	ds_read_b128 v[204:207], v150 offset:16384
	ds_read_b128 v[208:211], v150 offset:17408
	ds_read_b128 v[212:215], v149 offset:16384
	ds_read_b128 v[232:235], v149 offset:17408
	global_load_lds_dwordx4 v[164:165], off
	v_add_u32_e32 v164, 0x2000, v148
	v_lshl_add_u64 v[166:167], v[238:239], 0, s[18:19]
	v_readfirstlane_b32 s43, v164
	s_mov_b32 m0, s43
	s_nop 0
	global_load_lds_dwordx4 v[166:167], off
	s_barrier
	s_waitcnt lgkmcnt(0)
	s_waitcnt lgkmcnt(0)
	v_mfma_f32_16x16x32_bf16 v[60:63], v[172:175], v[188:191], v[60:63]
	v_mfma_f32_16x16x32_bf16 v[56:59], v[180:183], v[188:191], v[56:59]
	v_mfma_f32_16x16x32_bf16 v[52:55], v[172:175], v[196:199], v[52:55]
	v_mfma_f32_16x16x32_bf16 v[48:51], v[180:183], v[196:199], v[48:51]
	v_mfma_f32_16x16x32_bf16 v[44:47], v[172:175], v[204:207], v[44:47]
	v_mfma_f32_16x16x32_bf16 v[40:43], v[180:183], v[204:207], v[40:43]
	v_mfma_f32_16x16x32_bf16 v[36:39], v[172:175], v[212:215], v[36:39]
	v_mfma_f32_16x16x32_bf16 v[32:35], v[180:183], v[212:215], v[32:35]
	v_mfma_f32_16x16x32_bf16 v[60:63], v[176:179], v[192:195], v[60:63]
	v_mfma_f32_16x16x32_bf16 v[56:59], v[184:187], v[192:195], v[56:59]
	v_mfma_f32_16x16x32_bf16 v[52:55], v[176:179], v[200:203], v[52:55]
	v_mfma_f32_16x16x32_bf16 v[48:51], v[184:187], v[200:203], v[48:51]
	v_mfma_f32_16x16x32_bf16 v[44:47], v[176:179], v[208:211], v[44:47]
	v_mfma_f32_16x16x32_bf16 v[40:43], v[184:187], v[208:211], v[40:43]
	v_mfma_f32_16x16x32_bf16 v[36:39], v[176:179], v[232:235], v[36:39]
	v_mfma_f32_16x16x32_bf16 v[32:35], v[184:187], v[232:235], v[32:35]
	s_barrier
; #define STAGE(P, BASE, LD, br, kt) do { const char* _g = (const char*)((BASE) + (size_t)(br) * (LD) + (size_t)(kt) * 64); \
;     for (int _i = 0; _i < 2; ++_i) { int _b = tidx * 16 + _i * 8192; int _r, _c; stage_rc(_b, _r, _c); \
;       __builtin_amdgcn_global_load_lds((const unsigned*)(_g + (unsigned)((_r * (LD) + _c) * 2)), (unsigned*)((char*)(P) + _b), 16, 0, 0); } } while (0)
; #define LDA(dst, b, h) for (int m = 0; m < 4; ++m) for (int k = 0; k < 2; ++k) \
;     dst[m][k] = *reinterpret_cast<const bf16x8*>((char*)SA(b, h) + lds_byte(wr * 64 + m * 16 + fr, k * 32 + fq * 8))
; #define LDB(dst, b, h) for (int n = 0; n < 2; ++n) for (int k = 0; k < 2; ++k) \
;     dst[n][k] = *reinterpret_cast<const bf16x8*>((char*)SB(b, h) + lds_byte(wc * 32 + n * 16 + fr, k * 32 + fq * 8))
; #define MMA(ai, bj, At_, Bt_) do { __builtin_amdgcn_s_setprio(1); \
;     for (int k = 0; k < 2; ++k) for (int m = 0; m < 4; ++m) for (int n = 0; n < 2; ++n) \
;       acc[ai][bj][m][n] = __builtin_amdgcn_mfma_f32_16x16x32_bf16(At_[m][k], Bt_[n][k], acc[ai][bj][m][n], 0, 0, 0); \
;     __builtin_amdgcn_s_setprio(0); } while (0)
; #define WAIT_V(n) asm volatile("s_waitcnt vmcnt(" #n ")" ::: "memory")
; #define WAIT_L(n) asm volatile("s_waitcnt lgkmcnt(" #n ")" ::: "memory")
; #define BAR __builtin_amdgcn_s_barrier()
; #define SCHED __builtin_amdgcn_sched_barrier(0)
; template <int EPI, int lda, int ldb, int N, int K>
; __device__ __forceinline__ void gemm_phase(const u16* __restrict__ A, const u16* __restrict__ Bt, const GemmEpi ep, int wv) {
;     ...
;       STAGE(SB(0, 1), Bt, ldb, bcol + HALF, t + 2);
;       WAIT_V(6); BAR; MMA(1, 1, At, B1); BAR;
;       LDB(B0, 1, 0); SCHED; LDA(At, 1, 0); STAGE(SA(0, 1), Ab, lda, brow + HALF, t + 2);
;       WAIT_L(8); BAR; WAIT_L(0); MMA(0, 0, At, B0); BAR; SCHED;
;       LDB(B1, 1, 1); STAGE(SB(1, 0), Bt, ldb, bcol, t + 3);
;       BAR; WAIT_L(0); MMA(0, 1, At, B1); BAR;
	v_add_u32_e32 v165, s53, v153
	v_lshl_add_u64 v[166:167], v[240:241], 0, s[20:21]
	v_readfirstlane_b32 s43, v165
	s_mov_b32 m0, s43
	v_lshl_add_u64 v[172:173], v[242:243], 0, s[20:21]
	global_load_lds_dwordx4 v[166:167], off
	v_add_u32_e32 v166, 0x2000, v165
	s_nop 0
	v_readfirstlane_b32 s43, v166
	s_mov_b32 m0, s43
	s_nop 0
	global_load_lds_dwordx4 v[172:173], off
	s_waitcnt vmcnt(8)
	s_barrier
	v_mfma_f32_16x16x32_bf16 v[28:31], v[216:219], v[188:191], v[28:31]
	v_mfma_f32_16x16x32_bf16 v[24:27], v[224:227], v[188:191], v[24:27]
	v_mfma_f32_16x16x32_bf16 v[20:23], v[216:219], v[196:199], v[20:23]
	v_mfma_f32_16x16x32_bf16 v[16:19], v[224:227], v[196:199], v[16:19]
	v_mfma_f32_16x16x32_bf16 v[12:15], v[216:219], v[204:207], v[12:15]
	v_mfma_f32_16x16x32_bf16 v[8:11], v[224:227], v[204:207], v[8:11]
	v_mfma_f32_16x16x32_bf16 v[4:7], v[216:219], v[212:215], v[4:7]
	v_mfma_f32_16x16x32_bf16 v[0:3], v[224:227], v[212:215], v[0:3]
	v_mfma_f32_16x16x32_bf16 v[28:31], v[220:223], v[192:195], v[28:31]
	v_mfma_f32_16x16x32_bf16 v[24:27], v[228:231], v[192:195], v[24:27]
	v_mfma_f32_16x16x32_bf16 v[20:23], v[220:223], v[200:203], v[20:23]
	v_mfma_f32_16x16x32_bf16 v[16:19], v[228:231], v[200:203], v[16:19]
	v_mfma_f32_16x16x32_bf16 v[12:15], v[220:223], v[208:211], v[12:15]
	v_mfma_f32_16x16x32_bf16 v[8:11], v[228:231], v[208:211], v[8:11]
	v_mfma_f32_16x16x32_bf16 v[4:7], v[220:223], v[232:235], v[4:7]
	v_mfma_f32_16x16x32_bf16 v[0:3], v[228:231], v[232:235], v[0:3]
	s_barrier
	ds_read_b128 v[172:175], v156
	ds_read_b128 v[176:179], v156 offset:1024
	ds_read_b128 v[180:183], v156 offset:2048
	ds_read_b128 v[184:187], v156 offset:3072
	v_add_u32_e32 v167, 0x4000, v148
	v_add_u32_e32 v168, 0x6000, v148
	v_readfirstlane_b32 s43, v167
	v_lshl_add_u64 v[220:221], v[236:237], 0, s[22:23]
	s_mov_b32 m0, s43
	v_readfirstlane_b32 s43, v168
	ds_read_b128 v[188:191], v152 offset:32768
	ds_read_b128 v[192:195], v152 offset:33792
	ds_read_b128 v[196:199], v151 offset:32768
	ds_read_b128 v[200:203], v151 offset:33792
	ds_read_b128 v[204:207], v150 offset:32768
	ds_read_b128 v[208:211], v150 offset:33792
	ds_read_b128 v[212:215], v149 offset:32768
	ds_read_b128 v[216:219], v149 offset:33792
	global_load_lds_dwordx4 v[220:221], off
	v_lshl_add_u64 v[220:221], v[238:239], 0, s[22:23]
	s_mov_b32 m0, s43
	s_nop 0
	global_load_lds_dwordx4 v[220:221], off
	s_waitcnt lgkmcnt(8)
	s_barrier
	s_waitcnt lgkmcnt(0)
	s_waitcnt lgkmcnt(0)
	v_mfma_f32_16x16x32_bf16 v[124:127], v[172:175], v[188:191], v[124:127]
	v_mfma_f32_16x16x32_bf16 v[120:123], v[180:183], v[188:191], v[120:123]
	v_mfma_f32_16x16x32_bf16 v[116:119], v[172:175], v[196:199], v[116:119]
	v_mfma_f32_16x16x32_bf16 v[112:115], v[180:183], v[196:199], v[112:115]
	v_mfma_f32_16x16x32_bf16 v[108:111], v[172:175], v[204:207], v[108:111]
	v_mfma_f32_16x16x32_bf16 v[104:107], v[180:183], v[204:207], v[104:107]
	v_mfma_f32_16x16x32_bf16 v[100:103], v[172:175], v[212:215], v[100:103]
	v_mfma_f32_16x16x32_bf16 v[96:99], v[180:183], v[212:215], v[96:99]
	v_mfma_f32_16x16x32_bf16 v[124:127], v[176:179], v[192:195], v[124:127]
	v_mfma_f32_16x16x32_bf16 v[120:123], v[184:187], v[192:195], v[120:123]
	v_mfma_f32_16x16x32_bf16 v[116:119], v[176:179], v[200:203], v[116:119]
	v_mfma_f32_16x16x32_bf16 v[112:115], v[184:187], v[200:203], v[112:115]
	v_mfma_f32_16x16x32_bf16 v[108:111], v[176:179], v[208:211], v[108:111]
	v_mfma_f32_16x16x32_bf16 v[104:107], v[184:187], v[208:211], v[104:107]
	v_mfma_f32_16x16x32_bf16 v[100:103], v[176:179], v[216:219], v[100:103]
	v_mfma_f32_16x16x32_bf16 v[96:99], v[184:187], v[216:219], v[96:99]
	s_barrier
	v_readfirstlane_b32 s43, v155
	v_add_u32_e32 v171, 0x2000, v155
	v_lshl_add_u64 v[244:245], v[240:241], 0, s[24:25]
	s_mov_b32 m0, s43
	v_readfirstlane_b32 s43, v171
	ds_read_b128 v[220:223], v154
	ds_read_b128 v[224:227], v154 offset:1024
	ds_read_b128 v[228:231], v154 offset:2048
	ds_read_b128 v[232:235], v154 offset:3072
	global_load_lds_dwordx4 v[244:245], off
	v_lshl_add_u64 v[244:245], v[242:243], 0, s[24:25]
	s_mov_b32 m0, s43
	s_nop 0
	global_load_lds_dwordx4 v[244:245], off
	s_waitcnt vmcnt(10)
	s_barrier
	s_waitcnt lgkmcnt(0)
	s_waitcnt lgkmcnt(0)
	v_mfma_f32_16x16x32_bf16 v[92:95], v[220:223], v[188:191], v[92:95]
	v_mfma_f32_16x16x32_bf16 v[88:91], v[228:231], v[188:191], v[88:91]
	v_mfma_f32_16x16x32_bf16 v[84:87], v[220:223], v[196:199], v[84:87]
	v_mfma_f32_16x16x32_bf16 v[80:83], v[228:231], v[196:199], v[80:83]
	v_mfma_f32_16x16x32_bf16 v[76:79], v[220:223], v[204:207], v[76:79]
	v_mfma_f32_16x16x32_bf16 v[72:75], v[228:231], v[204:207], v[72:75]
	v_mfma_f32_16x16x32_bf16 v[68:71], v[220:223], v[212:215], v[68:71]
	v_mfma_f32_16x16x32_bf16 v[64:67], v[228:231], v[212:215], v[64:67]
	v_mfma_f32_16x16x32_bf16 v[92:95], v[224:227], v[192:195], v[92:95]
	v_mfma_f32_16x16x32_bf16 v[88:91], v[232:235], v[192:195], v[88:91]
	v_mfma_f32_16x16x32_bf16 v[84:87], v[224:227], v[200:203], v[84:87]
	v_mfma_f32_16x16x32_bf16 v[80:83], v[232:235], v[200:203], v[80:83]
	v_mfma_f32_16x16x32_bf16 v[76:79], v[224:227], v[208:211], v[76:79]
	v_mfma_f32_16x16x32_bf16 v[72:75], v[232:235], v[208:211], v[72:75]
	v_mfma_f32_16x16x32_bf16 v[68:71], v[224:227], v[216:219], v[68:71]
	v_mfma_f32_16x16x32_bf16 v[64:67], v[232:235], v[216:219], v[64:67]
	v_readfirstlane_b32 s43, v157
	v_lshl_add_u64 v[236:237], v[236:237], 0, s[26:27]
	s_mov_b32 m0, s43
	v_readfirstlane_b32 s43, v158
	s_barrier
; #define STAGE(P, BASE, LD, br, kt) do { const char* _g = (const char*)((BASE) + (size_t)(br) * (LD) + (size_t)(kt) * 64); \
;     for (int _i = 0; _i < 2; ++_i) { int _b = tidx * 16 + _i * 8192; int _r, _c; stage_rc(_b, _r, _c); \
;       __builtin_amdgcn_global_load_lds((const unsigned*)(_g + (unsigned)((_r * (LD) + _c) * 2)), (unsigned*)((char*)(P) + _b), 16, 0, 0); } } while (0)
; #define LDA(dst, b, h) for (int m = 0; m < 4; ++m) for (int k = 0; k < 2; ++k) \
;     dst[m][k] = *reinterpret_cast<const bf16x8*>((char*)SA(b, h) + lds_byte(wr * 64 + m * 16 + fr, k * 32 + fq * 8))
; #define LDB(dst, b, h) for (int n = 0; n < 2; ++n) for (int k = 0; k < 2; ++k) \
;     dst[n][k] = *reinterpret_cast<const bf16x8*>((char*)SB(b, h) + lds_byte(wc * 32 + n * 16 + fr, k * 32 + fq * 8))
; #define MMA(ai, bj, At_, Bt_) do { __builtin_amdgcn_s_setprio(1); \
;     for (int k = 0; k < 2; ++k) for (int m = 0; m < 4; ++m) for (int n = 0; n < 2; ++n) \
;       acc[ai][bj][m][n] = __builtin_amdgcn_mfma_f32_16x16x32_bf16(At_[m][k], Bt_[n][k], acc[ai][bj][m][n], 0, 0, 0); \
;     __builtin_amdgcn_s_setprio(0); } while (0)
; #define WAIT_V(n) asm volatile("s_waitcnt vmcnt(" #n ")" ::: "memory")
; #define WAIT_L(n) asm volatile("s_waitcnt lgkmcnt(" #n ")" ::: "memory")
; #define BAR __builtin_amdgcn_s_barrier()
; #define SCHED __builtin_amdgcn_sched_barrier(0)
; template <int EPI, int lda, int ldb, int N, int K>
; __device__ __forceinline__ void gemm_phase(const u16* __restrict__ A, const u16* __restrict__ Bt, const GemmEpi ep, int wv) {
;     ...
;       LDA(At, 1, 1); STAGE(SA(1, 0), Ab, lda, brow, t + 3);
;       BAR; WAIT_L(0); MMA(1, 0, At, B0); BAR; SCHED;
;       STAGE(SB(1, 1), Bt, ldb, bcol + HALF, t + 3);
;       WAIT_V(6); BAR; MMA(1, 1, At, B1); BAR;
;     }
;     { LDB(B0, 0, 0); LDA(At, 0, 0); STAGE(SA(1, 1), Ab, lda, brow + HALF, nt - 1);
;       BAR; WAIT_L(0); MMA(0, 0, At, B0); BAR;
;       LDB(B1, 0, 1); BAR; WAIT_L(0); MMA(0, 1, At, B1); BAR;
	ds_read_b128 v[188:191], v152 offset:49152
	ds_read_b128 v[192:195], v152 offset:50176
	ds_read_b128 v[196:199], v151 offset:49152
	ds_read_b128 v[200:203], v151 offset:50176
	ds_read_b128 v[204:207], v150 offset:49152
	ds_read_b128 v[208:211], v150 offset:50176
	ds_read_b128 v[212:215], v149 offset:49152
	ds_read_b128 v[216:219], v149 offset:50176
	global_load_lds_dwordx4 v[236:237], off
	v_lshl_add_u64 v[236:237], v[238:239], 0, s[26:27]
	s_mov_b32 m0, s43
	s_nop 0
	global_load_lds_dwordx4 v[236:237], off
	s_barrier
	s_waitcnt lgkmcnt(0)
	s_waitcnt lgkmcnt(0)
	v_mfma_f32_16x16x32_bf16 v[60:63], v[172:175], v[188:191], v[60:63]
	v_mfma_f32_16x16x32_bf16 v[56:59], v[180:183], v[188:191], v[56:59]
	v_mfma_f32_16x16x32_bf16 v[52:55], v[172:175], v[196:199], v[52:55]
	v_mfma_f32_16x16x32_bf16 v[48:51], v[180:183], v[196:199], v[48:51]
	v_mfma_f32_16x16x32_bf16 v[44:47], v[172:175], v[204:207], v[44:47]
	v_mfma_f32_16x16x32_bf16 v[40:43], v[180:183], v[204:207], v[40:43]
	v_mfma_f32_16x16x32_bf16 v[36:39], v[172:175], v[212:215], v[36:39]
	v_mfma_f32_16x16x32_bf16 v[32:35], v[180:183], v[212:215], v[32:35]
	v_mfma_f32_16x16x32_bf16 v[60:63], v[176:179], v[192:195], v[60:63]
	v_mfma_f32_16x16x32_bf16 v[56:59], v[184:187], v[192:195], v[56:59]
	v_mfma_f32_16x16x32_bf16 v[52:55], v[176:179], v[200:203], v[52:55]
	v_mfma_f32_16x16x32_bf16 v[48:51], v[184:187], v[200:203], v[48:51]
	v_mfma_f32_16x16x32_bf16 v[44:47], v[176:179], v[208:211], v[44:47]
	v_mfma_f32_16x16x32_bf16 v[40:43], v[184:187], v[208:211], v[40:43]
	v_mfma_f32_16x16x32_bf16 v[36:39], v[176:179], v[216:219], v[36:39]
	v_mfma_f32_16x16x32_bf16 v[32:35], v[184:187], v[216:219], v[32:35]
	s_barrier
	v_readfirstlane_b32 s43, v159
	v_add_u32_e32 v171, 0x2000, v159
	v_lshl_add_u64 v[172:173], v[240:241], 0, s[34:35]
	s_mov_b32 m0, s43
	v_readfirstlane_b32 s43, v171
	global_load_lds_dwordx4 v[172:173], off
	v_lshl_add_u64 v[172:173], v[242:243], 0, s[34:35]
	s_mov_b32 m0, s43
	s_nop 0
	global_load_lds_dwordx4 v[172:173], off
	s_waitcnt vmcnt(8)
	s_barrier
	v_mfma_f32_16x16x32_bf16 v[28:31], v[220:223], v[188:191], v[28:31]
	v_mfma_f32_16x16x32_bf16 v[24:27], v[228:231], v[188:191], v[24:27]
	v_mfma_f32_16x16x32_bf16 v[20:23], v[220:223], v[196:199], v[20:23]
	v_mfma_f32_16x16x32_bf16 v[16:19], v[228:231], v[196:199], v[16:19]
	v_mfma_f32_16x16x32_bf16 v[12:15], v[220:223], v[204:207], v[12:15]
	v_mfma_f32_16x16x32_bf16 v[8:11], v[228:231], v[204:207], v[8:11]
	v_mfma_f32_16x16x32_bf16 v[4:7], v[220:223], v[212:215], v[4:7]
	v_mfma_f32_16x16x32_bf16 v[0:3], v[228:231], v[212:215], v[0:3]
	v_mfma_f32_16x16x32_bf16 v[28:31], v[224:227], v[192:195], v[28:31]
	v_mfma_f32_16x16x32_bf16 v[24:27], v[232:235], v[192:195], v[24:27]
	v_mfma_f32_16x16x32_bf16 v[20:23], v[224:227], v[200:203], v[20:23]
	v_mfma_f32_16x16x32_bf16 v[16:19], v[232:235], v[200:203], v[16:19]
	v_mfma_f32_16x16x32_bf16 v[12:15], v[224:227], v[208:211], v[12:15]
	v_mfma_f32_16x16x32_bf16 v[8:11], v[232:235], v[208:211], v[8:11]
	v_mfma_f32_16x16x32_bf16 v[4:7], v[224:227], v[216:219], v[4:7]
	v_mfma_f32_16x16x32_bf16 v[0:3], v[232:235], v[216:219], v[0:3]
	s_add_i32 s42, s42, 2
	s_add_u32 s40, s40, 0x100
	s_addc_u32 s41, s41, 0
	s_cmp_gt_u32 s42, 27
	s_barrier
	s_cbranch_scc0 .LBB0_1564
	s_add_i32 s40, s38, 0x80
	s_mul_hi_i32 s41, s40, 0x1080
	s_mulk_i32 s40, 0x1080
	s_add_u32 s40, s49, s40
	s_addc_u32 s41, s50, s41
	v_lshl_add_u64 v[158:159], s[40:41], 0, v[128:129]
	v_readfirstlane_b32 s42, v169
	v_lshl_add_u64 v[158:159], v[158:159], 0, s[36:37]
	s_mov_b32 m0, s42
	ds_read_b128 v[134:137], v161
	ds_read_b128 v[138:141], v161 offset:1024
	ds_read_b128 v[172:175], v161 offset:2048
	ds_read_b128 v[176:179], v161 offset:3072
	ds_read_b128 v[180:183], v152
	ds_read_b128 v[184:187], v152 offset:1024
	ds_read_b128 v[188:191], v151
	ds_read_b128 v[192:195], v151 offset:1024
	ds_read_b128 v[196:199], v150
	ds_read_b128 v[200:203], v150 offset:1024
	ds_read_b128 v[204:207], v149
	ds_read_b128 v[208:211], v149 offset:1024
	global_load_lds_dwordx4 v[158:159], off
	v_lshl_add_u64 v[158:159], s[40:41], 0, v[132:133]
	v_readfirstlane_b32 s40, v170
	v_lshl_add_u64 v[158:159], v[158:159], 0, s[36:37]
	s_mov_b32 m0, s40
	s_nop 0
	global_load_lds_dwordx4 v[158:159], off
	s_barrier
	s_waitcnt lgkmcnt(0)
	s_waitcnt lgkmcnt(0)
	v_mfma_f32_16x16x32_bf16 v[124:127], v[134:137], v[180:183], v[124:127]
	v_mfma_f32_16x16x32_bf16 v[120:123], v[172:175], v[180:183], v[120:123]
	v_mfma_f32_16x16x32_bf16 v[116:119], v[134:137], v[188:191], v[116:119]
	v_mfma_f32_16x16x32_bf16 v[112:115], v[172:175], v[188:191], v[112:115]
	v_mfma_f32_16x16x32_bf16 v[108:111], v[134:137], v[196:199], v[108:111]
	v_mfma_f32_16x16x32_bf16 v[104:107], v[172:175], v[196:199], v[104:107]
	v_mfma_f32_16x16x32_bf16 v[100:103], v[134:137], v[204:207], v[100:103]
	v_mfma_f32_16x16x32_bf16 v[96:99], v[172:175], v[204:207], v[96:99]
	v_mfma_f32_16x16x32_bf16 v[124:127], v[138:141], v[184:187], v[124:127]
	v_mfma_f32_16x16x32_bf16 v[120:123], v[176:179], v[184:187], v[120:123]
	v_mfma_f32_16x16x32_bf16 v[116:119], v[138:141], v[192:195], v[116:119]
	v_mfma_f32_16x16x32_bf16 v[112:115], v[176:179], v[192:195], v[112:115]
	v_mfma_f32_16x16x32_bf16 v[108:111], v[138:141], v[200:203], v[108:111]
	v_mfma_f32_16x16x32_bf16 v[104:107], v[176:179], v[200:203], v[104:107]
	v_mfma_f32_16x16x32_bf16 v[100:103], v[138:141], v[208:211], v[100:103]
	v_mfma_f32_16x16x32_bf16 v[96:99], v[176:179], v[208:211], v[96:99]
	s_barrier
	ds_read_b128 v[212:215], v160
	ds_read_b128 v[216:219], v160 offset:1024
	ds_read_b128 v[220:223], v160 offset:2048
	ds_read_b128 v[158:161], v160 offset:3072
	s_waitcnt vmcnt(8)
	s_barrier
; #define LDA(dst, b, h) for (int m = 0; m < 4; ++m) for (int k = 0; k < 2; ++k) \
;     dst[m][k] = *reinterpret_cast<const bf16x8*>((char*)SA(b, h) + lds_byte(wr * 64 + m * 16 + fr, k * 32 + fq * 8))
; #define LDB(dst, b, h) for (int n = 0; n < 2; ++n) for (int k = 0; k < 2; ++k) \
;     dst[n][k] = *reinterpret_cast<const bf16x8*>((char*)SB(b, h) + lds_byte(wc * 32 + n * 16 + fr, k * 32 + fq * 8))
; #define MMA(ai, bj, At_, Bt_) do { __builtin_amdgcn_s_setprio(1); \
;     for (int k = 0; k < 2; ++k) for (int m = 0; m < 4; ++m) for (int n = 0; n < 2; ++n) \
;       acc[ai][bj][m][n] = __builtin_amdgcn_mfma_f32_16x16x32_bf16(At_[m][k], Bt_[n][k], acc[ai][bj][m][n], 0, 0, 0); \
;     __builtin_amdgcn_s_setprio(0); } while (0)
; #define WAIT_V(n) asm volatile("s_waitcnt vmcnt(" #n ")" ::: "memory")
; #define WAIT_L(n) asm volatile("s_waitcnt lgkmcnt(" #n ")" ::: "memory")
; #define BAR __builtin_amdgcn_s_barrier()
; template <int EPI, int lda, int ldb, int N, int K>
; __device__ __forceinline__ void gemm_phase(const u16* __restrict__ A, const u16* __restrict__ Bt, const GemmEpi ep, int wv) {
;     ...
;       LDB(B1, 0, 1); BAR; WAIT_L(0); MMA(0, 1, At, B1); BAR;
;       LDA(At, 0, 1); WAIT_V(4); BAR; WAIT_L(0); MMA(1, 0, At, B0); MMA(1, 1, At, B1); BAR; }
;     { LDB(B0, 1, 0); LDA(At, 1, 0); WAIT_V(2); BAR; WAIT_L(0); MMA(0, 0, At, B0); BAR;
	s_waitcnt lgkmcnt(0)
	s_waitcnt lgkmcnt(0)
	v_mfma_f32_16x16x32_bf16 v[92:95], v[212:215], v[180:183], v[92:95]
	v_mfma_f32_16x16x32_bf16 v[88:91], v[220:223], v[180:183], v[88:91]
	v_mfma_f32_16x16x32_bf16 v[76:79], v[212:215], v[196:199], v[76:79]
	v_mfma_f32_16x16x32_bf16 v[72:75], v[220:223], v[196:199], v[72:75]
	v_mfma_f32_16x16x32_bf16 v[84:87], v[212:215], v[188:191], v[84:87]
	v_mfma_f32_16x16x32_bf16 v[80:83], v[220:223], v[188:191], v[80:83]
	v_mfma_f32_16x16x32_bf16 v[68:71], v[212:215], v[204:207], v[68:71]
	v_mfma_f32_16x16x32_bf16 v[64:67], v[220:223], v[204:207], v[64:67]
	v_mfma_f32_16x16x32_bf16 v[92:95], v[216:219], v[184:187], v[92:95]
	v_mfma_f32_16x16x32_bf16 v[88:91], v[158:161], v[184:187], v[88:91]
	v_mfma_f32_16x16x32_bf16 v[76:79], v[216:219], v[200:203], v[76:79]
	v_mfma_f32_16x16x32_bf16 v[72:75], v[158:161], v[200:203], v[72:75]
	v_mfma_f32_16x16x32_bf16 v[180:183], v[216:219], v[192:195], v[84:87]
	v_mfma_f32_16x16x32_bf16 v[184:187], v[158:161], v[192:195], v[80:83]
	v_mfma_f32_16x16x32_bf16 v[188:191], v[216:219], v[208:211], v[68:71]
	v_mfma_f32_16x16x32_bf16 v[192:195], v[158:161], v[208:211], v[64:67]
	s_barrier
	s_nop 0
	ds_read_b128 v[64:67], v152 offset:16384
	ds_read_b128 v[68:71], v152 offset:17408
	ds_read_b128 v[80:83], v151 offset:16384
	ds_read_b128 v[84:87], v151 offset:17408
	ds_read_b128 v[196:199], v150 offset:16384
	ds_read_b128 v[200:203], v150 offset:17408
	ds_read_b128 v[204:207], v149 offset:16384
	ds_read_b128 v[208:211], v149 offset:17408
	s_waitcnt vmcnt(4)
	s_barrier
	s_waitcnt lgkmcnt(0)
	s_waitcnt lgkmcnt(0)
	v_mfma_f32_16x16x32_bf16 v[60:63], v[134:137], v[64:67], v[60:63]
	v_mfma_f32_16x16x32_bf16 v[56:59], v[172:175], v[64:67], v[56:59]
	v_mfma_f32_16x16x32_bf16 v[52:55], v[134:137], v[80:83], v[52:55]
	v_mfma_f32_16x16x32_bf16 v[48:51], v[172:175], v[80:83], v[48:51]
	v_mfma_f32_16x16x32_bf16 v[44:47], v[134:137], v[196:199], v[44:47]
	v_mfma_f32_16x16x32_bf16 v[40:43], v[172:175], v[196:199], v[40:43]
	v_mfma_f32_16x16x32_bf16 v[36:39], v[134:137], v[204:207], v[36:39]
	v_mfma_f32_16x16x32_bf16 v[32:35], v[172:175], v[204:207], v[32:35]
	v_mfma_f32_16x16x32_bf16 v[60:63], v[138:141], v[68:71], v[60:63]
	v_mfma_f32_16x16x32_bf16 v[56:59], v[176:179], v[68:71], v[56:59]
	v_mfma_f32_16x16x32_bf16 v[52:55], v[138:141], v[84:87], v[52:55]
	v_mfma_f32_16x16x32_bf16 v[48:51], v[176:179], v[84:87], v[48:51]
	v_mfma_f32_16x16x32_bf16 v[44:47], v[138:141], v[200:203], v[44:47]
	v_mfma_f32_16x16x32_bf16 v[40:43], v[176:179], v[200:203], v[40:43]
	v_mfma_f32_16x16x32_bf16 v[36:39], v[138:141], v[208:211], v[36:39]
	v_mfma_f32_16x16x32_bf16 v[32:35], v[176:179], v[208:211], v[32:35]
	v_mfma_f32_16x16x32_bf16 v[28:31], v[212:215], v[64:67], v[28:31]
	v_mfma_f32_16x16x32_bf16 v[24:27], v[220:223], v[64:67], v[24:27]
	v_mfma_f32_16x16x32_bf16 v[12:15], v[212:215], v[196:199], v[12:15]
	v_mfma_f32_16x16x32_bf16 v[8:11], v[220:223], v[196:199], v[8:11]
	v_mfma_f32_16x16x32_bf16 v[20:23], v[212:215], v[80:83], v[20:23]
	v_mfma_f32_16x16x32_bf16 v[16:19], v[220:223], v[80:83], v[16:19]
	v_mfma_f32_16x16x32_bf16 v[4:7], v[212:215], v[204:207], v[4:7]
	v_mfma_f32_16x16x32_bf16 v[0:3], v[220:223], v[204:207], v[0:3]
	v_mfma_f32_16x16x32_bf16 v[28:31], v[216:219], v[68:71], v[28:31]
	v_mfma_f32_16x16x32_bf16 v[24:27], v[158:161], v[68:71], v[24:27]
	v_mfma_f32_16x16x32_bf16 v[12:15], v[216:219], v[200:203], v[12:15]
	v_mfma_f32_16x16x32_bf16 v[8:11], v[158:161], v[200:203], v[8:11]
	v_mfma_f32_16x16x32_bf16 v[134:137], v[216:219], v[84:87], v[20:23]
	v_mfma_f32_16x16x32_bf16 v[138:141], v[158:161], v[84:87], v[16:19]
	v_mfma_f32_16x16x32_bf16 v[170:173], v[216:219], v[208:211], v[4:7]
	v_mfma_f32_16x16x32_bf16 v[158:161], v[158:161], v[208:211], v[0:3]
	s_barrier
	s_nop 0
	ds_read_b128 v[0:3], v156
	ds_read_b128 v[4:7], v156 offset:1024
	ds_read_b128 v[16:19], v156 offset:2048
	ds_read_b128 v[174:177], v156 offset:3072
	ds_read_b128 v[20:23], v152 offset:32768
	ds_read_b128 v[196:199], v152 offset:33792
	ds_read_b128 v[200:203], v151 offset:32768
	ds_read_b128 v[204:207], v151 offset:33792
	ds_read_b128 v[208:211], v150 offset:32768
	ds_read_b128 v[212:215], v150 offset:33792
	ds_read_b128 v[216:219], v149 offset:32768
	ds_read_b128 v[220:223], v149 offset:33792
	s_waitcnt vmcnt(2)
	s_barrier
; #define LDA(dst, b, h) for (int m = 0; m < 4; ++m) for (int k = 0; k < 2; ++k) \
;     dst[m][k] = *reinterpret_cast<const bf16x8*>((char*)SA(b, h) + lds_byte(wr * 64 + m * 16 + fr, k * 32 + fq * 8))
; #define LDB(dst, b, h) for (int n = 0; n < 2; ++n) for (int k = 0; k < 2; ++k) \
;     dst[n][k] = *reinterpret_cast<const bf16x8*>((char*)SB(b, h) + lds_byte(wc * 32 + n * 16 + fr, k * 32 + fq * 8))
; #define MMA(ai, bj, At_, Bt_) do { __builtin_amdgcn_s_setprio(1); \
;     for (int k = 0; k < 2; ++k) for (int m = 0; m < 4; ++m) for (int n = 0; n < 2; ++n) \
;       acc[ai][bj][m][n] = __builtin_amdgcn_mfma_f32_16x16x32_bf16(At_[m][k], Bt_[n][k], acc[ai][bj][m][n], 0, 0, 0); \
;     __builtin_amdgcn_s_setprio(0); } while (0)
; #define WAIT_V(n) asm volatile("s_waitcnt vmcnt(" #n ")" ::: "memory")
; #define WAIT_L(n) asm volatile("s_waitcnt lgkmcnt(" #n ")" ::: "memory")
; #define BAR __builtin_amdgcn_s_barrier()
; template <int EPI, int lda, int ldb, int N, int K>
; __device__ __forceinline__ void gemm_phase(const u16* __restrict__ A, const u16* __restrict__ Bt, const GemmEpi ep, int wv) {
;     ...
;     { LDB(B0, 1, 0); LDA(At, 1, 0); WAIT_V(2); BAR; WAIT_L(0); MMA(0, 0, At, B0); BAR;
;       LDB(B1, 1, 1); WAIT_V(0); BAR; WAIT_L(0); MMA(0, 1, At, B1); BAR;
;       LDA(At, 1, 1); BAR; WAIT_L(0); MMA(1, 0, At, B0); MMA(1, 1, At, B1); BAR; }
;     if (wr == 0) BAR;
	s_waitcnt lgkmcnt(0)
	s_waitcnt lgkmcnt(0)
	v_mfma_f32_16x16x32_bf16 v[64:67], v[0:3], v[20:23], v[124:127]
	v_mfma_f32_16x16x32_bf16 v[68:71], v[16:19], v[20:23], v[120:123]
	v_mfma_f32_16x16x32_bf16 v[80:83], v[0:3], v[200:203], v[116:119]
	v_mfma_f32_16x16x32_bf16 v[84:87], v[16:19], v[200:203], v[112:115]
	v_mfma_f32_16x16x32_bf16 v[108:111], v[0:3], v[208:211], v[108:111]
	v_mfma_f32_16x16x32_bf16 v[104:107], v[16:19], v[208:211], v[104:107]
	v_mfma_f32_16x16x32_bf16 v[120:123], v[0:3], v[216:219], v[100:103]
	v_mfma_f32_16x16x32_bf16 v[124:127], v[16:19], v[216:219], v[96:99]
	v_mfma_f32_16x16x32_bf16 v[116:119], v[4:7], v[196:199], v[64:67]
	v_mfma_f32_16x16x32_bf16 v[112:115], v[174:177], v[196:199], v[68:71]
	v_mfma_f32_16x16x32_bf16 v[100:103], v[4:7], v[204:207], v[80:83]
	v_mfma_f32_16x16x32_bf16 v[96:99], v[174:177], v[204:207], v[84:87]
	v_mfma_f32_16x16x32_bf16 v[84:87], v[4:7], v[212:215], v[108:111]
	v_mfma_f32_16x16x32_bf16 v[80:83], v[174:177], v[212:215], v[104:107]
	v_mfma_f32_16x16x32_bf16 v[68:71], v[4:7], v[220:223], v[120:123]
	v_mfma_f32_16x16x32_bf16 v[64:67], v[174:177], v[220:223], v[124:127]
	s_barrier
	ds_read_b128 v[224:227], v154
	ds_read_b128 v[228:231], v154 offset:1024
	ds_read_b128 v[232:235], v154 offset:2048
	ds_read_b128 v[154:157], v154 offset:3072
	s_waitcnt vmcnt(0)
	s_barrier
	s_waitcnt lgkmcnt(0)
	s_waitcnt lgkmcnt(0)
	v_mfma_f32_16x16x32_bf16 v[92:95], v[224:227], v[20:23], v[92:95]
	v_mfma_f32_16x16x32_bf16 v[20:23], v[232:235], v[20:23], v[88:91]
	v_mfma_f32_16x16x32_bf16 v[88:91], v[224:227], v[200:203], v[180:183]
	v_mfma_f32_16x16x32_bf16 v[104:107], v[232:235], v[200:203], v[184:187]
	v_mfma_f32_16x16x32_bf16 v[76:79], v[224:227], v[208:211], v[76:79]
	v_mfma_f32_16x16x32_bf16 v[72:75], v[232:235], v[208:211], v[72:75]
	v_mfma_f32_16x16x32_bf16 v[178:181], v[224:227], v[216:219], v[188:191]
	v_mfma_f32_16x16x32_bf16 v[182:185], v[232:235], v[216:219], v[192:195]
	v_mfma_f32_16x16x32_bf16 v[124:127], v[228:231], v[196:199], v[92:95]
	v_mfma_f32_16x16x32_bf16 v[120:123], v[154:157], v[196:199], v[20:23]
	v_mfma_f32_16x16x32_bf16 v[108:111], v[228:231], v[204:207], v[88:91]
	v_mfma_f32_16x16x32_bf16 v[104:107], v[154:157], v[204:207], v[104:107]
	v_mfma_f32_16x16x32_bf16 v[92:95], v[228:231], v[212:215], v[76:79]
	v_mfma_f32_16x16x32_bf16 v[88:91], v[154:157], v[212:215], v[72:75]
	v_mfma_f32_16x16x32_bf16 v[76:79], v[228:231], v[220:223], v[178:181]
	v_mfma_f32_16x16x32_bf16 v[72:75], v[154:157], v[220:223], v[182:185]
	s_barrier
	ds_read_b128 v[178:181], v152 offset:49152
	ds_read_b128 v[182:185], v152 offset:50176
	ds_read_b128 v[186:189], v151 offset:49152
	ds_read_b128 v[190:193], v151 offset:50176
	ds_read_b128 v[194:197], v150 offset:49152
	ds_read_b128 v[150:153], v150 offset:50176
	ds_read_b128 v[198:201], v149 offset:49152
	ds_read_b128 v[202:205], v149 offset:50176
	s_barrier
	s_waitcnt lgkmcnt(0)
	s_waitcnt lgkmcnt(0)
	v_mfma_f32_16x16x32_bf16 v[20:23], v[0:3], v[178:181], v[60:63]
	v_mfma_f32_16x16x32_bf16 v[56:59], v[16:19], v[178:181], v[56:59]
	v_mfma_f32_16x16x32_bf16 v[60:63], v[0:3], v[186:189], v[52:55]
	v_mfma_f32_16x16x32_bf16 v[206:209], v[16:19], v[186:189], v[48:51]
	v_mfma_f32_16x16x32_bf16 v[44:47], v[0:3], v[194:197], v[44:47]
	v_mfma_f32_16x16x32_bf16 v[40:43], v[16:19], v[194:197], v[40:43]
	v_mfma_f32_16x16x32_bf16 v[0:3], v[0:3], v[198:201], v[36:39]
	v_mfma_f32_16x16x32_bf16 v[210:213], v[16:19], v[198:201], v[32:35]
	v_mfma_f32_16x16x32_bf16 v[52:55], v[4:7], v[182:185], v[20:23]
	v_mfma_f32_16x16x32_bf16 v[48:51], v[174:177], v[182:185], v[56:59]
	v_mfma_f32_16x16x32_bf16 v[36:39], v[4:7], v[190:193], v[60:63]
	v_mfma_f32_16x16x32_bf16 v[32:35], v[174:177], v[190:193], v[206:209]
	v_mfma_f32_16x16x32_bf16 v[20:23], v[4:7], v[150:153], v[44:47]
	v_mfma_f32_16x16x32_bf16 v[16:19], v[174:177], v[150:153], v[40:43]
	v_mfma_f32_16x16x32_bf16 v[4:7], v[4:7], v[202:205], v[0:3]
	v_mfma_f32_16x16x32_bf16 v[0:3], v[174:177], v[202:205], v[210:213]
	v_mfma_f32_16x16x32_bf16 v[28:31], v[224:227], v[178:181], v[28:31]
	v_mfma_f32_16x16x32_bf16 v[24:27], v[232:235], v[178:181], v[24:27]
	v_mfma_f32_16x16x32_bf16 v[40:43], v[224:227], v[186:189], v[134:137]
	v_mfma_f32_16x16x32_bf16 v[134:137], v[232:235], v[186:189], v[138:141]
	v_mfma_f32_16x16x32_bf16 v[12:15], v[224:227], v[194:197], v[12:15]
	v_mfma_f32_16x16x32_bf16 v[8:11], v[232:235], v[194:197], v[8:11]
	v_mfma_f32_16x16x32_bf16 v[138:141], v[224:227], v[198:201], v[170:173]
	v_mfma_f32_16x16x32_bf16 v[158:161], v[232:235], v[198:201], v[158:161]
	v_mfma_f32_16x16x32_bf16 v[60:63], v[228:231], v[182:185], v[28:31]
	v_mfma_f32_16x16x32_bf16 v[56:59], v[154:157], v[182:185], v[24:27]
	v_mfma_f32_16x16x32_bf16 v[44:47], v[228:231], v[190:193], v[40:43]
	v_mfma_f32_16x16x32_bf16 v[40:43], v[154:157], v[190:193], v[134:137]
	v_mfma_f32_16x16x32_bf16 v[28:31], v[228:231], v[150:153], v[12:15]
	v_mfma_f32_16x16x32_bf16 v[24:27], v[154:157], v[150:153], v[8:11]
	v_mfma_f32_16x16x32_bf16 v[12:15], v[228:231], v[202:205], v[138:141]
	v_mfma_f32_16x16x32_bf16 v[8:11], v[154:157], v[202:205], v[158:161]
	v_cmp_gt_u32_e32 vcc, s54, v130
	s_barrier
	s_and_saveexec_b64 s[40:41], vcc
	s_cbranch_execz .LBB0_1567
	s_barrier

; #define STAGE(P, BASE, LD, br, kt) do { const char* _g = (const char*)((BASE) + (size_t)(br) * (LD) + (size_t)(kt) * 64); \
;     for (int _i = 0; _i < 2; ++_i) { int _b = tidx * 16 + _i * 8192; int _r, _c; stage_rc(_b, _r, _c); \
;       __builtin_amdgcn_global_load_lds((const unsigned*)(_g + (unsigned)((_r * (LD) + _c) * 2)), (unsigned*)((char*)(P) + _b), 16, 0, 0); } } while (0)
; #define LDA(dst, b, h) for (int m = 0; m < 4; ++m) for (int k = 0; k < 2; ++k) \
;     dst[m][k] = *reinterpret_cast<const bf16x8*>((char*)SA(b, h) + lds_byte(wr * 64 + m * 16 + fr, k * 32 + fq * 8))
; #define LDB(dst, b, h) for (int n = 0; n < 2; ++n) for (int k = 0; k < 2; ++k) \
;     dst[n][k] = *reinterpret_cast<const bf16x8*>((char*)SB(b, h) + lds_byte(wc * 32 + n * 16 + fr, k * 32 + fq * 8))
; #define MMA(ai, bj, At_, Bt_) do { __builtin_amdgcn_s_setprio(1); \
;     for (int k = 0; k < 2; ++k) for (int m = 0; m < 4; ++m) for (int n = 0; n < 2; ++n) \
;       acc[ai][bj][m][n] = __builtin_amdgcn_mfma_f32_16x16x32_bf16(At_[m][k], Bt_[n][k], acc[ai][bj][m][n], 0, 0, 0); \
;     __builtin_amdgcn_s_setprio(0); } while (0)
; #define WAIT_V(n) asm volatile("s_waitcnt vmcnt(" #n ")" ::: "memory")
; #define WAIT_L(n) asm volatile("s_waitcnt lgkmcnt(" #n ")" ::: "memory")
; #define BAR __builtin_amdgcn_s_barrier()
; #define SCHED __builtin_amdgcn_sched_barrier(0)
; template <int EPI, int lda, int ldb, int N, int K>
; __device__ __forceinline__ void gemm_phase(const u16* __restrict__ A, const u16* __restrict__ Bt, const GemmEpi ep, int wv) {
;     ...
;     for (int t = 0; t < nt - 2; t += 2) {
;       LDB(B0, 0, 0); SCHED; LDA(At, 0, 0); STAGE(SA(1, 1), Ab, lda, brow + HALF, t + 1);
;       WAIT_L(8); BAR; WAIT_L(0); MMA(0, 0, At, B0); BAR; SCHED;
;       LDB(B1, 0, 1); STAGE(SB(0, 0), Bt, ldb, bcol, t + 2);
;       BAR; WAIT_L(0); MMA(0, 1, At, B1); BAR;
;       LDA(At, 0, 1); STAGE(SA(0, 0), Ab, lda, brow, t + 2);
;       BAR; WAIT_L(0); MMA(1, 0, At, B0); BAR; SCHED;
;       STAGE(SB(0, 1), Bt, ldb, bcol + HALF, t + 2);
;       WAIT_V(6); BAR; MMA(1, 1, At, B1); BAR;
;       LDB(B0, 1, 0); SCHED; LDA(At, 1, 0); STAGE(SA(0, 1), Ab, lda, brow + HALF, t + 2);
;       WAIT_L(8); BAR; WAIT_L(0); MMA(0, 0, At, B0); BAR; SCHED;
.LBB0_1624:
	ds_read_b128 v[174:177], v163
	ds_read_b128 v[178:181], v163 offset:1024
	ds_read_b128 v[182:185], v163 offset:2048
	ds_read_b128 v[186:189], v163 offset:3072
	v_add_u32_e32 v171, 0xc000, v149
	v_lshl_add_u64 v[238:239], v[134:135], 0, s[28:29]
	v_readfirstlane_b32 s50, v171
	v_add_u32_e32 v172, 0xe000, v149
	v_lshl_add_u64 v[164:165], v[238:239], 0, s[10:11]
	s_mov_b32 m0, s50
	v_lshl_add_u64 v[240:241], v[132:133], 0, s[28:29]
	v_readfirstlane_b32 s50, v172
	ds_read_b128 v[166:169], v154
	ds_read_b128 v[190:193], v154 offset:1024
	ds_read_b128 v[194:197], v153
	ds_read_b128 v[198:201], v153 offset:1024
	ds_read_b128 v[202:205], v151
	ds_read_b128 v[206:209], v151 offset:1024
	ds_read_b128 v[210:213], v150
	ds_read_b128 v[214:217], v150 offset:1024
	global_load_lds_dwordx4 v[164:165], off
	v_lshl_add_u64 v[164:165], v[240:241], 0, s[10:11]
	s_mov_b32 m0, s50
	s_nop 0
	global_load_lds_dwordx4 v[164:165], off
	s_waitcnt lgkmcnt(8)
	s_barrier
	s_waitcnt lgkmcnt(0)
	s_waitcnt lgkmcnt(0)
	v_mfma_f32_16x16x32_bf16 v[124:127], v[166:169], v[174:177], v[124:127]
	v_mfma_f32_16x16x32_bf16 v[120:123], v[166:169], v[182:185], v[120:123]
	v_mfma_f32_16x16x32_bf16 v[116:119], v[194:197], v[174:177], v[116:119]
	v_mfma_f32_16x16x32_bf16 v[112:115], v[194:197], v[182:185], v[112:115]
	v_mfma_f32_16x16x32_bf16 v[108:111], v[202:205], v[174:177], v[108:111]
	v_mfma_f32_16x16x32_bf16 v[104:107], v[202:205], v[182:185], v[104:107]
	v_mfma_f32_16x16x32_bf16 v[100:103], v[210:213], v[174:177], v[100:103]
	v_mfma_f32_16x16x32_bf16 v[96:99], v[210:213], v[182:185], v[96:99]
	v_mfma_f32_16x16x32_bf16 v[124:127], v[190:193], v[178:181], v[124:127]
	v_mfma_f32_16x16x32_bf16 v[120:123], v[190:193], v[186:189], v[120:123]
	v_mfma_f32_16x16x32_bf16 v[116:119], v[198:201], v[178:181], v[116:119]
	v_mfma_f32_16x16x32_bf16 v[112:115], v[198:201], v[186:189], v[112:115]
	v_mfma_f32_16x16x32_bf16 v[108:111], v[206:209], v[178:181], v[108:111]
	v_mfma_f32_16x16x32_bf16 v[104:107], v[206:209], v[186:189], v[104:107]
	v_mfma_f32_16x16x32_bf16 v[100:103], v[214:217], v[178:181], v[100:103]
	v_mfma_f32_16x16x32_bf16 v[96:99], v[214:217], v[186:189], v[96:99]
	s_barrier
	v_add_u32_e32 v164, s40, v155
	v_lshl_add_u64 v[242:243], v[142:143], 0, s[28:29]
	v_readfirstlane_b32 s50, v164
	v_add_u32_e32 v165, 0x2000, v164
	v_lshl_add_u64 v[234:235], v[242:243], 0, s[12:13]
	s_mov_b32 m0, s50
	v_lshl_add_u64 v[244:245], v[140:141], 0, s[28:29]
	v_readfirstlane_b32 s50, v165
	ds_read_b128 v[218:221], v162
	ds_read_b128 v[222:225], v162 offset:1024
	ds_read_b128 v[226:229], v162 offset:2048
	ds_read_b128 v[230:233], v162 offset:3072
	global_load_lds_dwordx4 v[234:235], off
	v_lshl_add_u64 v[234:235], v[244:245], 0, s[12:13]
	s_mov_b32 m0, s50
	s_nop 0
	global_load_lds_dwordx4 v[234:235], off
	s_waitcnt vmcnt(10)
	s_barrier
	s_waitcnt lgkmcnt(0)
	s_waitcnt lgkmcnt(0)
	v_mfma_f32_16x16x32_bf16 v[92:95], v[166:169], v[218:221], v[92:95]
	v_mfma_f32_16x16x32_bf16 v[88:91], v[166:169], v[226:229], v[88:91]
	v_mfma_f32_16x16x32_bf16 v[84:87], v[194:197], v[218:221], v[84:87]
	v_mfma_f32_16x16x32_bf16 v[80:83], v[194:197], v[226:229], v[80:83]
	v_mfma_f32_16x16x32_bf16 v[76:79], v[202:205], v[218:221], v[76:79]
	v_mfma_f32_16x16x32_bf16 v[72:75], v[202:205], v[226:229], v[72:75]
	v_mfma_f32_16x16x32_bf16 v[68:71], v[210:213], v[218:221], v[68:71]
	v_mfma_f32_16x16x32_bf16 v[64:67], v[210:213], v[226:229], v[64:67]
	v_mfma_f32_16x16x32_bf16 v[92:95], v[190:193], v[222:225], v[92:95]
	v_mfma_f32_16x16x32_bf16 v[88:91], v[190:193], v[230:233], v[88:91]
	v_mfma_f32_16x16x32_bf16 v[84:87], v[198:201], v[222:225], v[84:87]
	v_mfma_f32_16x16x32_bf16 v[80:83], v[198:201], v[230:233], v[80:83]
	v_mfma_f32_16x16x32_bf16 v[76:79], v[206:209], v[222:225], v[76:79]
	v_mfma_f32_16x16x32_bf16 v[72:75], v[206:209], v[230:233], v[72:75]
	v_mfma_f32_16x16x32_bf16 v[68:71], v[214:217], v[222:225], v[68:71]
	v_mfma_f32_16x16x32_bf16 v[64:67], v[214:217], v[230:233], v[64:67]
	v_readfirstlane_b32 s50, v149
	v_lshl_add_u64 v[166:167], v[238:239], 0, s[14:15]
	s_mov_b32 m0, s50
	s_barrier
	ds_read_b128 v[190:193], v154 offset:16384
	ds_read_b128 v[194:197], v154 offset:17408
	ds_read_b128 v[198:201], v153 offset:16384
	ds_read_b128 v[202:205], v153 offset:17408
	ds_read_b128 v[206:209], v151 offset:16384
	ds_read_b128 v[210:213], v151 offset:17408
	ds_read_b128 v[214:217], v150 offset:16384
	ds_read_b128 v[234:237], v150 offset:17408
	global_load_lds_dwordx4 v[166:167], off
	v_add_u32_e32 v166, 0x2000, v149
	v_lshl_add_u64 v[168:169], v[240:241], 0, s[14:15]
	v_readfirstlane_b32 s50, v166
	s_mov_b32 m0, s50
	s_nop 0
	global_load_lds_dwordx4 v[168:169], off
	s_barrier
	s_waitcnt lgkmcnt(0)
	s_waitcnt lgkmcnt(0)
	v_mfma_f32_16x16x32_bf16 v[60:63], v[190:193], v[174:177], v[60:63]
	v_mfma_f32_16x16x32_bf16 v[56:59], v[190:193], v[182:185], v[56:59]
	v_mfma_f32_16x16x32_bf16 v[52:55], v[198:201], v[174:177], v[52:55]
	v_mfma_f32_16x16x32_bf16 v[48:51], v[198:201], v[182:185], v[48:51]
	v_mfma_f32_16x16x32_bf16 v[44:47], v[206:209], v[174:177], v[44:47]
	v_mfma_f32_16x16x32_bf16 v[40:43], v[206:209], v[182:185], v[40:43]
	v_mfma_f32_16x16x32_bf16 v[36:39], v[214:217], v[174:177], v[36:39]
	v_mfma_f32_16x16x32_bf16 v[32:35], v[214:217], v[182:185], v[32:35]
	v_mfma_f32_16x16x32_bf16 v[60:63], v[194:197], v[178:181], v[60:63]
	v_mfma_f32_16x16x32_bf16 v[56:59], v[194:197], v[186:189], v[56:59]
	v_mfma_f32_16x16x32_bf16 v[52:55], v[202:205], v[178:181], v[52:55]
	v_mfma_f32_16x16x32_bf16 v[48:51], v[202:205], v[186:189], v[48:51]
	v_mfma_f32_16x16x32_bf16 v[44:47], v[210:213], v[178:181], v[44:47]
	v_mfma_f32_16x16x32_bf16 v[40:43], v[210:213], v[186:189], v[40:43]
	v_mfma_f32_16x16x32_bf16 v[36:39], v[234:237], v[178:181], v[36:39]
	v_mfma_f32_16x16x32_bf16 v[32:35], v[234:237], v[186:189], v[32:35]
	s_barrier
; #define STAGE(P, BASE, LD, br, kt) do { const char* _g = (const char*)((BASE) + (size_t)(br) * (LD) + (size_t)(kt) * 64); \
;     for (int _i = 0; _i < 2; ++_i) { int _b = tidx * 16 + _i * 8192; int _r, _c; stage_rc(_b, _r, _c); \
;       __builtin_amdgcn_global_load_lds((const unsigned*)(_g + (unsigned)((_r * (LD) + _c) * 2)), (unsigned*)((char*)(P) + _b), 16, 0, 0); } } while (0)
; #define LDA(dst, b, h) for (int m = 0; m < 4; ++m) for (int k = 0; k < 2; ++k) \
;     dst[m][k] = *reinterpret_cast<const bf16x8*>((char*)SA(b, h) + lds_byte(wr * 64 + m * 16 + fr, k * 32 + fq * 8))
; #define LDB(dst, b, h) for (int n = 0; n < 2; ++n) for (int k = 0; k < 2; ++k) \
;     dst[n][k] = *reinterpret_cast<const bf16x8*>((char*)SB(b, h) + lds_byte(wc * 32 + n * 16 + fr, k * 32 + fq * 8))
; #define MMA(ai, bj, At_, Bt_) do { __builtin_amdgcn_s_setprio(1); \
;     for (int k = 0; k < 2; ++k) for (int m = 0; m < 4; ++m) for (int n = 0; n < 2; ++n) \
;       acc[ai][bj][m][n] = __builtin_amdgcn_mfma_f32_16x16x32_bf16(At_[m][k], Bt_[n][k], acc[ai][bj][m][n], 0, 0, 0); \
;     __builtin_amdgcn_s_setprio(0); } while (0)
; #define WAIT_V(n) asm volatile("s_waitcnt vmcnt(" #n ")" ::: "memory")
; #define WAIT_L(n) asm volatile("s_waitcnt lgkmcnt(" #n ")" ::: "memory")
; #define BAR __builtin_amdgcn_s_barrier()
; #define SCHED __builtin_amdgcn_sched_barrier(0)
; template <int EPI, int lda, int ldb, int N, int K>
; __device__ __forceinline__ void gemm_phase(const u16* __restrict__ A, const u16* __restrict__ Bt, const GemmEpi ep, int wv) {
;     ...
;       STAGE(SB(0, 1), Bt, ldb, bcol + HALF, t + 2);
;       WAIT_V(6); BAR; MMA(1, 1, At, B1); BAR;
;       LDB(B0, 1, 0); SCHED; LDA(At, 1, 0); STAGE(SA(0, 1), Ab, lda, brow + HALF, t + 2);
;       WAIT_L(8); BAR; WAIT_L(0); MMA(0, 0, At, B0); BAR; SCHED;
;       LDB(B1, 1, 1); STAGE(SB(1, 0), Bt, ldb, bcol, t + 3);
;       BAR; WAIT_L(0); MMA(0, 1, At, B1); BAR;
;       LDA(At, 1, 1); STAGE(SA(1, 0), Ab, lda, brow, t + 3);
;       BAR; WAIT_L(0); MMA(1, 0, At, B0); BAR; SCHED;
	v_add_u32_e32 v167, s41, v155
	v_lshl_add_u64 v[246:247], v[138:139], 0, s[28:29]
	v_readfirstlane_b32 s50, v167
	v_lshl_add_u64 v[168:169], v[246:247], 0, s[16:17]
	s_mov_b32 m0, s50
	v_lshl_add_u64 v[248:249], v[136:137], 0, s[28:29]
	global_load_lds_dwordx4 v[168:169], off
	v_add_u32_e32 v168, 0x2000, v167
	v_lshl_add_u64 v[174:175], v[248:249], 0, s[16:17]
	v_readfirstlane_b32 s50, v168
	s_mov_b32 m0, s50
	s_nop 0
	global_load_lds_dwordx4 v[174:175], off
	s_waitcnt vmcnt(8)
	s_barrier
	v_mfma_f32_16x16x32_bf16 v[28:31], v[190:193], v[218:221], v[28:31]
	v_mfma_f32_16x16x32_bf16 v[24:27], v[190:193], v[226:229], v[24:27]
	v_mfma_f32_16x16x32_bf16 v[20:23], v[198:201], v[218:221], v[20:23]
	v_mfma_f32_16x16x32_bf16 v[16:19], v[198:201], v[226:229], v[16:19]
	v_mfma_f32_16x16x32_bf16 v[12:15], v[206:209], v[218:221], v[12:15]
	v_mfma_f32_16x16x32_bf16 v[8:11], v[206:209], v[226:229], v[8:11]
	v_mfma_f32_16x16x32_bf16 v[4:7], v[214:217], v[218:221], v[4:7]
	v_mfma_f32_16x16x32_bf16 v[0:3], v[214:217], v[226:229], v[0:3]
	v_mfma_f32_16x16x32_bf16 v[28:31], v[194:197], v[222:225], v[28:31]
	v_mfma_f32_16x16x32_bf16 v[24:27], v[194:197], v[230:233], v[24:27]
	v_mfma_f32_16x16x32_bf16 v[20:23], v[202:205], v[222:225], v[20:23]
	v_mfma_f32_16x16x32_bf16 v[16:19], v[202:205], v[230:233], v[16:19]
	v_mfma_f32_16x16x32_bf16 v[12:15], v[210:213], v[222:225], v[12:15]
	v_mfma_f32_16x16x32_bf16 v[8:11], v[210:213], v[230:233], v[8:11]
	v_mfma_f32_16x16x32_bf16 v[4:7], v[234:237], v[222:225], v[4:7]
	v_mfma_f32_16x16x32_bf16 v[0:3], v[234:237], v[230:233], v[0:3]
	s_barrier
	ds_read_b128 v[174:177], v158
	ds_read_b128 v[178:181], v158 offset:1024
	ds_read_b128 v[182:185], v158 offset:2048
	ds_read_b128 v[186:189], v158 offset:3072
	v_add_u32_e32 v169, 0x4000, v149
	v_add_u32_e32 v170, 0x6000, v149
	v_readfirstlane_b32 s50, v169
	v_lshl_add_u64 v[222:223], v[238:239], 0, s[18:19]
	s_mov_b32 m0, s50
	v_readfirstlane_b32 s50, v170
	ds_read_b128 v[190:193], v154 offset:32768
	ds_read_b128 v[194:197], v154 offset:33792
	ds_read_b128 v[198:201], v153 offset:32768
	ds_read_b128 v[202:205], v153 offset:33792
	ds_read_b128 v[206:209], v151 offset:32768
	ds_read_b128 v[210:213], v151 offset:33792
	ds_read_b128 v[214:217], v150 offset:32768
	ds_read_b128 v[218:221], v150 offset:33792
	global_load_lds_dwordx4 v[222:223], off
	v_lshl_add_u64 v[222:223], v[240:241], 0, s[18:19]
	s_mov_b32 m0, s50
	s_nop 0
	global_load_lds_dwordx4 v[222:223], off
	s_waitcnt lgkmcnt(8)
	s_barrier
	s_waitcnt lgkmcnt(0)
	s_waitcnt lgkmcnt(0)
	v_mfma_f32_16x16x32_bf16 v[124:127], v[190:193], v[174:177], v[124:127]
	v_mfma_f32_16x16x32_bf16 v[120:123], v[190:193], v[182:185], v[120:123]
	v_mfma_f32_16x16x32_bf16 v[116:119], v[198:201], v[174:177], v[116:119]
	v_mfma_f32_16x16x32_bf16 v[112:115], v[198:201], v[182:185], v[112:115]
	v_mfma_f32_16x16x32_bf16 v[108:111], v[206:209], v[174:177], v[108:111]
	v_mfma_f32_16x16x32_bf16 v[104:107], v[206:209], v[182:185], v[104:107]
	v_mfma_f32_16x16x32_bf16 v[100:103], v[214:217], v[174:177], v[100:103]
	v_mfma_f32_16x16x32_bf16 v[96:99], v[214:217], v[182:185], v[96:99]
	v_mfma_f32_16x16x32_bf16 v[124:127], v[194:197], v[178:181], v[124:127]
	v_mfma_f32_16x16x32_bf16 v[120:123], v[194:197], v[186:189], v[120:123]
	v_mfma_f32_16x16x32_bf16 v[116:119], v[202:205], v[178:181], v[116:119]
	v_mfma_f32_16x16x32_bf16 v[112:115], v[202:205], v[186:189], v[112:115]
	v_mfma_f32_16x16x32_bf16 v[108:111], v[210:213], v[178:181], v[108:111]
	v_mfma_f32_16x16x32_bf16 v[104:107], v[210:213], v[186:189], v[104:107]
	v_mfma_f32_16x16x32_bf16 v[100:103], v[218:221], v[178:181], v[100:103]
	v_mfma_f32_16x16x32_bf16 v[96:99], v[218:221], v[186:189], v[96:99]
	s_barrier
	v_readfirstlane_b32 s50, v157
	v_add_u32_e32 v173, 0x2000, v157
	v_lshl_add_u64 v[242:243], v[242:243], 0, s[20:21]
	s_mov_b32 m0, s50
	v_readfirstlane_b32 s50, v173
	ds_read_b128 v[222:225], v156
	ds_read_b128 v[226:229], v156 offset:1024
	ds_read_b128 v[230:233], v156 offset:2048
	ds_read_b128 v[234:237], v156 offset:3072
	global_load_lds_dwordx4 v[242:243], off
	v_lshl_add_u64 v[242:243], v[244:245], 0, s[20:21]
	s_mov_b32 m0, s50
	s_nop 0
	global_load_lds_dwordx4 v[242:243], off
	s_waitcnt vmcnt(10)
	s_barrier
	s_waitcnt lgkmcnt(0)
	s_waitcnt lgkmcnt(0)
	v_mfma_f32_16x16x32_bf16 v[92:95], v[190:193], v[222:225], v[92:95]
	v_mfma_f32_16x16x32_bf16 v[88:91], v[190:193], v[230:233], v[88:91]
	v_mfma_f32_16x16x32_bf16 v[84:87], v[198:201], v[222:225], v[84:87]
	v_mfma_f32_16x16x32_bf16 v[80:83], v[198:201], v[230:233], v[80:83]
	v_mfma_f32_16x16x32_bf16 v[76:79], v[206:209], v[222:225], v[76:79]
	v_mfma_f32_16x16x32_bf16 v[72:75], v[206:209], v[230:233], v[72:75]
	v_mfma_f32_16x16x32_bf16 v[68:71], v[214:217], v[222:225], v[68:71]
	v_mfma_f32_16x16x32_bf16 v[64:67], v[214:217], v[230:233], v[64:67]
	v_mfma_f32_16x16x32_bf16 v[92:95], v[194:197], v[226:229], v[92:95]
	v_mfma_f32_16x16x32_bf16 v[88:91], v[194:197], v[234:237], v[88:91]
	v_mfma_f32_16x16x32_bf16 v[84:87], v[202:205], v[226:229], v[84:87]
	v_mfma_f32_16x16x32_bf16 v[80:83], v[202:205], v[234:237], v[80:83]
	v_mfma_f32_16x16x32_bf16 v[76:79], v[210:213], v[226:229], v[76:79]
	v_mfma_f32_16x16x32_bf16 v[72:75], v[210:213], v[234:237], v[72:75]
	v_mfma_f32_16x16x32_bf16 v[68:71], v[218:221], v[226:229], v[68:71]
	v_mfma_f32_16x16x32_bf16 v[64:67], v[218:221], v[234:237], v[64:67]
	v_readfirstlane_b32 s50, v159
	v_lshl_add_u64 v[238:239], v[238:239], 0, s[22:23]
	s_mov_b32 m0, s50
	v_readfirstlane_b32 s50, v160
	s_barrier
; #define STAGE(P, BASE, LD, br, kt) do { const char* _g = (const char*)((BASE) + (size_t)(br) * (LD) + (size_t)(kt) * 64); \
;     for (int _i = 0; _i < 2; ++_i) { int _b = tidx * 16 + _i * 8192; int _r, _c; stage_rc(_b, _r, _c); \
;       __builtin_amdgcn_global_load_lds((const unsigned*)(_g + (unsigned)((_r * (LD) + _c) * 2)), (unsigned*)((char*)(P) + _b), 16, 0, 0); } } while (0)
; #define LDA(dst, b, h) for (int m = 0; m < 4; ++m) for (int k = 0; k < 2; ++k) \
;     dst[m][k] = *reinterpret_cast<const bf16x8*>((char*)SA(b, h) + lds_byte(wr * 64 + m * 16 + fr, k * 32 + fq * 8))
; #define LDB(dst, b, h) for (int n = 0; n < 2; ++n) for (int k = 0; k < 2; ++k) \
;     dst[n][k] = *reinterpret_cast<const bf16x8*>((char*)SB(b, h) + lds_byte(wc * 32 + n * 16 + fr, k * 32 + fq * 8))
; #define MMA(ai, bj, At_, Bt_) do { __builtin_amdgcn_s_setprio(1); \
;     for (int k = 0; k < 2; ++k) for (int m = 0; m < 4; ++m) for (int n = 0; n < 2; ++n) \
;       acc[ai][bj][m][n] = __builtin_amdgcn_mfma_f32_16x16x32_bf16(At_[m][k], Bt_[n][k], acc[ai][bj][m][n], 0, 0, 0); \
;     __builtin_amdgcn_s_setprio(0); } while (0)
; #define WAIT_V(n) asm volatile("s_waitcnt vmcnt(" #n ")" ::: "memory")
; #define WAIT_L(n) asm volatile("s_waitcnt lgkmcnt(" #n ")" ::: "memory")
; #define BAR __builtin_amdgcn_s_barrier()
; #define SCHED __builtin_amdgcn_sched_barrier(0)
; template <int EPI, int lda, int ldb, int N, int K>
; __device__ __forceinline__ void gemm_phase(const u16* __restrict__ A, const u16* __restrict__ Bt, const GemmEpi ep, int wv) {
;     ...
;       LDA(At, 1, 1); STAGE(SA(1, 0), Ab, lda, brow, t + 3);
;       BAR; WAIT_L(0); MMA(1, 0, At, B0); BAR; SCHED;
;       STAGE(SB(1, 1), Bt, ldb, bcol + HALF, t + 3);
;       WAIT_V(6); BAR; MMA(1, 1, At, B1); BAR;
;     }
;     { LDB(B0, 0, 0); LDA(At, 0, 0); STAGE(SA(1, 1), Ab, lda, brow + HALF, nt - 1);
;       BAR; WAIT_L(0); MMA(0, 0, At, B0); BAR;
;       LDB(B1, 0, 1); BAR; WAIT_L(0); MMA(0, 1, At, B1); BAR;
;       LDA(At, 0, 1); WAIT_V(4); BAR; WAIT_L(0); MMA(1, 0, At, B0); MMA(1, 1, At, B1); BAR; }
	ds_read_b128 v[190:193], v154 offset:49152
	ds_read_b128 v[194:197], v154 offset:50176
	ds_read_b128 v[198:201], v153 offset:49152
	ds_read_b128 v[202:205], v153 offset:50176
	ds_read_b128 v[206:209], v151 offset:49152
	ds_read_b128 v[210:213], v151 offset:50176
	ds_read_b128 v[214:217], v150 offset:49152
	ds_read_b128 v[218:221], v150 offset:50176
	global_load_lds_dwordx4 v[238:239], off
	v_lshl_add_u64 v[238:239], v[240:241], 0, s[22:23]
	s_mov_b32 m0, s50
	s_nop 0
	global_load_lds_dwordx4 v[238:239], off
	s_barrier
	s_waitcnt lgkmcnt(0)
	s_waitcnt lgkmcnt(0)
	v_mfma_f32_16x16x32_bf16 v[60:63], v[190:193], v[174:177], v[60:63]
	v_mfma_f32_16x16x32_bf16 v[56:59], v[190:193], v[182:185], v[56:59]
	v_mfma_f32_16x16x32_bf16 v[52:55], v[198:201], v[174:177], v[52:55]
	v_mfma_f32_16x16x32_bf16 v[48:51], v[198:201], v[182:185], v[48:51]
	v_mfma_f32_16x16x32_bf16 v[44:47], v[206:209], v[174:177], v[44:47]
	v_mfma_f32_16x16x32_bf16 v[40:43], v[206:209], v[182:185], v[40:43]
	v_mfma_f32_16x16x32_bf16 v[36:39], v[214:217], v[174:177], v[36:39]
	v_mfma_f32_16x16x32_bf16 v[32:35], v[214:217], v[182:185], v[32:35]
	v_mfma_f32_16x16x32_bf16 v[60:63], v[194:197], v[178:181], v[60:63]
	v_mfma_f32_16x16x32_bf16 v[56:59], v[194:197], v[186:189], v[56:59]
	v_mfma_f32_16x16x32_bf16 v[52:55], v[202:205], v[178:181], v[52:55]
	v_mfma_f32_16x16x32_bf16 v[48:51], v[202:205], v[186:189], v[48:51]
	v_mfma_f32_16x16x32_bf16 v[44:47], v[210:213], v[178:181], v[44:47]
	v_mfma_f32_16x16x32_bf16 v[40:43], v[210:213], v[186:189], v[40:43]
	v_mfma_f32_16x16x32_bf16 v[36:39], v[218:221], v[178:181], v[36:39]
	v_mfma_f32_16x16x32_bf16 v[32:35], v[218:221], v[186:189], v[32:35]
	s_barrier
	v_readfirstlane_b32 s50, v161
	v_add_u32_e32 v173, 0x2000, v161
	v_lshl_add_u64 v[174:175], v[246:247], 0, s[24:25]
	s_mov_b32 m0, s50
	v_readfirstlane_b32 s50, v173
	global_load_lds_dwordx4 v[174:175], off
	v_lshl_add_u64 v[174:175], v[248:249], 0, s[24:25]
	s_mov_b32 m0, s50
	s_nop 0
	global_load_lds_dwordx4 v[174:175], off
	s_waitcnt vmcnt(8)
	s_barrier
	v_mfma_f32_16x16x32_bf16 v[28:31], v[190:193], v[222:225], v[28:31]
	v_mfma_f32_16x16x32_bf16 v[24:27], v[190:193], v[230:233], v[24:27]
	v_mfma_f32_16x16x32_bf16 v[20:23], v[198:201], v[222:225], v[20:23]
	v_mfma_f32_16x16x32_bf16 v[16:19], v[198:201], v[230:233], v[16:19]
	v_mfma_f32_16x16x32_bf16 v[12:15], v[206:209], v[222:225], v[12:15]
	v_mfma_f32_16x16x32_bf16 v[8:11], v[206:209], v[230:233], v[8:11]
	v_mfma_f32_16x16x32_bf16 v[4:7], v[214:217], v[222:225], v[4:7]
	v_mfma_f32_16x16x32_bf16 v[0:3], v[214:217], v[230:233], v[0:3]
	v_mfma_f32_16x16x32_bf16 v[28:31], v[194:197], v[226:229], v[28:31]
	v_mfma_f32_16x16x32_bf16 v[24:27], v[194:197], v[234:237], v[24:27]
	v_mfma_f32_16x16x32_bf16 v[20:23], v[202:205], v[226:229], v[20:23]
	v_mfma_f32_16x16x32_bf16 v[16:19], v[202:205], v[234:237], v[16:19]
	v_mfma_f32_16x16x32_bf16 v[12:15], v[210:213], v[226:229], v[12:15]
	v_mfma_f32_16x16x32_bf16 v[8:11], v[210:213], v[234:237], v[8:11]
	v_mfma_f32_16x16x32_bf16 v[4:7], v[218:221], v[226:229], v[4:7]
	v_mfma_f32_16x16x32_bf16 v[0:3], v[218:221], v[234:237], v[0:3]
	s_add_i32 s49, s49, 2
	s_add_u32 s28, s28, 0x100
	s_addc_u32 s29, s29, 0
	s_cmpk_gt_u32 s49, 0x51
	s_barrier
	s_cbranch_scc0 .LBB0_1624
	s_add_i32 s28, s48, 0x80
	s_mul_hi_i32 s29, s28, 0x2b00
	s_mulk_i32 s28, 0x2b00
	s_add_u32 s28, s34, s28
	s_addc_u32 s29, s35, s29
	s_add_u32 s28, s28, 0x2a80
	s_addc_u32 s29, s29, 0
	v_readfirstlane_b32 s49, v171
	v_lshl_add_u64 v[160:161], s[28:29], 0, v[128:129]
	s_mov_b32 m0, s49
	ds_read_b128 v[132:135], v163
	ds_read_b128 v[136:139], v163 offset:1024
	ds_read_b128 v[140:143], v163 offset:2048
	ds_read_b128 v[174:177], v163 offset:3072
	ds_read_b128 v[178:181], v154
	ds_read_b128 v[182:185], v154 offset:1024
	ds_read_b128 v[186:189], v153
	ds_read_b128 v[190:193], v153 offset:1024
	ds_read_b128 v[194:197], v151
	ds_read_b128 v[198:201], v151 offset:1024
	ds_read_b128 v[202:205], v150
	ds_read_b128 v[206:209], v150 offset:1024
	global_load_lds_dwordx4 v[160:161], off
	v_lshl_add_u64 v[160:161], s[28:29], 0, v[130:131]
	v_readfirstlane_b32 s28, v172
	s_mov_b32 m0, s28
	s_nop 0
	global_load_lds_dwordx4 v[160:161], off
	s_barrier
	s_waitcnt lgkmcnt(0)
	s_waitcnt lgkmcnt(0)
	v_mfma_f32_16x16x32_bf16 v[124:127], v[178:181], v[132:135], v[124:127]
	v_mfma_f32_16x16x32_bf16 v[120:123], v[178:181], v[140:143], v[120:123]
	v_mfma_f32_16x16x32_bf16 v[116:119], v[186:189], v[132:135], v[116:119]
	v_mfma_f32_16x16x32_bf16 v[112:115], v[186:189], v[140:143], v[112:115]
	v_mfma_f32_16x16x32_bf16 v[108:111], v[194:197], v[132:135], v[108:111]
	v_mfma_f32_16x16x32_bf16 v[104:107], v[194:197], v[140:143], v[104:107]
	v_mfma_f32_16x16x32_bf16 v[100:103], v[202:205], v[132:135], v[100:103]
	v_mfma_f32_16x16x32_bf16 v[96:99], v[202:205], v[140:143], v[96:99]
	v_mfma_f32_16x16x32_bf16 v[124:127], v[182:185], v[136:139], v[124:127]
	v_mfma_f32_16x16x32_bf16 v[120:123], v[182:185], v[174:177], v[120:123]
	v_mfma_f32_16x16x32_bf16 v[116:119], v[190:193], v[136:139], v[116:119]
	v_mfma_f32_16x16x32_bf16 v[112:115], v[190:193], v[174:177], v[112:115]
	v_mfma_f32_16x16x32_bf16 v[108:111], v[198:201], v[136:139], v[108:111]
	v_mfma_f32_16x16x32_bf16 v[104:107], v[198:201], v[174:177], v[104:107]
	v_mfma_f32_16x16x32_bf16 v[100:103], v[206:209], v[136:139], v[100:103]
	v_mfma_f32_16x16x32_bf16 v[96:99], v[206:209], v[174:177], v[96:99]
	s_barrier
	ds_read_b128 v[210:213], v162
	ds_read_b128 v[214:217], v162 offset:1024
	ds_read_b128 v[218:221], v162 offset:2048
	ds_read_b128 v[160:163], v162 offset:3072
	s_waitcnt vmcnt(8)
	s_barrier
; #define LDA(dst, b, h) for (int m = 0; m < 4; ++m) for (int k = 0; k < 2; ++k) \
;     dst[m][k] = *reinterpret_cast<const bf16x8*>((char*)SA(b, h) + lds_byte(wr * 64 + m * 16 + fr, k * 32 + fq * 8))
; #define LDB(dst, b, h) for (int n = 0; n < 2; ++n) for (int k = 0; k < 2; ++k) \
;     dst[n][k] = *reinterpret_cast<const bf16x8*>((char*)SB(b, h) + lds_byte(wc * 32 + n * 16 + fr, k * 32 + fq * 8))
; #define MMA(ai, bj, At_, Bt_) do { __builtin_amdgcn_s_setprio(1); \
;     for (int k = 0; k < 2; ++k) for (int m = 0; m < 4; ++m) for (int n = 0; n < 2; ++n) \
;       acc[ai][bj][m][n] = __builtin_amdgcn_mfma_f32_16x16x32_bf16(At_[m][k], Bt_[n][k], acc[ai][bj][m][n], 0, 0, 0); \
;     __builtin_amdgcn_s_setprio(0); } while (0)
; #define WAIT_V(n) asm volatile("s_waitcnt vmcnt(" #n ")" ::: "memory")
; #define WAIT_L(n) asm volatile("s_waitcnt lgkmcnt(" #n ")" ::: "memory")
; #define BAR __builtin_amdgcn_s_barrier()
; template <int EPI, int lda, int ldb, int N, int K>
; __device__ __forceinline__ void gemm_phase(const u16* __restrict__ A, const u16* __restrict__ Bt, const GemmEpi ep, int wv) {
;     ...
;       BAR; WAIT_L(0); MMA(0, 0, At, B0); BAR;
;       LDB(B1, 0, 1); BAR; WAIT_L(0); MMA(0, 1, At, B1); BAR;
;       LDA(At, 0, 1); WAIT_V(4); BAR; WAIT_L(0); MMA(1, 0, At, B0); MMA(1, 1, At, B1); BAR; }
;     { LDB(B0, 1, 0); LDA(At, 1, 0); WAIT_V(2); BAR; WAIT_L(0); MMA(0, 0, At, B0); BAR;
	s_waitcnt lgkmcnt(0)
	s_waitcnt lgkmcnt(0)
	v_mfma_f32_16x16x32_bf16 v[92:95], v[178:181], v[210:213], v[92:95]
	v_mfma_f32_16x16x32_bf16 v[88:91], v[178:181], v[218:221], v[88:91]
	v_mfma_f32_16x16x32_bf16 v[72:75], v[194:197], v[218:221], v[72:75]
	v_mfma_f32_16x16x32_bf16 v[68:71], v[202:205], v[210:213], v[68:71]
	v_mfma_f32_16x16x32_bf16 v[84:87], v[186:189], v[210:213], v[84:87]
	v_mfma_f32_16x16x32_bf16 v[80:83], v[186:189], v[218:221], v[80:83]
	v_mfma_f32_16x16x32_bf16 v[76:79], v[194:197], v[210:213], v[76:79]
	v_mfma_f32_16x16x32_bf16 v[64:67], v[202:205], v[218:221], v[64:67]
	v_mfma_f32_16x16x32_bf16 v[92:95], v[182:185], v[214:217], v[92:95]
	v_mfma_f32_16x16x32_bf16 v[88:91], v[182:185], v[160:163], v[88:91]
	v_mfma_f32_16x16x32_bf16 v[72:75], v[198:201], v[160:163], v[72:75]
	v_mfma_f32_16x16x32_bf16 v[68:71], v[206:209], v[214:217], v[68:71]
	v_mfma_f32_16x16x32_bf16 v[178:181], v[190:193], v[214:217], v[84:87]
	v_mfma_f32_16x16x32_bf16 v[182:185], v[190:193], v[160:163], v[80:83]
	v_mfma_f32_16x16x32_bf16 v[186:189], v[198:201], v[214:217], v[76:79]
	v_mfma_f32_16x16x32_bf16 v[190:193], v[206:209], v[160:163], v[64:67]
	s_barrier
	s_nop 0
	ds_read_b128 v[64:67], v154 offset:16384
	ds_read_b128 v[76:79], v154 offset:17408
	ds_read_b128 v[80:83], v153 offset:16384
	ds_read_b128 v[84:87], v153 offset:17408
	ds_read_b128 v[194:197], v151 offset:16384
	ds_read_b128 v[198:201], v151 offset:17408
	ds_read_b128 v[202:205], v150 offset:16384
	ds_read_b128 v[206:209], v150 offset:17408
	s_waitcnt vmcnt(4)
	s_barrier
	s_waitcnt lgkmcnt(0)
	s_waitcnt lgkmcnt(0)
	v_mfma_f32_16x16x32_bf16 v[60:63], v[64:67], v[132:135], v[60:63]
	v_mfma_f32_16x16x32_bf16 v[56:59], v[64:67], v[140:143], v[56:59]
	v_mfma_f32_16x16x32_bf16 v[52:55], v[80:83], v[132:135], v[52:55]
	v_mfma_f32_16x16x32_bf16 v[48:51], v[80:83], v[140:143], v[48:51]
	v_mfma_f32_16x16x32_bf16 v[44:47], v[194:197], v[132:135], v[44:47]
	v_mfma_f32_16x16x32_bf16 v[40:43], v[194:197], v[140:143], v[40:43]
	v_mfma_f32_16x16x32_bf16 v[36:39], v[202:205], v[132:135], v[36:39]
	v_mfma_f32_16x16x32_bf16 v[32:35], v[202:205], v[140:143], v[32:35]
	v_mfma_f32_16x16x32_bf16 v[60:63], v[76:79], v[136:139], v[60:63]
	v_mfma_f32_16x16x32_bf16 v[56:59], v[76:79], v[174:177], v[56:59]
	v_mfma_f32_16x16x32_bf16 v[52:55], v[84:87], v[136:139], v[52:55]
	v_mfma_f32_16x16x32_bf16 v[48:51], v[84:87], v[174:177], v[48:51]
	v_mfma_f32_16x16x32_bf16 v[44:47], v[198:201], v[136:139], v[44:47]
	v_mfma_f32_16x16x32_bf16 v[40:43], v[198:201], v[174:177], v[40:43]
	v_mfma_f32_16x16x32_bf16 v[36:39], v[206:209], v[136:139], v[36:39]
	v_mfma_f32_16x16x32_bf16 v[32:35], v[206:209], v[174:177], v[32:35]
	v_mfma_f32_16x16x32_bf16 v[28:31], v[64:67], v[210:213], v[28:31]
	v_mfma_f32_16x16x32_bf16 v[24:27], v[64:67], v[218:221], v[24:27]
	v_mfma_f32_16x16x32_bf16 v[12:15], v[194:197], v[210:213], v[12:15]
	v_mfma_f32_16x16x32_bf16 v[8:11], v[194:197], v[218:221], v[8:11]
	v_mfma_f32_16x16x32_bf16 v[20:23], v[80:83], v[210:213], v[20:23]
	v_mfma_f32_16x16x32_bf16 v[16:19], v[80:83], v[218:221], v[16:19]
	v_mfma_f32_16x16x32_bf16 v[4:7], v[202:205], v[210:213], v[4:7]
	v_mfma_f32_16x16x32_bf16 v[0:3], v[202:205], v[218:221], v[0:3]
	v_mfma_f32_16x16x32_bf16 v[28:31], v[76:79], v[214:217], v[28:31]
	v_mfma_f32_16x16x32_bf16 v[24:27], v[76:79], v[160:163], v[24:27]
	v_mfma_f32_16x16x32_bf16 v[12:15], v[198:201], v[214:217], v[12:15]
	v_mfma_f32_16x16x32_bf16 v[8:11], v[198:201], v[160:163], v[8:11]
	v_mfma_f32_16x16x32_bf16 v[132:135], v[84:87], v[214:217], v[20:23]
	v_mfma_f32_16x16x32_bf16 v[136:139], v[84:87], v[160:163], v[16:19]
	v_mfma_f32_16x16x32_bf16 v[140:143], v[206:209], v[214:217], v[4:7]
	v_mfma_f32_16x16x32_bf16 v[160:163], v[206:209], v[160:163], v[0:3]
	s_barrier
	s_nop 0
	ds_read_b128 v[0:3], v158
	ds_read_b128 v[4:7], v158 offset:1024
	ds_read_b128 v[16:19], v158 offset:2048
	ds_read_b128 v[172:175], v158 offset:3072
	ds_read_b128 v[20:23], v154 offset:32768
	ds_read_b128 v[194:197], v154 offset:33792
	ds_read_b128 v[198:201], v153 offset:32768
	ds_read_b128 v[202:205], v153 offset:33792
	ds_read_b128 v[206:209], v151 offset:32768
	ds_read_b128 v[210:213], v151 offset:33792
	ds_read_b128 v[214:217], v150 offset:32768
	ds_read_b128 v[218:221], v150 offset:33792
	s_waitcnt vmcnt(2)
	s_barrier
; #define LDA(dst, b, h) for (int m = 0; m < 4; ++m) for (int k = 0; k < 2; ++k) \
;     dst[m][k] = *reinterpret_cast<const bf16x8*>((char*)SA(b, h) + lds_byte(wr * 64 + m * 16 + fr, k * 32 + fq * 8))
; #define LDB(dst, b, h) for (int n = 0; n < 2; ++n) for (int k = 0; k < 2; ++k) \
;     dst[n][k] = *reinterpret_cast<const bf16x8*>((char*)SB(b, h) + lds_byte(wc * 32 + n * 16 + fr, k * 32 + fq * 8))
; #define MMA(ai, bj, At_, Bt_) do { __builtin_amdgcn_s_setprio(1); \
;     for (int k = 0; k < 2; ++k) for (int m = 0; m < 4; ++m) for (int n = 0; n < 2; ++n) \
;       acc[ai][bj][m][n] = __builtin_amdgcn_mfma_f32_16x16x32_bf16(At_[m][k], Bt_[n][k], acc[ai][bj][m][n], 0, 0, 0); \
;     __builtin_amdgcn_s_setprio(0); } while (0)
; #define WAIT_V(n) asm volatile("s_waitcnt vmcnt(" #n ")" ::: "memory")
; #define WAIT_L(n) asm volatile("s_waitcnt lgkmcnt(" #n ")" ::: "memory")
; #define BAR __builtin_amdgcn_s_barrier()
; template <int EPI, int lda, int ldb, int N, int K>
; __device__ __forceinline__ void gemm_phase(const u16* __restrict__ A, const u16* __restrict__ Bt, const GemmEpi ep, int wv) {
;     ...
;     { LDB(B0, 1, 0); LDA(At, 1, 0); WAIT_V(2); BAR; WAIT_L(0); MMA(0, 0, At, B0); BAR;
;       LDB(B1, 1, 1); WAIT_V(0); BAR; WAIT_L(0); MMA(0, 1, At, B1); BAR;
;       LDA(At, 1, 1); BAR; WAIT_L(0); MMA(1, 0, At, B0); MMA(1, 1, At, B1); BAR; }
;     if (wr == 0) BAR;
	s_waitcnt lgkmcnt(0)
	s_waitcnt lgkmcnt(0)
	v_mfma_f32_16x16x32_bf16 v[64:67], v[20:23], v[0:3], v[124:127]
	v_mfma_f32_16x16x32_bf16 v[76:79], v[20:23], v[16:19], v[120:123]
	v_mfma_f32_16x16x32_bf16 v[80:83], v[198:201], v[0:3], v[116:119]
	v_mfma_f32_16x16x32_bf16 v[84:87], v[198:201], v[16:19], v[112:115]
	v_mfma_f32_16x16x32_bf16 v[108:111], v[206:209], v[0:3], v[108:111]
	v_mfma_f32_16x16x32_bf16 v[104:107], v[206:209], v[16:19], v[104:107]
	v_mfma_f32_16x16x32_bf16 v[120:123], v[214:217], v[0:3], v[100:103]
	v_mfma_f32_16x16x32_bf16 v[124:127], v[214:217], v[16:19], v[96:99]
	v_mfma_f32_16x16x32_bf16 v[116:119], v[194:197], v[4:7], v[64:67]
	v_mfma_f32_16x16x32_bf16 v[112:115], v[194:197], v[172:175], v[76:79]
	v_mfma_f32_16x16x32_bf16 v[100:103], v[202:205], v[4:7], v[80:83]
	v_mfma_f32_16x16x32_bf16 v[96:99], v[202:205], v[172:175], v[84:87]
	v_mfma_f32_16x16x32_bf16 v[84:87], v[210:213], v[4:7], v[108:111]
	v_mfma_f32_16x16x32_bf16 v[80:83], v[210:213], v[172:175], v[104:107]
	v_mfma_f32_16x16x32_bf16 v[76:79], v[218:221], v[4:7], v[120:123]
	v_mfma_f32_16x16x32_bf16 v[64:67], v[218:221], v[172:175], v[124:127]
	s_barrier
	ds_read_b128 v[222:225], v156
	ds_read_b128 v[226:229], v156 offset:1024
	ds_read_b128 v[230:233], v156 offset:2048
	ds_read_b128 v[156:159], v156 offset:3072
	s_waitcnt vmcnt(0)
	s_barrier
	s_waitcnt lgkmcnt(0)
	s_waitcnt lgkmcnt(0)
	v_mfma_f32_16x16x32_bf16 v[92:95], v[20:23], v[222:225], v[92:95]
	v_mfma_f32_16x16x32_bf16 v[20:23], v[20:23], v[230:233], v[88:91]
	v_mfma_f32_16x16x32_bf16 v[88:91], v[198:201], v[222:225], v[178:181]
	v_mfma_f32_16x16x32_bf16 v[104:107], v[198:201], v[230:233], v[182:185]
	v_mfma_f32_16x16x32_bf16 v[176:179], v[206:209], v[222:225], v[186:189]
	v_mfma_f32_16x16x32_bf16 v[72:75], v[206:209], v[230:233], v[72:75]
	v_mfma_f32_16x16x32_bf16 v[68:71], v[214:217], v[222:225], v[68:71]
	v_mfma_f32_16x16x32_bf16 v[180:183], v[214:217], v[230:233], v[190:193]
	v_mfma_f32_16x16x32_bf16 v[124:127], v[194:197], v[226:229], v[92:95]
	v_mfma_f32_16x16x32_bf16 v[120:123], v[194:197], v[156:159], v[20:23]
	v_mfma_f32_16x16x32_bf16 v[108:111], v[202:205], v[226:229], v[88:91]
	v_mfma_f32_16x16x32_bf16 v[104:107], v[202:205], v[156:159], v[104:107]
	v_mfma_f32_16x16x32_bf16 v[92:95], v[210:213], v[226:229], v[176:179]
	v_mfma_f32_16x16x32_bf16 v[88:91], v[210:213], v[156:159], v[72:75]
	v_mfma_f32_16x16x32_bf16 v[72:75], v[218:221], v[226:229], v[68:71]
	v_mfma_f32_16x16x32_bf16 v[68:71], v[218:221], v[156:159], v[180:183]
	s_barrier
	ds_read_b128 v[176:179], v154 offset:49152
	ds_read_b128 v[180:183], v154 offset:50176
	ds_read_b128 v[184:187], v153 offset:49152
	ds_read_b128 v[188:191], v153 offset:50176
	ds_read_b128 v[192:195], v151 offset:49152
	ds_read_b128 v[196:199], v151 offset:50176
	ds_read_b128 v[200:203], v150 offset:49152
	ds_read_b128 v[204:207], v150 offset:50176
	s_barrier
	s_waitcnt lgkmcnt(0)
	s_waitcnt lgkmcnt(0)
	v_mfma_f32_16x16x32_bf16 v[20:23], v[176:179], v[0:3], v[60:63]
	v_mfma_f32_16x16x32_bf16 v[56:59], v[176:179], v[16:19], v[56:59]
	v_mfma_f32_16x16x32_bf16 v[60:63], v[184:187], v[0:3], v[52:55]
	v_mfma_f32_16x16x32_bf16 v[208:211], v[184:187], v[16:19], v[48:51]
	v_mfma_f32_16x16x32_bf16 v[44:47], v[192:195], v[0:3], v[44:47]
	v_mfma_f32_16x16x32_bf16 v[40:43], v[192:195], v[16:19], v[40:43]
	v_mfma_f32_16x16x32_bf16 v[0:3], v[200:203], v[0:3], v[36:39]
	v_mfma_f32_16x16x32_bf16 v[212:215], v[200:203], v[16:19], v[32:35]
	v_mfma_f32_16x16x32_bf16 v[52:55], v[180:183], v[4:7], v[20:23]
	v_mfma_f32_16x16x32_bf16 v[48:51], v[180:183], v[172:175], v[56:59]
	v_mfma_f32_16x16x32_bf16 v[36:39], v[188:191], v[4:7], v[60:63]
	v_mfma_f32_16x16x32_bf16 v[32:35], v[188:191], v[172:175], v[208:211]
	v_mfma_f32_16x16x32_bf16 v[20:23], v[196:199], v[4:7], v[44:47]
	v_mfma_f32_16x16x32_bf16 v[16:19], v[196:199], v[172:175], v[40:43]
	v_mfma_f32_16x16x32_bf16 v[4:7], v[204:207], v[4:7], v[0:3]
	v_mfma_f32_16x16x32_bf16 v[0:3], v[204:207], v[172:175], v[212:215]
	v_mfma_f32_16x16x32_bf16 v[28:31], v[176:179], v[222:225], v[28:31]
	v_mfma_f32_16x16x32_bf16 v[24:27], v[176:179], v[230:233], v[24:27]
	v_mfma_f32_16x16x32_bf16 v[40:43], v[184:187], v[222:225], v[132:135]
	v_mfma_f32_16x16x32_bf16 v[132:135], v[184:187], v[230:233], v[136:139]
	v_mfma_f32_16x16x32_bf16 v[12:15], v[192:195], v[222:225], v[12:15]
	v_mfma_f32_16x16x32_bf16 v[8:11], v[192:195], v[230:233], v[8:11]
	v_mfma_f32_16x16x32_bf16 v[136:139], v[200:203], v[222:225], v[140:143]
	v_mfma_f32_16x16x32_bf16 v[140:143], v[200:203], v[230:233], v[160:163]
	v_mfma_f32_16x16x32_bf16 v[60:63], v[180:183], v[226:229], v[28:31]
	v_mfma_f32_16x16x32_bf16 v[56:59], v[180:183], v[156:159], v[24:27]
	v_mfma_f32_16x16x32_bf16 v[44:47], v[188:191], v[226:229], v[40:43]
	v_mfma_f32_16x16x32_bf16 v[40:43], v[188:191], v[156:159], v[132:135]
	v_mfma_f32_16x16x32_bf16 v[28:31], v[196:199], v[226:229], v[12:15]
	v_mfma_f32_16x16x32_bf16 v[24:27], v[196:199], v[156:159], v[8:11]
	v_mfma_f32_16x16x32_bf16 v[12:15], v[204:207], v[226:229], v[136:139]
	v_mfma_f32_16x16x32_bf16 v[8:11], v[204:207], v[156:159], v[140:143]
	v_cmp_gt_u32_e32 vcc, s46, v147
	s_barrier
	s_and_saveexec_b64 s[28:29], vcc
	s_cbranch_execz .LBB0_1627
	s_barrier
